# row-statistics partials stored slot-major: two rows per 16-byte piece, whole 128-byte lines (sites 0-2); both P11 table builds rewritten
# baseline (speedup 1.0000x reference)
; #define LAS __attribute__((address_space(3)))
;     __device__ __forceinline__ void operator()(const f32x4 (&acc)[2][2][4][2], const Unit& u, int wr, int wc, int fr, int fq, const EpiCtx& X) const {
;     ...
;         char* yb = nullptr; char* xb = (char*)(XB + (size_t)u.pm * BM * DM + (size_t)(u.pn * 4 + wc) * (BM * 64));
;         unsigned lo = (unsigned)((wr * 64 + fe) * 64 + o32 + 8 * fq) * 2u; EPI_OPAQUE(lo);
;         const int col = u.pn * BM + wc * 64 + o32 + 8 * fq;
;         f32x4 g0, g1, b0, b1;
;         if (RESN) { ensure_tbl(PSp, sidp, u.pm, X);
;             g0 = *(const f32x4*)(gp + col); g1 = *(const f32x4*)(gp + col + 4); b0 = *(const f32x4*)(bp + col) * ALPHA; b1 = *(const f32x4*)(bp + col + 4) * ALPHA; }
;         const LAS f32x2* tbl = (const LAS f32x2*)(X.lds + TBL_OFF) + wr * 64 + fe;
;         f32x2* ps = PSn + ((size_t)u.pm * BM + wr * 64 + fe) * 64 + u.pn * 4 + wc;
; #pragma unroll
;         for (int ai = 0; ai < 2; ++ai) {
;             u32x4 raw[8];
; #pragma unroll
;             for (int m = 0; m < 4; ++m) { const unsigned off = lo + (unsigned)((ai * HALF + m * 16) * 64) * 2u; raw[2 * m] = *(const u32x4*)(xb + off); raw[2 * m + 1] = *(const u32x4*)(xb + off + 128); }
; #pragma unroll
;             for (int m = 0; m < 4; ++m) {
;                 const int rl = ai * HALF + m * 16; const unsigned off = lo + (unsigned)(rl * 64) * 2u;
;                 const f32x4 o0a = acc[ai][0][m][0], o0b = acc[ai][0][m][1], o1a = acc[ai][1][m][0], o1b = acc[ai][1][m][1];
;                 const f32x4 ra_ = dpp_swap1(odd ? o0a : o1a), rb_ = dpp_swap1(odd ? o0b : o1b);
;                 const f32x4 pa[2] = {odd ? ra_ : o0a, odd ? o1a : ra_}, pb[2] = {odd ? rb_ : o0b, odd ? o1b : rb_};
; #pragma unroll
;                 for (int q = 0; q < 2; ++q) {
;                     const u32x4 w0 = raw[2 * m + q];
;                     const f32x4 r0 = (f32x4){bf_lo(w0.x), bf_hi(w0.x), bf_lo(w0.y), bf_hi(w0.y)}, r1 = (f32x4){bf_lo(w0.z), bf_hi(w0.z), bf_lo(w0.w), bf_hi(w0.w)};
;                     f32x4 y0, y1;
;                     if (RESN) { const f32x2 t = tbl[rl + q]; const float mu = t.x, ra = t.y * ALPHA; y0 = (r0 - mu) * ra * g0 + b0 + pa[q]; y1 = (r1 - mu) * ra * g1 + b1 + pb[q]; }
;                     else { y0 = r0 * ALPHA + pa[q]; y1 = r1 * ALPHA + pb[q]; }
;                     { const u32x4 w = pack8f(y0, y1); *(u32x4*)(xb + off + q * 128) = w;
.LBB0_582:
	s_ashr_i32 s57, s56, 31
	s_load_dwordx2 s[94:95], s[0:1], 0xb0
	s_lshl_b32 s52, s54, 2
	s_or_b32 s52, s52, s41
	s_lshl_b32 s52, s52, 17
	s_lshl_b32 s53, s56, 11
	s_add_u32 s52, s52, s53
	s_add_u32 s52, s52, 0x5b800000
	v_lshrrev_b32_e32 v249, 4, v183
	s_waitcnt lgkmcnt(0)
	s_add_u32 s94, s94, s52
	s_addc_u32 s95, s95, 0
	s_lshl_b64 s[52:53], s[56:57], 21
	s_add_u32 s21, s46, s52
	s_addc_u32 s23, s47, s53
	s_lshl_b32 s58, s54, 2
	s_or_b32 s52, s58, s41
	s_ashr_i32 s53, s52, 31
	s_lshl_b64 s[52:53], s[52:53], 15
	s_add_u32 s54, s21, s52
	s_addc_u32 s55, s23, s53
	v_mov_b32_e32 v164, v183
	global_load_dwordx4 v[194:197], v164, s[54:55]
	v_add_u32_e32 v180, 0x800, v164
	v_add_u32_e32 v178, 0x1000, v164
	v_add_u32_e32 v176, 0x1800, v164
	global_load_dwordx4 v[152:155], v164, s[54:55] offset:128
	global_load_dwordx4 v[148:151], v180, s[54:55]
	global_load_dwordx4 v[144:147], v180, s[54:55] offset:128
	global_load_dwordx4 v[140:143], v178, s[54:55]
	global_load_dwordx4 v[136:139], v178, s[54:55] offset:128
	global_load_dwordx4 v[132:135], v176, s[54:55]
	global_load_dwordx4 v[120:123], v176, s[54:55] offset:128
	v_cndmask_b32_e64 v199, v129, v117, s[8:9]
	v_cndmask_b32_e64 v200, v128, v116, s[8:9]
	v_mov_b32_e32 v177, 0
	v_mov_b32_e32 v181, 0
	v_cndmask_b32_e64 v201, v127, v115, s[8:9]
	v_cndmask_b32_e64 v202, v126, v114, s[8:9]
	v_cndmask_b32_e64 v203, v125, v113, s[8:9]
	v_cndmask_b32_e64 v204, v124, v112, s[8:9]
	v_mov_b32_e32 v189, 0
	v_mov_b32_e32 v191, 0
	v_mov_b32_e32 v190, 0
	v_mov_b32_e32 v192, 0
	v_cndmask_b32_e64 v193, v131, v119, s[8:9]
	v_cndmask_b32_e64 v198, v130, v118, s[8:9]
	v_mov_b32_e32 v179, 0
	v_mov_b32_e32 v188, 0
	v_mov_b32_dpp v177, v200 quad_perm:[1,0,3,2] row_mask:0xf bank_mask:0xf
	v_mov_b32_dpp v181, v199 quad_perm:[1,0,3,2] row_mask:0xf bank_mask:0xf
	v_mov_b32_dpp v189, v204 quad_perm:[1,0,3,2] row_mask:0xf bank_mask:0xf
	v_mov_b32_dpp v191, v203 quad_perm:[1,0,3,2] row_mask:0xf bank_mask:0xf
	v_mov_b32_dpp v190, v202 quad_perm:[1,0,3,2] row_mask:0xf bank_mask:0xf
	v_mov_b32_dpp v192, v201 quad_perm:[1,0,3,2] row_mask:0xf bank_mask:0xf
	v_mov_b32_dpp v179, v198 quad_perm:[1,0,3,2] row_mask:0xf bank_mask:0xf
	v_mov_b32_dpp v188, v193 quad_perm:[1,0,3,2] row_mask:0xf bank_mask:0xf
	v_cndmask_b32_e64 v129, v181, v129, s[8:9]
	v_cndmask_b32_e64 v128, v177, v128, s[8:9]
	v_cndmask_b32_e64 v125, v191, v125, s[8:9]
	v_cndmask_b32_e64 v124, v189, v124, s[8:9]
	v_cndmask_b32_e64 v127, v192, v127, s[8:9]
	v_cndmask_b32_e64 v126, v190, v126, s[8:9]
	v_and_b32_e32 v206, 64, v187
	v_cndmask_b32_e64 v131, v188, v131, s[8:9]
	v_cndmask_b32_e64 v130, v179, v130, s[8:9]
	v_xor_b32_e32 v205, 16, v187
	v_add_u32_e32 v193, 64, v206
	v_cmp_lt_i32_e32 vcc, v205, v193
	s_lshl_b64 s[52:53], s[56:57], 17
	v_lshl_add_u64 v[198:199], v[166:167], 0, s[52:53]
	v_cndmask_b32_e32 v210, v187, v205, vcc
	s_ashr_i32 s59, s58, 31
	v_add_u32_e32 v246, 0x4000, v164
	v_add_u32_e32 v247, 0x4800, v164
	global_load_dwordx4 v[230:233], v246, s[54:55]
	global_load_dwordx4 v[234:237], v246, s[54:55] offset:128
	global_load_dwordx4 v[238:241], v247, s[54:55]
	global_load_dwordx4 v[242:245], v247, s[54:55] offset:128
	s_waitcnt vmcnt(0)
	v_lshlrev_b32_e32 v200, 16, v194
	v_and_b32_e32 v201, 0xffff0000, v194
	v_lshlrev_b32_e32 v202, 16, v196
	v_and_b32_e32 v203, 0xffff0000, v196
	v_lshlrev_b32_e32 v196, 16, v197
	v_and_b32_e32 v197, 0xffff0000, v197
	v_lshlrev_b32_e32 v194, 16, v195
	v_and_b32_e32 v195, 0xffff0000, v195
	v_pk_fma_f32 v[128:129], v[200:201], s[18:19], v[128:129] op_sel_hi:[1,0,1]
	v_pk_fma_f32 v[126:127], v[196:197], s[18:19], v[126:127] op_sel_hi:[1,0,1]
	v_pk_fma_f32 v[124:125], v[202:203], s[18:19], v[124:125] op_sel_hi:[1,0,1]
	v_pk_fma_f32 v[130:131], v[194:195], s[18:19], v[130:131] op_sel_hi:[1,0,1]
	v_cvt_pk_bf16_f32 v194, v128, v129
	s_nop 0
	v_cvt_pk_bf16_f32 v195, v130, v131
	v_cvt_pk_bf16_f32 v196, v124, v125
	v_cvt_pk_bf16_f32 v197, v126, v127
	v_lshlrev_b32_e32 v124, 16, v194
	v_and_b32_e32 v126, 0xffff0000, v194
	v_lshlrev_b32_e32 v128, 16, v195
	v_and_b32_e32 v200, 0xffff0000, v195
	v_lshlrev_b32_e32 v202, 16, v196
	v_and_b32_e32 v204, 0xffff0000, v196
	v_lshlrev_b32_e32 v206, 16, v197
	v_and_b32_e32 v208, 0xffff0000, v197
	v_mul_f32_e32 v125, v124, v124
	v_mul_f32_e32 v127, v126, v126
	v_mul_f32_e32 v129, v128, v128
	v_mul_f32_e32 v201, v200, v200
	v_mul_f32_e32 v203, v202, v202
	v_mul_f32_e32 v205, v204, v204
	v_mul_f32_e32 v207, v206, v206
	v_mul_f32_e32 v209, v208, v208
	v_pk_add_f32 v[124:125], v[124:125], v[126:127]
	v_pk_add_f32 v[126:127], v[128:129], v[200:201]
	v_pk_add_f32 v[128:129], v[206:207], v[208:209]
	v_pk_add_f32 v[124:125], v[124:125], v[126:127]
	v_pk_add_f32 v[126:127], v[202:203], v[204:205]
	v_lshlrev_b32_e32 v130, 2, v210
	v_pk_add_f32 v[126:127], v[126:127], v[128:129]
	v_xor_b32_e32 v128, 32, v187
	v_pk_add_f32 v[124:125], v[124:125], v[126:127]
	v_mov_b32_e32 v126, 0
	v_mov_b32_e32 v127, 0
	v_cmp_lt_i32_e32 vcc, v128, v193
	v_mov_b32_dpp v126, v124 quad_perm:[1,0,3,2] row_mask:0xf bank_mask:0xf
	v_mov_b32_dpp v127, v125 quad_perm:[1,0,3,2] row_mask:0xf bank_mask:0xf
	v_pk_add_f32 v[124:125], v[124:125], v[126:127]
	ds_bpermute_b32 v126, v130, v124
	ds_bpermute_b32 v127, v130, v125
	v_cndmask_b32_e32 v128, v187, v128, vcc
	v_lshlrev_b32_e32 v131, 2, v128
	global_store_dwordx4 v164, v[194:197], s[54:55]
	s_waitcnt lgkmcnt(0)
	v_pk_add_f32 v[126:127], v[124:125], v[126:127]
	ds_bpermute_b32 v128, v131, v126
	ds_bpermute_b32 v129, v131, v127
	v_lshl_add_u64 v[124:125], s[58:59], 3, v[198:199]
	v_lshl_add_u64 v[124:125], v[124:125], 0, s[14:15]
	s_and_saveexec_b64 s[52:53], s[10:11]
	s_cbranch_execz .LBB0_584
	s_waitcnt lgkmcnt(0)
	v_pk_add_f32 v[126:127], v[126:127], v[128:129]
	v_mov_b32_e32 v250, v126
	v_mov_b32_e32 v251, v127
;     __device__ __forceinline__ void operator()(const f32x4 (&acc)[2][2][4][2], const Unit& u, int wr, int wc, int fr, int fq, const EpiCtx& X) const {
;     ...
;             for (int m = 0; m < 4; ++m) { const unsigned off = lo + (unsigned)((ai * HALF + m * 16) * 64) * 2u; raw[2 * m] = *(const u32x4*)(xb + off); raw[2 * m + 1] = *(const u32x4*)(xb + off + 128); }
; #pragma unroll
;             for (int m = 0; m < 4; ++m) {
;                 const int rl = ai * HALF + m * 16; const unsigned off = lo + (unsigned)(rl * 64) * 2u;
;                 const f32x4 o0a = acc[ai][0][m][0], o0b = acc[ai][0][m][1], o1a = acc[ai][1][m][0], o1b = acc[ai][1][m][1];
;                 const f32x4 ra_ = dpp_swap1(odd ? o0a : o1a), rb_ = dpp_swap1(odd ? o0b : o1b);
;                 const f32x4 pa[2] = {odd ? ra_ : o0a, odd ? o1a : ra_}, pb[2] = {odd ? rb_ : o0b, odd ? o1b : rb_};
; #pragma unroll
;                 for (int q = 0; q < 2; ++q) {
;                     const u32x4 w0 = raw[2 * m + q];
;                     const f32x4 r0 = (f32x4){bf_lo(w0.x), bf_hi(w0.x), bf_lo(w0.y), bf_hi(w0.y)}, r1 = (f32x4){bf_lo(w0.z), bf_hi(w0.z), bf_lo(w0.w), bf_hi(w0.w)};
;                     f32x4 y0, y1;
;                     if (RESN) { const f32x2 t = tbl[rl + q]; const float mu = t.x, ra = t.y * ALPHA; y0 = (r0 - mu) * ra * g0 + b0 + pa[q]; y1 = (r1 - mu) * ra * g1 + b1 + pb[q]; }
;                     else { y0 = r0 * ALPHA + pa[q]; y1 = r1 * ALPHA + pb[q]; }
;                     { const u32x4 w = pack8f(y0, y1); *(u32x4*)(xb + off + q * 128) = w;
;                         y0 = (f32x4){bf_lo(w.x), bf_hi(w.x), bf_lo(w.y), bf_hi(w.y)}; y1 = (f32x4){bf_lo(w.z), bf_hi(w.z), bf_lo(w.w), bf_hi(w.w)}; }
;                     float sa = ((y0[0] + y0[1]) + (y0[2] + y0[3])) + ((y1[0] + y1[1]) + (y1[2] + y1[3]));
;                     float sb = ((y0[0] * y0[0] + y0[1] * y0[1]) + (y0[2] * y0[2] + y0[3] * y0[3])) + ((y1[0] * y1[0] + y1[1] * y1[1]) + (y1[2] * y1[2] + y1[3] * y1[3]));
;                     sa += dpp_x1(sa);
;                     sb += dpp_x1(sb);
;                     sa += __shfl_xor(sa, 16); sa += __shfl_xor(sa, 32); sb += __shfl_xor(sb, 16); sb += __shfl_xor(sb, 32);
;                     if (fq == 0 && !odd) ps[(size_t)(rl + q) * 64] = (f32x2){sa, sb};
.LBB0_584:
	s_or_b64 exec, exec, s[52:53]
	v_cndmask_b32_e64 v117, v117, v181, s[8:9]
	v_cndmask_b32_e64 v116, v116, v177, s[8:9]
	v_cndmask_b32_e64 v119, v119, v188, s[8:9]
	v_cndmask_b32_e64 v118, v118, v179, s[8:9]
	v_cndmask_b32_e64 v113, v113, v191, s[8:9]
	v_cndmask_b32_e64 v112, v112, v189, s[8:9]
	v_cndmask_b32_e64 v115, v115, v192, s[8:9]
	v_cndmask_b32_e64 v114, v114, v190, s[8:9]
	v_lshlrev_b32_e32 v126, 16, v152
	v_and_b32_e32 v127, 0xffff0000, v152
	s_waitcnt lgkmcnt(1)
	v_lshlrev_b32_e32 v128, 16, v153
	s_waitcnt lgkmcnt(0)
	v_and_b32_e32 v129, 0xffff0000, v153
	v_lshlrev_b32_e32 v152, 16, v154
	v_and_b32_e32 v153, 0xffff0000, v154
	v_lshlrev_b32_e32 v154, 16, v155
	v_and_b32_e32 v155, 0xffff0000, v155
	v_pk_fma_f32 v[118:119], v[128:129], s[18:19], v[118:119] op_sel_hi:[1,0,1]
	v_pk_fma_f32 v[116:117], v[126:127], s[18:19], v[116:117] op_sel_hi:[1,0,1]
	v_pk_fma_f32 v[114:115], v[154:155], s[18:19], v[114:115] op_sel_hi:[1,0,1]
	v_pk_fma_f32 v[112:113], v[152:153], s[18:19], v[112:113] op_sel_hi:[1,0,1]
	v_cvt_pk_bf16_f32 v116, v116, v117
	v_cvt_pk_bf16_f32 v117, v118, v119
	s_nop 0
	v_cvt_pk_bf16_f32 v118, v112, v113
	v_cvt_pk_bf16_f32 v119, v114, v115
	v_lshlrev_b32_e32 v112, 16, v116
	v_and_b32_e32 v114, 0xffff0000, v116
	v_lshlrev_b32_e32 v126, 16, v117
	v_and_b32_e32 v128, 0xffff0000, v117
	v_lshlrev_b32_e32 v152, 16, v118
	v_and_b32_e32 v154, 0xffff0000, v118
	v_lshlrev_b32_e32 v188, 16, v119
	v_and_b32_e32 v190, 0xffff0000, v119
	v_mul_f32_e32 v113, v112, v112
	v_mul_f32_e32 v115, v114, v114
	v_mul_f32_e32 v127, v126, v126
	v_mul_f32_e32 v129, v128, v128
	v_mul_f32_e32 v153, v152, v152
	v_mul_f32_e32 v155, v154, v154
	v_mul_f32_e32 v189, v188, v188
	v_mul_f32_e32 v191, v190, v190
	v_pk_add_f32 v[112:113], v[112:113], v[114:115]
	v_pk_add_f32 v[114:115], v[126:127], v[128:129]
	v_pk_add_f32 v[126:127], v[188:189], v[190:191]
	v_pk_add_f32 v[112:113], v[112:113], v[114:115]
	v_pk_add_f32 v[114:115], v[152:153], v[154:155]
	s_nop 0
	v_pk_add_f32 v[114:115], v[114:115], v[126:127]
	v_lshl_add_u64 v[126:127], s[54:55], 0, v[164:165]
	v_pk_add_f32 v[112:113], v[112:113], v[114:115]
	v_mov_b32_e32 v114, v165
	v_mov_b32_e32 v115, v165
	global_store_dwordx4 v[126:127], v[116:119], off offset:128
	v_mov_b32_dpp v114, v112 quad_perm:[1,0,3,2] row_mask:0xf bank_mask:0xf
	v_mov_b32_dpp v115, v113 quad_perm:[1,0,3,2] row_mask:0xf bank_mask:0xf
	v_pk_add_f32 v[112:113], v[112:113], v[114:115]
	ds_bpermute_b32 v114, v130, v112
	ds_bpermute_b32 v115, v130, v113
	s_waitcnt lgkmcnt(0)
	v_pk_add_f32 v[112:113], v[112:113], v[114:115]
	ds_bpermute_b32 v114, v131, v112
	ds_bpermute_b32 v115, v131, v113
	s_and_saveexec_b64 s[52:53], s[10:11]
	s_cbranch_execz .LBB0_586
	s_waitcnt lgkmcnt(0)
	v_pk_add_f32 v[112:113], v[112:113], v[114:115]
	v_mov_b32_e32 v252, v250
	v_mov_b32_e32 v253, v251
	v_mov_b32_e32 v254, v112
	v_mov_b32_e32 v255, v113
	global_store_dwordx4 v249, v[252:255], s[94:95]
.LBB0_586:
	s_or_b64 exec, exec, s[52:53]
	s_waitcnt lgkmcnt(1)
	v_cndmask_b32_e64 v114, v108, v100, s[8:9]
	v_mov_b32_e32 v112, 0
	v_cndmask_b32_e64 v113, v109, v101, s[8:9]
	s_waitcnt lgkmcnt(0)
	v_cndmask_b32_e64 v115, v110, v102, s[8:9]
	v_mov_b32_dpp v112, v114 quad_perm:[1,0,3,2] row_mask:0xf bank_mask:0xf
	v_mov_b32_e32 v114, 0
	v_cndmask_b32_e64 v116, v111, v103, s[8:9]
	v_cndmask_b32_e64 v118, v104, v96, s[8:9]
	v_mov_b32_dpp v114, v113 quad_perm:[1,0,3,2] row_mask:0xf bank_mask:0xf
	v_mov_b32_e32 v113, 0
	v_cndmask_b32_e64 v117, v105, v97, s[8:9]
	v_cndmask_b32_e64 v119, v106, v98, s[8:9]
	v_mov_b32_dpp v113, v115 quad_perm:[1,0,3,2] row_mask:0xf bank_mask:0xf
	v_mov_b32_e32 v115, 0
	v_cndmask_b32_e64 v126, v107, v99, s[8:9]
	v_cndmask_b32_e64 v109, v114, v109, s[8:9]
	v_mov_b32_dpp v115, v116 quad_perm:[1,0,3,2] row_mask:0xf bank_mask:0xf
	v_mov_b32_e32 v116, 0
	v_cndmask_b32_e64 v108, v112, v108, s[8:9]
	v_cndmask_b32_e64 v111, v115, v111, s[8:9]
	v_mov_b32_dpp v116, v118 quad_perm:[1,0,3,2] row_mask:0xf bank_mask:0xf
	v_mov_b32_e32 v118, 0
	v_cndmask_b32_e64 v110, v113, v110, s[8:9]
	v_cndmask_b32_e64 v104, v116, v104, s[8:9]
	v_mov_b32_dpp v118, v117 quad_perm:[1,0,3,2] row_mask:0xf bank_mask:0xf
	v_mov_b32_e32 v117, 0
	v_cndmask_b32_e64 v105, v118, v105, s[8:9]
	v_and_b32_e32 v127, 0xffff0000, v148
	v_mov_b32_dpp v117, v119 quad_perm:[1,0,3,2] row_mask:0xf bank_mask:0xf
	v_mov_b32_e32 v119, 0
	v_cndmask_b32_e64 v106, v117, v106, s[8:9]
	v_lshlrev_b32_e32 v128, 16, v149
	v_mov_b32_dpp v119, v126 quad_perm:[1,0,3,2] row_mask:0xf bank_mask:0xf
	v_cndmask_b32_e64 v107, v119, v107, s[8:9]
	v_lshlrev_b32_e32 v126, 16, v148
	v_and_b32_e32 v129, 0xffff0000, v149
	v_lshlrev_b32_e32 v148, 16, v150
	v_and_b32_e32 v149, 0xffff0000, v150
	v_lshlrev_b32_e32 v150, 16, v151
	v_and_b32_e32 v151, 0xffff0000, v151
	v_pk_fma_f32 v[110:111], v[128:129], s[18:19], v[110:111] op_sel_hi:[1,0,1]
	v_pk_fma_f32 v[108:109], v[126:127], s[18:19], v[108:109] op_sel_hi:[1,0,1]
	v_pk_fma_f32 v[106:107], v[150:151], s[18:19], v[106:107] op_sel_hi:[1,0,1]
	v_pk_fma_f32 v[104:105], v[148:149], s[18:19], v[104:105] op_sel_hi:[1,0,1]
	v_cvt_pk_bf16_f32 v126, v108, v109
	v_cvt_pk_bf16_f32 v127, v110, v111
	v_mov_b32_e32 v181, v165
	v_cvt_pk_bf16_f32 v128, v104, v105
	v_cvt_pk_bf16_f32 v129, v106, v107
	v_lshlrev_b32_e32 v104, 16, v126
	v_and_b32_e32 v106, 0xffff0000, v126
	v_lshlrev_b32_e32 v108, 16, v127
	v_and_b32_e32 v110, 0xffff0000, v127
	v_lshlrev_b32_e32 v148, 16, v128
	v_and_b32_e32 v150, 0xffff0000, v128
	v_lshlrev_b32_e32 v152, 16, v129
	v_and_b32_e32 v154, 0xffff0000, v129
	v_mul_f32_e32 v105, v104, v104
	v_mul_f32_e32 v107, v106, v106
	v_mul_f32_e32 v109, v108, v108
	v_mul_f32_e32 v111, v110, v110
	v_mul_f32_e32 v149, v148, v148
	v_mul_f32_e32 v151, v150, v150
	v_mul_f32_e32 v153, v152, v152
	v_mul_f32_e32 v155, v154, v154
	v_pk_add_f32 v[104:105], v[104:105], v[106:107]
	v_pk_add_f32 v[106:107], v[108:109], v[110:111]
	v_pk_add_f32 v[108:109], v[152:153], v[154:155]
	v_pk_add_f32 v[104:105], v[104:105], v[106:107]
	v_pk_add_f32 v[106:107], v[148:149], v[150:151]
	s_nop 0
	v_pk_add_f32 v[106:107], v[106:107], v[108:109]
	s_nop 0
	v_pk_add_f32 v[104:105], v[104:105], v[106:107]
	v_mov_b32_e32 v106, v165
	v_mov_b32_e32 v107, v165
	s_nop 0
	v_mov_b32_dpp v106, v104 quad_perm:[1,0,3,2] row_mask:0xf bank_mask:0xf
	v_mov_b32_dpp v107, v105 quad_perm:[1,0,3,2] row_mask:0xf bank_mask:0xf
	v_pk_add_f32 v[104:105], v[104:105], v[106:107]
	ds_bpermute_b32 v106, v130, v104
	ds_bpermute_b32 v107, v130, v105
	s_waitcnt lgkmcnt(0)
	v_pk_add_f32 v[106:107], v[104:105], v[106:107]
	ds_bpermute_b32 v108, v131, v106
	ds_bpermute_b32 v109, v131, v107
	v_lshl_add_u64 v[104:105], s[54:55], 0, v[180:181]
	global_store_dwordx4 v[104:105], v[126:129], off
	s_and_saveexec_b64 s[56:57], s[10:11]
	s_cbranch_execz .LBB0_588
	s_waitcnt lgkmcnt(0)
	v_pk_add_f32 v[106:107], v[106:107], v[108:109]
	v_add_co_u32_e32 v108, vcc, 0x2000, v124
	s_nop 1
	v_addc_co_u32_e32 v109, vcc, 0, v125, vcc
	v_mov_b32_e32 v250, v106
	v_mov_b32_e32 v251, v107
;     __device__ __forceinline__ void operator()(const f32x4 (&acc)[2][2][4][2], const Unit& u, int wr, int wc, int fr, int fq, const EpiCtx& X) const {
;     ...
;             for (int m = 0; m < 4; ++m) { const unsigned off = lo + (unsigned)((ai * HALF + m * 16) * 64) * 2u; raw[2 * m] = *(const u32x4*)(xb + off); raw[2 * m + 1] = *(const u32x4*)(xb + off + 128); }
; #pragma unroll
;             for (int m = 0; m < 4; ++m) {
;                 const int rl = ai * HALF + m * 16; const unsigned off = lo + (unsigned)(rl * 64) * 2u;
;                 const f32x4 o0a = acc[ai][0][m][0], o0b = acc[ai][0][m][1], o1a = acc[ai][1][m][0], o1b = acc[ai][1][m][1];
;                 const f32x4 ra_ = dpp_swap1(odd ? o0a : o1a), rb_ = dpp_swap1(odd ? o0b : o1b);
;                 const f32x4 pa[2] = {odd ? ra_ : o0a, odd ? o1a : ra_}, pb[2] = {odd ? rb_ : o0b, odd ? o1b : rb_};
; #pragma unroll
;                 for (int q = 0; q < 2; ++q) {
;                     const u32x4 w0 = raw[2 * m + q];
;                     const f32x4 r0 = (f32x4){bf_lo(w0.x), bf_hi(w0.x), bf_lo(w0.y), bf_hi(w0.y)}, r1 = (f32x4){bf_lo(w0.z), bf_hi(w0.z), bf_lo(w0.w), bf_hi(w0.w)};
;                     f32x4 y0, y1;
;                     if (RESN) { const f32x2 t = tbl[rl + q]; const float mu = t.x, ra = t.y * ALPHA; y0 = (r0 - mu) * ra * g0 + b0 + pa[q]; y1 = (r1 - mu) * ra * g1 + b1 + pb[q]; }
;                     else { y0 = r0 * ALPHA + pa[q]; y1 = r1 * ALPHA + pb[q]; }
;                     { const u32x4 w = pack8f(y0, y1); *(u32x4*)(xb + off + q * 128) = w;
;                         y0 = (f32x4){bf_lo(w.x), bf_hi(w.x), bf_lo(w.y), bf_hi(w.y)}; y1 = (f32x4){bf_lo(w.z), bf_hi(w.z), bf_lo(w.w), bf_hi(w.w)}; }
;                     float sa = ((y0[0] + y0[1]) + (y0[2] + y0[3])) + ((y1[0] + y1[1]) + (y1[2] + y1[3]));
;                     float sb = ((y0[0] * y0[0] + y0[1] * y0[1]) + (y0[2] * y0[2] + y0[3] * y0[3])) + ((y1[0] * y1[0] + y1[1] * y1[1]) + (y1[2] * y1[2] + y1[3] * y1[3]));
;                     sa += dpp_x1(sa);
;                     sb += dpp_x1(sb);
;                     sa += __shfl_xor(sa, 16); sa += __shfl_xor(sa, 32); sb += __shfl_xor(sb, 16); sb += __shfl_xor(sb, 32);
;                     if (fq == 0 && !odd) ps[(size_t)(rl + q) * 64] = (f32x2){sa, sb};
.LBB0_588:
	s_or_b64 exec, exec, s[56:57]
	v_cndmask_b32_e64 v101, v101, v114, s[8:9]
	v_cndmask_b32_e64 v100, v100, v112, s[8:9]
	v_cndmask_b32_e64 v103, v103, v115, s[8:9]
	v_cndmask_b32_e64 v102, v102, v113, s[8:9]
	v_cndmask_b32_e64 v97, v97, v118, s[8:9]
	v_cndmask_b32_e64 v96, v96, v116, s[8:9]
	v_cndmask_b32_e64 v99, v99, v119, s[8:9]
	v_cndmask_b32_e64 v98, v98, v117, s[8:9]
	v_lshlrev_b32_e32 v106, 16, v144
	v_and_b32_e32 v107, 0xffff0000, v144
	s_waitcnt lgkmcnt(1)
	v_lshlrev_b32_e32 v108, 16, v145
	s_waitcnt lgkmcnt(0)
	v_and_b32_e32 v109, 0xffff0000, v145
	v_lshlrev_b32_e32 v110, 16, v146
	v_and_b32_e32 v111, 0xffff0000, v146
	v_lshlrev_b32_e32 v112, 16, v147
	v_and_b32_e32 v113, 0xffff0000, v147
	v_pk_fma_f32 v[102:103], v[108:109], s[18:19], v[102:103] op_sel_hi:[1,0,1]
	v_pk_fma_f32 v[100:101], v[106:107], s[18:19], v[100:101] op_sel_hi:[1,0,1]
	v_pk_fma_f32 v[98:99], v[112:113], s[18:19], v[98:99] op_sel_hi:[1,0,1]
	v_pk_fma_f32 v[96:97], v[110:111], s[18:19], v[96:97] op_sel_hi:[1,0,1]
	v_cvt_pk_bf16_f32 v100, v100, v101
	v_cvt_pk_bf16_f32 v101, v102, v103
	s_nop 0
	v_cvt_pk_bf16_f32 v102, v96, v97
	v_cvt_pk_bf16_f32 v103, v98, v99
	v_lshlrev_b32_e32 v96, 16, v100
	v_and_b32_e32 v98, 0xffff0000, v100
	v_lshlrev_b32_e32 v106, 16, v101
	v_and_b32_e32 v108, 0xffff0000, v101
	v_lshlrev_b32_e32 v110, 16, v102
	v_and_b32_e32 v112, 0xffff0000, v102
	v_lshlrev_b32_e32 v114, 16, v103
	v_and_b32_e32 v116, 0xffff0000, v103
	v_mul_f32_e32 v97, v96, v96
	v_mul_f32_e32 v99, v98, v98
	v_mul_f32_e32 v107, v106, v106
	v_mul_f32_e32 v109, v108, v108
	v_mul_f32_e32 v111, v110, v110
	v_mul_f32_e32 v113, v112, v112
	v_mul_f32_e32 v115, v114, v114
	v_mul_f32_e32 v117, v116, v116
	v_pk_add_f32 v[96:97], v[96:97], v[98:99]
	v_pk_add_f32 v[98:99], v[106:107], v[108:109]
	v_pk_add_f32 v[106:107], v[114:115], v[116:117]
	v_pk_add_f32 v[96:97], v[96:97], v[98:99]
	v_pk_add_f32 v[98:99], v[110:111], v[112:113]
	global_store_dwordx4 v[104:105], v[100:103], off offset:128
	v_pk_add_f32 v[98:99], v[98:99], v[106:107]
	s_nop 0
	v_pk_add_f32 v[96:97], v[96:97], v[98:99]
	v_mov_b32_e32 v98, v165
	v_mov_b32_e32 v99, v165
	s_nop 0
	v_mov_b32_dpp v98, v96 quad_perm:[1,0,3,2] row_mask:0xf bank_mask:0xf
	v_mov_b32_dpp v99, v97 quad_perm:[1,0,3,2] row_mask:0xf bank_mask:0xf
	v_pk_add_f32 v[96:97], v[96:97], v[98:99]
	ds_bpermute_b32 v98, v130, v96
	ds_bpermute_b32 v99, v130, v97
	s_waitcnt lgkmcnt(0)
	v_pk_add_f32 v[96:97], v[96:97], v[98:99]
	ds_bpermute_b32 v98, v131, v96
	ds_bpermute_b32 v99, v131, v97
	s_and_saveexec_b64 s[56:57], s[10:11]
	s_cbranch_execz .LBB0_590
	s_waitcnt lgkmcnt(0)
	v_pk_add_f32 v[96:97], v[96:97], v[98:99]
	v_add_co_u32_e32 v98, vcc, 0x2000, v124
	s_nop 1
	v_addc_co_u32_e32 v99, vcc, 0, v125, vcc
	v_mov_b32_e32 v252, v250
	v_mov_b32_e32 v253, v251
	v_mov_b32_e32 v254, v96
	v_mov_b32_e32 v255, v97
	global_store_dwordx4 v249, v[252:255], s[94:95] offset:128
.LBB0_590:
	s_or_b64 exec, exec, s[56:57]
	s_waitcnt lgkmcnt(1)
	v_cndmask_b32_e64 v98, v92, v84, s[8:9]
	v_mov_b32_e32 v96, 0
	v_cndmask_b32_e64 v97, v93, v85, s[8:9]
	s_waitcnt lgkmcnt(0)
	v_cndmask_b32_e64 v99, v94, v86, s[8:9]
	v_mov_b32_dpp v96, v98 quad_perm:[1,0,3,2] row_mask:0xf bank_mask:0xf
	v_mov_b32_e32 v98, 0
	v_cndmask_b32_e64 v100, v95, v87, s[8:9]
	v_cndmask_b32_e64 v102, v88, v80, s[8:9]
	v_mov_b32_dpp v98, v97 quad_perm:[1,0,3,2] row_mask:0xf bank_mask:0xf
	v_mov_b32_e32 v97, 0
	v_cndmask_b32_e64 v101, v89, v81, s[8:9]
	v_cndmask_b32_e64 v103, v90, v82, s[8:9]
	v_mov_b32_dpp v97, v99 quad_perm:[1,0,3,2] row_mask:0xf bank_mask:0xf
	v_mov_b32_e32 v99, 0
	v_cndmask_b32_e64 v104, v91, v83, s[8:9]
	v_cndmask_b32_e64 v93, v98, v93, s[8:9]
	v_mov_b32_dpp v99, v100 quad_perm:[1,0,3,2] row_mask:0xf bank_mask:0xf
	v_mov_b32_e32 v100, 0
	v_cndmask_b32_e64 v92, v96, v92, s[8:9]
	v_cndmask_b32_e64 v95, v99, v95, s[8:9]
	v_mov_b32_dpp v100, v102 quad_perm:[1,0,3,2] row_mask:0xf bank_mask:0xf
	v_mov_b32_e32 v102, 0
	v_cndmask_b32_e64 v94, v97, v94, s[8:9]
	v_cndmask_b32_e64 v88, v100, v88, s[8:9]
	v_mov_b32_dpp v102, v101 quad_perm:[1,0,3,2] row_mask:0xf bank_mask:0xf
	v_mov_b32_e32 v101, 0
	v_cndmask_b32_e64 v89, v102, v89, s[8:9]
	v_and_b32_e32 v105, 0xffff0000, v140
	v_mov_b32_dpp v101, v103 quad_perm:[1,0,3,2] row_mask:0xf bank_mask:0xf
	v_mov_b32_e32 v103, 0
	v_cndmask_b32_e64 v90, v101, v90, s[8:9]
	v_lshlrev_b32_e32 v106, 16, v141
	v_mov_b32_dpp v103, v104 quad_perm:[1,0,3,2] row_mask:0xf bank_mask:0xf
	v_cndmask_b32_e64 v91, v103, v91, s[8:9]
	v_lshlrev_b32_e32 v104, 16, v140
	v_and_b32_e32 v107, 0xffff0000, v141
	v_lshlrev_b32_e32 v108, 16, v142
	v_and_b32_e32 v109, 0xffff0000, v142
	v_lshlrev_b32_e32 v110, 16, v143
	v_and_b32_e32 v111, 0xffff0000, v143
	v_pk_fma_f32 v[94:95], v[106:107], s[18:19], v[94:95] op_sel_hi:[1,0,1]
	v_pk_fma_f32 v[92:93], v[104:105], s[18:19], v[92:93] op_sel_hi:[1,0,1]
	v_pk_fma_f32 v[90:91], v[110:111], s[18:19], v[90:91] op_sel_hi:[1,0,1]
	v_pk_fma_f32 v[88:89], v[108:109], s[18:19], v[88:89] op_sel_hi:[1,0,1]
	v_cvt_pk_bf16_f32 v104, v92, v93
	v_cvt_pk_bf16_f32 v105, v94, v95
	v_mov_b32_e32 v179, v165
	v_cvt_pk_bf16_f32 v106, v88, v89
	v_cvt_pk_bf16_f32 v107, v90, v91
	v_lshlrev_b32_e32 v88, 16, v104
	v_and_b32_e32 v90, 0xffff0000, v104
	v_lshlrev_b32_e32 v92, 16, v105
	v_and_b32_e32 v94, 0xffff0000, v105
	v_lshlrev_b32_e32 v108, 16, v106
	v_and_b32_e32 v110, 0xffff0000, v106
	v_lshlrev_b32_e32 v112, 16, v107
	v_and_b32_e32 v114, 0xffff0000, v107
	v_mul_f32_e32 v89, v88, v88
	v_mul_f32_e32 v91, v90, v90
	v_mul_f32_e32 v93, v92, v92
	v_mul_f32_e32 v95, v94, v94
	v_mul_f32_e32 v109, v108, v108
	v_mul_f32_e32 v111, v110, v110
	v_mul_f32_e32 v113, v112, v112
	v_mul_f32_e32 v115, v114, v114
	v_pk_add_f32 v[88:89], v[88:89], v[90:91]
	v_pk_add_f32 v[90:91], v[92:93], v[94:95]
	v_pk_add_f32 v[92:93], v[112:113], v[114:115]
	v_pk_add_f32 v[88:89], v[88:89], v[90:91]
	v_pk_add_f32 v[90:91], v[108:109], v[110:111]
	s_nop 0
	v_pk_add_f32 v[90:91], v[90:91], v[92:93]
	s_nop 0
	v_pk_add_f32 v[88:89], v[88:89], v[90:91]
	v_mov_b32_e32 v90, v165
	v_mov_b32_e32 v91, v165
	s_nop 0
	v_mov_b32_dpp v90, v88 quad_perm:[1,0,3,2] row_mask:0xf bank_mask:0xf
	v_mov_b32_dpp v91, v89 quad_perm:[1,0,3,2] row_mask:0xf bank_mask:0xf
	v_pk_add_f32 v[88:89], v[88:89], v[90:91]
	ds_bpermute_b32 v90, v130, v88
	ds_bpermute_b32 v91, v130, v89
	s_waitcnt lgkmcnt(0)
	v_pk_add_f32 v[90:91], v[88:89], v[90:91]
	ds_bpermute_b32 v92, v131, v90
	ds_bpermute_b32 v93, v131, v91
	v_lshl_add_u64 v[88:89], s[54:55], 0, v[178:179]
	global_store_dwordx4 v[88:89], v[104:107], off
	s_and_saveexec_b64 s[56:57], s[10:11]
	s_cbranch_execz .LBB0_592
	s_waitcnt lgkmcnt(0)
	v_pk_add_f32 v[90:91], v[90:91], v[92:93]
	v_add_co_u32_e32 v92, vcc, 0x4000, v124
	s_nop 1
	v_addc_co_u32_e32 v93, vcc, 0, v125, vcc
	v_mov_b32_e32 v250, v90
	v_mov_b32_e32 v251, v91
;     __device__ __forceinline__ void operator()(const f32x4 (&acc)[2][2][4][2], const Unit& u, int wr, int wc, int fr, int fq, const EpiCtx& X) const {
;     ...
;             for (int m = 0; m < 4; ++m) { const unsigned off = lo + (unsigned)((ai * HALF + m * 16) * 64) * 2u; raw[2 * m] = *(const u32x4*)(xb + off); raw[2 * m + 1] = *(const u32x4*)(xb + off + 128); }
; #pragma unroll
;             for (int m = 0; m < 4; ++m) {
;                 const int rl = ai * HALF + m * 16; const unsigned off = lo + (unsigned)(rl * 64) * 2u;
;                 const f32x4 o0a = acc[ai][0][m][0], o0b = acc[ai][0][m][1], o1a = acc[ai][1][m][0], o1b = acc[ai][1][m][1];
;                 const f32x4 ra_ = dpp_swap1(odd ? o0a : o1a), rb_ = dpp_swap1(odd ? o0b : o1b);
;                 const f32x4 pa[2] = {odd ? ra_ : o0a, odd ? o1a : ra_}, pb[2] = {odd ? rb_ : o0b, odd ? o1b : rb_};
; #pragma unroll
;                 for (int q = 0; q < 2; ++q) {
;                     const u32x4 w0 = raw[2 * m + q];
;                     const f32x4 r0 = (f32x4){bf_lo(w0.x), bf_hi(w0.x), bf_lo(w0.y), bf_hi(w0.y)}, r1 = (f32x4){bf_lo(w0.z), bf_hi(w0.z), bf_lo(w0.w), bf_hi(w0.w)};
;                     f32x4 y0, y1;
;                     if (RESN) { const f32x2 t = tbl[rl + q]; const float mu = t.x, ra = t.y * ALPHA; y0 = (r0 - mu) * ra * g0 + b0 + pa[q]; y1 = (r1 - mu) * ra * g1 + b1 + pb[q]; }
;                     else { y0 = r0 * ALPHA + pa[q]; y1 = r1 * ALPHA + pb[q]; }
;                     { const u32x4 w = pack8f(y0, y1); *(u32x4*)(xb + off + q * 128) = w;
;                         y0 = (f32x4){bf_lo(w.x), bf_hi(w.x), bf_lo(w.y), bf_hi(w.y)}; y1 = (f32x4){bf_lo(w.z), bf_hi(w.z), bf_lo(w.w), bf_hi(w.w)}; }
;                     float sa = ((y0[0] + y0[1]) + (y0[2] + y0[3])) + ((y1[0] + y1[1]) + (y1[2] + y1[3]));
;                     float sb = ((y0[0] * y0[0] + y0[1] * y0[1]) + (y0[2] * y0[2] + y0[3] * y0[3])) + ((y1[0] * y1[0] + y1[1] * y1[1]) + (y1[2] * y1[2] + y1[3] * y1[3]));
;                     sa += dpp_x1(sa);
;                     sb += dpp_x1(sb);
;                     sa += __shfl_xor(sa, 16); sa += __shfl_xor(sa, 32); sb += __shfl_xor(sb, 16); sb += __shfl_xor(sb, 32);
;                     if (fq == 0 && !odd) ps[(size_t)(rl + q) * 64] = (f32x2){sa, sb};
.LBB0_592:
	s_or_b64 exec, exec, s[56:57]
	v_cndmask_b32_e64 v85, v85, v98, s[8:9]
	v_cndmask_b32_e64 v84, v84, v96, s[8:9]
	v_cndmask_b32_e64 v87, v87, v99, s[8:9]
	v_cndmask_b32_e64 v86, v86, v97, s[8:9]
	v_cndmask_b32_e64 v81, v81, v102, s[8:9]
	v_cndmask_b32_e64 v80, v80, v100, s[8:9]
	v_cndmask_b32_e64 v83, v83, v103, s[8:9]
	v_cndmask_b32_e64 v82, v82, v101, s[8:9]
	v_lshlrev_b32_e32 v90, 16, v136
	v_and_b32_e32 v91, 0xffff0000, v136
	s_waitcnt lgkmcnt(1)
	v_lshlrev_b32_e32 v92, 16, v137
	s_waitcnt lgkmcnt(0)
	v_and_b32_e32 v93, 0xffff0000, v137
	v_lshlrev_b32_e32 v94, 16, v138
	v_and_b32_e32 v95, 0xffff0000, v138
	v_lshlrev_b32_e32 v96, 16, v139
	v_and_b32_e32 v97, 0xffff0000, v139
	v_pk_fma_f32 v[86:87], v[92:93], s[18:19], v[86:87] op_sel_hi:[1,0,1]
	v_pk_fma_f32 v[84:85], v[90:91], s[18:19], v[84:85] op_sel_hi:[1,0,1]
	v_pk_fma_f32 v[82:83], v[96:97], s[18:19], v[82:83] op_sel_hi:[1,0,1]
	v_pk_fma_f32 v[80:81], v[94:95], s[18:19], v[80:81] op_sel_hi:[1,0,1]
	v_cvt_pk_bf16_f32 v84, v84, v85
	v_cvt_pk_bf16_f32 v85, v86, v87
	s_nop 0
	v_cvt_pk_bf16_f32 v86, v80, v81
	v_cvt_pk_bf16_f32 v87, v82, v83
	v_lshlrev_b32_e32 v80, 16, v84
	v_and_b32_e32 v82, 0xffff0000, v84
	v_lshlrev_b32_e32 v90, 16, v85
	v_and_b32_e32 v92, 0xffff0000, v85
	v_lshlrev_b32_e32 v94, 16, v86
	v_and_b32_e32 v96, 0xffff0000, v86
	v_lshlrev_b32_e32 v98, 16, v87
	v_and_b32_e32 v100, 0xffff0000, v87
	v_mul_f32_e32 v81, v80, v80
	v_mul_f32_e32 v83, v82, v82
	v_mul_f32_e32 v91, v90, v90
	v_mul_f32_e32 v93, v92, v92
	v_mul_f32_e32 v95, v94, v94
	v_mul_f32_e32 v97, v96, v96
	v_mul_f32_e32 v99, v98, v98
	v_mul_f32_e32 v101, v100, v100
	v_pk_add_f32 v[80:81], v[80:81], v[82:83]
	v_pk_add_f32 v[82:83], v[90:91], v[92:93]
	v_pk_add_f32 v[90:91], v[98:99], v[100:101]
	v_pk_add_f32 v[80:81], v[80:81], v[82:83]
	v_pk_add_f32 v[82:83], v[94:95], v[96:97]
	global_store_dwordx4 v[88:89], v[84:87], off offset:128
	v_pk_add_f32 v[82:83], v[82:83], v[90:91]
	s_nop 0
	v_pk_add_f32 v[80:81], v[80:81], v[82:83]
	v_mov_b32_e32 v82, v165
	v_mov_b32_e32 v83, v165
	s_nop 0
	v_mov_b32_dpp v82, v80 quad_perm:[1,0,3,2] row_mask:0xf bank_mask:0xf
	v_mov_b32_dpp v83, v81 quad_perm:[1,0,3,2] row_mask:0xf bank_mask:0xf
	v_pk_add_f32 v[80:81], v[80:81], v[82:83]
	ds_bpermute_b32 v82, v130, v80
	ds_bpermute_b32 v83, v130, v81
	s_waitcnt lgkmcnt(0)
	v_pk_add_f32 v[80:81], v[80:81], v[82:83]
	ds_bpermute_b32 v82, v131, v80
	ds_bpermute_b32 v83, v131, v81
	s_and_saveexec_b64 s[56:57], s[10:11]
	s_cbranch_execz .LBB0_594
	s_waitcnt lgkmcnt(0)
	v_pk_add_f32 v[80:81], v[80:81], v[82:83]
	v_add_co_u32_e32 v82, vcc, 0x4000, v124
	s_nop 1
	v_addc_co_u32_e32 v83, vcc, 0, v125, vcc
	v_mov_b32_e32 v252, v250
	v_mov_b32_e32 v253, v251
	v_mov_b32_e32 v254, v80
	v_mov_b32_e32 v255, v81
	global_store_dwordx4 v249, v[252:255], s[94:95] offset:256
.LBB0_594:
	s_or_b64 exec, exec, s[56:57]
	s_waitcnt lgkmcnt(1)
	v_cndmask_b32_e64 v82, v76, v68, s[8:9]
	v_mov_b32_e32 v80, 0
	v_cndmask_b32_e64 v81, v77, v69, s[8:9]
	s_waitcnt lgkmcnt(0)
	v_cndmask_b32_e64 v83, v78, v70, s[8:9]
	v_mov_b32_dpp v80, v82 quad_perm:[1,0,3,2] row_mask:0xf bank_mask:0xf
	v_mov_b32_e32 v82, 0
	v_cndmask_b32_e64 v84, v79, v71, s[8:9]
	v_cndmask_b32_e64 v86, v72, v64, s[8:9]
	v_mov_b32_dpp v82, v81 quad_perm:[1,0,3,2] row_mask:0xf bank_mask:0xf
	v_mov_b32_e32 v81, 0
	v_cndmask_b32_e64 v85, v73, v65, s[8:9]
	v_cndmask_b32_e64 v87, v74, v66, s[8:9]
	v_mov_b32_dpp v81, v83 quad_perm:[1,0,3,2] row_mask:0xf bank_mask:0xf
	v_mov_b32_e32 v83, 0
	v_cndmask_b32_e64 v88, v75, v67, s[8:9]
	v_cndmask_b32_e64 v77, v82, v77, s[8:9]
	v_mov_b32_dpp v83, v84 quad_perm:[1,0,3,2] row_mask:0xf bank_mask:0xf
	v_mov_b32_e32 v84, 0
	v_cndmask_b32_e64 v76, v80, v76, s[8:9]
	v_cndmask_b32_e64 v79, v83, v79, s[8:9]
	v_mov_b32_dpp v84, v86 quad_perm:[1,0,3,2] row_mask:0xf bank_mask:0xf
	v_mov_b32_e32 v86, 0
	v_cndmask_b32_e64 v78, v81, v78, s[8:9]
	v_cndmask_b32_e64 v72, v84, v72, s[8:9]
	v_mov_b32_dpp v86, v85 quad_perm:[1,0,3,2] row_mask:0xf bank_mask:0xf
	v_mov_b32_e32 v85, 0
	v_cndmask_b32_e64 v73, v86, v73, s[8:9]
	v_and_b32_e32 v89, 0xffff0000, v132
	v_mov_b32_dpp v85, v87 quad_perm:[1,0,3,2] row_mask:0xf bank_mask:0xf
	v_mov_b32_e32 v87, 0
	v_cndmask_b32_e64 v74, v85, v74, s[8:9]
	v_lshlrev_b32_e32 v90, 16, v133
	v_mov_b32_dpp v87, v88 quad_perm:[1,0,3,2] row_mask:0xf bank_mask:0xf
	v_cndmask_b32_e64 v75, v87, v75, s[8:9]
	v_lshlrev_b32_e32 v88, 16, v132
	v_and_b32_e32 v91, 0xffff0000, v133
	v_lshlrev_b32_e32 v92, 16, v134
	v_and_b32_e32 v93, 0xffff0000, v134
	v_lshlrev_b32_e32 v94, 16, v135
	v_and_b32_e32 v95, 0xffff0000, v135
	v_pk_fma_f32 v[78:79], v[90:91], s[18:19], v[78:79] op_sel_hi:[1,0,1]
	v_pk_fma_f32 v[76:77], v[88:89], s[18:19], v[76:77] op_sel_hi:[1,0,1]
	v_pk_fma_f32 v[74:75], v[94:95], s[18:19], v[74:75] op_sel_hi:[1,0,1]
	v_pk_fma_f32 v[72:73], v[92:93], s[18:19], v[72:73] op_sel_hi:[1,0,1]
	v_cvt_pk_bf16_f32 v88, v76, v77
	v_cvt_pk_bf16_f32 v89, v78, v79
	v_mov_b32_e32 v177, v165
	v_cvt_pk_bf16_f32 v90, v72, v73
	v_cvt_pk_bf16_f32 v91, v74, v75
	v_lshlrev_b32_e32 v72, 16, v88
	v_and_b32_e32 v74, 0xffff0000, v88
	v_lshlrev_b32_e32 v76, 16, v89
	v_and_b32_e32 v78, 0xffff0000, v89
	v_lshlrev_b32_e32 v92, 16, v90
	v_and_b32_e32 v94, 0xffff0000, v90
	v_lshlrev_b32_e32 v96, 16, v91
	v_and_b32_e32 v98, 0xffff0000, v91
	v_mul_f32_e32 v73, v72, v72
	v_mul_f32_e32 v75, v74, v74
	v_mul_f32_e32 v77, v76, v76
	v_mul_f32_e32 v79, v78, v78
	v_mul_f32_e32 v93, v92, v92
	v_mul_f32_e32 v95, v94, v94
	v_mul_f32_e32 v97, v96, v96
	v_mul_f32_e32 v99, v98, v98
	v_pk_add_f32 v[72:73], v[72:73], v[74:75]
	v_pk_add_f32 v[74:75], v[76:77], v[78:79]
	v_pk_add_f32 v[76:77], v[96:97], v[98:99]
	v_pk_add_f32 v[72:73], v[72:73], v[74:75]
	v_pk_add_f32 v[74:75], v[92:93], v[94:95]
	s_nop 0
	v_pk_add_f32 v[74:75], v[74:75], v[76:77]
	s_nop 0
	v_pk_add_f32 v[72:73], v[72:73], v[74:75]
	v_mov_b32_e32 v74, v165
	v_mov_b32_e32 v75, v165
	s_nop 0
	v_mov_b32_dpp v74, v72 quad_perm:[1,0,3,2] row_mask:0xf bank_mask:0xf
	v_mov_b32_dpp v75, v73 quad_perm:[1,0,3,2] row_mask:0xf bank_mask:0xf
	v_pk_add_f32 v[72:73], v[72:73], v[74:75]
	ds_bpermute_b32 v74, v130, v72
	ds_bpermute_b32 v75, v130, v73
	s_waitcnt lgkmcnt(0)
	v_pk_add_f32 v[74:75], v[72:73], v[74:75]
	ds_bpermute_b32 v76, v131, v74
	ds_bpermute_b32 v77, v131, v75
	v_lshl_add_u64 v[72:73], s[54:55], 0, v[176:177]
	global_store_dwordx4 v[72:73], v[88:91], off
	s_and_saveexec_b64 s[56:57], s[10:11]
	s_cbranch_execz .LBB0_596
	s_waitcnt lgkmcnt(0)
	v_pk_add_f32 v[74:75], v[74:75], v[76:77]
	v_add_co_u32_e32 v76, vcc, 0x6000, v124
	s_nop 1
	v_addc_co_u32_e32 v77, vcc, 0, v125, vcc
	v_mov_b32_e32 v250, v74
	v_mov_b32_e32 v251, v75
;     __device__ __forceinline__ void operator()(const f32x4 (&acc)[2][2][4][2], const Unit& u, int wr, int wc, int fr, int fq, const EpiCtx& X) const {
;     ...
;         for (int ai = 0; ai < 2; ++ai) {
;             u32x4 raw[8];
; #pragma unroll
;             for (int m = 0; m < 4; ++m) { const unsigned off = lo + (unsigned)((ai * HALF + m * 16) * 64) * 2u; raw[2 * m] = *(const u32x4*)(xb + off); raw[2 * m + 1] = *(const u32x4*)(xb + off + 128); }
; #pragma unroll
;             for (int m = 0; m < 4; ++m) {
;                 const int rl = ai * HALF + m * 16; const unsigned off = lo + (unsigned)(rl * 64) * 2u;
;                 const f32x4 o0a = acc[ai][0][m][0], o0b = acc[ai][0][m][1], o1a = acc[ai][1][m][0], o1b = acc[ai][1][m][1];
;                 const f32x4 ra_ = dpp_swap1(odd ? o0a : o1a), rb_ = dpp_swap1(odd ? o0b : o1b);
;                 const f32x4 pa[2] = {odd ? ra_ : o0a, odd ? o1a : ra_}, pb[2] = {odd ? rb_ : o0b, odd ? o1b : rb_};
; #pragma unroll
;                 for (int q = 0; q < 2; ++q) {
;                     const u32x4 w0 = raw[2 * m + q];
;                     const f32x4 r0 = (f32x4){bf_lo(w0.x), bf_hi(w0.x), bf_lo(w0.y), bf_hi(w0.y)}, r1 = (f32x4){bf_lo(w0.z), bf_hi(w0.z), bf_lo(w0.w), bf_hi(w0.w)};
;                     f32x4 y0, y1;
;                     if (RESN) { const f32x2 t = tbl[rl + q]; const float mu = t.x, ra = t.y * ALPHA; y0 = (r0 - mu) * ra * g0 + b0 + pa[q]; y1 = (r1 - mu) * ra * g1 + b1 + pb[q]; }
;                     else { y0 = r0 * ALPHA + pa[q]; y1 = r1 * ALPHA + pb[q]; }
;                     { const u32x4 w = pack8f(y0, y1); *(u32x4*)(xb + off + q * 128) = w;
;                         y0 = (f32x4){bf_lo(w.x), bf_hi(w.x), bf_lo(w.y), bf_hi(w.y)}; y1 = (f32x4){bf_lo(w.z), bf_hi(w.z), bf_lo(w.w), bf_hi(w.w)}; }
;                     float sa = ((y0[0] + y0[1]) + (y0[2] + y0[3])) + ((y1[0] + y1[1]) + (y1[2] + y1[3]));
;                     float sb = ((y0[0] * y0[0] + y0[1] * y0[1]) + (y0[2] * y0[2] + y0[3] * y0[3])) + ((y1[0] * y1[0] + y1[1] * y1[1]) + (y1[2] * y1[2] + y1[3] * y1[3]));
;                     sa += dpp_x1(sa);
;                     sb += dpp_x1(sb);
;                     sa += __shfl_xor(sa, 16); sa += __shfl_xor(sa, 32); sb += __shfl_xor(sb, 16); sb += __shfl_xor(sb, 32);
;                     if (fq == 0 && !odd) ps[(size_t)(rl + q) * 64] = (f32x2){sa, sb};
.LBB0_596:
	s_or_b64 exec, exec, s[56:57]
	v_cndmask_b32_e64 v69, v69, v82, s[8:9]
	v_cndmask_b32_e64 v68, v68, v80, s[8:9]
	v_cndmask_b32_e64 v71, v71, v83, s[8:9]
	v_cndmask_b32_e64 v70, v70, v81, s[8:9]
	v_cndmask_b32_e64 v65, v65, v86, s[8:9]
	v_cndmask_b32_e64 v64, v64, v84, s[8:9]
	v_cndmask_b32_e64 v67, v67, v87, s[8:9]
	v_cndmask_b32_e64 v66, v66, v85, s[8:9]
	v_lshlrev_b32_e32 v74, 16, v120
	v_and_b32_e32 v75, 0xffff0000, v120
	s_waitcnt lgkmcnt(1)
	v_lshlrev_b32_e32 v76, 16, v121
	s_waitcnt lgkmcnt(0)
	v_and_b32_e32 v77, 0xffff0000, v121
	v_lshlrev_b32_e32 v78, 16, v122
	v_and_b32_e32 v79, 0xffff0000, v122
	v_lshlrev_b32_e32 v80, 16, v123
	v_and_b32_e32 v81, 0xffff0000, v123
	v_pk_fma_f32 v[70:71], v[76:77], s[18:19], v[70:71] op_sel_hi:[1,0,1]
	v_pk_fma_f32 v[68:69], v[74:75], s[18:19], v[68:69] op_sel_hi:[1,0,1]
	v_pk_fma_f32 v[66:67], v[80:81], s[18:19], v[66:67] op_sel_hi:[1,0,1]
	v_pk_fma_f32 v[64:65], v[78:79], s[18:19], v[64:65] op_sel_hi:[1,0,1]
	v_cvt_pk_bf16_f32 v68, v68, v69
	v_cvt_pk_bf16_f32 v69, v70, v71
	s_nop 0
	v_cvt_pk_bf16_f32 v70, v64, v65
	v_cvt_pk_bf16_f32 v71, v66, v67
	v_lshlrev_b32_e32 v64, 16, v68
	v_and_b32_e32 v66, 0xffff0000, v68
	v_lshlrev_b32_e32 v74, 16, v69
	v_and_b32_e32 v76, 0xffff0000, v69
	v_lshlrev_b32_e32 v78, 16, v70
	v_and_b32_e32 v80, 0xffff0000, v70
	v_lshlrev_b32_e32 v82, 16, v71
	v_and_b32_e32 v84, 0xffff0000, v71
	v_mul_f32_e32 v65, v64, v64
	v_mul_f32_e32 v67, v66, v66
	v_mul_f32_e32 v75, v74, v74
	v_mul_f32_e32 v77, v76, v76
	v_mul_f32_e32 v79, v78, v78
	v_mul_f32_e32 v81, v80, v80
	v_mul_f32_e32 v83, v82, v82
	v_mul_f32_e32 v85, v84, v84
	v_pk_add_f32 v[64:65], v[64:65], v[66:67]
	v_pk_add_f32 v[66:67], v[74:75], v[76:77]
	v_pk_add_f32 v[74:75], v[82:83], v[84:85]
	v_pk_add_f32 v[64:65], v[64:65], v[66:67]
	v_pk_add_f32 v[66:67], v[78:79], v[80:81]
	global_store_dwordx4 v[72:73], v[68:71], off offset:128
	v_pk_add_f32 v[66:67], v[66:67], v[74:75]
	s_nop 0
	v_pk_add_f32 v[64:65], v[64:65], v[66:67]
	v_mov_b32_e32 v66, v165
	v_mov_b32_e32 v67, v165
	s_nop 0
	v_mov_b32_dpp v66, v64 quad_perm:[1,0,3,2] row_mask:0xf bank_mask:0xf
	v_mov_b32_dpp v67, v65 quad_perm:[1,0,3,2] row_mask:0xf bank_mask:0xf
	v_pk_add_f32 v[64:65], v[64:65], v[66:67]
	ds_bpermute_b32 v66, v130, v64
	ds_bpermute_b32 v67, v130, v65
	s_waitcnt lgkmcnt(0)
	v_pk_add_f32 v[64:65], v[64:65], v[66:67]
	ds_bpermute_b32 v66, v131, v64
	ds_bpermute_b32 v67, v131, v65
	s_and_saveexec_b64 s[56:57], s[10:11]
	s_cbranch_execz .LBB0_598
	s_waitcnt lgkmcnt(0)
	v_pk_add_f32 v[64:65], v[64:65], v[66:67]
	v_add_co_u32_e32 v66, vcc, 0x6000, v124
	s_nop 1
	v_addc_co_u32_e32 v67, vcc, 0, v125, vcc
	v_mov_b32_e32 v252, v250
	v_mov_b32_e32 v253, v251
	v_mov_b32_e32 v254, v64
	v_mov_b32_e32 v255, v65
	global_store_dwordx4 v249, v[252:255], s[94:95] offset:384
.LBB0_598:
	s_or_b64 exec, exec, s[56:57]
	v_add_u32_e32 v96, 0x4000, v164
	v_mov_b32_e32 v104, v230
	v_mov_b32_e32 v105, v231
	v_mov_b32_e32 v106, v232
	v_mov_b32_e32 v107, v233
	v_add_u32_e32 v94, 0x4800, v164
	v_add_u32_e32 v92, 0x5000, v164
	v_add_u32_e32 v164, 0x5800, v164
	v_mov_b32_e32 v88, v234
	v_mov_b32_e32 v89, v235
	v_mov_b32_e32 v90, v236
	v_mov_b32_e32 v91, v237
	v_mov_b32_e32 v84, v238
	v_mov_b32_e32 v85, v239
	v_mov_b32_e32 v86, v240
	v_mov_b32_e32 v87, v241
	v_mov_b32_e32 v80, v242
	v_mov_b32_e32 v81, v243
	v_mov_b32_e32 v82, v244
	v_mov_b32_e32 v83, v245
	global_load_dwordx4 v[76:79], v92, s[54:55]
	global_load_dwordx4 v[72:75], v92, s[54:55] offset:128
	global_load_dwordx4 v[68:71], v164, s[54:55]
	s_waitcnt lgkmcnt(0)
	global_load_dwordx4 v[64:67], v164, s[54:55] offset:128
	v_cndmask_b32_e64 v103, v63, v55, s[8:9]
	v_cndmask_b32_e64 v110, v62, v54, s[8:9]
	v_cndmask_b32_e64 v111, v61, v53, s[8:9]
	v_cndmask_b32_e64 v112, v60, v52, s[8:9]
	v_mov_b32_e32 v93, 0
	v_mov_b32_e32 v97, 0
	v_mov_b32_e32 v95, 0
	v_mov_b32_e32 v98, 0
	v_cndmask_b32_e64 v113, v59, v51, s[8:9]
	v_cndmask_b32_e64 v114, v58, v50, s[8:9]
	v_cndmask_b32_e64 v115, v57, v49, s[8:9]
	v_cndmask_b32_e64 v116, v56, v48, s[8:9]
	v_mov_b32_e32 v99, 0
	v_mov_b32_e32 v101, 0
	v_mov_b32_e32 v100, 0
	v_mov_b32_e32 v102, 0
	v_mov_b32_dpp v93, v112 quad_perm:[1,0,3,2] row_mask:0xf bank_mask:0xf
	v_mov_b32_dpp v97, v111 quad_perm:[1,0,3,2] row_mask:0xf bank_mask:0xf
	v_mov_b32_dpp v95, v110 quad_perm:[1,0,3,2] row_mask:0xf bank_mask:0xf
	v_mov_b32_dpp v98, v103 quad_perm:[1,0,3,2] row_mask:0xf bank_mask:0xf
	v_mov_b32_dpp v99, v116 quad_perm:[1,0,3,2] row_mask:0xf bank_mask:0xf
	v_mov_b32_dpp v101, v115 quad_perm:[1,0,3,2] row_mask:0xf bank_mask:0xf
	v_mov_b32_dpp v100, v114 quad_perm:[1,0,3,2] row_mask:0xf bank_mask:0xf
	v_mov_b32_dpp v102, v113 quad_perm:[1,0,3,2] row_mask:0xf bank_mask:0xf
	v_cndmask_b32_e64 v61, v97, v61, s[8:9]
	v_cndmask_b32_e64 v60, v93, v60, s[8:9]
	v_cndmask_b32_e64 v63, v98, v63, s[8:9]
	v_cndmask_b32_e64 v62, v95, v62, s[8:9]
	v_cndmask_b32_e64 v57, v101, v57, s[8:9]
	v_cndmask_b32_e64 v56, v99, v56, s[8:9]
	v_cndmask_b32_e64 v59, v102, v59, s[8:9]
	v_cndmask_b32_e64 v58, v100, v58, s[8:9]
	v_mov_b32_e32 v108, v165
	v_mov_b32_e32 v109, v165
	v_lshlrev_b32_e32 v110, 16, v104
	v_and_b32_e32 v111, 0xffff0000, v104
	v_lshlrev_b32_e32 v104, 16, v105
	v_and_b32_e32 v105, 0xffff0000, v105
	v_lshlrev_b32_e32 v112, 16, v106
	v_and_b32_e32 v113, 0xffff0000, v106
	v_lshlrev_b32_e32 v106, 16, v107
	v_and_b32_e32 v107, 0xffff0000, v107
	v_pk_fma_f32 v[62:63], v[104:105], s[18:19], v[62:63] op_sel_hi:[1,0,1]
	v_pk_fma_f32 v[60:61], v[110:111], s[18:19], v[60:61] op_sel_hi:[1,0,1]
	v_pk_fma_f32 v[58:59], v[106:107], s[18:19], v[58:59] op_sel_hi:[1,0,1]
	v_pk_fma_f32 v[56:57], v[112:113], s[18:19], v[56:57] op_sel_hi:[1,0,1]
	v_cvt_pk_bf16_f32 v60, v60, v61
	v_cvt_pk_bf16_f32 v61, v62, v63
	s_nop 0
	v_cvt_pk_bf16_f32 v62, v56, v57
	v_cvt_pk_bf16_f32 v63, v58, v59
	v_lshlrev_b32_e32 v56, 16, v60
	v_and_b32_e32 v58, 0xffff0000, v60
	v_lshlrev_b32_e32 v104, 16, v61
	v_and_b32_e32 v106, 0xffff0000, v61
	v_lshlrev_b32_e32 v110, 16, v62
	v_and_b32_e32 v112, 0xffff0000, v62
	v_lshlrev_b32_e32 v114, 16, v63
	v_and_b32_e32 v116, 0xffff0000, v63
	v_mul_f32_e32 v57, v56, v56
	v_mul_f32_e32 v59, v58, v58
	v_mul_f32_e32 v105, v104, v104
	v_mul_f32_e32 v107, v106, v106
	v_mul_f32_e32 v111, v110, v110
	v_mul_f32_e32 v113, v112, v112
	v_mul_f32_e32 v115, v114, v114
	v_mul_f32_e32 v117, v116, v116
	v_pk_add_f32 v[56:57], v[56:57], v[58:59]
	v_pk_add_f32 v[58:59], v[104:105], v[106:107]
	v_pk_add_f32 v[104:105], v[110:111], v[112:113]
	v_pk_add_f32 v[106:107], v[114:115], v[116:117]
	v_pk_add_f32 v[56:57], v[56:57], v[58:59]
	v_pk_add_f32 v[58:59], v[104:105], v[106:107]
	global_store_dwordx4 v96, v[60:63], s[54:55]
	v_pk_add_f32 v[56:57], v[56:57], v[58:59]
	s_nop 1
	v_mov_b32_dpp v108, v56 quad_perm:[1,0,3,2] row_mask:0xf bank_mask:0xf
	v_mov_b32_dpp v109, v57 quad_perm:[1,0,3,2] row_mask:0xf bank_mask:0xf
	v_pk_add_f32 v[56:57], v[56:57], v[108:109]
	ds_bpermute_b32 v58, v130, v56
	ds_bpermute_b32 v59, v130, v57
	s_waitcnt lgkmcnt(0)
;     __device__ __forceinline__ void operator()(const f32x4 (&acc)[2][2][4][2], const Unit& u, int wr, int wc, int fr, int fq, const EpiCtx& X) const {
;     ...
;             for (int m = 0; m < 4; ++m) { const unsigned off = lo + (unsigned)((ai * HALF + m * 16) * 64) * 2u; raw[2 * m] = *(const u32x4*)(xb + off); raw[2 * m + 1] = *(const u32x4*)(xb + off + 128); }
; #pragma unroll
;             for (int m = 0; m < 4; ++m) {
;                 const int rl = ai * HALF + m * 16; const unsigned off = lo + (unsigned)(rl * 64) * 2u;
;                 const f32x4 o0a = acc[ai][0][m][0], o0b = acc[ai][0][m][1], o1a = acc[ai][1][m][0], o1b = acc[ai][1][m][1];
;                 const f32x4 ra_ = dpp_swap1(odd ? o0a : o1a), rb_ = dpp_swap1(odd ? o0b : o1b);
;                 const f32x4 pa[2] = {odd ? ra_ : o0a, odd ? o1a : ra_}, pb[2] = {odd ? rb_ : o0b, odd ? o1b : rb_};
; #pragma unroll
;                 for (int q = 0; q < 2; ++q) {
;                     const u32x4 w0 = raw[2 * m + q];
;                     const f32x4 r0 = (f32x4){bf_lo(w0.x), bf_hi(w0.x), bf_lo(w0.y), bf_hi(w0.y)}, r1 = (f32x4){bf_lo(w0.z), bf_hi(w0.z), bf_lo(w0.w), bf_hi(w0.w)};
;                     f32x4 y0, y1;
;                     if (RESN) { const f32x2 t = tbl[rl + q]; const float mu = t.x, ra = t.y * ALPHA; y0 = (r0 - mu) * ra * g0 + b0 + pa[q]; y1 = (r1 - mu) * ra * g1 + b1 + pb[q]; }
;                     else { y0 = r0 * ALPHA + pa[q]; y1 = r1 * ALPHA + pb[q]; }
;                     { const u32x4 w = pack8f(y0, y1); *(u32x4*)(xb + off + q * 128) = w;
;                         y0 = (f32x4){bf_lo(w.x), bf_hi(w.x), bf_lo(w.y), bf_hi(w.y)}; y1 = (f32x4){bf_lo(w.z), bf_hi(w.z), bf_lo(w.w), bf_hi(w.w)}; }
;                     float sa = ((y0[0] + y0[1]) + (y0[2] + y0[3])) + ((y1[0] + y1[1]) + (y1[2] + y1[3]));
;                     float sb = ((y0[0] * y0[0] + y0[1] * y0[1]) + (y0[2] * y0[2] + y0[3] * y0[3])) + ((y1[0] * y1[0] + y1[1] * y1[1]) + (y1[2] * y1[2] + y1[3] * y1[3]));
;                     sa += dpp_x1(sa);
;                     sb += dpp_x1(sb);
;                     sa += __shfl_xor(sa, 16); sa += __shfl_xor(sa, 32); sb += __shfl_xor(sb, 16); sb += __shfl_xor(sb, 32);
;                     if (fq == 0 && !odd) ps[(size_t)(rl + q) * 64] = (f32x2){sa, sb};
	v_pk_add_f32 v[56:57], v[56:57], v[58:59]
	ds_bpermute_b32 v58, v131, v56
	ds_bpermute_b32 v59, v131, v57
	s_and_saveexec_b64 s[56:57], s[10:11]
	s_cbranch_execz .LBB0_600
	s_waitcnt lgkmcnt(0)
	v_pk_add_f32 v[56:57], v[56:57], v[58:59]
	v_add_co_u32_e32 v58, vcc, 0x10000, v124
	s_nop 1
	v_addc_co_u32_e32 v59, vcc, 0, v125, vcc
	v_mov_b32_e32 v250, v56
	v_mov_b32_e32 v251, v57
.LBB0_600:
	s_or_b64 exec, exec, s[56:57]
	v_cndmask_b32_e64 v53, v53, v97, s[8:9]
	v_cndmask_b32_e64 v52, v52, v93, s[8:9]
	v_cndmask_b32_e64 v55, v55, v98, s[8:9]
	v_cndmask_b32_e64 v54, v54, v95, s[8:9]
	v_cndmask_b32_e64 v49, v49, v101, s[8:9]
	v_cndmask_b32_e64 v48, v48, v99, s[8:9]
	v_cndmask_b32_e64 v51, v51, v102, s[8:9]
	v_cndmask_b32_e64 v50, v50, v100, s[8:9]
	v_lshlrev_b32_e32 v56, 16, v88
	v_and_b32_e32 v57, 0xffff0000, v88
	s_waitcnt lgkmcnt(1)
	v_lshlrev_b32_e32 v58, 16, v89
	s_waitcnt lgkmcnt(0)
	v_and_b32_e32 v59, 0xffff0000, v89
	v_lshlrev_b32_e32 v60, 16, v90
	v_and_b32_e32 v61, 0xffff0000, v90
	v_lshlrev_b32_e32 v62, 16, v91
	v_and_b32_e32 v63, 0xffff0000, v91
	v_pk_fma_f32 v[54:55], v[58:59], s[18:19], v[54:55] op_sel_hi:[1,0,1]
	v_pk_fma_f32 v[52:53], v[56:57], s[18:19], v[52:53] op_sel_hi:[1,0,1]
	v_pk_fma_f32 v[50:51], v[62:63], s[18:19], v[50:51] op_sel_hi:[1,0,1]
	v_pk_fma_f32 v[48:49], v[60:61], s[18:19], v[48:49] op_sel_hi:[1,0,1]
	v_cvt_pk_bf16_f32 v52, v52, v53
	v_cvt_pk_bf16_f32 v53, v54, v55
	v_mov_b32_e32 v97, v165
	v_cvt_pk_bf16_f32 v54, v48, v49
	v_cvt_pk_bf16_f32 v55, v50, v51
	v_lshlrev_b32_e32 v48, 16, v52
	v_and_b32_e32 v50, 0xffff0000, v52
	v_lshlrev_b32_e32 v56, 16, v53
	v_and_b32_e32 v58, 0xffff0000, v53
	v_lshlrev_b32_e32 v60, 16, v54
	v_and_b32_e32 v62, 0xffff0000, v54
	v_lshlrev_b32_e32 v88, 16, v55
	v_and_b32_e32 v90, 0xffff0000, v55
	v_mul_f32_e32 v49, v48, v48
	v_mul_f32_e32 v51, v50, v50
	v_mul_f32_e32 v57, v56, v56
	v_mul_f32_e32 v59, v58, v58
	v_mul_f32_e32 v61, v60, v60
	v_mul_f32_e32 v63, v62, v62
	v_mul_f32_e32 v89, v88, v88
	v_mul_f32_e32 v91, v90, v90
	v_pk_add_f32 v[48:49], v[48:49], v[50:51]
	v_pk_add_f32 v[50:51], v[56:57], v[58:59]
	v_pk_add_f32 v[56:57], v[88:89], v[90:91]
	v_pk_add_f32 v[48:49], v[48:49], v[50:51]
	v_pk_add_f32 v[50:51], v[60:61], v[62:63]
	s_nop 0
	v_pk_add_f32 v[50:51], v[50:51], v[56:57]
	v_lshl_add_u64 v[56:57], s[54:55], 0, v[96:97]
	v_pk_add_f32 v[48:49], v[48:49], v[50:51]
	v_mov_b32_e32 v50, v165
	v_mov_b32_e32 v51, v165
	global_store_dwordx4 v[56:57], v[52:55], off offset:128
	v_mov_b32_dpp v50, v48 quad_perm:[1,0,3,2] row_mask:0xf bank_mask:0xf
	v_mov_b32_dpp v51, v49 quad_perm:[1,0,3,2] row_mask:0xf bank_mask:0xf
	v_pk_add_f32 v[48:49], v[48:49], v[50:51]
	ds_bpermute_b32 v50, v130, v48
	ds_bpermute_b32 v51, v130, v49
	s_waitcnt lgkmcnt(0)
	v_pk_add_f32 v[48:49], v[48:49], v[50:51]
	ds_bpermute_b32 v50, v131, v48
	ds_bpermute_b32 v51, v131, v49
	s_and_saveexec_b64 s[56:57], s[10:11]
	s_cbranch_execz .LBB0_602
	s_waitcnt lgkmcnt(0)
	v_pk_add_f32 v[48:49], v[48:49], v[50:51]
	v_add_co_u32_e32 v50, vcc, 0x10000, v124
	s_nop 1
	v_addc_co_u32_e32 v51, vcc, 0, v125, vcc
	v_mov_b32_e32 v252, v250
	v_mov_b32_e32 v253, v251
	v_mov_b32_e32 v254, v48
	v_mov_b32_e32 v255, v49
	global_store_dwordx4 v249, v[252:255], s[94:95] offset:1024
.LBB0_602:
	s_or_b64 exec, exec, s[56:57]
	s_waitcnt lgkmcnt(1)
	v_cndmask_b32_e64 v50, v44, v36, s[8:9]
	v_mov_b32_e32 v48, 0
	v_cndmask_b32_e64 v49, v45, v37, s[8:9]
	s_waitcnt lgkmcnt(0)
	v_cndmask_b32_e64 v51, v46, v38, s[8:9]
	v_mov_b32_dpp v48, v50 quad_perm:[1,0,3,2] row_mask:0xf bank_mask:0xf
	v_mov_b32_e32 v50, 0
	v_cndmask_b32_e64 v52, v47, v39, s[8:9]
	v_cndmask_b32_e64 v54, v40, v32, s[8:9]
	v_mov_b32_dpp v50, v49 quad_perm:[1,0,3,2] row_mask:0xf bank_mask:0xf
	v_mov_b32_e32 v49, 0
	v_cndmask_b32_e64 v53, v41, v33, s[8:9]
	v_cndmask_b32_e64 v55, v42, v34, s[8:9]
	v_mov_b32_dpp v49, v51 quad_perm:[1,0,3,2] row_mask:0xf bank_mask:0xf
	v_mov_b32_e32 v51, 0
	v_cndmask_b32_e64 v56, v43, v35, s[8:9]
	v_cndmask_b32_e64 v45, v50, v45, s[8:9]
	v_mov_b32_dpp v51, v52 quad_perm:[1,0,3,2] row_mask:0xf bank_mask:0xf
	v_mov_b32_e32 v52, 0
	v_cndmask_b32_e64 v44, v48, v44, s[8:9]
	v_cndmask_b32_e64 v47, v51, v47, s[8:9]
	v_mov_b32_dpp v52, v54 quad_perm:[1,0,3,2] row_mask:0xf bank_mask:0xf
	v_mov_b32_e32 v54, 0
	v_cndmask_b32_e64 v46, v49, v46, s[8:9]
	v_cndmask_b32_e64 v40, v52, v40, s[8:9]
	v_mov_b32_dpp v54, v53 quad_perm:[1,0,3,2] row_mask:0xf bank_mask:0xf
	v_mov_b32_e32 v53, 0
	v_cndmask_b32_e64 v41, v54, v41, s[8:9]
	v_and_b32_e32 v57, 0xffff0000, v84
	v_mov_b32_dpp v53, v55 quad_perm:[1,0,3,2] row_mask:0xf bank_mask:0xf
	v_mov_b32_e32 v55, 0
	v_cndmask_b32_e64 v42, v53, v42, s[8:9]
	v_lshlrev_b32_e32 v58, 16, v85
	v_mov_b32_dpp v55, v56 quad_perm:[1,0,3,2] row_mask:0xf bank_mask:0xf
	v_cndmask_b32_e64 v43, v55, v43, s[8:9]
	v_lshlrev_b32_e32 v56, 16, v84
	v_and_b32_e32 v59, 0xffff0000, v85
	v_lshlrev_b32_e32 v60, 16, v86
	v_and_b32_e32 v61, 0xffff0000, v86
	v_lshlrev_b32_e32 v62, 16, v87
	v_and_b32_e32 v63, 0xffff0000, v87
	v_pk_fma_f32 v[46:47], v[58:59], s[18:19], v[46:47] op_sel_hi:[1,0,1]
	v_pk_fma_f32 v[44:45], v[56:57], s[18:19], v[44:45] op_sel_hi:[1,0,1]
	v_pk_fma_f32 v[42:43], v[62:63], s[18:19], v[42:43] op_sel_hi:[1,0,1]
	v_pk_fma_f32 v[40:41], v[60:61], s[18:19], v[40:41] op_sel_hi:[1,0,1]
	v_cvt_pk_bf16_f32 v56, v44, v45
	v_cvt_pk_bf16_f32 v57, v46, v47
	v_mov_b32_e32 v95, v165
	v_cvt_pk_bf16_f32 v58, v40, v41
	v_cvt_pk_bf16_f32 v59, v42, v43
	v_lshlrev_b32_e32 v40, 16, v56
	v_and_b32_e32 v42, 0xffff0000, v56
	v_lshlrev_b32_e32 v44, 16, v57
	v_and_b32_e32 v46, 0xffff0000, v57
	v_lshlrev_b32_e32 v60, 16, v58
	v_and_b32_e32 v62, 0xffff0000, v58
	v_lshlrev_b32_e32 v84, 16, v59
	v_and_b32_e32 v86, 0xffff0000, v59
	v_mul_f32_e32 v41, v40, v40
	v_mul_f32_e32 v43, v42, v42
	v_mul_f32_e32 v45, v44, v44
	v_mul_f32_e32 v47, v46, v46
	v_mul_f32_e32 v61, v60, v60
	v_mul_f32_e32 v63, v62, v62
	v_mul_f32_e32 v85, v84, v84
	v_mul_f32_e32 v87, v86, v86
	v_pk_add_f32 v[40:41], v[40:41], v[42:43]
	v_pk_add_f32 v[42:43], v[44:45], v[46:47]
	v_pk_add_f32 v[44:45], v[84:85], v[86:87]
	v_pk_add_f32 v[40:41], v[40:41], v[42:43]
	v_pk_add_f32 v[42:43], v[60:61], v[62:63]
	s_nop 0
	v_pk_add_f32 v[42:43], v[42:43], v[44:45]
	s_nop 0
	v_pk_add_f32 v[40:41], v[40:41], v[42:43]
	v_mov_b32_e32 v42, v165
	v_mov_b32_e32 v43, v165
	s_nop 0
	v_mov_b32_dpp v42, v40 quad_perm:[1,0,3,2] row_mask:0xf bank_mask:0xf
	v_mov_b32_dpp v43, v41 quad_perm:[1,0,3,2] row_mask:0xf bank_mask:0xf
	v_pk_add_f32 v[40:41], v[40:41], v[42:43]
	ds_bpermute_b32 v42, v130, v40
	ds_bpermute_b32 v43, v130, v41
	s_waitcnt lgkmcnt(0)
	v_pk_add_f32 v[42:43], v[40:41], v[42:43]
	ds_bpermute_b32 v44, v131, v42
	ds_bpermute_b32 v45, v131, v43
	v_lshl_add_u64 v[40:41], s[54:55], 0, v[94:95]
	global_store_dwordx4 v[40:41], v[56:59], off
	s_and_saveexec_b64 s[56:57], s[10:11]
	s_cbranch_execz .LBB0_604
;     __device__ __forceinline__ void operator()(const f32x4 (&acc)[2][2][4][2], const Unit& u, int wr, int wc, int fr, int fq, const EpiCtx& X) const {
;     ...
;             for (int m = 0; m < 4; ++m) { const unsigned off = lo + (unsigned)((ai * HALF + m * 16) * 64) * 2u; raw[2 * m] = *(const u32x4*)(xb + off); raw[2 * m + 1] = *(const u32x4*)(xb + off + 128); }
; #pragma unroll
;             for (int m = 0; m < 4; ++m) {
;                 const int rl = ai * HALF + m * 16; const unsigned off = lo + (unsigned)(rl * 64) * 2u;
;                 const f32x4 o0a = acc[ai][0][m][0], o0b = acc[ai][0][m][1], o1a = acc[ai][1][m][0], o1b = acc[ai][1][m][1];
;                 const f32x4 ra_ = dpp_swap1(odd ? o0a : o1a), rb_ = dpp_swap1(odd ? o0b : o1b);
;                 const f32x4 pa[2] = {odd ? ra_ : o0a, odd ? o1a : ra_}, pb[2] = {odd ? rb_ : o0b, odd ? o1b : rb_};
; #pragma unroll
;                 for (int q = 0; q < 2; ++q) {
;                     const u32x4 w0 = raw[2 * m + q];
;                     const f32x4 r0 = (f32x4){bf_lo(w0.x), bf_hi(w0.x), bf_lo(w0.y), bf_hi(w0.y)}, r1 = (f32x4){bf_lo(w0.z), bf_hi(w0.z), bf_lo(w0.w), bf_hi(w0.w)};
;                     f32x4 y0, y1;
;                     if (RESN) { const f32x2 t = tbl[rl + q]; const float mu = t.x, ra = t.y * ALPHA; y0 = (r0 - mu) * ra * g0 + b0 + pa[q]; y1 = (r1 - mu) * ra * g1 + b1 + pb[q]; }
;                     else { y0 = r0 * ALPHA + pa[q]; y1 = r1 * ALPHA + pb[q]; }
;                     { const u32x4 w = pack8f(y0, y1); *(u32x4*)(xb + off + q * 128) = w;
;                         y0 = (f32x4){bf_lo(w.x), bf_hi(w.x), bf_lo(w.y), bf_hi(w.y)}; y1 = (f32x4){bf_lo(w.z), bf_hi(w.z), bf_lo(w.w), bf_hi(w.w)}; }
;                     float sa = ((y0[0] + y0[1]) + (y0[2] + y0[3])) + ((y1[0] + y1[1]) + (y1[2] + y1[3]));
;                     float sb = ((y0[0] * y0[0] + y0[1] * y0[1]) + (y0[2] * y0[2] + y0[3] * y0[3])) + ((y1[0] * y1[0] + y1[1] * y1[1]) + (y1[2] * y1[2] + y1[3] * y1[3]));
;                     sa += dpp_x1(sa);
;                     sb += dpp_x1(sb);
;                     sa += __shfl_xor(sa, 16); sa += __shfl_xor(sa, 32); sb += __shfl_xor(sb, 16); sb += __shfl_xor(sb, 32);
;                     if (fq == 0 && !odd) ps[(size_t)(rl + q) * 64] = (f32x2){sa, sb};
	s_waitcnt lgkmcnt(0)
	v_pk_add_f32 v[42:43], v[42:43], v[44:45]
	v_add_co_u32_e32 v44, vcc, 0x12000, v124
	s_nop 1
	v_addc_co_u32_e32 v45, vcc, 0, v125, vcc
	v_mov_b32_e32 v250, v42
	v_mov_b32_e32 v251, v43
.LBB0_604:
	s_or_b64 exec, exec, s[56:57]
	v_cndmask_b32_e64 v37, v37, v50, s[8:9]
	v_cndmask_b32_e64 v36, v36, v48, s[8:9]
	v_cndmask_b32_e64 v39, v39, v51, s[8:9]
	v_cndmask_b32_e64 v38, v38, v49, s[8:9]
	v_cndmask_b32_e64 v33, v33, v54, s[8:9]
	v_cndmask_b32_e64 v32, v32, v52, s[8:9]
	v_cndmask_b32_e64 v35, v35, v55, s[8:9]
	v_cndmask_b32_e64 v34, v34, v53, s[8:9]
	v_lshlrev_b32_e32 v42, 16, v80
	v_and_b32_e32 v43, 0xffff0000, v80
	s_waitcnt lgkmcnt(1)
	v_lshlrev_b32_e32 v44, 16, v81
	s_waitcnt lgkmcnt(0)
	v_and_b32_e32 v45, 0xffff0000, v81
	v_lshlrev_b32_e32 v46, 16, v82
	v_and_b32_e32 v47, 0xffff0000, v82
	v_lshlrev_b32_e32 v48, 16, v83
	v_and_b32_e32 v49, 0xffff0000, v83
	v_pk_fma_f32 v[38:39], v[44:45], s[18:19], v[38:39] op_sel_hi:[1,0,1]
	v_pk_fma_f32 v[36:37], v[42:43], s[18:19], v[36:37] op_sel_hi:[1,0,1]
	v_pk_fma_f32 v[34:35], v[48:49], s[18:19], v[34:35] op_sel_hi:[1,0,1]
	v_pk_fma_f32 v[32:33], v[46:47], s[18:19], v[32:33] op_sel_hi:[1,0,1]
	v_cvt_pk_bf16_f32 v36, v36, v37
	v_cvt_pk_bf16_f32 v37, v38, v39
	s_nop 0
	v_cvt_pk_bf16_f32 v38, v32, v33
	v_cvt_pk_bf16_f32 v39, v34, v35
	v_lshlrev_b32_e32 v32, 16, v36
	v_and_b32_e32 v34, 0xffff0000, v36
	v_lshlrev_b32_e32 v42, 16, v37
	v_and_b32_e32 v44, 0xffff0000, v37
	v_lshlrev_b32_e32 v46, 16, v38
	v_and_b32_e32 v48, 0xffff0000, v38
	v_lshlrev_b32_e32 v50, 16, v39
	v_and_b32_e32 v52, 0xffff0000, v39
	v_mul_f32_e32 v33, v32, v32
	v_mul_f32_e32 v35, v34, v34
	v_mul_f32_e32 v43, v42, v42
	v_mul_f32_e32 v45, v44, v44
	v_mul_f32_e32 v47, v46, v46
	v_mul_f32_e32 v49, v48, v48
	v_mul_f32_e32 v51, v50, v50
	v_mul_f32_e32 v53, v52, v52
	v_pk_add_f32 v[32:33], v[32:33], v[34:35]
	v_pk_add_f32 v[34:35], v[42:43], v[44:45]
	v_pk_add_f32 v[42:43], v[50:51], v[52:53]
	v_pk_add_f32 v[32:33], v[32:33], v[34:35]
	v_pk_add_f32 v[34:35], v[46:47], v[48:49]
	global_store_dwordx4 v[40:41], v[36:39], off offset:128
	v_pk_add_f32 v[34:35], v[34:35], v[42:43]
	s_nop 0
	v_pk_add_f32 v[32:33], v[32:33], v[34:35]
	v_mov_b32_e32 v34, v165
	v_mov_b32_e32 v35, v165
	s_nop 0
	v_mov_b32_dpp v34, v32 quad_perm:[1,0,3,2] row_mask:0xf bank_mask:0xf
	v_mov_b32_dpp v35, v33 quad_perm:[1,0,3,2] row_mask:0xf bank_mask:0xf
	v_pk_add_f32 v[32:33], v[32:33], v[34:35]
	ds_bpermute_b32 v34, v130, v32
	ds_bpermute_b32 v35, v130, v33
	s_waitcnt lgkmcnt(0)
	v_pk_add_f32 v[32:33], v[32:33], v[34:35]
	ds_bpermute_b32 v34, v131, v32
	ds_bpermute_b32 v35, v131, v33
	s_and_saveexec_b64 s[56:57], s[10:11]
	s_cbranch_execz .LBB0_606
	s_waitcnt lgkmcnt(0)
	v_pk_add_f32 v[32:33], v[32:33], v[34:35]
	v_add_co_u32_e32 v34, vcc, 0x12000, v124
	s_nop 1
	v_addc_co_u32_e32 v35, vcc, 0, v125, vcc
	v_mov_b32_e32 v252, v250
	v_mov_b32_e32 v253, v251
	v_mov_b32_e32 v254, v32
	v_mov_b32_e32 v255, v33
	global_store_dwordx4 v249, v[252:255], s[94:95] offset:1152
.LBB0_606:
	s_or_b64 exec, exec, s[56:57]
	s_waitcnt lgkmcnt(1)
	v_cndmask_b32_e64 v34, v28, v20, s[8:9]
	v_mov_b32_e32 v32, 0
	v_cndmask_b32_e64 v33, v29, v21, s[8:9]
	s_waitcnt lgkmcnt(0)
	v_cndmask_b32_e64 v35, v30, v22, s[8:9]
	v_mov_b32_dpp v32, v34 quad_perm:[1,0,3,2] row_mask:0xf bank_mask:0xf
	v_mov_b32_e32 v34, 0
	v_cndmask_b32_e64 v36, v31, v23, s[8:9]
	v_cndmask_b32_e64 v38, v24, v16, s[8:9]
	v_mov_b32_dpp v34, v33 quad_perm:[1,0,3,2] row_mask:0xf bank_mask:0xf
	v_mov_b32_e32 v33, 0
	v_cndmask_b32_e64 v37, v25, v17, s[8:9]
	v_cndmask_b32_e64 v39, v26, v18, s[8:9]
	v_mov_b32_dpp v33, v35 quad_perm:[1,0,3,2] row_mask:0xf bank_mask:0xf
	v_mov_b32_e32 v35, 0
	v_cndmask_b32_e64 v40, v27, v19, s[8:9]
	v_cndmask_b32_e64 v29, v34, v29, s[8:9]
	v_mov_b32_dpp v35, v36 quad_perm:[1,0,3,2] row_mask:0xf bank_mask:0xf
	v_mov_b32_e32 v36, 0
	v_cndmask_b32_e64 v28, v32, v28, s[8:9]
	v_cndmask_b32_e64 v31, v35, v31, s[8:9]
	v_mov_b32_dpp v36, v38 quad_perm:[1,0,3,2] row_mask:0xf bank_mask:0xf
	v_mov_b32_e32 v38, 0
	v_cndmask_b32_e64 v30, v33, v30, s[8:9]
	v_cndmask_b32_e64 v24, v36, v24, s[8:9]
	v_mov_b32_dpp v38, v37 quad_perm:[1,0,3,2] row_mask:0xf bank_mask:0xf
	v_mov_b32_e32 v37, 0
	v_cndmask_b32_e64 v25, v38, v25, s[8:9]
	s_waitcnt vmcnt(9)
	v_and_b32_e32 v41, 0xffff0000, v76
	v_mov_b32_dpp v37, v39 quad_perm:[1,0,3,2] row_mask:0xf bank_mask:0xf
	v_mov_b32_e32 v39, 0
	v_cndmask_b32_e64 v26, v37, v26, s[8:9]
	v_lshlrev_b32_e32 v42, 16, v77
	v_mov_b32_dpp v39, v40 quad_perm:[1,0,3,2] row_mask:0xf bank_mask:0xf
	v_cndmask_b32_e64 v27, v39, v27, s[8:9]
	v_lshlrev_b32_e32 v40, 16, v76
	v_and_b32_e32 v43, 0xffff0000, v77
	v_lshlrev_b32_e32 v44, 16, v78
	v_and_b32_e32 v45, 0xffff0000, v78
	v_lshlrev_b32_e32 v46, 16, v79
	v_and_b32_e32 v47, 0xffff0000, v79
	v_pk_fma_f32 v[30:31], v[42:43], s[18:19], v[30:31] op_sel_hi:[1,0,1]
	v_pk_fma_f32 v[28:29], v[40:41], s[18:19], v[28:29] op_sel_hi:[1,0,1]
	v_pk_fma_f32 v[26:27], v[46:47], s[18:19], v[26:27] op_sel_hi:[1,0,1]
	v_pk_fma_f32 v[24:25], v[44:45], s[18:19], v[24:25] op_sel_hi:[1,0,1]
	v_cvt_pk_bf16_f32 v40, v28, v29
	v_cvt_pk_bf16_f32 v41, v30, v31
	v_mov_b32_e32 v93, v165
	v_cvt_pk_bf16_f32 v42, v24, v25
	v_cvt_pk_bf16_f32 v43, v26, v27
	v_lshlrev_b32_e32 v24, 16, v40
	v_and_b32_e32 v26, 0xffff0000, v40
	v_lshlrev_b32_e32 v28, 16, v41
	v_and_b32_e32 v30, 0xffff0000, v41
	v_lshlrev_b32_e32 v44, 16, v42
	v_and_b32_e32 v46, 0xffff0000, v42
	v_lshlrev_b32_e32 v48, 16, v43
	v_and_b32_e32 v50, 0xffff0000, v43
	v_mul_f32_e32 v25, v24, v24
	v_mul_f32_e32 v27, v26, v26
	v_mul_f32_e32 v29, v28, v28
	v_mul_f32_e32 v31, v30, v30
	v_mul_f32_e32 v45, v44, v44
	v_mul_f32_e32 v47, v46, v46
	v_mul_f32_e32 v49, v48, v48
	v_mul_f32_e32 v51, v50, v50
	v_pk_add_f32 v[24:25], v[24:25], v[26:27]
	v_pk_add_f32 v[26:27], v[28:29], v[30:31]
	v_pk_add_f32 v[28:29], v[48:49], v[50:51]
	v_pk_add_f32 v[24:25], v[24:25], v[26:27]
	v_pk_add_f32 v[26:27], v[44:45], v[46:47]
	s_nop 0
	v_pk_add_f32 v[26:27], v[26:27], v[28:29]
	s_nop 0
	v_pk_add_f32 v[24:25], v[24:25], v[26:27]
	v_mov_b32_e32 v26, v165
	v_mov_b32_e32 v27, v165
	s_nop 0
	v_mov_b32_dpp v26, v24 quad_perm:[1,0,3,2] row_mask:0xf bank_mask:0xf
	v_mov_b32_dpp v27, v25 quad_perm:[1,0,3,2] row_mask:0xf bank_mask:0xf
	v_pk_add_f32 v[24:25], v[24:25], v[26:27]
	ds_bpermute_b32 v26, v130, v24
	ds_bpermute_b32 v27, v130, v25
	s_waitcnt lgkmcnt(0)
	v_pk_add_f32 v[26:27], v[24:25], v[26:27]
	ds_bpermute_b32 v28, v131, v26
	ds_bpermute_b32 v29, v131, v27
	v_lshl_add_u64 v[24:25], s[54:55], 0, v[92:93]
	global_store_dwordx4 v[24:25], v[40:43], off
	s_and_saveexec_b64 s[56:57], s[10:11]
	s_cbranch_execz .LBB0_608
	s_waitcnt lgkmcnt(0)
	v_pk_add_f32 v[26:27], v[26:27], v[28:29]
	v_add_co_u32_e32 v28, vcc, 0x14000, v124
	s_nop 1
	v_addc_co_u32_e32 v29, vcc, 0, v125, vcc
	v_mov_b32_e32 v250, v26
	v_mov_b32_e32 v251, v27
;     __device__ __forceinline__ void operator()(const f32x4 (&acc)[2][2][4][2], const Unit& u, int wr, int wc, int fr, int fq, const EpiCtx& X) const {
;     ...
;             for (int m = 0; m < 4; ++m) { const unsigned off = lo + (unsigned)((ai * HALF + m * 16) * 64) * 2u; raw[2 * m] = *(const u32x4*)(xb + off); raw[2 * m + 1] = *(const u32x4*)(xb + off + 128); }
; #pragma unroll
;             for (int m = 0; m < 4; ++m) {
;                 const int rl = ai * HALF + m * 16; const unsigned off = lo + (unsigned)(rl * 64) * 2u;
;                 const f32x4 o0a = acc[ai][0][m][0], o0b = acc[ai][0][m][1], o1a = acc[ai][1][m][0], o1b = acc[ai][1][m][1];
;                 const f32x4 ra_ = dpp_swap1(odd ? o0a : o1a), rb_ = dpp_swap1(odd ? o0b : o1b);
;                 const f32x4 pa[2] = {odd ? ra_ : o0a, odd ? o1a : ra_}, pb[2] = {odd ? rb_ : o0b, odd ? o1b : rb_};
; #pragma unroll
;                 for (int q = 0; q < 2; ++q) {
;                     const u32x4 w0 = raw[2 * m + q];
;                     const f32x4 r0 = (f32x4){bf_lo(w0.x), bf_hi(w0.x), bf_lo(w0.y), bf_hi(w0.y)}, r1 = (f32x4){bf_lo(w0.z), bf_hi(w0.z), bf_lo(w0.w), bf_hi(w0.w)};
;                     f32x4 y0, y1;
;                     if (RESN) { const f32x2 t = tbl[rl + q]; const float mu = t.x, ra = t.y * ALPHA; y0 = (r0 - mu) * ra * g0 + b0 + pa[q]; y1 = (r1 - mu) * ra * g1 + b1 + pb[q]; }
;                     else { y0 = r0 * ALPHA + pa[q]; y1 = r1 * ALPHA + pb[q]; }
;                     { const u32x4 w = pack8f(y0, y1); *(u32x4*)(xb + off + q * 128) = w;
;                         y0 = (f32x4){bf_lo(w.x), bf_hi(w.x), bf_lo(w.y), bf_hi(w.y)}; y1 = (f32x4){bf_lo(w.z), bf_hi(w.z), bf_lo(w.w), bf_hi(w.w)}; }
;                     float sa = ((y0[0] + y0[1]) + (y0[2] + y0[3])) + ((y1[0] + y1[1]) + (y1[2] + y1[3]));
;                     float sb = ((y0[0] * y0[0] + y0[1] * y0[1]) + (y0[2] * y0[2] + y0[3] * y0[3])) + ((y1[0] * y1[0] + y1[1] * y1[1]) + (y1[2] * y1[2] + y1[3] * y1[3]));
;                     sa += dpp_x1(sa);
;                     sb += dpp_x1(sb);
;                     sa += __shfl_xor(sa, 16); sa += __shfl_xor(sa, 32); sb += __shfl_xor(sb, 16); sb += __shfl_xor(sb, 32);
;                     if (fq == 0 && !odd) ps[(size_t)(rl + q) * 64] = (f32x2){sa, sb};
.LBB0_608:
	s_or_b64 exec, exec, s[56:57]
	v_cndmask_b32_e64 v21, v21, v34, s[8:9]
	v_cndmask_b32_e64 v20, v20, v32, s[8:9]
	v_cndmask_b32_e64 v23, v23, v35, s[8:9]
	v_cndmask_b32_e64 v22, v22, v33, s[8:9]
	v_cndmask_b32_e64 v17, v17, v38, s[8:9]
	v_cndmask_b32_e64 v16, v16, v36, s[8:9]
	v_cndmask_b32_e64 v19, v19, v39, s[8:9]
	v_cndmask_b32_e64 v18, v18, v37, s[8:9]
	s_waitcnt vmcnt(9)
	v_lshlrev_b32_e32 v26, 16, v72
	v_and_b32_e32 v27, 0xffff0000, v72
	s_waitcnt lgkmcnt(1)
	v_lshlrev_b32_e32 v28, 16, v73
	s_waitcnt lgkmcnt(0)
	v_and_b32_e32 v29, 0xffff0000, v73
	v_lshlrev_b32_e32 v30, 16, v74
	v_and_b32_e32 v31, 0xffff0000, v74
	v_lshlrev_b32_e32 v32, 16, v75
	v_and_b32_e32 v33, 0xffff0000, v75
	v_pk_fma_f32 v[22:23], v[28:29], s[18:19], v[22:23] op_sel_hi:[1,0,1]
	v_pk_fma_f32 v[20:21], v[26:27], s[18:19], v[20:21] op_sel_hi:[1,0,1]
	v_pk_fma_f32 v[18:19], v[32:33], s[18:19], v[18:19] op_sel_hi:[1,0,1]
	v_pk_fma_f32 v[16:17], v[30:31], s[18:19], v[16:17] op_sel_hi:[1,0,1]
	v_cvt_pk_bf16_f32 v20, v20, v21
	v_cvt_pk_bf16_f32 v21, v22, v23
	s_nop 0
	v_cvt_pk_bf16_f32 v22, v16, v17
	v_cvt_pk_bf16_f32 v23, v18, v19
	v_lshlrev_b32_e32 v16, 16, v20
	v_and_b32_e32 v18, 0xffff0000, v20
	v_lshlrev_b32_e32 v26, 16, v21
	v_and_b32_e32 v28, 0xffff0000, v21
	v_lshlrev_b32_e32 v30, 16, v22
	v_and_b32_e32 v32, 0xffff0000, v22
	v_lshlrev_b32_e32 v34, 16, v23
	v_and_b32_e32 v36, 0xffff0000, v23
	v_mul_f32_e32 v17, v16, v16
	v_mul_f32_e32 v19, v18, v18
	v_mul_f32_e32 v27, v26, v26
	v_mul_f32_e32 v29, v28, v28
	v_mul_f32_e32 v31, v30, v30
	v_mul_f32_e32 v33, v32, v32
	v_mul_f32_e32 v35, v34, v34
	v_mul_f32_e32 v37, v36, v36
	v_pk_add_f32 v[16:17], v[16:17], v[18:19]
	v_pk_add_f32 v[18:19], v[26:27], v[28:29]
	v_pk_add_f32 v[26:27], v[34:35], v[36:37]
	v_pk_add_f32 v[16:17], v[16:17], v[18:19]
	v_pk_add_f32 v[18:19], v[30:31], v[32:33]
	global_store_dwordx4 v[24:25], v[20:23], off offset:128
	v_pk_add_f32 v[18:19], v[18:19], v[26:27]
	s_nop 0
	v_pk_add_f32 v[16:17], v[16:17], v[18:19]
	v_mov_b32_e32 v18, v165
	v_mov_b32_e32 v19, v165
	s_nop 0
	v_mov_b32_dpp v18, v16 quad_perm:[1,0,3,2] row_mask:0xf bank_mask:0xf
	v_mov_b32_dpp v19, v17 quad_perm:[1,0,3,2] row_mask:0xf bank_mask:0xf
	v_pk_add_f32 v[16:17], v[16:17], v[18:19]
	ds_bpermute_b32 v18, v130, v16
	ds_bpermute_b32 v19, v130, v17
	s_waitcnt lgkmcnt(0)
	v_pk_add_f32 v[16:17], v[16:17], v[18:19]
	ds_bpermute_b32 v18, v131, v16
	ds_bpermute_b32 v19, v131, v17
	s_and_saveexec_b64 s[56:57], s[10:11]
	s_cbranch_execz .LBB0_610
	s_waitcnt lgkmcnt(0)
	v_pk_add_f32 v[16:17], v[16:17], v[18:19]
	v_add_co_u32_e32 v18, vcc, 0x14000, v124
	s_nop 1
	v_addc_co_u32_e32 v19, vcc, 0, v125, vcc
	v_mov_b32_e32 v252, v250
	v_mov_b32_e32 v253, v251
	v_mov_b32_e32 v254, v16
	v_mov_b32_e32 v255, v17
	global_store_dwordx4 v249, v[252:255], s[94:95] offset:1280
;     __device__ __forceinline__ void operator()(const f32x4 (&acc)[2][2][4][2], const Unit& u, int wr, int wc, int fr, int fq, const EpiCtx& X) const {
;     ...
;             for (int m = 0; m < 4; ++m) { const unsigned off = lo + (unsigned)((ai * HALF + m * 16) * 64) * 2u; raw[2 * m] = *(const u32x4*)(xb + off); raw[2 * m + 1] = *(const u32x4*)(xb + off + 128); }
; #pragma unroll
;             for (int m = 0; m < 4; ++m) {
;                 const int rl = ai * HALF + m * 16; const unsigned off = lo + (unsigned)(rl * 64) * 2u;
;                 const f32x4 o0a = acc[ai][0][m][0], o0b = acc[ai][0][m][1], o1a = acc[ai][1][m][0], o1b = acc[ai][1][m][1];
;                 const f32x4 ra_ = dpp_swap1(odd ? o0a : o1a), rb_ = dpp_swap1(odd ? o0b : o1b);
;                 const f32x4 pa[2] = {odd ? ra_ : o0a, odd ? o1a : ra_}, pb[2] = {odd ? rb_ : o0b, odd ? o1b : rb_};
; #pragma unroll
;                 for (int q = 0; q < 2; ++q) {
;                     const u32x4 w0 = raw[2 * m + q];
;                     const f32x4 r0 = (f32x4){bf_lo(w0.x), bf_hi(w0.x), bf_lo(w0.y), bf_hi(w0.y)}, r1 = (f32x4){bf_lo(w0.z), bf_hi(w0.z), bf_lo(w0.w), bf_hi(w0.w)};
;                     f32x4 y0, y1;
;                     if (RESN) { const f32x2 t = tbl[rl + q]; const float mu = t.x, ra = t.y * ALPHA; y0 = (r0 - mu) * ra * g0 + b0 + pa[q]; y1 = (r1 - mu) * ra * g1 + b1 + pb[q]; }
;                     else { y0 = r0 * ALPHA + pa[q]; y1 = r1 * ALPHA + pb[q]; }
;                     { const u32x4 w = pack8f(y0, y1); *(u32x4*)(xb + off + q * 128) = w;
;                         y0 = (f32x4){bf_lo(w.x), bf_hi(w.x), bf_lo(w.y), bf_hi(w.y)}; y1 = (f32x4){bf_lo(w.z), bf_hi(w.z), bf_lo(w.w), bf_hi(w.w)}; }
;                     float sa = ((y0[0] + y0[1]) + (y0[2] + y0[3])) + ((y1[0] + y1[1]) + (y1[2] + y1[3]));
;                     float sb = ((y0[0] * y0[0] + y0[1] * y0[1]) + (y0[2] * y0[2] + y0[3] * y0[3])) + ((y1[0] * y1[0] + y1[1] * y1[1]) + (y1[2] * y1[2] + y1[3] * y1[3]));
;                     sa += dpp_x1(sa);
;                     sb += dpp_x1(sb);
;                     sa += __shfl_xor(sa, 16); sa += __shfl_xor(sa, 32); sb += __shfl_xor(sb, 16); sb += __shfl_xor(sb, 32);
;                     if (fq == 0 && !odd) ps[(size_t)(rl + q) * 64] = (f32x2){sa, sb};
.LBB0_610:
	s_or_b64 exec, exec, s[56:57]
	s_waitcnt lgkmcnt(1)
	v_cndmask_b32_e64 v18, v12, v4, s[8:9]
	v_mov_b32_e32 v16, 0
	v_cndmask_b32_e64 v17, v13, v5, s[8:9]
	s_waitcnt lgkmcnt(0)
	v_cndmask_b32_e64 v19, v14, v6, s[8:9]
	v_mov_b32_dpp v16, v18 quad_perm:[1,0,3,2] row_mask:0xf bank_mask:0xf
	v_mov_b32_e32 v18, 0
	v_cndmask_b32_e64 v20, v15, v7, s[8:9]
	v_cndmask_b32_e64 v22, v8, v0, s[8:9]
	v_mov_b32_dpp v18, v17 quad_perm:[1,0,3,2] row_mask:0xf bank_mask:0xf
	v_mov_b32_e32 v17, 0
	v_cndmask_b32_e64 v21, v9, v1, s[8:9]
	v_cndmask_b32_e64 v23, v10, v2, s[8:9]
	v_mov_b32_dpp v17, v19 quad_perm:[1,0,3,2] row_mask:0xf bank_mask:0xf
	v_mov_b32_e32 v19, 0
	v_cndmask_b32_e64 v24, v11, v3, s[8:9]
	v_cndmask_b32_e64 v13, v18, v13, s[8:9]
	v_mov_b32_dpp v19, v20 quad_perm:[1,0,3,2] row_mask:0xf bank_mask:0xf
	v_mov_b32_e32 v20, 0
	v_cndmask_b32_e64 v12, v16, v12, s[8:9]
	v_cndmask_b32_e64 v15, v19, v15, s[8:9]
	v_mov_b32_dpp v20, v22 quad_perm:[1,0,3,2] row_mask:0xf bank_mask:0xf
	v_mov_b32_e32 v22, 0
	v_cndmask_b32_e64 v14, v17, v14, s[8:9]
	v_cndmask_b32_e64 v8, v20, v8, s[8:9]
	v_mov_b32_dpp v22, v21 quad_perm:[1,0,3,2] row_mask:0xf bank_mask:0xf
	v_mov_b32_e32 v21, 0
	v_cndmask_b32_e64 v9, v22, v9, s[8:9]
	s_waitcnt vmcnt(10)
	v_and_b32_e32 v25, 0xffff0000, v68
	v_mov_b32_dpp v21, v23 quad_perm:[1,0,3,2] row_mask:0xf bank_mask:0xf
	v_mov_b32_e32 v23, 0
	v_cndmask_b32_e64 v10, v21, v10, s[8:9]
	v_lshlrev_b32_e32 v26, 16, v69
	v_mov_b32_dpp v23, v24 quad_perm:[1,0,3,2] row_mask:0xf bank_mask:0xf
	v_cndmask_b32_e64 v11, v23, v11, s[8:9]
	v_lshlrev_b32_e32 v24, 16, v68
	v_and_b32_e32 v27, 0xffff0000, v69
	v_lshlrev_b32_e32 v28, 16, v70
	v_and_b32_e32 v29, 0xffff0000, v70
	v_lshlrev_b32_e32 v30, 16, v71
	v_and_b32_e32 v31, 0xffff0000, v71
	v_pk_fma_f32 v[14:15], v[26:27], s[18:19], v[14:15] op_sel_hi:[1,0,1]
	v_pk_fma_f32 v[12:13], v[24:25], s[18:19], v[12:13] op_sel_hi:[1,0,1]
	v_pk_fma_f32 v[10:11], v[30:31], s[18:19], v[10:11] op_sel_hi:[1,0,1]
	v_pk_fma_f32 v[8:9], v[28:29], s[18:19], v[8:9] op_sel_hi:[1,0,1]
	v_cvt_pk_bf16_f32 v24, v12, v13
	v_cvt_pk_bf16_f32 v25, v14, v15
	s_nop 0
	v_cvt_pk_bf16_f32 v26, v8, v9
	v_cvt_pk_bf16_f32 v27, v10, v11
	v_lshlrev_b32_e32 v8, 16, v24
	v_and_b32_e32 v10, 0xffff0000, v24
	v_lshlrev_b32_e32 v12, 16, v25
	v_and_b32_e32 v14, 0xffff0000, v25
	v_lshlrev_b32_e32 v28, 16, v26
	v_and_b32_e32 v30, 0xffff0000, v26
	v_lshlrev_b32_e32 v32, 16, v27
	v_and_b32_e32 v34, 0xffff0000, v27
	v_mul_f32_e32 v9, v8, v8
	v_mul_f32_e32 v11, v10, v10
	v_mul_f32_e32 v13, v12, v12
	v_mul_f32_e32 v15, v14, v14
	v_mul_f32_e32 v29, v28, v28
	v_mul_f32_e32 v31, v30, v30
	v_mul_f32_e32 v33, v32, v32
	v_mul_f32_e32 v35, v34, v34
	v_pk_add_f32 v[8:9], v[8:9], v[10:11]
	v_pk_add_f32 v[10:11], v[12:13], v[14:15]
	v_pk_add_f32 v[12:13], v[32:33], v[34:35]
	v_pk_add_f32 v[8:9], v[8:9], v[10:11]
	v_pk_add_f32 v[10:11], v[28:29], v[30:31]
	s_nop 0
	v_pk_add_f32 v[10:11], v[10:11], v[12:13]
	s_nop 0
	v_pk_add_f32 v[8:9], v[8:9], v[10:11]
	v_mov_b32_e32 v10, v165
	v_mov_b32_e32 v11, v165
	s_nop 0
	v_mov_b32_dpp v10, v8 quad_perm:[1,0,3,2] row_mask:0xf bank_mask:0xf
	v_mov_b32_dpp v11, v9 quad_perm:[1,0,3,2] row_mask:0xf bank_mask:0xf
	v_pk_add_f32 v[8:9], v[8:9], v[10:11]
	ds_bpermute_b32 v10, v130, v8
	ds_bpermute_b32 v11, v130, v9
	s_waitcnt lgkmcnt(0)
	v_pk_add_f32 v[10:11], v[8:9], v[10:11]
	ds_bpermute_b32 v12, v131, v10
	ds_bpermute_b32 v13, v131, v11
	v_lshl_add_u64 v[8:9], s[54:55], 0, v[164:165]
	global_store_dwordx4 v[8:9], v[24:27], off
	s_and_saveexec_b64 s[54:55], s[10:11]
	s_cbranch_execz .LBB0_612
	s_waitcnt lgkmcnt(0)
	v_pk_add_f32 v[10:11], v[10:11], v[12:13]
	v_add_co_u32_e32 v12, vcc, 0x16000, v124
	s_nop 1
	v_addc_co_u32_e32 v13, vcc, 0, v125, vcc
	v_mov_b32_e32 v250, v10
	v_mov_b32_e32 v251, v11
.LBB0_612:
	s_or_b64 exec, exec, s[54:55]
	v_cndmask_b32_e64 v5, v5, v18, s[8:9]
	v_cndmask_b32_e64 v4, v4, v16, s[8:9]
	v_cndmask_b32_e64 v7, v7, v19, s[8:9]
	v_cndmask_b32_e64 v6, v6, v17, s[8:9]
	v_cndmask_b32_e64 v1, v1, v22, s[8:9]
	v_cndmask_b32_e64 v0, v0, v20, s[8:9]
	v_cndmask_b32_e64 v3, v3, v23, s[8:9]
	v_cndmask_b32_e64 v2, v2, v21, s[8:9]
	s_waitcnt vmcnt(10)
	v_lshlrev_b32_e32 v10, 16, v64
	v_and_b32_e32 v11, 0xffff0000, v64
	s_waitcnt lgkmcnt(1)
	v_lshlrev_b32_e32 v12, 16, v65
	s_waitcnt lgkmcnt(0)
	v_and_b32_e32 v13, 0xffff0000, v65
	v_lshlrev_b32_e32 v14, 16, v66
	v_and_b32_e32 v15, 0xffff0000, v66
	v_lshlrev_b32_e32 v16, 16, v67
	v_and_b32_e32 v17, 0xffff0000, v67
	v_pk_fma_f32 v[6:7], v[12:13], s[18:19], v[6:7] op_sel_hi:[1,0,1]
	v_pk_fma_f32 v[4:5], v[10:11], s[18:19], v[4:5] op_sel_hi:[1,0,1]
	v_pk_fma_f32 v[2:3], v[16:17], s[18:19], v[2:3] op_sel_hi:[1,0,1]
	v_pk_fma_f32 v[0:1], v[14:15], s[18:19], v[0:1] op_sel_hi:[1,0,1]
	v_cvt_pk_bf16_f32 v4, v4, v5
	v_cvt_pk_bf16_f32 v5, v6, v7
	s_nop 0
	v_cvt_pk_bf16_f32 v6, v0, v1
	v_cvt_pk_bf16_f32 v7, v2, v3
	v_lshlrev_b32_e32 v0, 16, v4
	v_and_b32_e32 v2, 0xffff0000, v4
	v_lshlrev_b32_e32 v10, 16, v5
	v_and_b32_e32 v12, 0xffff0000, v5
	v_lshlrev_b32_e32 v14, 16, v6
	v_and_b32_e32 v16, 0xffff0000, v6
	v_lshlrev_b32_e32 v18, 16, v7
	v_and_b32_e32 v20, 0xffff0000, v7
	v_mul_f32_e32 v1, v0, v0
	v_mul_f32_e32 v3, v2, v2
	v_mul_f32_e32 v11, v10, v10
	v_mul_f32_e32 v13, v12, v12
	v_mul_f32_e32 v15, v14, v14
	v_mul_f32_e32 v17, v16, v16
	v_mul_f32_e32 v19, v18, v18
	v_mul_f32_e32 v21, v20, v20
	v_pk_add_f32 v[0:1], v[0:1], v[2:3]
	v_pk_add_f32 v[2:3], v[10:11], v[12:13]
	v_pk_add_f32 v[10:11], v[18:19], v[20:21]
	v_pk_add_f32 v[0:1], v[0:1], v[2:3]
	v_pk_add_f32 v[2:3], v[14:15], v[16:17]
	global_store_dwordx4 v[8:9], v[4:7], off offset:128
	v_pk_add_f32 v[2:3], v[2:3], v[10:11]
	s_nop 0
	v_pk_add_f32 v[0:1], v[0:1], v[2:3]
	v_mov_b32_e32 v2, v165
	v_mov_b32_e32 v3, v165
	s_nop 0
	v_mov_b32_dpp v2, v0 quad_perm:[1,0,3,2] row_mask:0xf bank_mask:0xf
	v_mov_b32_dpp v3, v1 quad_perm:[1,0,3,2] row_mask:0xf bank_mask:0xf
	v_pk_add_f32 v[0:1], v[0:1], v[2:3]
	ds_bpermute_b32 v2, v130, v0
	ds_bpermute_b32 v3, v130, v1
	s_waitcnt lgkmcnt(0)
	v_pk_add_f32 v[0:1], v[0:1], v[2:3]
	ds_bpermute_b32 v2, v131, v0
	ds_bpermute_b32 v3, v131, v1
	s_and_saveexec_b64 s[54:55], s[10:11]
	s_cbranch_execz .LBB0_614
	s_waitcnt lgkmcnt(0)
	v_pk_add_f32 v[0:1], v[0:1], v[2:3]
	v_add_co_u32_e32 v2, vcc, 0x16000, v124
	s_nop 1
	v_addc_co_u32_e32 v3, vcc, 0, v125, vcc
	v_mov_b32_e32 v252, v250
	v_mov_b32_e32 v253, v251
	v_mov_b32_e32 v254, v0
	v_mov_b32_e32 v255, v1
	global_store_dwordx4 v249, v[252:255], s[94:95] offset:1408

; #define LAS __attribute__((address_space(3)))
; __device__ __forceinline__ void build_tbl(const f32x2* PS, int pm, LAS unsigned char* lds, int wid, int lane) {
;     LAS f32x2* tbl = (LAS f32x2*)(lds + TBL_OFF);
;     const f32x2* p = PS + ((size_t)pm * BM + wid * 32) * 64 + lane;
; #pragma unroll 8
;     for (int i = 0; i < 32; ++i) {
;         const f32x2 v = p[(size_t)i * 64];
;         const float a = wave_sum(v.x), b = wave_sum(v.y);
;         if (lane == 0) { const float mu = a * (1.f / DM), var = fmaxf(b * (1.f / DM) - mu * mu, 0.f); tbl[wid * 32 + i] = (f32x2){mu, 1.f / sqrtf(var + LN_EPS)}; }
;     }
; }
; __device__ __forceinline__ void ensure_tbl(const f32x2* PS, int sid, int pm, const EpiCtx& X) {
;     volatile LAS unsigned* keyw = (volatile LAS unsigned*)(X.lds + MISC_OFF) + KEY_WORD;
;     const unsigned key = (unsigned)(sid * 64 + pm + 1);
;     if ((unsigned)__builtin_amdgcn_readfirstlane((int)keyw[0]) != key) {
;         build_tbl(PS, pm, X.lds, X.wid, X.lane);
;         asm volatile("s_waitcnt lgkmcnt(0)" ::: "memory"); __builtin_amdgcn_s_barrier(); asm volatile("" ::: "memory");
;         if (X.tid == 0) keyw[0] = key;
;     }
; }
.LBB0_692:
	v_mov_b32_e32 v128, s54
	ds_read_b32 v128, v128
	s_add_i32 s25, s60, 1
	s_ashr_i32 s61, s60, 31
	s_waitcnt lgkmcnt(0)
	v_readfirstlane_b32 s18, v128
	s_cmp_eq_u32 s18, s25
	s_cbranch_scc1 .LBB0_714
	s_ashr_i32 s61, s60, 31
	s_load_dwordx2 s[18:19], s[0:1], 0xb0
	s_lshl_b32 s62, s60, 11
	s_add_u32 s62, s62, s52
	s_add_u32 s62, s62, 0x5b800000
	v_lshlrev_b32_e32 v222, 17, v168
	s_waitcnt lgkmcnt(0)
	s_add_u32 s18, s18, s62
	s_addc_u32 s19, s19, 0
	global_load_dwordx4 v[128:131], v222, s[18:19]
	global_load_dwordx4 v[132:135], v222, s[18:19] offset:16
	global_load_dwordx4 v[136:139], v222, s[18:19] offset:32
	global_load_dwordx4 v[170:173], v222, s[18:19] offset:48
	global_load_dwordx4 v[174:177], v222, s[18:19] offset:64
	global_load_dwordx4 v[178:181], v222, s[18:19] offset:80
	global_load_dwordx4 v[182:185], v222, s[18:19] offset:96
	global_load_dwordx4 v[186:189], v222, s[18:19] offset:112
	global_load_dwordx4 v[190:193], v222, s[18:19] offset:128
	global_load_dwordx4 v[194:197], v222, s[18:19] offset:144
	global_load_dwordx4 v[198:201], v222, s[18:19] offset:160
	global_load_dwordx4 v[202:205], v222, s[18:19] offset:176
	global_load_dwordx4 v[206:209], v222, s[18:19] offset:192
	global_load_dwordx4 v[210:213], v222, s[18:19] offset:208
	global_load_dwordx4 v[214:217], v222, s[18:19] offset:224
	global_load_dwordx4 v[218:221], v222, s[18:19] offset:240
	s_waitcnt vmcnt(0)
	v_permlane32_swap_b32_e32 v128, v190
	v_permlane32_swap_b32_e32 v129, v191
	v_permlane32_swap_b32_e32 v130, v192
	v_permlane32_swap_b32_e32 v131, v193
	v_permlane32_swap_b32_e32 v132, v194
	v_permlane32_swap_b32_e32 v133, v195
	v_permlane32_swap_b32_e32 v134, v196
	v_permlane32_swap_b32_e32 v135, v197
	v_permlane32_swap_b32_e32 v136, v198
	v_permlane32_swap_b32_e32 v137, v199
	v_permlane32_swap_b32_e32 v138, v200
	v_permlane32_swap_b32_e32 v139, v201
	v_permlane32_swap_b32_e32 v170, v202
	v_permlane32_swap_b32_e32 v171, v203
	v_permlane32_swap_b32_e32 v172, v204
	v_permlane32_swap_b32_e32 v173, v205
	v_permlane32_swap_b32_e32 v174, v206
	v_permlane32_swap_b32_e32 v175, v207
	v_permlane32_swap_b32_e32 v176, v208
	v_permlane32_swap_b32_e32 v177, v209
	v_permlane32_swap_b32_e32 v178, v210
	v_permlane32_swap_b32_e32 v179, v211
	v_permlane32_swap_b32_e32 v180, v212
	v_permlane32_swap_b32_e32 v181, v213
	v_permlane32_swap_b32_e32 v182, v214
	v_permlane32_swap_b32_e32 v183, v215
	v_permlane32_swap_b32_e32 v184, v216
	v_permlane32_swap_b32_e32 v185, v217
	v_permlane32_swap_b32_e32 v186, v218
	v_permlane32_swap_b32_e32 v187, v219
	v_permlane32_swap_b32_e32 v188, v220
	v_permlane32_swap_b32_e32 v189, v221
	v_pk_add_f32 v[128:129], v[128:129], v[190:191]
	v_pk_add_f32 v[130:131], v[130:131], v[192:193]
	v_pk_add_f32 v[132:133], v[132:133], v[194:195]
	v_pk_add_f32 v[134:135], v[134:135], v[196:197]
	v_pk_add_f32 v[136:137], v[136:137], v[198:199]
	v_pk_add_f32 v[138:139], v[138:139], v[200:201]
	v_pk_add_f32 v[170:171], v[170:171], v[202:203]
	v_pk_add_f32 v[172:173], v[172:173], v[204:205]
	v_pk_add_f32 v[174:175], v[174:175], v[206:207]
	v_pk_add_f32 v[176:177], v[176:177], v[208:209]
	v_pk_add_f32 v[178:179], v[178:179], v[210:211]
	v_pk_add_f32 v[180:181], v[180:181], v[212:213]
	v_pk_add_f32 v[182:183], v[182:183], v[214:215]
	v_pk_add_f32 v[184:185], v[184:185], v[216:217]
	v_pk_add_f32 v[186:187], v[186:187], v[218:219]
	v_pk_add_f32 v[188:189], v[188:189], v[220:221]
	s_nop 1
	v_permlane16_swap_b32_e32 v128, v174
	v_permlane16_swap_b32_e32 v129, v175
	v_permlane16_swap_b32_e32 v130, v176
	v_permlane16_swap_b32_e32 v131, v177
	v_permlane16_swap_b32_e32 v132, v178
	v_permlane16_swap_b32_e32 v133, v179
	v_permlane16_swap_b32_e32 v134, v180
	v_permlane16_swap_b32_e32 v135, v181
	v_permlane16_swap_b32_e32 v136, v182
	v_permlane16_swap_b32_e32 v137, v183
	v_permlane16_swap_b32_e32 v138, v184
	v_permlane16_swap_b32_e32 v139, v185
	v_permlane16_swap_b32_e32 v170, v186
	v_permlane16_swap_b32_e32 v171, v187
	v_permlane16_swap_b32_e32 v172, v188
	v_permlane16_swap_b32_e32 v173, v189
	v_pk_add_f32 v[128:129], v[128:129], v[174:175]
	v_pk_add_f32 v[130:131], v[130:131], v[176:177]
	v_pk_add_f32 v[132:133], v[132:133], v[178:179]
	v_pk_add_f32 v[134:135], v[134:135], v[180:181]
	v_pk_add_f32 v[136:137], v[136:137], v[182:183]
	v_pk_add_f32 v[138:139], v[138:139], v[184:185]
	v_pk_add_f32 v[170:171], v[170:171], v[186:187]
	v_pk_add_f32 v[172:173], v[172:173], v[188:189]
	s_nop 1
	v_add_f32_dpp v128, v128, v128 row_ror:8 row_mask:0xf bank_mask:0xf
	v_add_f32_dpp v129, v129, v129 row_ror:8 row_mask:0xf bank_mask:0xf
	v_add_f32_dpp v130, v130, v130 row_ror:8 row_mask:0xf bank_mask:0xf
	v_add_f32_dpp v131, v131, v131 row_ror:8 row_mask:0xf bank_mask:0xf
	v_add_f32_dpp v132, v132, v132 row_ror:8 row_mask:0xf bank_mask:0xf
	v_add_f32_dpp v133, v133, v133 row_ror:8 row_mask:0xf bank_mask:0xf
	v_add_f32_dpp v134, v134, v134 row_ror:8 row_mask:0xf bank_mask:0xf
	v_add_f32_dpp v135, v135, v135 row_ror:8 row_mask:0xf bank_mask:0xf
	v_add_f32_dpp v136, v136, v136 row_ror:8 row_mask:0xf bank_mask:0xf
	v_add_f32_dpp v137, v137, v137 row_ror:8 row_mask:0xf bank_mask:0xf
	v_add_f32_dpp v138, v138, v138 row_ror:8 row_mask:0xf bank_mask:0xf
	v_add_f32_dpp v139, v139, v139 row_ror:8 row_mask:0xf bank_mask:0xf
	v_add_f32_dpp v170, v170, v170 row_ror:8 row_mask:0xf bank_mask:0xf
	v_add_f32_dpp v171, v171, v171 row_ror:8 row_mask:0xf bank_mask:0xf
	v_add_f32_dpp v172, v172, v172 row_ror:8 row_mask:0xf bank_mask:0xf
	v_add_f32_dpp v173, v173, v173 row_ror:8 row_mask:0xf bank_mask:0xf
	v_add_f32_dpp v128, v128, v128 row_ror:4 row_mask:0xf bank_mask:0xf
	v_add_f32_dpp v129, v129, v129 row_ror:4 row_mask:0xf bank_mask:0xf
; __device__ __forceinline__ void build_tbl(const f32x2* PS, int pm, LAS unsigned char* lds, int wid, int lane) {
;     ...
;         const f32x2 v = p[(size_t)i * 64];
;         const float a = wave_sum(v.x), b = wave_sum(v.y);
;         if (lane == 0) { const float mu = a * (1.f / DM), var = fmaxf(b * (1.f / DM) - mu * mu, 0.f); tbl[wid * 32 + i] = (f32x2){mu, 1.f / sqrtf(var + LN_EPS)}; }
	v_add_f32_dpp v130, v130, v130 row_ror:4 row_mask:0xf bank_mask:0xf
	v_add_f32_dpp v131, v131, v131 row_ror:4 row_mask:0xf bank_mask:0xf
	v_add_f32_dpp v132, v132, v132 row_ror:4 row_mask:0xf bank_mask:0xf
	v_add_f32_dpp v133, v133, v133 row_ror:4 row_mask:0xf bank_mask:0xf
	v_add_f32_dpp v134, v134, v134 row_ror:4 row_mask:0xf bank_mask:0xf
	v_add_f32_dpp v135, v135, v135 row_ror:4 row_mask:0xf bank_mask:0xf
	v_add_f32_dpp v136, v136, v136 row_ror:4 row_mask:0xf bank_mask:0xf
	v_add_f32_dpp v137, v137, v137 row_ror:4 row_mask:0xf bank_mask:0xf
	v_add_f32_dpp v138, v138, v138 row_ror:4 row_mask:0xf bank_mask:0xf
	v_add_f32_dpp v139, v139, v139 row_ror:4 row_mask:0xf bank_mask:0xf
	v_add_f32_dpp v170, v170, v170 row_ror:4 row_mask:0xf bank_mask:0xf
	v_add_f32_dpp v171, v171, v171 row_ror:4 row_mask:0xf bank_mask:0xf
	v_add_f32_dpp v172, v172, v172 row_ror:4 row_mask:0xf bank_mask:0xf
	v_add_f32_dpp v173, v173, v173 row_ror:4 row_mask:0xf bank_mask:0xf
	v_add_f32_dpp v128, v128, v128 row_ror:2 row_mask:0xf bank_mask:0xf
	v_add_f32_dpp v129, v129, v129 row_ror:2 row_mask:0xf bank_mask:0xf
	v_add_f32_dpp v130, v130, v130 row_ror:2 row_mask:0xf bank_mask:0xf
	v_add_f32_dpp v131, v131, v131 row_ror:2 row_mask:0xf bank_mask:0xf
	v_add_f32_dpp v132, v132, v132 row_ror:2 row_mask:0xf bank_mask:0xf
	v_add_f32_dpp v133, v133, v133 row_ror:2 row_mask:0xf bank_mask:0xf
	v_add_f32_dpp v134, v134, v134 row_ror:2 row_mask:0xf bank_mask:0xf
	v_add_f32_dpp v135, v135, v135 row_ror:2 row_mask:0xf bank_mask:0xf
	v_add_f32_dpp v136, v136, v136 row_ror:2 row_mask:0xf bank_mask:0xf
	v_add_f32_dpp v137, v137, v137 row_ror:2 row_mask:0xf bank_mask:0xf
	v_add_f32_dpp v138, v138, v138 row_ror:2 row_mask:0xf bank_mask:0xf
	v_add_f32_dpp v139, v139, v139 row_ror:2 row_mask:0xf bank_mask:0xf
	v_add_f32_dpp v170, v170, v170 row_ror:2 row_mask:0xf bank_mask:0xf
	v_add_f32_dpp v171, v171, v171 row_ror:2 row_mask:0xf bank_mask:0xf
	v_add_f32_dpp v172, v172, v172 row_ror:2 row_mask:0xf bank_mask:0xf
	v_add_f32_dpp v173, v173, v173 row_ror:2 row_mask:0xf bank_mask:0xf
	v_add_f32_dpp v128, v128, v128 row_ror:1 row_mask:0xf bank_mask:0xf
	v_add_f32_dpp v129, v129, v129 row_ror:1 row_mask:0xf bank_mask:0xf
	v_add_f32_dpp v130, v130, v130 row_ror:1 row_mask:0xf bank_mask:0xf
	v_add_f32_dpp v131, v131, v131 row_ror:1 row_mask:0xf bank_mask:0xf
	v_add_f32_dpp v132, v132, v132 row_ror:1 row_mask:0xf bank_mask:0xf
	v_add_f32_dpp v133, v133, v133 row_ror:1 row_mask:0xf bank_mask:0xf
	v_add_f32_dpp v134, v134, v134 row_ror:1 row_mask:0xf bank_mask:0xf
	v_add_f32_dpp v135, v135, v135 row_ror:1 row_mask:0xf bank_mask:0xf
	v_add_f32_dpp v136, v136, v136 row_ror:1 row_mask:0xf bank_mask:0xf
	v_add_f32_dpp v137, v137, v137 row_ror:1 row_mask:0xf bank_mask:0xf
	v_add_f32_dpp v138, v138, v138 row_ror:1 row_mask:0xf bank_mask:0xf
	v_add_f32_dpp v139, v139, v139 row_ror:1 row_mask:0xf bank_mask:0xf
	v_add_f32_dpp v170, v170, v170 row_ror:1 row_mask:0xf bank_mask:0xf
	v_add_f32_dpp v171, v171, v171 row_ror:1 row_mask:0xf bank_mask:0xf
	v_add_f32_dpp v172, v172, v172 row_ror:1 row_mask:0xf bank_mask:0xf
	v_add_f32_dpp v173, v173, v173 row_ror:1 row_mask:0xf bank_mask:0xf
	s_nop 1
	v_mul_f32_e32 v128, s22, v128
	v_mul_f32_e32 v129, s22, v129
	v_fma_f32 v129, -v128, v128, v129
	v_max_f32_e32 v129, 0, v129
	v_add_f32_e32 v129, 0x3727c5ac, v129
	v_mul_f32_e32 v224, 0x4f800000, v129
	v_cmp_gt_f32_e32 vcc, s55, v129
	s_nop 1
	v_cndmask_b32_e32 v129, v129, v224, vcc
	v_sqrt_f32_e32 v224, v129
	s_nop 0
	v_add_u32_e32 v225, -1, v224
	v_fma_f32 v227, -v225, v224, v129
	v_add_u32_e32 v226, 1, v224
	v_cmp_ge_f32_e64 s[18:19], 0, v227
	s_nop 1
	v_cndmask_b32_e64 v225, v224, v225, s[18:19]
	v_fma_f32 v224, -v226, v224, v129
	v_cmp_lt_f32_e64 s[18:19], 0, v224
	s_nop 1
	v_cndmask_b32_e64 v224, v225, v226, s[18:19]
	v_mul_f32_e32 v225, 0x37800000, v224
	v_cndmask_b32_e32 v224, v224, v225, vcc
	v_cmp_class_f32_e32 vcc, v129, v167
	s_nop 1
	v_cndmask_b32_e32 v129, v224, v129, vcc
	v_div_scale_f32 v224, s[18:19], v129, v129, 1.0
	v_rcp_f32_e32 v225, v224
	s_nop 0
	v_fma_f32 v226, -v224, v225, 1.0
	v_fmac_f32_e32 v225, v226, v225
	v_div_scale_f32 v226, vcc, 1.0, v129, 1.0
	v_mul_f32_e32 v227, v226, v225
	v_fma_f32 v228, -v224, v227, v226
	v_fmac_f32_e32 v227, v228, v225
	v_fma_f32 v224, -v224, v227, v226
	v_div_fmas_f32 v224, v224, v225, v227
	v_div_fixup_f32 v129, v224, v129, 1.0
	v_mul_f32_e32 v130, s22, v130
	v_mul_f32_e32 v131, s22, v131
	v_fma_f32 v131, -v130, v130, v131
	v_max_f32_e32 v131, 0, v131
	v_add_f32_e32 v131, 0x3727c5ac, v131
	v_mul_f32_e32 v224, 0x4f800000, v131
	v_cmp_gt_f32_e32 vcc, s55, v131
	s_nop 1
	v_cndmask_b32_e32 v131, v131, v224, vcc
	v_sqrt_f32_e32 v224, v131
	s_nop 0
	v_add_u32_e32 v225, -1, v224
	v_fma_f32 v227, -v225, v224, v131
	v_add_u32_e32 v226, 1, v224
	v_cmp_ge_f32_e64 s[18:19], 0, v227
	s_nop 1
	v_cndmask_b32_e64 v225, v224, v225, s[18:19]
	v_fma_f32 v224, -v226, v224, v131
	v_cmp_lt_f32_e64 s[18:19], 0, v224
	s_nop 1
	v_cndmask_b32_e64 v224, v225, v226, s[18:19]
	v_mul_f32_e32 v225, 0x37800000, v224
	v_cndmask_b32_e32 v224, v224, v225, vcc
	v_cmp_class_f32_e32 vcc, v131, v167
	s_nop 1
	v_cndmask_b32_e32 v131, v224, v131, vcc
	v_div_scale_f32 v224, s[18:19], v131, v131, 1.0
	v_rcp_f32_e32 v225, v224
	s_nop 0
	v_fma_f32 v226, -v224, v225, 1.0
	v_fmac_f32_e32 v225, v226, v225
	v_div_scale_f32 v226, vcc, 1.0, v131, 1.0
	v_mul_f32_e32 v227, v226, v225
	v_fma_f32 v228, -v224, v227, v226
	v_fmac_f32_e32 v227, v228, v225
	v_fma_f32 v224, -v224, v227, v226
	v_div_fmas_f32 v224, v224, v225, v227
	v_div_fixup_f32 v131, v224, v131, 1.0
	v_mul_f32_e32 v132, s22, v132
	v_mul_f32_e32 v133, s22, v133
; __device__ __forceinline__ void build_tbl(const f32x2* PS, int pm, LAS unsigned char* lds, int wid, int lane) {
;     ...
;         if (lane == 0) { const float mu = a * (1.f / DM), var = fmaxf(b * (1.f / DM) - mu * mu, 0.f); tbl[wid * 32 + i] = (f32x2){mu, 1.f / sqrtf(var + LN_EPS)}; }
	v_fma_f32 v133, -v132, v132, v133
	v_max_f32_e32 v133, 0, v133
	v_add_f32_e32 v133, 0x3727c5ac, v133
	v_mul_f32_e32 v224, 0x4f800000, v133
	v_cmp_gt_f32_e32 vcc, s55, v133
	s_nop 1
	v_cndmask_b32_e32 v133, v133, v224, vcc
	v_sqrt_f32_e32 v224, v133
	s_nop 0
	v_add_u32_e32 v225, -1, v224
	v_fma_f32 v227, -v225, v224, v133
	v_add_u32_e32 v226, 1, v224
	v_cmp_ge_f32_e64 s[18:19], 0, v227
	s_nop 1
	v_cndmask_b32_e64 v225, v224, v225, s[18:19]
	v_fma_f32 v224, -v226, v224, v133
	v_cmp_lt_f32_e64 s[18:19], 0, v224
	s_nop 1
	v_cndmask_b32_e64 v224, v225, v226, s[18:19]
	v_mul_f32_e32 v225, 0x37800000, v224
	v_cndmask_b32_e32 v224, v224, v225, vcc
	v_cmp_class_f32_e32 vcc, v133, v167
	s_nop 1
	v_cndmask_b32_e32 v133, v224, v133, vcc
	v_div_scale_f32 v224, s[18:19], v133, v133, 1.0
	v_rcp_f32_e32 v225, v224
	s_nop 0
	v_fma_f32 v226, -v224, v225, 1.0
	v_fmac_f32_e32 v225, v226, v225
	v_div_scale_f32 v226, vcc, 1.0, v133, 1.0
	v_mul_f32_e32 v227, v226, v225
	v_fma_f32 v228, -v224, v227, v226
	v_fmac_f32_e32 v227, v228, v225
	v_fma_f32 v224, -v224, v227, v226
	v_div_fmas_f32 v224, v224, v225, v227
	v_div_fixup_f32 v133, v224, v133, 1.0
	v_mul_f32_e32 v134, s22, v134
	v_mul_f32_e32 v135, s22, v135
	v_fma_f32 v135, -v134, v134, v135
	v_max_f32_e32 v135, 0, v135
	v_add_f32_e32 v135, 0x3727c5ac, v135
	v_mul_f32_e32 v224, 0x4f800000, v135
	v_cmp_gt_f32_e32 vcc, s55, v135
	s_nop 1
	v_cndmask_b32_e32 v135, v135, v224, vcc
	v_sqrt_f32_e32 v224, v135
	s_nop 0
	v_add_u32_e32 v225, -1, v224
	v_fma_f32 v227, -v225, v224, v135
	v_add_u32_e32 v226, 1, v224
	v_cmp_ge_f32_e64 s[18:19], 0, v227
	s_nop 1
	v_cndmask_b32_e64 v225, v224, v225, s[18:19]
	v_fma_f32 v224, -v226, v224, v135
	v_cmp_lt_f32_e64 s[18:19], 0, v224
	s_nop 1
	v_cndmask_b32_e64 v224, v225, v226, s[18:19]
	v_mul_f32_e32 v225, 0x37800000, v224
	v_cndmask_b32_e32 v224, v224, v225, vcc
	v_cmp_class_f32_e32 vcc, v135, v167
	s_nop 1
	v_cndmask_b32_e32 v135, v224, v135, vcc
	v_div_scale_f32 v224, s[18:19], v135, v135, 1.0
	v_rcp_f32_e32 v225, v224
	s_nop 0
	v_fma_f32 v226, -v224, v225, 1.0
	v_fmac_f32_e32 v225, v226, v225
	v_div_scale_f32 v226, vcc, 1.0, v135, 1.0
	v_mul_f32_e32 v227, v226, v225
	v_fma_f32 v228, -v224, v227, v226
	v_fmac_f32_e32 v227, v228, v225
	v_fma_f32 v224, -v224, v227, v226
	v_div_fmas_f32 v224, v224, v225, v227
	v_div_fixup_f32 v135, v224, v135, 1.0
	v_mul_f32_e32 v136, s22, v136
	v_mul_f32_e32 v137, s22, v137
	v_fma_f32 v137, -v136, v136, v137
	v_max_f32_e32 v137, 0, v137
	v_add_f32_e32 v137, 0x3727c5ac, v137
	v_mul_f32_e32 v224, 0x4f800000, v137
	v_cmp_gt_f32_e32 vcc, s55, v137
	s_nop 1
	v_cndmask_b32_e32 v137, v137, v224, vcc
	v_sqrt_f32_e32 v224, v137
	s_nop 0
	v_add_u32_e32 v225, -1, v224
	v_fma_f32 v227, -v225, v224, v137
	v_add_u32_e32 v226, 1, v224
	v_cmp_ge_f32_e64 s[18:19], 0, v227
	s_nop 1
	v_cndmask_b32_e64 v225, v224, v225, s[18:19]
	v_fma_f32 v224, -v226, v224, v137
	v_cmp_lt_f32_e64 s[18:19], 0, v224
	s_nop 1
	v_cndmask_b32_e64 v224, v225, v226, s[18:19]
	v_mul_f32_e32 v225, 0x37800000, v224
	v_cndmask_b32_e32 v224, v224, v225, vcc
	v_cmp_class_f32_e32 vcc, v137, v167
	s_nop 1
	v_cndmask_b32_e32 v137, v224, v137, vcc
	v_div_scale_f32 v224, s[18:19], v137, v137, 1.0
	v_rcp_f32_e32 v225, v224
	s_nop 0
	v_fma_f32 v226, -v224, v225, 1.0
	v_fmac_f32_e32 v225, v226, v225
	v_div_scale_f32 v226, vcc, 1.0, v137, 1.0
	v_mul_f32_e32 v227, v226, v225
	v_fma_f32 v228, -v224, v227, v226
	v_fmac_f32_e32 v227, v228, v225
	v_fma_f32 v224, -v224, v227, v226
	v_div_fmas_f32 v224, v224, v225, v227
	v_div_fixup_f32 v137, v224, v137, 1.0
	v_mul_f32_e32 v138, s22, v138
	v_mul_f32_e32 v139, s22, v139
	v_fma_f32 v139, -v138, v138, v139
	v_max_f32_e32 v139, 0, v139
	v_add_f32_e32 v139, 0x3727c5ac, v139
	v_mul_f32_e32 v224, 0x4f800000, v139
	v_cmp_gt_f32_e32 vcc, s55, v139
	s_nop 1
	v_cndmask_b32_e32 v139, v139, v224, vcc
	v_sqrt_f32_e32 v224, v139
; __device__ __forceinline__ void build_tbl(const f32x2* PS, int pm, LAS unsigned char* lds, int wid, int lane) {
;     ...
;         if (lane == 0) { const float mu = a * (1.f / DM), var = fmaxf(b * (1.f / DM) - mu * mu, 0.f); tbl[wid * 32 + i] = (f32x2){mu, 1.f / sqrtf(var + LN_EPS)}; }
	s_nop 0
	v_add_u32_e32 v225, -1, v224
	v_fma_f32 v227, -v225, v224, v139
	v_add_u32_e32 v226, 1, v224
	v_cmp_ge_f32_e64 s[18:19], 0, v227
	s_nop 1
	v_cndmask_b32_e64 v225, v224, v225, s[18:19]
	v_fma_f32 v224, -v226, v224, v139
	v_cmp_lt_f32_e64 s[18:19], 0, v224
	s_nop 1
	v_cndmask_b32_e64 v224, v225, v226, s[18:19]
	v_mul_f32_e32 v225, 0x37800000, v224
	v_cndmask_b32_e32 v224, v224, v225, vcc
	v_cmp_class_f32_e32 vcc, v139, v167
	s_nop 1
	v_cndmask_b32_e32 v139, v224, v139, vcc
	v_div_scale_f32 v224, s[18:19], v139, v139, 1.0
	v_rcp_f32_e32 v225, v224
	s_nop 0
	v_fma_f32 v226, -v224, v225, 1.0
	v_fmac_f32_e32 v225, v226, v225
	v_div_scale_f32 v226, vcc, 1.0, v139, 1.0
	v_mul_f32_e32 v227, v226, v225
	v_fma_f32 v228, -v224, v227, v226
	v_fmac_f32_e32 v227, v228, v225
	v_fma_f32 v224, -v224, v227, v226
	v_div_fmas_f32 v224, v224, v225, v227
	v_div_fixup_f32 v139, v224, v139, 1.0
	v_mul_f32_e32 v170, s22, v170
	v_mul_f32_e32 v171, s22, v171
	v_fma_f32 v171, -v170, v170, v171
	v_max_f32_e32 v171, 0, v171
	v_add_f32_e32 v171, 0x3727c5ac, v171
	v_mul_f32_e32 v224, 0x4f800000, v171
	v_cmp_gt_f32_e32 vcc, s55, v171
	s_nop 1
	v_cndmask_b32_e32 v171, v171, v224, vcc
	v_sqrt_f32_e32 v224, v171
	s_nop 0
	v_add_u32_e32 v225, -1, v224
	v_fma_f32 v227, -v225, v224, v171
	v_add_u32_e32 v226, 1, v224
	v_cmp_ge_f32_e64 s[18:19], 0, v227
	s_nop 1
	v_cndmask_b32_e64 v225, v224, v225, s[18:19]
	v_fma_f32 v224, -v226, v224, v171
	v_cmp_lt_f32_e64 s[18:19], 0, v224
	s_nop 1
	v_cndmask_b32_e64 v224, v225, v226, s[18:19]
	v_mul_f32_e32 v225, 0x37800000, v224
	v_cndmask_b32_e32 v224, v224, v225, vcc
	v_cmp_class_f32_e32 vcc, v171, v167
	s_nop 1
	v_cndmask_b32_e32 v171, v224, v171, vcc
	v_div_scale_f32 v224, s[18:19], v171, v171, 1.0
	v_rcp_f32_e32 v225, v224
	s_nop 0
	v_fma_f32 v226, -v224, v225, 1.0
	v_fmac_f32_e32 v225, v226, v225
	v_div_scale_f32 v226, vcc, 1.0, v171, 1.0
	v_mul_f32_e32 v227, v226, v225
	v_fma_f32 v228, -v224, v227, v226
	v_fmac_f32_e32 v227, v228, v225
	v_fma_f32 v224, -v224, v227, v226
	v_div_fmas_f32 v224, v224, v225, v227
	v_div_fixup_f32 v171, v224, v171, 1.0
	v_mul_f32_e32 v172, s22, v172
	v_mul_f32_e32 v173, s22, v173
	v_fma_f32 v173, -v172, v172, v173
	v_max_f32_e32 v173, 0, v173
	v_add_f32_e32 v173, 0x3727c5ac, v173
	v_mul_f32_e32 v224, 0x4f800000, v173
	v_cmp_gt_f32_e32 vcc, s55, v173
	s_nop 1
	v_cndmask_b32_e32 v173, v173, v224, vcc
	v_sqrt_f32_e32 v224, v173
	s_nop 0
	v_add_u32_e32 v225, -1, v224
	v_fma_f32 v227, -v225, v224, v173
	v_add_u32_e32 v226, 1, v224
	v_cmp_ge_f32_e64 s[18:19], 0, v227
	s_nop 1
	v_cndmask_b32_e64 v225, v224, v225, s[18:19]
	v_fma_f32 v224, -v226, v224, v173
	v_cmp_lt_f32_e64 s[18:19], 0, v224
	s_nop 1
	v_cndmask_b32_e64 v224, v225, v226, s[18:19]
	v_mul_f32_e32 v225, 0x37800000, v224
	v_cndmask_b32_e32 v224, v224, v225, vcc
	v_cmp_class_f32_e32 vcc, v173, v167
	s_nop 1
	v_cndmask_b32_e32 v173, v224, v173, vcc
	v_div_scale_f32 v224, s[18:19], v173, v173, 1.0
	v_rcp_f32_e32 v225, v224
	s_nop 0
	v_fma_f32 v226, -v224, v225, 1.0
	v_fmac_f32_e32 v225, v226, v225
	v_div_scale_f32 v226, vcc, 1.0, v173, 1.0
	v_mul_f32_e32 v227, v226, v225
	v_fma_f32 v228, -v224, v227, v226
	v_fmac_f32_e32 v227, v228, v225
	v_fma_f32 v224, -v224, v227, v226
	v_div_fmas_f32 v224, v224, v225, v227
	v_div_fixup_f32 v173, v224, v173, 1.0
	v_lshrrev_b32_e32 v229, 4, v168
	v_lshlrev_b32_e32 v229, 6, v229
	s_add_i32 s18, s52, 0x20400
	v_add_u32_e32 v229, s18, v229
	s_mov_b64 s[62:63], exec
	s_mov_b32 exec_lo, 0x10001
	s_mov_b32 exec_hi, 0x10001
	ds_write_b64 v229, v[128:129]
	ds_write_b64 v229, v[130:131] offset:8
	ds_write_b64 v229, v[132:133] offset:16
	ds_write_b64 v229, v[134:135] offset:24
	ds_write_b64 v229, v[136:137] offset:32
	ds_write_b64 v229, v[138:139] offset:40
	ds_write_b64 v229, v[170:171] offset:48
	ds_write_b64 v229, v[172:173] offset:56
	s_mov_b64 exec, s[62:63]

; #define LAS __attribute__((address_space(3)))
;     __device__ __forceinline__ void operator()(const f32x4 (&acc)[2][2][4][2], const Unit& u, int wr, int wc, int fr, int fq, const EpiCtx& X) const {
;     ...
;         char* yb = nullptr; char* xb = (char*)(XB + (size_t)u.pm * BM * DM + (size_t)(u.pn * 4 + wc) * (BM * 64));
;         unsigned lo = (unsigned)((wr * 64 + fe) * 64 + o32 + 8 * fq) * 2u; EPI_OPAQUE(lo);
;         const int col = u.pn * BM + wc * 64 + o32 + 8 * fq;
;         f32x4 g0, g1, b0, b1;
;         if (RESN) { ensure_tbl(PSp, sidp, u.pm, X);
;             g0 = *(const f32x4*)(gp + col); g1 = *(const f32x4*)(gp + col + 4); b0 = *(const f32x4*)(bp + col) * ALPHA; b1 = *(const f32x4*)(bp + col + 4) * ALPHA; }
;         const LAS f32x2* tbl = (const LAS f32x2*)(X.lds + TBL_OFF) + wr * 64 + fe;
;         f32x2* ps = PSn + ((size_t)u.pm * BM + wr * 64 + fe) * 64 + u.pn * 4 + wc;
; #pragma unroll
;         for (int ai = 0; ai < 2; ++ai) {
;             u32x4 raw[8];
; #pragma unroll
;             for (int m = 0; m < 4; ++m) { const unsigned off = lo + (unsigned)((ai * HALF + m * 16) * 64) * 2u; raw[2 * m] = *(const u32x4*)(xb + off); raw[2 * m + 1] = *(const u32x4*)(xb + off + 128); }
; #pragma unroll
;             for (int m = 0; m < 4; ++m) {
;                 const int rl = ai * HALF + m * 16; const unsigned off = lo + (unsigned)(rl * 64) * 2u;
;                 const f32x4 o0a = acc[ai][0][m][0], o0b = acc[ai][0][m][1], o1a = acc[ai][1][m][0], o1b = acc[ai][1][m][1];
;                 const f32x4 ra_ = dpp_swap1(odd ? o0a : o1a), rb_ = dpp_swap1(odd ? o0b : o1b);
;                 const f32x4 pa[2] = {odd ? ra_ : o0a, odd ? o1a : ra_}, pb[2] = {odd ? rb_ : o0b, odd ? o1b : rb_};
; #pragma unroll
;                 for (int q = 0; q < 2; ++q) {
;                     const u32x4 w0 = raw[2 * m + q];
;                     const f32x4 r0 = (f32x4){bf_lo(w0.x), bf_hi(w0.x), bf_lo(w0.y), bf_hi(w0.y)}, r1 = (f32x4){bf_lo(w0.z), bf_hi(w0.z), bf_lo(w0.w), bf_hi(w0.w)};
;                     f32x4 y0, y1;
;                     if (RESN) { const f32x2 t = tbl[rl + q]; const float mu = t.x, ra = t.y * ALPHA; y0 = (r0 - mu) * ra * g0 + b0 + pa[q]; y1 = (r1 - mu) * ra * g1 + b1 + pb[q]; }
;                     else { y0 = r0 * ALPHA + pa[q]; y1 = r1 * ALPHA + pb[q]; }
;                     { const u32x4 w = pack8f(y0, y1); *(u32x4*)(xb + off + q * 128) = w;
.LBB0_816:
	s_load_dwordx2 s[94:95], s[0:1], 0xb0
	s_lshl_b32 s4, s68, 2
	s_or_b32 s4, s4, s41
	s_lshl_b32 s4, s4, 17
	s_lshl_b32 s5, s70, 11
	s_add_u32 s4, s4, s5
	s_add_u32 s4, s4, 0x5c000000
	v_lshrrev_b32_e32 v249, 4, v199
	s_waitcnt lgkmcnt(0)
	s_add_u32 s94, s94, s4
	s_addc_u32 s95, s95, 0
	s_lshl_b64 s[4:5], s[70:71], 21
	s_add_u32 s20, s57, s4
	s_addc_u32 s21, s59, s5
	s_lshl_b32 s70, s68, 2
	s_or_b32 s4, s70, s41
	s_ashr_i32 s5, s4, 31
	v_lshl_add_u32 v72, s68, 8, v200
	v_ashrrev_i32_e32 v73, 31, v72
	s_lshl_b64 s[4:5], s[4:5], 15
	v_lshlrev_b64 v[72:73], 2, v[72:73]
	s_add_u32 s20, s20, s4
	v_lshl_add_u64 v[74:75], s[26:27], 0, v[72:73]
	s_addc_u32 s21, s21, s5
	global_load_dwordx4 v[194:197], v[74:75], off offset:16
	global_load_dwordx4 v[178:181], v[74:75], off
	global_load_dwordx4 v[214:217], v164, s[20:21]
	v_lshl_add_u64 v[72:73], s[24:25], 0, v[72:73]
	s_waitcnt lgkmcnt(0)
	global_load_dwordx4 v[76:79], v[72:73], off
	s_nop 0
	global_load_dwordx4 v[72:75], v[72:73], off offset:16
	v_cndmask_b32_e64 v136, v135, v127, s[10:11]
	v_cndmask_b32_e64 v137, v134, v126, s[10:11]
	v_cndmask_b32_e64 v138, v133, v125, s[10:11]
	v_cndmask_b32_e64 v139, v132, v124, s[10:11]
	v_mov_b32_e32 v189, 0
	v_mov_b32_e32 v193, 0
	v_mov_b32_e32 v191, 0
	v_mov_b32_e32 v209, 0
	v_cndmask_b32_e64 v140, v131, v123, s[10:11]
	v_cndmask_b32_e64 v141, v130, v122, s[10:11]
	v_cndmask_b32_e64 v142, v129, v121, s[10:11]
	v_cndmask_b32_e64 v143, v128, v120, s[10:11]
	v_mov_b32_e32 v210, 0
	v_mov_b32_e32 v212, 0
	v_mov_b32_e32 v211, 0
	v_mov_b32_e32 v213, 0
	v_mov_b32_dpp v189, v139 quad_perm:[1,0,3,2] row_mask:0xf bank_mask:0xf
	v_mov_b32_dpp v193, v138 quad_perm:[1,0,3,2] row_mask:0xf bank_mask:0xf
	v_mov_b32_dpp v191, v137 quad_perm:[1,0,3,2] row_mask:0xf bank_mask:0xf
	v_mov_b32_dpp v209, v136 quad_perm:[1,0,3,2] row_mask:0xf bank_mask:0xf
	v_mov_b32_dpp v210, v143 quad_perm:[1,0,3,2] row_mask:0xf bank_mask:0xf
	v_mov_b32_dpp v212, v142 quad_perm:[1,0,3,2] row_mask:0xf bank_mask:0xf
	v_mov_b32_dpp v211, v141 quad_perm:[1,0,3,2] row_mask:0xf bank_mask:0xf
	v_mov_b32_dpp v213, v140 quad_perm:[1,0,3,2] row_mask:0xf bank_mask:0xf
	v_add_u32_e32 v192, 0x800, v164
	v_add_u32_e32 v190, 0x1000, v164
	v_add_u32_e32 v188, 0x1800, v164
	ds_read_b64 v[218:219], v201
	v_cndmask_b32_e64 v221, v193, v133, s[10:11]
	v_cndmask_b32_e64 v220, v189, v132, s[10:11]
	v_cndmask_b32_e64 v223, v209, v135, s[10:11]
	v_cndmask_b32_e64 v222, v191, v134, s[10:11]
	v_cndmask_b32_e64 v225, v212, v129, s[10:11]
	v_cndmask_b32_e64 v224, v210, v128, s[10:11]
	v_cndmask_b32_e64 v227, v213, v131, s[10:11]
	v_cndmask_b32_e64 v226, v211, v130, s[10:11]
	global_load_dwordx4 v[152:155], v164, s[20:21] offset:128
	global_load_dwordx4 v[148:151], v192, s[20:21]
	global_load_dwordx4 v[144:147], v192, s[20:21] offset:128
	global_load_dwordx4 v[140:143], v190, s[20:21]
	global_load_dwordx4 v[136:139], v190, s[20:21] offset:128
	global_load_dwordx4 v[132:135], v188, s[20:21]
	global_load_dwordx4 v[128:131], v188, s[20:21] offset:128
	s_waitcnt lgkmcnt(0)
	v_mul_f32_e32 v208, 0x3fb504f3, v219
	v_lshl_add_u64 v[186:187], v[166:167], 0, s[72:73]
	s_ashr_i32 s71, s70, 31
	v_lshl_add_u64 v[186:187], s[70:71], 3, v[186:187]
	v_lshl_add_u64 v[186:187], v[186:187], 0, s[22:23]
	v_add_u32_e32 v246, 0x4000, v164
	v_add_u32_e32 v247, 0x4800, v164
	global_load_dwordx4 v[230:233], v246, s[20:21]
	global_load_dwordx4 v[234:237], v246, s[20:21] offset:128
	global_load_dwordx4 v[238:241], v247, s[20:21]
	global_load_dwordx4 v[242:245], v247, s[20:21] offset:128
	s_waitcnt vmcnt(0)
	v_pk_mul_f32 v[182:183], v[180:181], s[58:59] op_sel_hi:[1,0]
	v_pk_mul_f32 v[184:185], v[178:179], s[58:59] op_sel_hi:[1,0]
	v_pk_mul_f32 v[178:179], v[196:197], s[58:59] op_sel_hi:[1,0]
	v_pk_mul_f32 v[180:181], v[194:195], s[58:59] op_sel_hi:[1,0]
	v_lshlrev_b32_e32 v194, 16, v214
	v_and_b32_e32 v195, 0xffff0000, v214
	v_lshlrev_b32_e32 v196, 16, v215
	v_and_b32_e32 v197, 0xffff0000, v215
	v_lshlrev_b32_e32 v207, 16, v216
	v_and_b32_e32 v214, 0xffff0000, v216
	v_lshlrev_b32_e32 v216, 16, v217
	v_and_b32_e32 v217, 0xffff0000, v217
	v_sub_f32_e32 v195, v195, v218
	v_sub_f32_e32 v194, v194, v218
	v_sub_f32_e32 v197, v197, v218
	v_sub_f32_e32 v196, v196, v218
	v_sub_f32_e32 v215, v214, v218
	v_sub_f32_e32 v214, v207, v218
	v_sub_f32_e32 v217, v217, v218
	v_sub_f32_e32 v216, v216, v218
	v_pk_mul_f32 v[196:197], v[196:197], v[208:209] op_sel_hi:[1,0]
	v_pk_mul_f32 v[194:195], v[194:195], v[208:209] op_sel_hi:[1,0]
	v_pk_mul_f32 v[216:217], v[216:217], v[208:209] op_sel_hi:[1,0]
	v_pk_mul_f32 v[214:215], v[214:215], v[208:209] op_sel_hi:[1,0]
	v_pk_fma_f32 v[194:195], v[76:77], v[194:195], v[184:185]
	v_pk_fma_f32 v[196:197], v[78:79], v[196:197], v[182:183]
	v_pk_fma_f32 v[214:215], v[72:73], v[214:215], v[180:181]
	v_pk_fma_f32 v[216:217], v[74:75], v[216:217], v[178:179]
	v_pk_add_f32 v[196:197], v[222:223], v[196:197]
	v_pk_add_f32 v[194:195], v[220:221], v[194:195]
	v_pk_add_f32 v[218:219], v[226:227], v[216:217]
	v_pk_add_f32 v[216:217], v[224:225], v[214:215]
	v_cvt_pk_bf16_f32 v214, v194, v195
	v_cvt_pk_bf16_f32 v215, v196, v197
	v_and_b32_e32 v208, 64, v206
	v_cvt_pk_bf16_f32 v216, v216, v217
	v_cvt_pk_bf16_f32 v217, v218, v219
	v_lshlrev_b32_e32 v194, 16, v214
	v_and_b32_e32 v196, 0xffff0000, v214
	v_lshlrev_b32_e32 v218, 16, v215
	v_and_b32_e32 v220, 0xffff0000, v215
	v_lshlrev_b32_e32 v222, 16, v216
	v_and_b32_e32 v224, 0xffff0000, v216
	v_lshlrev_b32_e32 v226, 16, v217
	v_and_b32_e32 v228, 0xffff0000, v217
	v_mul_f32_e32 v195, v194, v194
	v_mul_f32_e32 v197, v196, v196
	v_mul_f32_e32 v219, v218, v218
	v_mul_f32_e32 v221, v220, v220
	v_mul_f32_e32 v223, v222, v222
	v_mul_f32_e32 v225, v224, v224
	v_mul_f32_e32 v227, v226, v226
	v_mul_f32_e32 v229, v228, v228
	v_pk_add_f32 v[194:195], v[194:195], v[196:197]
	v_pk_add_f32 v[196:197], v[218:219], v[220:221]
	v_pk_add_f32 v[218:219], v[226:227], v[228:229]
	v_pk_add_f32 v[194:195], v[194:195], v[196:197]
	v_pk_add_f32 v[196:197], v[222:223], v[224:225]
	v_xor_b32_e32 v207, 16, v206
	v_add_u32_e32 v208, 64, v208
	v_pk_add_f32 v[196:197], v[196:197], v[218:219]
	v_cmp_lt_i32_e32 vcc, v207, v208
	v_pk_add_f32 v[194:195], v[194:195], v[196:197]
	v_mov_b32_e32 v196, 0
	v_mov_b32_e32 v197, 0
	v_cndmask_b32_e32 v207, v206, v207, vcc
	v_mov_b32_dpp v196, v194 quad_perm:[1,0,3,2] row_mask:0xf bank_mask:0xf
	v_mov_b32_dpp v197, v195 quad_perm:[1,0,3,2] row_mask:0xf bank_mask:0xf
	v_lshlrev_b32_e32 v207, 2, v207
	v_pk_add_f32 v[194:195], v[194:195], v[196:197]
	ds_bpermute_b32 v196, v207, v194
	ds_bpermute_b32 v197, v207, v195
	v_xor_b32_e32 v218, 32, v206
	v_cmp_lt_i32_e32 vcc, v218, v208
	global_store_dwordx4 v164, v[214:217], s[20:21]
	s_waitcnt lgkmcnt(0)
	v_pk_add_f32 v[194:195], v[194:195], v[196:197]
	v_cndmask_b32_e32 v208, v206, v218, vcc
	v_lshlrev_b32_e32 v208, 2, v208
	ds_bpermute_b32 v196, v208, v194
	ds_bpermute_b32 v197, v208, v195
	s_and_saveexec_b64 s[52:53], s[16:17]
	s_cbranch_execz .LBB0_818
;     __device__ __forceinline__ void operator()(const f32x4 (&acc)[2][2][4][2], const Unit& u, int wr, int wc, int fr, int fq, const EpiCtx& X) const {
;     ...
;             for (int m = 0; m < 4; ++m) { const unsigned off = lo + (unsigned)((ai * HALF + m * 16) * 64) * 2u; raw[2 * m] = *(const u32x4*)(xb + off); raw[2 * m + 1] = *(const u32x4*)(xb + off + 128); }
; #pragma unroll
;             for (int m = 0; m < 4; ++m) {
;                 const int rl = ai * HALF + m * 16; const unsigned off = lo + (unsigned)(rl * 64) * 2u;
;                 const f32x4 o0a = acc[ai][0][m][0], o0b = acc[ai][0][m][1], o1a = acc[ai][1][m][0], o1b = acc[ai][1][m][1];
;                 const f32x4 ra_ = dpp_swap1(odd ? o0a : o1a), rb_ = dpp_swap1(odd ? o0b : o1b);
;                 const f32x4 pa[2] = {odd ? ra_ : o0a, odd ? o1a : ra_}, pb[2] = {odd ? rb_ : o0b, odd ? o1b : rb_};
; #pragma unroll
;                 for (int q = 0; q < 2; ++q) {
;                     const u32x4 w0 = raw[2 * m + q];
;                     const f32x4 r0 = (f32x4){bf_lo(w0.x), bf_hi(w0.x), bf_lo(w0.y), bf_hi(w0.y)}, r1 = (f32x4){bf_lo(w0.z), bf_hi(w0.z), bf_lo(w0.w), bf_hi(w0.w)};
;                     f32x4 y0, y1;
;                     if (RESN) { const f32x2 t = tbl[rl + q]; const float mu = t.x, ra = t.y * ALPHA; y0 = (r0 - mu) * ra * g0 + b0 + pa[q]; y1 = (r1 - mu) * ra * g1 + b1 + pb[q]; }
;                     else { y0 = r0 * ALPHA + pa[q]; y1 = r1 * ALPHA + pb[q]; }
;                     { const u32x4 w = pack8f(y0, y1); *(u32x4*)(xb + off + q * 128) = w;
;                         y0 = (f32x4){bf_lo(w.x), bf_hi(w.x), bf_lo(w.y), bf_hi(w.y)}; y1 = (f32x4){bf_lo(w.z), bf_hi(w.z), bf_lo(w.w), bf_hi(w.w)}; }
;                     float sa = ((y0[0] + y0[1]) + (y0[2] + y0[3])) + ((y1[0] + y1[1]) + (y1[2] + y1[3]));
;                     float sb = ((y0[0] * y0[0] + y0[1] * y0[1]) + (y0[2] * y0[2] + y0[3] * y0[3])) + ((y1[0] * y1[0] + y1[1] * y1[1]) + (y1[2] * y1[2] + y1[3] * y1[3]));
;                     sa += dpp_x1(sa);
;                     sb += dpp_x1(sb);
;                     sa += __shfl_xor(sa, 16); sa += __shfl_xor(sa, 32); sb += __shfl_xor(sb, 16); sb += __shfl_xor(sb, 32);
;                     if (fq == 0 && !odd) ps[(size_t)(rl + q) * 64] = (f32x2){sa, sb};
	s_waitcnt lgkmcnt(0)
	v_pk_add_f32 v[194:195], v[194:195], v[196:197]
	v_mov_b32_e32 v250, v194
	v_mov_b32_e32 v251, v195
.LBB0_818:
	s_or_b64 exec, exec, s[52:53]
	v_cndmask_b32_e64 v125, v125, v193, s[10:11]
	v_cndmask_b32_e64 v124, v124, v189, s[10:11]
	v_cndmask_b32_e64 v126, v126, v191, s[10:11]
	v_lshlrev_b32_e32 v189, 16, v152
	v_and_b32_e32 v191, 0xffff0000, v152
	v_lshlrev_b32_e32 v193, 16, v153
	s_waitcnt lgkmcnt(1)
	v_and_b32_e32 v196, 0xffff0000, v153
	ds_read_b64 v[152:153], v201 offset:8
	v_cndmask_b32_e64 v127, v127, v209, s[10:11]
	v_cndmask_b32_e64 v120, v120, v210, s[10:11]
	v_cndmask_b32_e64 v122, v122, v211, s[10:11]
	v_lshlrev_b32_e32 v209, 16, v154
	v_and_b32_e32 v210, 0xffff0000, v154
	v_lshlrev_b32_e32 v211, 16, v155
	v_and_b32_e32 v155, 0xffff0000, v155
	s_waitcnt lgkmcnt(0)
	v_mul_f32_e32 v154, 0x3fb504f3, v153
	v_sub_f32_e32 v195, v191, v152
	v_sub_f32_e32 v194, v189, v152
	v_pk_mul_f32 v[194:195], v[194:195], v[154:155] op_sel_hi:[1,0]
	v_sub_f32_e32 v197, v196, v152
	v_pk_fma_f32 v[194:195], v[76:77], v[194:195], v[184:185]
	v_sub_f32_e32 v196, v193, v152
	v_pk_add_f32 v[124:125], v[124:125], v[194:195]
	v_sub_f32_e32 v195, v210, v152
	v_sub_f32_e32 v194, v209, v152
	v_sub_f32_e32 v153, v155, v152
	v_sub_f32_e32 v152, v211, v152
	v_pk_mul_f32 v[196:197], v[196:197], v[154:155] op_sel_hi:[1,0]
	v_pk_mul_f32 v[152:153], v[152:153], v[154:155] op_sel_hi:[1,0]
	v_pk_mul_f32 v[154:155], v[194:195], v[154:155] op_sel_hi:[1,0]
	v_cndmask_b32_e64 v121, v121, v212, s[10:11]
	v_cndmask_b32_e64 v123, v123, v213, s[10:11]
	v_pk_fma_f32 v[196:197], v[78:79], v[196:197], v[182:183]
	v_pk_fma_f32 v[154:155], v[72:73], v[154:155], v[180:181]
	v_pk_fma_f32 v[152:153], v[74:75], v[152:153], v[178:179]
	v_pk_add_f32 v[126:127], v[126:127], v[196:197]
	v_pk_add_f32 v[122:123], v[122:123], v[152:153]
	v_pk_add_f32 v[120:121], v[120:121], v[154:155]
	v_cvt_pk_bf16_f32 v124, v124, v125
	v_cvt_pk_bf16_f32 v125, v126, v127
	s_nop 0
	v_cvt_pk_bf16_f32 v126, v120, v121
	v_cvt_pk_bf16_f32 v127, v122, v123
	v_lshlrev_b32_e32 v120, 16, v124
	v_and_b32_e32 v122, 0xffff0000, v124
	v_lshlrev_b32_e32 v152, 16, v125
	v_and_b32_e32 v154, 0xffff0000, v125
	v_lshlrev_b32_e32 v194, 16, v126
	v_and_b32_e32 v196, 0xffff0000, v126
	v_lshlrev_b32_e32 v210, 16, v127
	v_and_b32_e32 v212, 0xffff0000, v127
	v_mul_f32_e32 v121, v120, v120
	v_mul_f32_e32 v123, v122, v122
	v_mul_f32_e32 v153, v152, v152
	v_mul_f32_e32 v155, v154, v154
	v_mul_f32_e32 v195, v194, v194
	v_mul_f32_e32 v197, v196, v196
	v_mul_f32_e32 v211, v210, v210
	v_mul_f32_e32 v213, v212, v212
	v_pk_add_f32 v[120:121], v[120:121], v[122:123]
	v_pk_add_f32 v[122:123], v[152:153], v[154:155]
	v_pk_add_f32 v[152:153], v[210:211], v[212:213]
	v_pk_add_f32 v[120:121], v[120:121], v[122:123]
	v_pk_add_f32 v[122:123], v[194:195], v[196:197]
	s_nop 0
	v_pk_add_f32 v[122:123], v[122:123], v[152:153]
	v_lshl_add_u64 v[152:153], s[20:21], 0, v[164:165]
	v_pk_add_f32 v[120:121], v[120:121], v[122:123]
	v_mov_b32_e32 v122, v165
	v_mov_b32_e32 v123, v165
	global_store_dwordx4 v[152:153], v[124:127], off offset:128
	v_mov_b32_dpp v122, v120 quad_perm:[1,0,3,2] row_mask:0xf bank_mask:0xf
	v_mov_b32_dpp v123, v121 quad_perm:[1,0,3,2] row_mask:0xf bank_mask:0xf
	v_pk_add_f32 v[120:121], v[120:121], v[122:123]
	ds_bpermute_b32 v122, v207, v120
	ds_bpermute_b32 v123, v207, v121
	s_waitcnt lgkmcnt(0)
	v_pk_add_f32 v[120:121], v[120:121], v[122:123]
	ds_bpermute_b32 v122, v208, v120
	ds_bpermute_b32 v123, v208, v121
	s_and_saveexec_b64 s[52:53], s[16:17]
	s_cbranch_execz .LBB0_820
	s_waitcnt lgkmcnt(0)
	v_pk_add_f32 v[120:121], v[120:121], v[122:123]
	v_mov_b32_e32 v252, v250
	v_mov_b32_e32 v253, v251
	v_mov_b32_e32 v254, v120
	v_mov_b32_e32 v255, v121
	global_store_dwordx4 v249, v[252:255], s[94:95]
.LBB0_820:
	s_or_b64 exec, exec, s[52:53]
	s_waitcnt lgkmcnt(1)
	v_cndmask_b32_e64 v122, v116, v108, s[10:11]
	v_mov_b32_e32 v120, 0
	v_cndmask_b32_e64 v121, v117, v109, s[10:11]
	s_waitcnt lgkmcnt(0)
	v_cndmask_b32_e64 v123, v118, v110, s[10:11]
	v_mov_b32_dpp v120, v122 quad_perm:[1,0,3,2] row_mask:0xf bank_mask:0xf
	v_mov_b32_e32 v122, 0
	v_cndmask_b32_e64 v124, v119, v111, s[10:11]
	v_cndmask_b32_e64 v126, v112, v104, s[10:11]
	v_mov_b32_dpp v122, v121 quad_perm:[1,0,3,2] row_mask:0xf bank_mask:0xf
	v_mov_b32_e32 v121, 0
	v_cndmask_b32_e64 v125, v113, v105, s[10:11]
	v_cndmask_b32_e64 v127, v114, v106, s[10:11]
	v_mov_b32_dpp v121, v123 quad_perm:[1,0,3,2] row_mask:0xf bank_mask:0xf
	v_mov_b32_e32 v123, 0
	v_cndmask_b32_e64 v152, v115, v107, s[10:11]
	v_and_b32_e32 v153, 0xffff0000, v148
	v_mov_b32_dpp v123, v124 quad_perm:[1,0,3,2] row_mask:0xf bank_mask:0xf
	v_mov_b32_e32 v124, 0
	v_lshlrev_b32_e32 v154, 16, v149
	v_and_b32_e32 v155, 0xffff0000, v149
	v_mov_b32_dpp v124, v126 quad_perm:[1,0,3,2] row_mask:0xf bank_mask:0xf
	v_mov_b32_e32 v126, 0
	v_lshlrev_b32_e32 v189, 16, v150
	v_and_b32_e32 v191, 0xffff0000, v150
	v_mov_b32_dpp v126, v125 quad_perm:[1,0,3,2] row_mask:0xf bank_mask:0xf
	v_mov_b32_e32 v125, 0
	v_lshlrev_b32_e32 v193, 16, v151
	v_and_b32_e32 v151, 0xffff0000, v151
	v_mov_b32_dpp v125, v127 quad_perm:[1,0,3,2] row_mask:0xf bank_mask:0xf
	v_mov_b32_e32 v127, 0
	v_cndmask_b32_e64 v117, v122, v117, s[10:11]
	v_cndmask_b32_e64 v116, v120, v116, s[10:11]
	v_mov_b32_dpp v127, v152 quad_perm:[1,0,3,2] row_mask:0xf bank_mask:0xf
	v_lshlrev_b32_e32 v152, 16, v148
	ds_read_b64 v[148:149], v201 offset:128
	v_cndmask_b32_e64 v119, v123, v119, s[10:11]
	v_cndmask_b32_e64 v118, v121, v118, s[10:11]
	v_cndmask_b32_e64 v113, v126, v113, s[10:11]
	v_cndmask_b32_e64 v112, v124, v112, s[10:11]
	s_waitcnt lgkmcnt(0)
;     __device__ __forceinline__ void operator()(const f32x4 (&acc)[2][2][4][2], const Unit& u, int wr, int wc, int fr, int fq, const EpiCtx& X) const {
;     ...
;             for (int m = 0; m < 4; ++m) { const unsigned off = lo + (unsigned)((ai * HALF + m * 16) * 64) * 2u; raw[2 * m] = *(const u32x4*)(xb + off); raw[2 * m + 1] = *(const u32x4*)(xb + off + 128); }
; #pragma unroll
;             for (int m = 0; m < 4; ++m) {
;                 const int rl = ai * HALF + m * 16; const unsigned off = lo + (unsigned)(rl * 64) * 2u;
;                 const f32x4 o0a = acc[ai][0][m][0], o0b = acc[ai][0][m][1], o1a = acc[ai][1][m][0], o1b = acc[ai][1][m][1];
;                 const f32x4 ra_ = dpp_swap1(odd ? o0a : o1a), rb_ = dpp_swap1(odd ? o0b : o1b);
;                 const f32x4 pa[2] = {odd ? ra_ : o0a, odd ? o1a : ra_}, pb[2] = {odd ? rb_ : o0b, odd ? o1b : rb_};
; #pragma unroll
;                 for (int q = 0; q < 2; ++q) {
;                     const u32x4 w0 = raw[2 * m + q];
;                     const f32x4 r0 = (f32x4){bf_lo(w0.x), bf_hi(w0.x), bf_lo(w0.y), bf_hi(w0.y)}, r1 = (f32x4){bf_lo(w0.z), bf_hi(w0.z), bf_lo(w0.w), bf_hi(w0.w)};
;                     f32x4 y0, y1;
;                     if (RESN) { const f32x2 t = tbl[rl + q]; const float mu = t.x, ra = t.y * ALPHA; y0 = (r0 - mu) * ra * g0 + b0 + pa[q]; y1 = (r1 - mu) * ra * g1 + b1 + pb[q]; }
;                     else { y0 = r0 * ALPHA + pa[q]; y1 = r1 * ALPHA + pb[q]; }
;                     { const u32x4 w = pack8f(y0, y1); *(u32x4*)(xb + off + q * 128) = w;
;                         y0 = (f32x4){bf_lo(w.x), bf_hi(w.x), bf_lo(w.y), bf_hi(w.y)}; y1 = (f32x4){bf_lo(w.z), bf_hi(w.z), bf_lo(w.w), bf_hi(w.w)}; }
;                     float sa = ((y0[0] + y0[1]) + (y0[2] + y0[3])) + ((y1[0] + y1[1]) + (y1[2] + y1[3]));
;                     float sb = ((y0[0] * y0[0] + y0[1] * y0[1]) + (y0[2] * y0[2] + y0[3] * y0[3])) + ((y1[0] * y1[0] + y1[1] * y1[1]) + (y1[2] * y1[2] + y1[3] * y1[3]));
;                     sa += dpp_x1(sa);
;                     sb += dpp_x1(sb);
;                     sa += __shfl_xor(sa, 16); sa += __shfl_xor(sa, 32); sb += __shfl_xor(sb, 16); sb += __shfl_xor(sb, 32);
;                     if (fq == 0 && !odd) ps[(size_t)(rl + q) * 64] = (f32x2){sa, sb};
	v_mul_f32_e32 v150, 0x3fb504f3, v149
	v_sub_f32_e32 v153, v153, v148
	v_sub_f32_e32 v152, v152, v148
	v_pk_mul_f32 v[152:153], v[152:153], v[150:151] op_sel_hi:[1,0]
	v_sub_f32_e32 v155, v155, v148
	v_pk_fma_f32 v[152:153], v[76:77], v[152:153], v[184:185]
	v_sub_f32_e32 v154, v154, v148
	v_pk_add_f32 v[116:117], v[116:117], v[152:153]
	v_sub_f32_e32 v153, v191, v148
	v_sub_f32_e32 v152, v189, v148
	v_sub_f32_e32 v149, v151, v148
	v_sub_f32_e32 v148, v193, v148
	v_pk_mul_f32 v[154:155], v[154:155], v[150:151] op_sel_hi:[1,0]
	v_pk_mul_f32 v[148:149], v[148:149], v[150:151] op_sel_hi:[1,0]
	v_pk_mul_f32 v[150:151], v[152:153], v[150:151] op_sel_hi:[1,0]
	v_cndmask_b32_e64 v115, v127, v115, s[10:11]
	v_cndmask_b32_e64 v114, v125, v114, s[10:11]
	v_pk_fma_f32 v[154:155], v[78:79], v[154:155], v[182:183]
	v_pk_fma_f32 v[150:151], v[72:73], v[150:151], v[180:181]
	v_pk_fma_f32 v[148:149], v[74:75], v[148:149], v[178:179]
	v_pk_add_f32 v[118:119], v[118:119], v[154:155]
	v_pk_add_f32 v[114:115], v[114:115], v[148:149]
	v_pk_add_f32 v[112:113], v[112:113], v[150:151]
	v_cvt_pk_bf16_f32 v148, v116, v117
	v_cvt_pk_bf16_f32 v149, v118, v119
	v_mov_b32_e32 v193, v165
	v_cvt_pk_bf16_f32 v150, v112, v113
	v_cvt_pk_bf16_f32 v151, v114, v115
	v_lshlrev_b32_e32 v112, 16, v148
	v_and_b32_e32 v114, 0xffff0000, v148
	v_lshlrev_b32_e32 v116, 16, v149
	v_and_b32_e32 v118, 0xffff0000, v149
	v_lshlrev_b32_e32 v152, 16, v150
	v_and_b32_e32 v154, 0xffff0000, v150
	v_lshlrev_b32_e32 v194, 16, v151
	v_and_b32_e32 v196, 0xffff0000, v151
	v_mul_f32_e32 v113, v112, v112
	v_mul_f32_e32 v115, v114, v114
	v_mul_f32_e32 v117, v116, v116
	v_mul_f32_e32 v119, v118, v118
	v_mul_f32_e32 v153, v152, v152
	v_mul_f32_e32 v155, v154, v154
	v_mul_f32_e32 v195, v194, v194
	v_mul_f32_e32 v197, v196, v196
	v_pk_add_f32 v[112:113], v[112:113], v[114:115]
	v_pk_add_f32 v[114:115], v[116:117], v[118:119]
	v_pk_add_f32 v[116:117], v[194:195], v[196:197]
	v_pk_add_f32 v[112:113], v[112:113], v[114:115]
	v_pk_add_f32 v[114:115], v[152:153], v[154:155]
	s_nop 0
	v_pk_add_f32 v[114:115], v[114:115], v[116:117]
	s_nop 0
	v_pk_add_f32 v[112:113], v[112:113], v[114:115]
	v_mov_b32_e32 v114, v165
	v_mov_b32_e32 v115, v165
	s_nop 0
	v_mov_b32_dpp v114, v112 quad_perm:[1,0,3,2] row_mask:0xf bank_mask:0xf
	v_mov_b32_dpp v115, v113 quad_perm:[1,0,3,2] row_mask:0xf bank_mask:0xf
	v_pk_add_f32 v[112:113], v[112:113], v[114:115]
	ds_bpermute_b32 v114, v207, v112
	ds_bpermute_b32 v115, v207, v113
	s_waitcnt lgkmcnt(0)
	v_pk_add_f32 v[114:115], v[112:113], v[114:115]
	ds_bpermute_b32 v116, v208, v114
	ds_bpermute_b32 v117, v208, v115
	v_lshl_add_u64 v[112:113], s[20:21], 0, v[192:193]
	global_store_dwordx4 v[112:113], v[148:151], off
	s_and_saveexec_b64 s[68:69], s[16:17]
	s_cbranch_execz .LBB0_822
	s_waitcnt lgkmcnt(0)
	v_pk_add_f32 v[114:115], v[114:115], v[116:117]
	v_add_co_u32_e32 v116, vcc, 0x2000, v186
	s_nop 1
	v_addc_co_u32_e32 v117, vcc, 0, v187, vcc
	v_mov_b32_e32 v250, v114
	v_mov_b32_e32 v251, v115
.LBB0_822:
	s_or_b64 exec, exec, s[68:69]
	ds_read_b64 v[114:115], v201 offset:136
	s_waitcnt lgkmcnt(1)
	v_lshlrev_b32_e32 v117, 16, v144
	v_and_b32_e32 v118, 0xffff0000, v144
	v_cndmask_b32_e64 v109, v109, v122, s[10:11]
	v_cndmask_b32_e64 v108, v108, v120, s[10:11]
	s_waitcnt lgkmcnt(0)
	v_mul_f32_e32 v116, 0x3fb504f3, v115
	v_sub_f32_e32 v119, v118, v114
	v_sub_f32_e32 v118, v117, v114
	v_pk_mul_f32 v[118:119], v[118:119], v[116:117] op_sel_hi:[1,0]
	v_cndmask_b32_e64 v111, v111, v123, s[10:11]
	v_cndmask_b32_e64 v110, v110, v121, s[10:11]
	v_cndmask_b32_e64 v104, v104, v124, s[10:11]
	v_cndmask_b32_e64 v106, v106, v125, s[10:11]
	v_lshlrev_b32_e32 v120, 16, v145
	v_and_b32_e32 v121, 0xffff0000, v145
	v_lshlrev_b32_e32 v122, 16, v146
	v_and_b32_e32 v123, 0xffff0000, v146
	v_lshlrev_b32_e32 v124, 16, v147
	v_and_b32_e32 v125, 0xffff0000, v147
	v_pk_fma_f32 v[118:119], v[76:77], v[118:119], v[184:185]
	v_sub_f32_e32 v121, v121, v114
	v_sub_f32_e32 v120, v120, v114
	v_pk_add_f32 v[108:109], v[108:109], v[118:119]
	v_sub_f32_e32 v119, v123, v114
	v_sub_f32_e32 v118, v122, v114
	v_sub_f32_e32 v115, v125, v114
	v_sub_f32_e32 v114, v124, v114
	v_pk_mul_f32 v[120:121], v[120:121], v[116:117] op_sel_hi:[1,0]
	v_pk_mul_f32 v[114:115], v[114:115], v[116:117] op_sel_hi:[1,0]
	v_pk_mul_f32 v[116:117], v[118:119], v[116:117] op_sel_hi:[1,0]
	v_cndmask_b32_e64 v105, v105, v126, s[10:11]
	v_cndmask_b32_e64 v107, v107, v127, s[10:11]
	v_pk_fma_f32 v[120:121], v[78:79], v[120:121], v[182:183]
	v_pk_fma_f32 v[116:117], v[72:73], v[116:117], v[180:181]
	v_pk_fma_f32 v[114:115], v[74:75], v[114:115], v[178:179]
	v_pk_add_f32 v[110:111], v[110:111], v[120:121]
	v_pk_add_f32 v[106:107], v[106:107], v[114:115]
	v_pk_add_f32 v[104:105], v[104:105], v[116:117]
	v_cvt_pk_bf16_f32 v108, v108, v109
	v_cvt_pk_bf16_f32 v109, v110, v111
	s_nop 0
	v_cvt_pk_bf16_f32 v110, v104, v105
	v_cvt_pk_bf16_f32 v111, v106, v107
	v_lshlrev_b32_e32 v104, 16, v108
	v_and_b32_e32 v106, 0xffff0000, v108
	v_lshlrev_b32_e32 v114, 16, v109
	v_and_b32_e32 v116, 0xffff0000, v109
	v_lshlrev_b32_e32 v118, 16, v110
	v_and_b32_e32 v120, 0xffff0000, v110
	v_lshlrev_b32_e32 v122, 16, v111
	v_and_b32_e32 v124, 0xffff0000, v111
	v_mul_f32_e32 v105, v104, v104
	v_mul_f32_e32 v107, v106, v106
	v_mul_f32_e32 v115, v114, v114
	v_mul_f32_e32 v117, v116, v116
	v_mul_f32_e32 v119, v118, v118
	v_mul_f32_e32 v121, v120, v120
	v_mul_f32_e32 v123, v122, v122
	v_mul_f32_e32 v125, v124, v124
	v_pk_add_f32 v[104:105], v[104:105], v[106:107]
	v_pk_add_f32 v[106:107], v[114:115], v[116:117]
	v_pk_add_f32 v[114:115], v[122:123], v[124:125]
	v_pk_add_f32 v[104:105], v[104:105], v[106:107]
	v_pk_add_f32 v[106:107], v[118:119], v[120:121]
	global_store_dwordx4 v[112:113], v[108:111], off offset:128
	v_pk_add_f32 v[106:107], v[106:107], v[114:115]
	s_nop 0
	v_pk_add_f32 v[104:105], v[104:105], v[106:107]
	v_mov_b32_e32 v106, v165
	v_mov_b32_e32 v107, v165
	s_nop 0
	v_mov_b32_dpp v106, v104 quad_perm:[1,0,3,2] row_mask:0xf bank_mask:0xf
	v_mov_b32_dpp v107, v105 quad_perm:[1,0,3,2] row_mask:0xf bank_mask:0xf
	v_pk_add_f32 v[104:105], v[104:105], v[106:107]
	ds_bpermute_b32 v106, v207, v104
	ds_bpermute_b32 v107, v207, v105
	s_waitcnt lgkmcnt(0)
	v_pk_add_f32 v[104:105], v[104:105], v[106:107]
	ds_bpermute_b32 v106, v208, v104
	ds_bpermute_b32 v107, v208, v105
	s_and_saveexec_b64 s[68:69], s[16:17]
	s_cbranch_execz .LBB0_824
	s_waitcnt lgkmcnt(0)
	v_pk_add_f32 v[104:105], v[104:105], v[106:107]
	v_add_co_u32_e32 v106, vcc, 0x2000, v186
	s_nop 1
	v_addc_co_u32_e32 v107, vcc, 0, v187, vcc
	v_mov_b32_e32 v252, v250
	v_mov_b32_e32 v253, v251
	v_mov_b32_e32 v254, v104
	v_mov_b32_e32 v255, v105
	global_store_dwordx4 v249, v[252:255], s[94:95] offset:128
;     __device__ __forceinline__ void operator()(const f32x4 (&acc)[2][2][4][2], const Unit& u, int wr, int wc, int fr, int fq, const EpiCtx& X) const {
;     ...
;             for (int m = 0; m < 4; ++m) { const unsigned off = lo + (unsigned)((ai * HALF + m * 16) * 64) * 2u; raw[2 * m] = *(const u32x4*)(xb + off); raw[2 * m + 1] = *(const u32x4*)(xb + off + 128); }
; #pragma unroll
;             for (int m = 0; m < 4; ++m) {
;                 const int rl = ai * HALF + m * 16; const unsigned off = lo + (unsigned)(rl * 64) * 2u;
;                 const f32x4 o0a = acc[ai][0][m][0], o0b = acc[ai][0][m][1], o1a = acc[ai][1][m][0], o1b = acc[ai][1][m][1];
;                 const f32x4 ra_ = dpp_swap1(odd ? o0a : o1a), rb_ = dpp_swap1(odd ? o0b : o1b);
;                 const f32x4 pa[2] = {odd ? ra_ : o0a, odd ? o1a : ra_}, pb[2] = {odd ? rb_ : o0b, odd ? o1b : rb_};
; #pragma unroll
;                 for (int q = 0; q < 2; ++q) {
;                     const u32x4 w0 = raw[2 * m + q];
;                     const f32x4 r0 = (f32x4){bf_lo(w0.x), bf_hi(w0.x), bf_lo(w0.y), bf_hi(w0.y)}, r1 = (f32x4){bf_lo(w0.z), bf_hi(w0.z), bf_lo(w0.w), bf_hi(w0.w)};
;                     f32x4 y0, y1;
;                     if (RESN) { const f32x2 t = tbl[rl + q]; const float mu = t.x, ra = t.y * ALPHA; y0 = (r0 - mu) * ra * g0 + b0 + pa[q]; y1 = (r1 - mu) * ra * g1 + b1 + pb[q]; }
;                     else { y0 = r0 * ALPHA + pa[q]; y1 = r1 * ALPHA + pb[q]; }
;                     { const u32x4 w = pack8f(y0, y1); *(u32x4*)(xb + off + q * 128) = w;
;                         y0 = (f32x4){bf_lo(w.x), bf_hi(w.x), bf_lo(w.y), bf_hi(w.y)}; y1 = (f32x4){bf_lo(w.z), bf_hi(w.z), bf_lo(w.w), bf_hi(w.w)}; }
;                     float sa = ((y0[0] + y0[1]) + (y0[2] + y0[3])) + ((y1[0] + y1[1]) + (y1[2] + y1[3]));
;                     float sb = ((y0[0] * y0[0] + y0[1] * y0[1]) + (y0[2] * y0[2] + y0[3] * y0[3])) + ((y1[0] * y1[0] + y1[1] * y1[1]) + (y1[2] * y1[2] + y1[3] * y1[3]));
;                     sa += dpp_x1(sa);
;                     sb += dpp_x1(sb);
;                     sa += __shfl_xor(sa, 16); sa += __shfl_xor(sa, 32); sb += __shfl_xor(sb, 16); sb += __shfl_xor(sb, 32);
;                     if (fq == 0 && !odd) ps[(size_t)(rl + q) * 64] = (f32x2){sa, sb};
.LBB0_824:
	s_or_b64 exec, exec, s[68:69]
	s_waitcnt lgkmcnt(1)
	v_cndmask_b32_e64 v106, v100, v92, s[10:11]
	v_mov_b32_e32 v104, 0
	v_cndmask_b32_e64 v105, v101, v93, s[10:11]
	s_waitcnt lgkmcnt(0)
	v_cndmask_b32_e64 v107, v102, v94, s[10:11]
	v_mov_b32_dpp v104, v106 quad_perm:[1,0,3,2] row_mask:0xf bank_mask:0xf
	v_mov_b32_e32 v106, 0
	v_cndmask_b32_e64 v108, v103, v95, s[10:11]
	v_cndmask_b32_e64 v110, v96, v88, s[10:11]
	v_mov_b32_dpp v106, v105 quad_perm:[1,0,3,2] row_mask:0xf bank_mask:0xf
	v_mov_b32_e32 v105, 0
	v_cndmask_b32_e64 v109, v97, v89, s[10:11]
	v_cndmask_b32_e64 v111, v98, v90, s[10:11]
	v_mov_b32_dpp v105, v107 quad_perm:[1,0,3,2] row_mask:0xf bank_mask:0xf
	v_mov_b32_e32 v107, 0
	v_cndmask_b32_e64 v112, v99, v91, s[10:11]
	v_lshlrev_b32_e32 v115, 16, v140
	v_mov_b32_dpp v107, v108 quad_perm:[1,0,3,2] row_mask:0xf bank_mask:0xf
	v_mov_b32_e32 v108, 0
	v_and_b32_e32 v116, 0xffff0000, v140
	v_cndmask_b32_e64 v101, v106, v101, s[10:11]
	v_mov_b32_dpp v108, v110 quad_perm:[1,0,3,2] row_mask:0xf bank_mask:0xf
	v_mov_b32_e32 v110, 0
	v_cndmask_b32_e64 v100, v104, v100, s[10:11]
	v_lshlrev_b32_e32 v118, 16, v141
	v_mov_b32_dpp v110, v109 quad_perm:[1,0,3,2] row_mask:0xf bank_mask:0xf
	v_mov_b32_e32 v109, 0
	v_and_b32_e32 v119, 0xffff0000, v141
	v_lshlrev_b32_e32 v120, 16, v142
	v_mov_b32_dpp v109, v111 quad_perm:[1,0,3,2] row_mask:0xf bank_mask:0xf
	v_mov_b32_e32 v111, 0
	v_and_b32_e32 v121, 0xffff0000, v142
	v_lshlrev_b32_e32 v122, 16, v143
	v_mov_b32_dpp v111, v112 quad_perm:[1,0,3,2] row_mask:0xf bank_mask:0xf
	ds_read_b64 v[112:113], v201 offset:256
	v_and_b32_e32 v123, 0xffff0000, v143
	v_cndmask_b32_e64 v103, v107, v103, s[10:11]
	v_cndmask_b32_e64 v102, v105, v102, s[10:11]
	v_cndmask_b32_e64 v97, v110, v97, s[10:11]
	s_waitcnt lgkmcnt(0)
	v_mul_f32_e32 v114, 0x3fb504f3, v113
	v_sub_f32_e32 v117, v116, v112
	v_sub_f32_e32 v116, v115, v112
	v_pk_mul_f32 v[116:117], v[116:117], v[114:115] op_sel_hi:[1,0]
	v_sub_f32_e32 v119, v119, v112
	v_pk_fma_f32 v[116:117], v[76:77], v[116:117], v[184:185]
	v_sub_f32_e32 v118, v118, v112
	v_pk_add_f32 v[100:101], v[100:101], v[116:117]
	v_sub_f32_e32 v117, v121, v112
	v_sub_f32_e32 v116, v120, v112
	v_sub_f32_e32 v113, v123, v112
	v_sub_f32_e32 v112, v122, v112
	v_pk_mul_f32 v[118:119], v[118:119], v[114:115] op_sel_hi:[1,0]
	v_pk_mul_f32 v[112:113], v[112:113], v[114:115] op_sel_hi:[1,0]
	v_pk_mul_f32 v[114:115], v[116:117], v[114:115] op_sel_hi:[1,0]
	v_cndmask_b32_e64 v96, v108, v96, s[10:11]
	v_cndmask_b32_e64 v99, v111, v99, s[10:11]
	v_cndmask_b32_e64 v98, v109, v98, s[10:11]
	v_pk_fma_f32 v[118:119], v[78:79], v[118:119], v[182:183]
	v_pk_fma_f32 v[114:115], v[72:73], v[114:115], v[180:181]
	v_pk_fma_f32 v[112:113], v[74:75], v[112:113], v[178:179]
	v_pk_add_f32 v[102:103], v[102:103], v[118:119]
	v_pk_add_f32 v[98:99], v[98:99], v[112:113]
	v_pk_add_f32 v[96:97], v[96:97], v[114:115]
	v_cvt_pk_bf16_f32 v112, v100, v101
	v_cvt_pk_bf16_f32 v113, v102, v103
	v_mov_b32_e32 v191, v165
	v_cvt_pk_bf16_f32 v114, v96, v97
	v_cvt_pk_bf16_f32 v115, v98, v99
	v_lshlrev_b32_e32 v96, 16, v112
	v_and_b32_e32 v98, 0xffff0000, v112
	v_lshlrev_b32_e32 v100, 16, v113
	v_and_b32_e32 v102, 0xffff0000, v113
	v_lshlrev_b32_e32 v116, 16, v114
	v_and_b32_e32 v118, 0xffff0000, v114
	v_lshlrev_b32_e32 v120, 16, v115
	v_and_b32_e32 v122, 0xffff0000, v115
	v_mul_f32_e32 v97, v96, v96
	v_mul_f32_e32 v99, v98, v98
	v_mul_f32_e32 v101, v100, v100
	v_mul_f32_e32 v103, v102, v102
	v_mul_f32_e32 v117, v116, v116
	v_mul_f32_e32 v119, v118, v118
	v_mul_f32_e32 v121, v120, v120
	v_mul_f32_e32 v123, v122, v122
	v_pk_add_f32 v[96:97], v[96:97], v[98:99]
	v_pk_add_f32 v[98:99], v[100:101], v[102:103]
	v_pk_add_f32 v[100:101], v[120:121], v[122:123]
	v_pk_add_f32 v[96:97], v[96:97], v[98:99]
	v_pk_add_f32 v[98:99], v[116:117], v[118:119]
	s_nop 0
	v_pk_add_f32 v[98:99], v[98:99], v[100:101]
	s_nop 0
	v_pk_add_f32 v[96:97], v[96:97], v[98:99]
	v_mov_b32_e32 v98, v165
	v_mov_b32_e32 v99, v165
	s_nop 0
	v_mov_b32_dpp v98, v96 quad_perm:[1,0,3,2] row_mask:0xf bank_mask:0xf
	v_mov_b32_dpp v99, v97 quad_perm:[1,0,3,2] row_mask:0xf bank_mask:0xf
	v_pk_add_f32 v[96:97], v[96:97], v[98:99]
	ds_bpermute_b32 v98, v207, v96
	ds_bpermute_b32 v99, v207, v97
	s_waitcnt lgkmcnt(0)
	v_pk_add_f32 v[98:99], v[96:97], v[98:99]
	ds_bpermute_b32 v100, v208, v98
	ds_bpermute_b32 v101, v208, v99
	v_lshl_add_u64 v[96:97], s[20:21], 0, v[190:191]
	global_store_dwordx4 v[96:97], v[112:115], off
	s_and_saveexec_b64 s[68:69], s[16:17]
	s_cbranch_execz .LBB0_826
	s_waitcnt lgkmcnt(0)
	v_pk_add_f32 v[98:99], v[98:99], v[100:101]
	v_add_co_u32_e32 v100, vcc, 0x4000, v186
	s_nop 1
	v_addc_co_u32_e32 v101, vcc, 0, v187, vcc
	v_mov_b32_e32 v250, v98
	v_mov_b32_e32 v251, v99
;     __device__ __forceinline__ void operator()(const f32x4 (&acc)[2][2][4][2], const Unit& u, int wr, int wc, int fr, int fq, const EpiCtx& X) const {
;     ...
;             for (int m = 0; m < 4; ++m) { const unsigned off = lo + (unsigned)((ai * HALF + m * 16) * 64) * 2u; raw[2 * m] = *(const u32x4*)(xb + off); raw[2 * m + 1] = *(const u32x4*)(xb + off + 128); }
; #pragma unroll
;             for (int m = 0; m < 4; ++m) {
;                 const int rl = ai * HALF + m * 16; const unsigned off = lo + (unsigned)(rl * 64) * 2u;
;                 const f32x4 o0a = acc[ai][0][m][0], o0b = acc[ai][0][m][1], o1a = acc[ai][1][m][0], o1b = acc[ai][1][m][1];
;                 const f32x4 ra_ = dpp_swap1(odd ? o0a : o1a), rb_ = dpp_swap1(odd ? o0b : o1b);
;                 const f32x4 pa[2] = {odd ? ra_ : o0a, odd ? o1a : ra_}, pb[2] = {odd ? rb_ : o0b, odd ? o1b : rb_};
; #pragma unroll
;                 for (int q = 0; q < 2; ++q) {
;                     const u32x4 w0 = raw[2 * m + q];
;                     const f32x4 r0 = (f32x4){bf_lo(w0.x), bf_hi(w0.x), bf_lo(w0.y), bf_hi(w0.y)}, r1 = (f32x4){bf_lo(w0.z), bf_hi(w0.z), bf_lo(w0.w), bf_hi(w0.w)};
;                     f32x4 y0, y1;
;                     if (RESN) { const f32x2 t = tbl[rl + q]; const float mu = t.x, ra = t.y * ALPHA; y0 = (r0 - mu) * ra * g0 + b0 + pa[q]; y1 = (r1 - mu) * ra * g1 + b1 + pb[q]; }
;                     else { y0 = r0 * ALPHA + pa[q]; y1 = r1 * ALPHA + pb[q]; }
;                     { const u32x4 w = pack8f(y0, y1); *(u32x4*)(xb + off + q * 128) = w;
;                         y0 = (f32x4){bf_lo(w.x), bf_hi(w.x), bf_lo(w.y), bf_hi(w.y)}; y1 = (f32x4){bf_lo(w.z), bf_hi(w.z), bf_lo(w.w), bf_hi(w.w)}; }
;                     float sa = ((y0[0] + y0[1]) + (y0[2] + y0[3])) + ((y1[0] + y1[1]) + (y1[2] + y1[3]));
;                     float sb = ((y0[0] * y0[0] + y0[1] * y0[1]) + (y0[2] * y0[2] + y0[3] * y0[3])) + ((y1[0] * y1[0] + y1[1] * y1[1]) + (y1[2] * y1[2] + y1[3] * y1[3]));
;                     sa += dpp_x1(sa);
;                     sb += dpp_x1(sb);
;                     sa += __shfl_xor(sa, 16); sa += __shfl_xor(sa, 32); sb += __shfl_xor(sb, 16); sb += __shfl_xor(sb, 32);
;                     if (fq == 0 && !odd) ps[(size_t)(rl + q) * 64] = (f32x2){sa, sb};
.LBB0_826:
	s_or_b64 exec, exec, s[68:69]
	ds_read_b64 v[98:99], v201 offset:264
	s_waitcnt lgkmcnt(1)
	v_lshlrev_b32_e32 v101, 16, v136
	v_and_b32_e32 v102, 0xffff0000, v136
	v_cndmask_b32_e64 v93, v93, v106, s[10:11]
	v_cndmask_b32_e64 v92, v92, v104, s[10:11]
	s_waitcnt lgkmcnt(0)
	v_mul_f32_e32 v100, 0x3fb504f3, v99
	v_sub_f32_e32 v103, v102, v98
	v_sub_f32_e32 v102, v101, v98
	v_pk_mul_f32 v[102:103], v[102:103], v[100:101] op_sel_hi:[1,0]
	v_cndmask_b32_e64 v95, v95, v107, s[10:11]
	v_cndmask_b32_e64 v94, v94, v105, s[10:11]
	v_cndmask_b32_e64 v88, v88, v108, s[10:11]
	v_cndmask_b32_e64 v90, v90, v109, s[10:11]
	v_lshlrev_b32_e32 v104, 16, v137
	v_and_b32_e32 v105, 0xffff0000, v137
	v_lshlrev_b32_e32 v106, 16, v138
	v_and_b32_e32 v107, 0xffff0000, v138
	v_lshlrev_b32_e32 v108, 16, v139
	v_and_b32_e32 v109, 0xffff0000, v139
	v_pk_fma_f32 v[102:103], v[76:77], v[102:103], v[184:185]
	v_sub_f32_e32 v105, v105, v98
	v_sub_f32_e32 v104, v104, v98
	v_pk_add_f32 v[92:93], v[92:93], v[102:103]
	v_sub_f32_e32 v103, v107, v98
	v_sub_f32_e32 v102, v106, v98
	v_sub_f32_e32 v99, v109, v98
	v_sub_f32_e32 v98, v108, v98
	v_pk_mul_f32 v[104:105], v[104:105], v[100:101] op_sel_hi:[1,0]
	v_pk_mul_f32 v[98:99], v[98:99], v[100:101] op_sel_hi:[1,0]
	v_pk_mul_f32 v[100:101], v[102:103], v[100:101] op_sel_hi:[1,0]
	v_cndmask_b32_e64 v89, v89, v110, s[10:11]
	v_cndmask_b32_e64 v91, v91, v111, s[10:11]
	v_pk_fma_f32 v[104:105], v[78:79], v[104:105], v[182:183]
	v_pk_fma_f32 v[100:101], v[72:73], v[100:101], v[180:181]
	v_pk_fma_f32 v[98:99], v[74:75], v[98:99], v[178:179]
	v_pk_add_f32 v[94:95], v[94:95], v[104:105]
	v_pk_add_f32 v[90:91], v[90:91], v[98:99]
	v_pk_add_f32 v[88:89], v[88:89], v[100:101]
	v_cvt_pk_bf16_f32 v92, v92, v93
	v_cvt_pk_bf16_f32 v93, v94, v95
	s_nop 0
	v_cvt_pk_bf16_f32 v94, v88, v89
	v_cvt_pk_bf16_f32 v95, v90, v91
	v_lshlrev_b32_e32 v88, 16, v92
	v_and_b32_e32 v90, 0xffff0000, v92
	v_lshlrev_b32_e32 v98, 16, v93
	v_and_b32_e32 v100, 0xffff0000, v93
	v_lshlrev_b32_e32 v102, 16, v94
	v_and_b32_e32 v104, 0xffff0000, v94
	v_lshlrev_b32_e32 v106, 16, v95
	v_and_b32_e32 v108, 0xffff0000, v95
	v_mul_f32_e32 v89, v88, v88
	v_mul_f32_e32 v91, v90, v90
	v_mul_f32_e32 v99, v98, v98
	v_mul_f32_e32 v101, v100, v100
	v_mul_f32_e32 v103, v102, v102
	v_mul_f32_e32 v105, v104, v104
	v_mul_f32_e32 v107, v106, v106
	v_mul_f32_e32 v109, v108, v108
	v_pk_add_f32 v[88:89], v[88:89], v[90:91]
	v_pk_add_f32 v[90:91], v[98:99], v[100:101]
	v_pk_add_f32 v[98:99], v[106:107], v[108:109]
	v_pk_add_f32 v[88:89], v[88:89], v[90:91]
	v_pk_add_f32 v[90:91], v[102:103], v[104:105]
	global_store_dwordx4 v[96:97], v[92:95], off offset:128
	v_pk_add_f32 v[90:91], v[90:91], v[98:99]
	s_nop 0
	v_pk_add_f32 v[88:89], v[88:89], v[90:91]
	v_mov_b32_e32 v90, v165
	v_mov_b32_e32 v91, v165
	s_nop 0
	v_mov_b32_dpp v90, v88 quad_perm:[1,0,3,2] row_mask:0xf bank_mask:0xf
	v_mov_b32_dpp v91, v89 quad_perm:[1,0,3,2] row_mask:0xf bank_mask:0xf
	v_pk_add_f32 v[88:89], v[88:89], v[90:91]
	ds_bpermute_b32 v90, v207, v88
	ds_bpermute_b32 v91, v207, v89
	s_waitcnt lgkmcnt(0)
	v_pk_add_f32 v[88:89], v[88:89], v[90:91]
	ds_bpermute_b32 v90, v208, v88
	ds_bpermute_b32 v91, v208, v89
	s_and_saveexec_b64 s[68:69], s[16:17]
	s_cbranch_execz .LBB0_828
	s_waitcnt lgkmcnt(0)
	v_pk_add_f32 v[88:89], v[88:89], v[90:91]
	v_add_co_u32_e32 v90, vcc, 0x4000, v186
	s_nop 1
	v_addc_co_u32_e32 v91, vcc, 0, v187, vcc
	v_mov_b32_e32 v252, v250
	v_mov_b32_e32 v253, v251
	v_mov_b32_e32 v254, v88
	v_mov_b32_e32 v255, v89
	global_store_dwordx4 v249, v[252:255], s[94:95] offset:256
.LBB0_828:
	s_or_b64 exec, exec, s[68:69]
	s_waitcnt lgkmcnt(1)
	v_cndmask_b32_e64 v90, v84, v68, s[10:11]
	v_mov_b32_e32 v88, 0
	v_cndmask_b32_e64 v89, v85, v69, s[10:11]
	s_waitcnt lgkmcnt(0)
	v_cndmask_b32_e64 v91, v86, v70, s[10:11]
	v_mov_b32_dpp v88, v90 quad_perm:[1,0,3,2] row_mask:0xf bank_mask:0xf
	v_mov_b32_e32 v90, 0
	v_cndmask_b32_e64 v92, v87, v71, s[10:11]
	v_cndmask_b32_e64 v94, v80, v64, s[10:11]
	v_mov_b32_dpp v90, v89 quad_perm:[1,0,3,2] row_mask:0xf bank_mask:0xf
	v_mov_b32_e32 v89, 0
	v_cndmask_b32_e64 v93, v81, v65, s[10:11]
	v_cndmask_b32_e64 v95, v82, v66, s[10:11]
	v_mov_b32_dpp v89, v91 quad_perm:[1,0,3,2] row_mask:0xf bank_mask:0xf
	v_mov_b32_e32 v91, 0
	v_cndmask_b32_e64 v96, v83, v67, s[10:11]
	v_lshlrev_b32_e32 v99, 16, v132
	v_mov_b32_dpp v91, v92 quad_perm:[1,0,3,2] row_mask:0xf bank_mask:0xf
	v_mov_b32_e32 v92, 0
	v_and_b32_e32 v100, 0xffff0000, v132
	v_cndmask_b32_e64 v85, v90, v85, s[10:11]
	v_mov_b32_dpp v92, v94 quad_perm:[1,0,3,2] row_mask:0xf bank_mask:0xf
	v_mov_b32_e32 v94, 0
	v_cndmask_b32_e64 v84, v88, v84, s[10:11]
	v_lshlrev_b32_e32 v102, 16, v133
	v_mov_b32_dpp v94, v93 quad_perm:[1,0,3,2] row_mask:0xf bank_mask:0xf
	v_mov_b32_e32 v93, 0
	v_and_b32_e32 v103, 0xffff0000, v133
	v_lshlrev_b32_e32 v104, 16, v134
	v_mov_b32_dpp v93, v95 quad_perm:[1,0,3,2] row_mask:0xf bank_mask:0xf
	v_mov_b32_e32 v95, 0
	v_and_b32_e32 v105, 0xffff0000, v134
	v_lshlrev_b32_e32 v106, 16, v135
	v_mov_b32_dpp v95, v96 quad_perm:[1,0,3,2] row_mask:0xf bank_mask:0xf
	ds_read_b64 v[96:97], v201 offset:384
	v_and_b32_e32 v107, 0xffff0000, v135
	v_cndmask_b32_e64 v87, v91, v87, s[10:11]
	v_cndmask_b32_e64 v86, v89, v86, s[10:11]
	v_cndmask_b32_e64 v81, v94, v81, s[10:11]
	s_waitcnt lgkmcnt(0)
;     __device__ __forceinline__ void operator()(const f32x4 (&acc)[2][2][4][2], const Unit& u, int wr, int wc, int fr, int fq, const EpiCtx& X) const {
;     ...
;             for (int m = 0; m < 4; ++m) { const unsigned off = lo + (unsigned)((ai * HALF + m * 16) * 64) * 2u; raw[2 * m] = *(const u32x4*)(xb + off); raw[2 * m + 1] = *(const u32x4*)(xb + off + 128); }
; #pragma unroll
;             for (int m = 0; m < 4; ++m) {
;                 const int rl = ai * HALF + m * 16; const unsigned off = lo + (unsigned)(rl * 64) * 2u;
;                 const f32x4 o0a = acc[ai][0][m][0], o0b = acc[ai][0][m][1], o1a = acc[ai][1][m][0], o1b = acc[ai][1][m][1];
;                 const f32x4 ra_ = dpp_swap1(odd ? o0a : o1a), rb_ = dpp_swap1(odd ? o0b : o1b);
;                 const f32x4 pa[2] = {odd ? ra_ : o0a, odd ? o1a : ra_}, pb[2] = {odd ? rb_ : o0b, odd ? o1b : rb_};
; #pragma unroll
;                 for (int q = 0; q < 2; ++q) {
;                     const u32x4 w0 = raw[2 * m + q];
;                     const f32x4 r0 = (f32x4){bf_lo(w0.x), bf_hi(w0.x), bf_lo(w0.y), bf_hi(w0.y)}, r1 = (f32x4){bf_lo(w0.z), bf_hi(w0.z), bf_lo(w0.w), bf_hi(w0.w)};
;                     f32x4 y0, y1;
;                     if (RESN) { const f32x2 t = tbl[rl + q]; const float mu = t.x, ra = t.y * ALPHA; y0 = (r0 - mu) * ra * g0 + b0 + pa[q]; y1 = (r1 - mu) * ra * g1 + b1 + pb[q]; }
;                     else { y0 = r0 * ALPHA + pa[q]; y1 = r1 * ALPHA + pb[q]; }
;                     { const u32x4 w = pack8f(y0, y1); *(u32x4*)(xb + off + q * 128) = w;
;                         y0 = (f32x4){bf_lo(w.x), bf_hi(w.x), bf_lo(w.y), bf_hi(w.y)}; y1 = (f32x4){bf_lo(w.z), bf_hi(w.z), bf_lo(w.w), bf_hi(w.w)}; }
;                     float sa = ((y0[0] + y0[1]) + (y0[2] + y0[3])) + ((y1[0] + y1[1]) + (y1[2] + y1[3]));
;                     float sb = ((y0[0] * y0[0] + y0[1] * y0[1]) + (y0[2] * y0[2] + y0[3] * y0[3])) + ((y1[0] * y1[0] + y1[1] * y1[1]) + (y1[2] * y1[2] + y1[3] * y1[3]));
;                     sa += dpp_x1(sa);
;                     sb += dpp_x1(sb);
;                     sa += __shfl_xor(sa, 16); sa += __shfl_xor(sa, 32); sb += __shfl_xor(sb, 16); sb += __shfl_xor(sb, 32);
;                     if (fq == 0 && !odd) ps[(size_t)(rl + q) * 64] = (f32x2){sa, sb};
	v_mul_f32_e32 v98, 0x3fb504f3, v97
	v_sub_f32_e32 v101, v100, v96
	v_sub_f32_e32 v100, v99, v96
	v_pk_mul_f32 v[100:101], v[100:101], v[98:99] op_sel_hi:[1,0]
	v_sub_f32_e32 v103, v103, v96
	v_pk_fma_f32 v[100:101], v[76:77], v[100:101], v[184:185]
	v_sub_f32_e32 v102, v102, v96
	v_pk_add_f32 v[84:85], v[84:85], v[100:101]
	v_sub_f32_e32 v101, v105, v96
	v_sub_f32_e32 v100, v104, v96
	v_sub_f32_e32 v97, v107, v96
	v_sub_f32_e32 v96, v106, v96
	v_pk_mul_f32 v[102:103], v[102:103], v[98:99] op_sel_hi:[1,0]
	v_pk_mul_f32 v[96:97], v[96:97], v[98:99] op_sel_hi:[1,0]
	v_pk_mul_f32 v[98:99], v[100:101], v[98:99] op_sel_hi:[1,0]
	v_cndmask_b32_e64 v80, v92, v80, s[10:11]
	v_cndmask_b32_e64 v83, v95, v83, s[10:11]
	v_cndmask_b32_e64 v82, v93, v82, s[10:11]
	v_pk_fma_f32 v[102:103], v[78:79], v[102:103], v[182:183]
	v_pk_fma_f32 v[98:99], v[72:73], v[98:99], v[180:181]
	v_pk_fma_f32 v[96:97], v[74:75], v[96:97], v[178:179]
	v_pk_add_f32 v[86:87], v[86:87], v[102:103]
	v_pk_add_f32 v[82:83], v[82:83], v[96:97]
	v_pk_add_f32 v[80:81], v[80:81], v[98:99]
	v_cvt_pk_bf16_f32 v96, v84, v85
	v_cvt_pk_bf16_f32 v97, v86, v87
	v_mov_b32_e32 v189, v165
	v_cvt_pk_bf16_f32 v98, v80, v81
	v_cvt_pk_bf16_f32 v99, v82, v83
	v_lshlrev_b32_e32 v80, 16, v96
	v_and_b32_e32 v82, 0xffff0000, v96
	v_lshlrev_b32_e32 v84, 16, v97
	v_and_b32_e32 v86, 0xffff0000, v97
	v_lshlrev_b32_e32 v100, 16, v98
	v_and_b32_e32 v102, 0xffff0000, v98
	v_lshlrev_b32_e32 v104, 16, v99
	v_and_b32_e32 v106, 0xffff0000, v99
	v_mul_f32_e32 v81, v80, v80
	v_mul_f32_e32 v83, v82, v82
	v_mul_f32_e32 v85, v84, v84
	v_mul_f32_e32 v87, v86, v86
	v_mul_f32_e32 v101, v100, v100
	v_mul_f32_e32 v103, v102, v102
	v_mul_f32_e32 v105, v104, v104
	v_mul_f32_e32 v107, v106, v106
	v_pk_add_f32 v[80:81], v[80:81], v[82:83]
	v_pk_add_f32 v[82:83], v[84:85], v[86:87]
	v_pk_add_f32 v[84:85], v[104:105], v[106:107]
	v_pk_add_f32 v[80:81], v[80:81], v[82:83]
	v_pk_add_f32 v[82:83], v[100:101], v[102:103]
	s_nop 0
	v_pk_add_f32 v[82:83], v[82:83], v[84:85]
	s_nop 0
	v_pk_add_f32 v[80:81], v[80:81], v[82:83]
	v_mov_b32_e32 v82, v165
	v_mov_b32_e32 v83, v165
	s_nop 0
	v_mov_b32_dpp v82, v80 quad_perm:[1,0,3,2] row_mask:0xf bank_mask:0xf
	v_mov_b32_dpp v83, v81 quad_perm:[1,0,3,2] row_mask:0xf bank_mask:0xf
	v_pk_add_f32 v[80:81], v[80:81], v[82:83]
	ds_bpermute_b32 v82, v207, v80
	ds_bpermute_b32 v83, v207, v81
	s_waitcnt lgkmcnt(0)
	v_pk_add_f32 v[82:83], v[80:81], v[82:83]
	ds_bpermute_b32 v84, v208, v82
	ds_bpermute_b32 v85, v208, v83
	v_lshl_add_u64 v[80:81], s[20:21], 0, v[188:189]
	global_store_dwordx4 v[80:81], v[96:99], off
	s_and_saveexec_b64 s[68:69], s[16:17]
	s_cbranch_execz .LBB0_830
	s_waitcnt lgkmcnt(0)
	v_pk_add_f32 v[82:83], v[82:83], v[84:85]
	v_add_co_u32_e32 v84, vcc, 0x6000, v186
	s_nop 1
	v_addc_co_u32_e32 v85, vcc, 0, v187, vcc
	v_mov_b32_e32 v250, v82
	v_mov_b32_e32 v251, v83
.LBB0_830:
	s_or_b64 exec, exec, s[68:69]
	ds_read_b64 v[82:83], v201 offset:392
	s_waitcnt lgkmcnt(1)
	v_lshlrev_b32_e32 v85, 16, v128
	v_and_b32_e32 v86, 0xffff0000, v128
	v_cndmask_b32_e64 v69, v69, v90, s[10:11]
	v_cndmask_b32_e64 v68, v68, v88, s[10:11]
	s_waitcnt lgkmcnt(0)
	v_mul_f32_e32 v84, 0x3fb504f3, v83
	v_sub_f32_e32 v87, v86, v82
	v_sub_f32_e32 v86, v85, v82
	v_pk_mul_f32 v[86:87], v[86:87], v[84:85] op_sel_hi:[1,0]
	v_cndmask_b32_e64 v71, v71, v91, s[10:11]
	v_cndmask_b32_e64 v70, v70, v89, s[10:11]
	v_cndmask_b32_e64 v64, v64, v92, s[10:11]
	v_cndmask_b32_e64 v66, v66, v93, s[10:11]
	v_lshlrev_b32_e32 v88, 16, v129
	v_and_b32_e32 v89, 0xffff0000, v129
	v_lshlrev_b32_e32 v90, 16, v130
	v_and_b32_e32 v91, 0xffff0000, v130
	v_lshlrev_b32_e32 v92, 16, v131
	v_and_b32_e32 v93, 0xffff0000, v131
	v_pk_fma_f32 v[86:87], v[76:77], v[86:87], v[184:185]
	v_sub_f32_e32 v89, v89, v82
	v_sub_f32_e32 v88, v88, v82
	v_pk_add_f32 v[68:69], v[68:69], v[86:87]
	v_sub_f32_e32 v87, v91, v82
	v_sub_f32_e32 v86, v90, v82
	v_sub_f32_e32 v83, v93, v82
	v_sub_f32_e32 v82, v92, v82
	v_pk_mul_f32 v[88:89], v[88:89], v[84:85] op_sel_hi:[1,0]
	v_pk_mul_f32 v[82:83], v[82:83], v[84:85] op_sel_hi:[1,0]
	v_pk_mul_f32 v[84:85], v[86:87], v[84:85] op_sel_hi:[1,0]
	v_cndmask_b32_e64 v65, v65, v94, s[10:11]
	v_cndmask_b32_e64 v67, v67, v95, s[10:11]
	v_pk_fma_f32 v[88:89], v[78:79], v[88:89], v[182:183]
	v_pk_fma_f32 v[84:85], v[72:73], v[84:85], v[180:181]
	v_pk_fma_f32 v[82:83], v[74:75], v[82:83], v[178:179]
	v_pk_add_f32 v[70:71], v[70:71], v[88:89]
	v_pk_add_f32 v[66:67], v[66:67], v[82:83]
	v_pk_add_f32 v[64:65], v[64:65], v[84:85]
	v_cvt_pk_bf16_f32 v68, v68, v69
	v_cvt_pk_bf16_f32 v69, v70, v71
	s_nop 0
	v_cvt_pk_bf16_f32 v70, v64, v65
	v_cvt_pk_bf16_f32 v71, v66, v67
	v_lshlrev_b32_e32 v64, 16, v68
	v_and_b32_e32 v66, 0xffff0000, v68
	v_lshlrev_b32_e32 v82, 16, v69
	v_and_b32_e32 v84, 0xffff0000, v69
	v_lshlrev_b32_e32 v86, 16, v70
	v_and_b32_e32 v88, 0xffff0000, v70
	v_lshlrev_b32_e32 v90, 16, v71
	v_and_b32_e32 v92, 0xffff0000, v71
	v_mul_f32_e32 v65, v64, v64
	v_mul_f32_e32 v67, v66, v66
	v_mul_f32_e32 v83, v82, v82
	v_mul_f32_e32 v85, v84, v84
	v_mul_f32_e32 v87, v86, v86
	v_mul_f32_e32 v89, v88, v88
	v_mul_f32_e32 v91, v90, v90
	v_mul_f32_e32 v93, v92, v92
	v_pk_add_f32 v[64:65], v[64:65], v[66:67]
	v_pk_add_f32 v[66:67], v[82:83], v[84:85]
	v_pk_add_f32 v[82:83], v[90:91], v[92:93]
	v_pk_add_f32 v[64:65], v[64:65], v[66:67]
	v_pk_add_f32 v[66:67], v[86:87], v[88:89]
	global_store_dwordx4 v[80:81], v[68:71], off offset:128
	v_pk_add_f32 v[66:67], v[66:67], v[82:83]
	s_nop 0
	v_pk_add_f32 v[64:65], v[64:65], v[66:67]
	v_mov_b32_e32 v66, v165
	v_mov_b32_e32 v67, v165
	s_nop 0
	v_mov_b32_dpp v66, v64 quad_perm:[1,0,3,2] row_mask:0xf bank_mask:0xf
	v_mov_b32_dpp v67, v65 quad_perm:[1,0,3,2] row_mask:0xf bank_mask:0xf
	v_pk_add_f32 v[64:65], v[64:65], v[66:67]
	ds_bpermute_b32 v66, v207, v64
	ds_bpermute_b32 v67, v207, v65
	s_waitcnt lgkmcnt(0)
	v_pk_add_f32 v[64:65], v[64:65], v[66:67]
	ds_bpermute_b32 v66, v208, v64
	ds_bpermute_b32 v67, v208, v65
	s_and_saveexec_b64 s[68:69], s[16:17]
	s_cbranch_execz .LBB0_832
	s_waitcnt lgkmcnt(0)
	v_pk_add_f32 v[64:65], v[64:65], v[66:67]
	v_add_co_u32_e32 v66, vcc, 0x6000, v186
	s_nop 1
	v_addc_co_u32_e32 v67, vcc, 0, v187, vcc
	v_mov_b32_e32 v252, v250
	v_mov_b32_e32 v253, v251
	v_mov_b32_e32 v254, v64
	v_mov_b32_e32 v255, v65
	global_store_dwordx4 v249, v[252:255], s[94:95] offset:384
;     __device__ __forceinline__ void operator()(const f32x4 (&acc)[2][2][4][2], const Unit& u, int wr, int wc, int fr, int fq, const EpiCtx& X) const {
;     ...
;             for (int m = 0; m < 4; ++m) { const unsigned off = lo + (unsigned)((ai * HALF + m * 16) * 64) * 2u; raw[2 * m] = *(const u32x4*)(xb + off); raw[2 * m + 1] = *(const u32x4*)(xb + off + 128); }
; #pragma unroll
;             for (int m = 0; m < 4; ++m) {
;                 const int rl = ai * HALF + m * 16; const unsigned off = lo + (unsigned)(rl * 64) * 2u;
;                 const f32x4 o0a = acc[ai][0][m][0], o0b = acc[ai][0][m][1], o1a = acc[ai][1][m][0], o1b = acc[ai][1][m][1];
;                 const f32x4 ra_ = dpp_swap1(odd ? o0a : o1a), rb_ = dpp_swap1(odd ? o0b : o1b);
;                 const f32x4 pa[2] = {odd ? ra_ : o0a, odd ? o1a : ra_}, pb[2] = {odd ? rb_ : o0b, odd ? o1b : rb_};
; #pragma unroll
;                 for (int q = 0; q < 2; ++q) {
;                     const u32x4 w0 = raw[2 * m + q];
;                     const f32x4 r0 = (f32x4){bf_lo(w0.x), bf_hi(w0.x), bf_lo(w0.y), bf_hi(w0.y)}, r1 = (f32x4){bf_lo(w0.z), bf_hi(w0.z), bf_lo(w0.w), bf_hi(w0.w)};
;                     f32x4 y0, y1;
;                     if (RESN) { const f32x2 t = tbl[rl + q]; const float mu = t.x, ra = t.y * ALPHA; y0 = (r0 - mu) * ra * g0 + b0 + pa[q]; y1 = (r1 - mu) * ra * g1 + b1 + pb[q]; }
;                     else { y0 = r0 * ALPHA + pa[q]; y1 = r1 * ALPHA + pb[q]; }
;                     { const u32x4 w = pack8f(y0, y1); *(u32x4*)(xb + off + q * 128) = w;
;                         y0 = (f32x4){bf_lo(w.x), bf_hi(w.x), bf_lo(w.y), bf_hi(w.y)}; y1 = (f32x4){bf_lo(w.z), bf_hi(w.z), bf_lo(w.w), bf_hi(w.w)}; }
;                     float sa = ((y0[0] + y0[1]) + (y0[2] + y0[3])) + ((y1[0] + y1[1]) + (y1[2] + y1[3]));
;                     float sb = ((y0[0] * y0[0] + y0[1] * y0[1]) + (y0[2] * y0[2] + y0[3] * y0[3])) + ((y1[0] * y1[0] + y1[1] * y1[1]) + (y1[2] * y1[2] + y1[3] * y1[3]));
;                     sa += dpp_x1(sa);
;                     sb += dpp_x1(sb);
;                     sa += __shfl_xor(sa, 16); sa += __shfl_xor(sa, 32); sb += __shfl_xor(sb, 16); sb += __shfl_xor(sb, 32);
;                     if (fq == 0 && !odd) ps[(size_t)(rl + q) * 64] = (f32x2){sa, sb};
.LBB0_832:
	s_or_b64 exec, exec, s[68:69]
	v_add_u32_e32 v104, 0x4000, v164
	v_mov_b32_e32 v112, v230
	v_mov_b32_e32 v113, v231
	v_mov_b32_e32 v114, v232
	v_mov_b32_e32 v115, v233
	v_add_u32_e32 v102, 0x4800, v164
	v_add_u32_e32 v100, 0x5000, v164
	v_add_u32_e32 v164, 0x5800, v164
	v_mov_b32_e32 v96, v234
	v_mov_b32_e32 v97, v235
	v_mov_b32_e32 v98, v236
	v_mov_b32_e32 v99, v237
	v_mov_b32_e32 v92, v238
	v_mov_b32_e32 v93, v239
	v_mov_b32_e32 v94, v240
	v_mov_b32_e32 v95, v241
	v_mov_b32_e32 v88, v242
	v_mov_b32_e32 v89, v243
	v_mov_b32_e32 v90, v244
	v_mov_b32_e32 v91, v245
	global_load_dwordx4 v[84:87], v100, s[20:21]
	global_load_dwordx4 v[80:83], v100, s[20:21] offset:128
	global_load_dwordx4 v[68:71], v164, s[20:21]
	s_waitcnt lgkmcnt(0)
	global_load_dwordx4 v[64:67], v164, s[20:21] offset:128
	v_cndmask_b32_e64 v116, v62, v54, s[10:11]
	v_cndmask_b32_e64 v117, v61, v53, s[10:11]
	v_mov_b32_e32 v105, 0
	v_mov_b32_e32 v103, 0
	v_cndmask_b32_e64 v111, v63, v55, s[10:11]
	v_mov_b32_dpp v105, v117 quad_perm:[1,0,3,2] row_mask:0xf bank_mask:0xf
	v_mov_b32_dpp v103, v116 quad_perm:[1,0,3,2] row_mask:0xf bank_mask:0xf
	ds_read_b64 v[116:117], v201 offset:1024
	v_cndmask_b32_e64 v118, v60, v52, s[10:11]
	v_mov_b32_e32 v101, 0
	v_mov_b32_e32 v106, 0
	v_cndmask_b32_e64 v119, v59, v51, s[10:11]
	v_cndmask_b32_e64 v120, v58, v50, s[10:11]
	v_cndmask_b32_e64 v121, v57, v49, s[10:11]
	v_cndmask_b32_e64 v122, v56, v48, s[10:11]
	v_mov_b32_e32 v107, 0
	v_mov_b32_e32 v109, 0
	v_mov_b32_e32 v108, 0
	v_mov_b32_e32 v110, 0
	v_mov_b32_dpp v101, v118 quad_perm:[1,0,3,2] row_mask:0xf bank_mask:0xf
	v_mov_b32_dpp v106, v111 quad_perm:[1,0,3,2] row_mask:0xf bank_mask:0xf
	v_mov_b32_dpp v107, v122 quad_perm:[1,0,3,2] row_mask:0xf bank_mask:0xf
	v_mov_b32_dpp v109, v121 quad_perm:[1,0,3,2] row_mask:0xf bank_mask:0xf
	v_mov_b32_dpp v108, v120 quad_perm:[1,0,3,2] row_mask:0xf bank_mask:0xf
	v_mov_b32_dpp v110, v119 quad_perm:[1,0,3,2] row_mask:0xf bank_mask:0xf
	s_waitcnt lgkmcnt(0)
	v_mul_f32_e32 v118, 0x3fb504f3, v117
	v_cndmask_b32_e64 v61, v105, v61, s[10:11]
	v_cndmask_b32_e64 v60, v101, v60, s[10:11]
	v_cndmask_b32_e64 v63, v106, v63, s[10:11]
	v_cndmask_b32_e64 v62, v103, v62, s[10:11]
	v_cndmask_b32_e64 v57, v109, v57, s[10:11]
	v_cndmask_b32_e64 v56, v107, v56, s[10:11]
	v_cndmask_b32_e64 v59, v110, v59, s[10:11]
	v_cndmask_b32_e64 v58, v108, v58, s[10:11]
	v_lshlrev_b32_e32 v111, 16, v112
	v_and_b32_e32 v112, 0xffff0000, v112
	v_lshlrev_b32_e32 v117, 16, v113
	v_and_b32_e32 v119, 0xffff0000, v113
	v_lshlrev_b32_e32 v120, 16, v114
	v_and_b32_e32 v121, 0xffff0000, v114
	v_lshlrev_b32_e32 v122, 16, v115
	v_and_b32_e32 v123, 0xffff0000, v115
	v_sub_f32_e32 v113, v112, v116
	v_sub_f32_e32 v112, v111, v116
	v_sub_f32_e32 v115, v119, v116
	v_sub_f32_e32 v114, v117, v116
	v_sub_f32_e32 v121, v121, v116
	v_sub_f32_e32 v120, v120, v116
	v_sub_f32_e32 v117, v123, v116
	v_sub_f32_e32 v116, v122, v116
	v_pk_mul_f32 v[114:115], v[114:115], v[118:119] op_sel_hi:[1,0]
	v_pk_mul_f32 v[112:113], v[112:113], v[118:119] op_sel_hi:[1,0]
	v_pk_mul_f32 v[116:117], v[116:117], v[118:119] op_sel_hi:[1,0]
	v_pk_mul_f32 v[118:119], v[120:121], v[118:119] op_sel_hi:[1,0]
	v_pk_fma_f32 v[112:113], v[76:77], v[112:113], v[184:185]
	v_pk_fma_f32 v[114:115], v[78:79], v[114:115], v[182:183]
	v_pk_fma_f32 v[118:119], v[72:73], v[118:119], v[180:181]
	v_pk_fma_f32 v[116:117], v[74:75], v[116:117], v[178:179]
	v_pk_add_f32 v[62:63], v[62:63], v[114:115]
	v_pk_add_f32 v[60:61], v[60:61], v[112:113]
	v_pk_add_f32 v[58:59], v[58:59], v[116:117]
	v_pk_add_f32 v[56:57], v[56:57], v[118:119]
	v_cvt_pk_bf16_f32 v60, v60, v61
	v_cvt_pk_bf16_f32 v61, v62, v63
	s_nop 0
	v_cvt_pk_bf16_f32 v62, v56, v57
	v_cvt_pk_bf16_f32 v63, v58, v59
	v_lshlrev_b32_e32 v56, 16, v60
	v_and_b32_e32 v58, 0xffff0000, v60
	v_lshlrev_b32_e32 v112, 16, v61
	v_and_b32_e32 v114, 0xffff0000, v61
	v_lshlrev_b32_e32 v116, 16, v62
	v_and_b32_e32 v118, 0xffff0000, v62
	v_lshlrev_b32_e32 v120, 16, v63
	v_and_b32_e32 v122, 0xffff0000, v63
	v_mul_f32_e32 v57, v56, v56
	v_mul_f32_e32 v59, v58, v58
	v_mul_f32_e32 v113, v112, v112
	v_mul_f32_e32 v115, v114, v114
	v_mul_f32_e32 v117, v116, v116
	v_mul_f32_e32 v119, v118, v118
	v_mul_f32_e32 v121, v120, v120
	v_mul_f32_e32 v123, v122, v122
	v_pk_add_f32 v[56:57], v[56:57], v[58:59]
	v_pk_add_f32 v[58:59], v[112:113], v[114:115]
	v_pk_add_f32 v[112:113], v[120:121], v[122:123]
	v_pk_add_f32 v[56:57], v[56:57], v[58:59]
	v_pk_add_f32 v[58:59], v[116:117], v[118:119]
	global_store_dwordx4 v104, v[60:63], s[20:21]
	v_pk_add_f32 v[58:59], v[58:59], v[112:113]
	s_nop 0
	v_pk_add_f32 v[56:57], v[56:57], v[58:59]
	v_mov_b32_e32 v58, v165
	v_mov_b32_e32 v59, v165
	s_nop 0
	v_mov_b32_dpp v58, v56 quad_perm:[1,0,3,2] row_mask:0xf bank_mask:0xf
	v_mov_b32_dpp v59, v57 quad_perm:[1,0,3,2] row_mask:0xf bank_mask:0xf
	v_pk_add_f32 v[56:57], v[56:57], v[58:59]
	ds_bpermute_b32 v58, v207, v56
	ds_bpermute_b32 v59, v207, v57
	s_waitcnt lgkmcnt(0)
	v_pk_add_f32 v[56:57], v[56:57], v[58:59]
	ds_bpermute_b32 v58, v208, v56
	ds_bpermute_b32 v59, v208, v57
	s_and_saveexec_b64 s[68:69], s[16:17]
	s_cbranch_execz .LBB0_834
	s_waitcnt lgkmcnt(0)
	v_pk_add_f32 v[56:57], v[56:57], v[58:59]
	v_add_co_u32_e32 v58, vcc, 0x10000, v186
	s_nop 1
	v_addc_co_u32_e32 v59, vcc, 0, v187, vcc
	v_mov_b32_e32 v250, v56
	v_mov_b32_e32 v251, v57
;     __device__ __forceinline__ void operator()(const f32x4 (&acc)[2][2][4][2], const Unit& u, int wr, int wc, int fr, int fq, const EpiCtx& X) const {
;     ...
;             for (int m = 0; m < 4; ++m) { const unsigned off = lo + (unsigned)((ai * HALF + m * 16) * 64) * 2u; raw[2 * m] = *(const u32x4*)(xb + off); raw[2 * m + 1] = *(const u32x4*)(xb + off + 128); }
; #pragma unroll
;             for (int m = 0; m < 4; ++m) {
;                 const int rl = ai * HALF + m * 16; const unsigned off = lo + (unsigned)(rl * 64) * 2u;
;                 const f32x4 o0a = acc[ai][0][m][0], o0b = acc[ai][0][m][1], o1a = acc[ai][1][m][0], o1b = acc[ai][1][m][1];
;                 const f32x4 ra_ = dpp_swap1(odd ? o0a : o1a), rb_ = dpp_swap1(odd ? o0b : o1b);
;                 const f32x4 pa[2] = {odd ? ra_ : o0a, odd ? o1a : ra_}, pb[2] = {odd ? rb_ : o0b, odd ? o1b : rb_};
; #pragma unroll
;                 for (int q = 0; q < 2; ++q) {
;                     const u32x4 w0 = raw[2 * m + q];
;                     const f32x4 r0 = (f32x4){bf_lo(w0.x), bf_hi(w0.x), bf_lo(w0.y), bf_hi(w0.y)}, r1 = (f32x4){bf_lo(w0.z), bf_hi(w0.z), bf_lo(w0.w), bf_hi(w0.w)};
;                     f32x4 y0, y1;
;                     if (RESN) { const f32x2 t = tbl[rl + q]; const float mu = t.x, ra = t.y * ALPHA; y0 = (r0 - mu) * ra * g0 + b0 + pa[q]; y1 = (r1 - mu) * ra * g1 + b1 + pb[q]; }
;                     else { y0 = r0 * ALPHA + pa[q]; y1 = r1 * ALPHA + pb[q]; }
;                     { const u32x4 w = pack8f(y0, y1); *(u32x4*)(xb + off + q * 128) = w;
;                         y0 = (f32x4){bf_lo(w.x), bf_hi(w.x), bf_lo(w.y), bf_hi(w.y)}; y1 = (f32x4){bf_lo(w.z), bf_hi(w.z), bf_lo(w.w), bf_hi(w.w)}; }
;                     float sa = ((y0[0] + y0[1]) + (y0[2] + y0[3])) + ((y1[0] + y1[1]) + (y1[2] + y1[3]));
;                     float sb = ((y0[0] * y0[0] + y0[1] * y0[1]) + (y0[2] * y0[2] + y0[3] * y0[3])) + ((y1[0] * y1[0] + y1[1] * y1[1]) + (y1[2] * y1[2] + y1[3] * y1[3]));
;                     sa += dpp_x1(sa);
;                     sb += dpp_x1(sb);
;                     sa += __shfl_xor(sa, 16); sa += __shfl_xor(sa, 32); sb += __shfl_xor(sb, 16); sb += __shfl_xor(sb, 32);
;                     if (fq == 0 && !odd) ps[(size_t)(rl + q) * 64] = (f32x2){sa, sb};
.LBB0_834:
	s_or_b64 exec, exec, s[68:69]
	ds_read_b64 v[56:57], v201 offset:1032
	s_waitcnt lgkmcnt(1)
	v_lshlrev_b32_e32 v59, 16, v96
	v_and_b32_e32 v60, 0xffff0000, v96
	v_cndmask_b32_e64 v53, v53, v105, s[10:11]
	v_cndmask_b32_e64 v52, v52, v101, s[10:11]
	s_waitcnt lgkmcnt(0)
	v_mul_f32_e32 v58, 0x3fb504f3, v57
	v_sub_f32_e32 v61, v60, v56
	v_sub_f32_e32 v60, v59, v56
	v_pk_mul_f32 v[60:61], v[60:61], v[58:59] op_sel_hi:[1,0]
	v_lshlrev_b32_e32 v62, 16, v97
	v_and_b32_e32 v63, 0xffff0000, v97
	v_lshlrev_b32_e32 v96, 16, v98
	v_and_b32_e32 v97, 0xffff0000, v98
	v_lshlrev_b32_e32 v98, 16, v99
	v_and_b32_e32 v99, 0xffff0000, v99
	v_pk_fma_f32 v[60:61], v[76:77], v[60:61], v[184:185]
	v_sub_f32_e32 v63, v63, v56
	v_sub_f32_e32 v62, v62, v56
	v_pk_add_f32 v[52:53], v[52:53], v[60:61]
	v_sub_f32_e32 v61, v97, v56
	v_sub_f32_e32 v60, v96, v56
	v_sub_f32_e32 v57, v99, v56
	v_sub_f32_e32 v56, v98, v56
	v_pk_mul_f32 v[62:63], v[62:63], v[58:59] op_sel_hi:[1,0]
	v_pk_mul_f32 v[56:57], v[56:57], v[58:59] op_sel_hi:[1,0]
	v_pk_mul_f32 v[58:59], v[60:61], v[58:59] op_sel_hi:[1,0]
	v_cndmask_b32_e64 v55, v55, v106, s[10:11]
	v_cndmask_b32_e64 v54, v54, v103, s[10:11]
	v_cndmask_b32_e64 v49, v49, v109, s[10:11]
	v_cndmask_b32_e64 v48, v48, v107, s[10:11]
	v_cndmask_b32_e64 v51, v51, v110, s[10:11]
	v_cndmask_b32_e64 v50, v50, v108, s[10:11]
	v_pk_fma_f32 v[62:63], v[78:79], v[62:63], v[182:183]
	v_pk_fma_f32 v[58:59], v[72:73], v[58:59], v[180:181]
	v_pk_fma_f32 v[56:57], v[74:75], v[56:57], v[178:179]
	v_pk_add_f32 v[54:55], v[54:55], v[62:63]
	v_pk_add_f32 v[50:51], v[50:51], v[56:57]
	v_pk_add_f32 v[48:49], v[48:49], v[58:59]
	v_cvt_pk_bf16_f32 v52, v52, v53
	v_cvt_pk_bf16_f32 v53, v54, v55
	v_mov_b32_e32 v105, v165
	v_cvt_pk_bf16_f32 v54, v48, v49
	v_cvt_pk_bf16_f32 v55, v50, v51
	v_lshlrev_b32_e32 v48, 16, v52
	v_and_b32_e32 v50, 0xffff0000, v52
	v_lshlrev_b32_e32 v56, 16, v53
	v_and_b32_e32 v58, 0xffff0000, v53
	v_lshlrev_b32_e32 v60, 16, v54
	v_and_b32_e32 v62, 0xffff0000, v54
	v_lshlrev_b32_e32 v96, 16, v55
	v_and_b32_e32 v98, 0xffff0000, v55
	v_mul_f32_e32 v49, v48, v48
	v_mul_f32_e32 v51, v50, v50
	v_mul_f32_e32 v57, v56, v56
	v_mul_f32_e32 v59, v58, v58
	v_mul_f32_e32 v61, v60, v60
	v_mul_f32_e32 v63, v62, v62
	v_mul_f32_e32 v97, v96, v96
	v_mul_f32_e32 v99, v98, v98
	v_pk_add_f32 v[48:49], v[48:49], v[50:51]
	v_pk_add_f32 v[50:51], v[56:57], v[58:59]
	v_pk_add_f32 v[56:57], v[96:97], v[98:99]
	v_pk_add_f32 v[48:49], v[48:49], v[50:51]
	v_pk_add_f32 v[50:51], v[60:61], v[62:63]
	s_nop 0
	v_pk_add_f32 v[50:51], v[50:51], v[56:57]
	v_lshl_add_u64 v[56:57], s[20:21], 0, v[104:105]
	v_pk_add_f32 v[48:49], v[48:49], v[50:51]
	v_mov_b32_e32 v50, v165
	v_mov_b32_e32 v51, v165
	global_store_dwordx4 v[56:57], v[52:55], off offset:128
	v_mov_b32_dpp v50, v48 quad_perm:[1,0,3,2] row_mask:0xf bank_mask:0xf
	v_mov_b32_dpp v51, v49 quad_perm:[1,0,3,2] row_mask:0xf bank_mask:0xf
	v_pk_add_f32 v[48:49], v[48:49], v[50:51]
	ds_bpermute_b32 v50, v207, v48
	ds_bpermute_b32 v51, v207, v49
	s_waitcnt lgkmcnt(0)
	v_pk_add_f32 v[48:49], v[48:49], v[50:51]
	ds_bpermute_b32 v50, v208, v48
	ds_bpermute_b32 v51, v208, v49
	s_and_saveexec_b64 s[68:69], s[16:17]
	s_cbranch_execz .LBB0_836
	s_waitcnt lgkmcnt(0)
	v_pk_add_f32 v[48:49], v[48:49], v[50:51]
	v_add_co_u32_e32 v50, vcc, 0x10000, v186
	s_nop 1
	v_addc_co_u32_e32 v51, vcc, 0, v187, vcc
	v_mov_b32_e32 v252, v250
	v_mov_b32_e32 v253, v251
	v_mov_b32_e32 v254, v48
	v_mov_b32_e32 v255, v49
	global_store_dwordx4 v249, v[252:255], s[94:95] offset:1024
.LBB0_836:
	s_or_b64 exec, exec, s[68:69]
	s_waitcnt lgkmcnt(1)
	v_cndmask_b32_e64 v50, v44, v36, s[10:11]
	v_mov_b32_e32 v48, 0
	v_cndmask_b32_e64 v49, v45, v37, s[10:11]
	s_waitcnt lgkmcnt(0)
	v_cndmask_b32_e64 v51, v46, v38, s[10:11]
	v_mov_b32_dpp v48, v50 quad_perm:[1,0,3,2] row_mask:0xf bank_mask:0xf
	v_mov_b32_e32 v50, 0
	v_cndmask_b32_e64 v52, v47, v39, s[10:11]
	v_cndmask_b32_e64 v54, v40, v32, s[10:11]
	v_mov_b32_dpp v50, v49 quad_perm:[1,0,3,2] row_mask:0xf bank_mask:0xf
	v_mov_b32_e32 v49, 0
	v_cndmask_b32_e64 v53, v41, v33, s[10:11]
	v_cndmask_b32_e64 v55, v42, v34, s[10:11]
	v_mov_b32_dpp v49, v51 quad_perm:[1,0,3,2] row_mask:0xf bank_mask:0xf
	v_mov_b32_e32 v51, 0
	v_cndmask_b32_e64 v56, v43, v35, s[10:11]
	v_lshlrev_b32_e32 v59, 16, v92
	v_mov_b32_dpp v51, v52 quad_perm:[1,0,3,2] row_mask:0xf bank_mask:0xf
	v_mov_b32_e32 v52, 0
	v_and_b32_e32 v60, 0xffff0000, v92
	v_cndmask_b32_e64 v45, v50, v45, s[10:11]
	v_mov_b32_dpp v52, v54 quad_perm:[1,0,3,2] row_mask:0xf bank_mask:0xf
	v_mov_b32_e32 v54, 0
	v_cndmask_b32_e64 v44, v48, v44, s[10:11]
	v_lshlrev_b32_e32 v62, 16, v93
	v_mov_b32_dpp v54, v53 quad_perm:[1,0,3,2] row_mask:0xf bank_mask:0xf
	v_mov_b32_e32 v53, 0
	v_and_b32_e32 v63, 0xffff0000, v93
	v_lshlrev_b32_e32 v92, 16, v94
	v_mov_b32_dpp v53, v55 quad_perm:[1,0,3,2] row_mask:0xf bank_mask:0xf
	v_mov_b32_e32 v55, 0
	v_and_b32_e32 v93, 0xffff0000, v94
	v_lshlrev_b32_e32 v94, 16, v95
	v_mov_b32_dpp v55, v56 quad_perm:[1,0,3,2] row_mask:0xf bank_mask:0xf
	ds_read_b64 v[56:57], v201 offset:1152
	v_and_b32_e32 v95, 0xffff0000, v95
	v_cndmask_b32_e64 v47, v51, v47, s[10:11]
	v_cndmask_b32_e64 v46, v49, v46, s[10:11]
	v_cndmask_b32_e64 v41, v54, v41, s[10:11]
	s_waitcnt lgkmcnt(0)
;     __device__ __forceinline__ void operator()(const f32x4 (&acc)[2][2][4][2], const Unit& u, int wr, int wc, int fr, int fq, const EpiCtx& X) const {
;     ...
;             for (int m = 0; m < 4; ++m) { const unsigned off = lo + (unsigned)((ai * HALF + m * 16) * 64) * 2u; raw[2 * m] = *(const u32x4*)(xb + off); raw[2 * m + 1] = *(const u32x4*)(xb + off + 128); }
; #pragma unroll
;             for (int m = 0; m < 4; ++m) {
;                 const int rl = ai * HALF + m * 16; const unsigned off = lo + (unsigned)(rl * 64) * 2u;
;                 const f32x4 o0a = acc[ai][0][m][0], o0b = acc[ai][0][m][1], o1a = acc[ai][1][m][0], o1b = acc[ai][1][m][1];
;                 const f32x4 ra_ = dpp_swap1(odd ? o0a : o1a), rb_ = dpp_swap1(odd ? o0b : o1b);
;                 const f32x4 pa[2] = {odd ? ra_ : o0a, odd ? o1a : ra_}, pb[2] = {odd ? rb_ : o0b, odd ? o1b : rb_};
; #pragma unroll
;                 for (int q = 0; q < 2; ++q) {
;                     const u32x4 w0 = raw[2 * m + q];
;                     const f32x4 r0 = (f32x4){bf_lo(w0.x), bf_hi(w0.x), bf_lo(w0.y), bf_hi(w0.y)}, r1 = (f32x4){bf_lo(w0.z), bf_hi(w0.z), bf_lo(w0.w), bf_hi(w0.w)};
;                     f32x4 y0, y1;
;                     if (RESN) { const f32x2 t = tbl[rl + q]; const float mu = t.x, ra = t.y * ALPHA; y0 = (r0 - mu) * ra * g0 + b0 + pa[q]; y1 = (r1 - mu) * ra * g1 + b1 + pb[q]; }
;                     else { y0 = r0 * ALPHA + pa[q]; y1 = r1 * ALPHA + pb[q]; }
;                     { const u32x4 w = pack8f(y0, y1); *(u32x4*)(xb + off + q * 128) = w;
;                         y0 = (f32x4){bf_lo(w.x), bf_hi(w.x), bf_lo(w.y), bf_hi(w.y)}; y1 = (f32x4){bf_lo(w.z), bf_hi(w.z), bf_lo(w.w), bf_hi(w.w)}; }
;                     float sa = ((y0[0] + y0[1]) + (y0[2] + y0[3])) + ((y1[0] + y1[1]) + (y1[2] + y1[3]));
;                     float sb = ((y0[0] * y0[0] + y0[1] * y0[1]) + (y0[2] * y0[2] + y0[3] * y0[3])) + ((y1[0] * y1[0] + y1[1] * y1[1]) + (y1[2] * y1[2] + y1[3] * y1[3]));
;                     sa += dpp_x1(sa);
;                     sb += dpp_x1(sb);
;                     sa += __shfl_xor(sa, 16); sa += __shfl_xor(sa, 32); sb += __shfl_xor(sb, 16); sb += __shfl_xor(sb, 32);
;                     if (fq == 0 && !odd) ps[(size_t)(rl + q) * 64] = (f32x2){sa, sb};
	v_mul_f32_e32 v58, 0x3fb504f3, v57
	v_sub_f32_e32 v61, v60, v56
	v_sub_f32_e32 v60, v59, v56
	v_pk_mul_f32 v[60:61], v[60:61], v[58:59] op_sel_hi:[1,0]
	v_sub_f32_e32 v63, v63, v56
	v_pk_fma_f32 v[60:61], v[76:77], v[60:61], v[184:185]
	v_sub_f32_e32 v62, v62, v56
	v_pk_add_f32 v[44:45], v[44:45], v[60:61]
	v_sub_f32_e32 v61, v93, v56
	v_sub_f32_e32 v60, v92, v56
	v_sub_f32_e32 v57, v95, v56
	v_sub_f32_e32 v56, v94, v56
	v_pk_mul_f32 v[62:63], v[62:63], v[58:59] op_sel_hi:[1,0]
	v_pk_mul_f32 v[56:57], v[56:57], v[58:59] op_sel_hi:[1,0]
	v_pk_mul_f32 v[58:59], v[60:61], v[58:59] op_sel_hi:[1,0]
	v_cndmask_b32_e64 v40, v52, v40, s[10:11]
	v_cndmask_b32_e64 v43, v55, v43, s[10:11]
	v_cndmask_b32_e64 v42, v53, v42, s[10:11]
	v_pk_fma_f32 v[62:63], v[78:79], v[62:63], v[182:183]
	v_pk_fma_f32 v[58:59], v[72:73], v[58:59], v[180:181]
	v_pk_fma_f32 v[56:57], v[74:75], v[56:57], v[178:179]
	v_pk_add_f32 v[46:47], v[46:47], v[62:63]
	v_pk_add_f32 v[42:43], v[42:43], v[56:57]
	v_pk_add_f32 v[40:41], v[40:41], v[58:59]
	v_cvt_pk_bf16_f32 v56, v44, v45
	v_cvt_pk_bf16_f32 v57, v46, v47
	v_mov_b32_e32 v103, v165
	v_cvt_pk_bf16_f32 v58, v40, v41
	v_cvt_pk_bf16_f32 v59, v42, v43
	v_lshlrev_b32_e32 v40, 16, v56
	v_and_b32_e32 v42, 0xffff0000, v56
	v_lshlrev_b32_e32 v44, 16, v57
	v_and_b32_e32 v46, 0xffff0000, v57
	v_lshlrev_b32_e32 v60, 16, v58
	v_and_b32_e32 v62, 0xffff0000, v58
	v_lshlrev_b32_e32 v92, 16, v59
	v_and_b32_e32 v94, 0xffff0000, v59
	v_mul_f32_e32 v41, v40, v40
	v_mul_f32_e32 v43, v42, v42
	v_mul_f32_e32 v45, v44, v44
	v_mul_f32_e32 v47, v46, v46
	v_mul_f32_e32 v61, v60, v60
	v_mul_f32_e32 v63, v62, v62
	v_mul_f32_e32 v93, v92, v92
	v_mul_f32_e32 v95, v94, v94
	v_pk_add_f32 v[40:41], v[40:41], v[42:43]
	v_pk_add_f32 v[42:43], v[44:45], v[46:47]
	v_pk_add_f32 v[44:45], v[92:93], v[94:95]
	v_pk_add_f32 v[40:41], v[40:41], v[42:43]
	v_pk_add_f32 v[42:43], v[60:61], v[62:63]
	s_nop 0
	v_pk_add_f32 v[42:43], v[42:43], v[44:45]
	s_nop 0
	v_pk_add_f32 v[40:41], v[40:41], v[42:43]
	v_mov_b32_e32 v42, v165
	v_mov_b32_e32 v43, v165
	s_nop 0
	v_mov_b32_dpp v42, v40 quad_perm:[1,0,3,2] row_mask:0xf bank_mask:0xf
	v_mov_b32_dpp v43, v41 quad_perm:[1,0,3,2] row_mask:0xf bank_mask:0xf
	v_pk_add_f32 v[40:41], v[40:41], v[42:43]
	ds_bpermute_b32 v42, v207, v40
	ds_bpermute_b32 v43, v207, v41
	s_waitcnt lgkmcnt(0)
	v_pk_add_f32 v[42:43], v[40:41], v[42:43]
	ds_bpermute_b32 v44, v208, v42
	ds_bpermute_b32 v45, v208, v43
	v_lshl_add_u64 v[40:41], s[20:21], 0, v[102:103]
	global_store_dwordx4 v[40:41], v[56:59], off
	s_and_saveexec_b64 s[68:69], s[16:17]
	s_cbranch_execz .LBB0_838
	s_waitcnt lgkmcnt(0)
	v_pk_add_f32 v[42:43], v[42:43], v[44:45]
	v_add_co_u32_e32 v44, vcc, 0x12000, v186
	s_nop 1
	v_addc_co_u32_e32 v45, vcc, 0, v187, vcc
	v_mov_b32_e32 v250, v42
	v_mov_b32_e32 v251, v43
.LBB0_838:
	s_or_b64 exec, exec, s[68:69]
	ds_read_b64 v[42:43], v201 offset:1160
	s_waitcnt lgkmcnt(1)
	v_lshlrev_b32_e32 v45, 16, v88
	v_and_b32_e32 v46, 0xffff0000, v88
	v_cndmask_b32_e64 v37, v37, v50, s[10:11]
	v_cndmask_b32_e64 v36, v36, v48, s[10:11]
	s_waitcnt lgkmcnt(0)
	v_mul_f32_e32 v44, 0x3fb504f3, v43
	v_sub_f32_e32 v47, v46, v42
	v_sub_f32_e32 v46, v45, v42
	v_pk_mul_f32 v[46:47], v[46:47], v[44:45] op_sel_hi:[1,0]
	v_cndmask_b32_e64 v39, v39, v51, s[10:11]
	v_cndmask_b32_e64 v38, v38, v49, s[10:11]
	v_cndmask_b32_e64 v32, v32, v52, s[10:11]
	v_cndmask_b32_e64 v34, v34, v53, s[10:11]
	v_lshlrev_b32_e32 v48, 16, v89
	v_and_b32_e32 v49, 0xffff0000, v89
	v_lshlrev_b32_e32 v50, 16, v90
	v_and_b32_e32 v51, 0xffff0000, v90
	v_lshlrev_b32_e32 v52, 16, v91
	v_and_b32_e32 v53, 0xffff0000, v91
	v_pk_fma_f32 v[46:47], v[76:77], v[46:47], v[184:185]
	v_sub_f32_e32 v49, v49, v42
	v_sub_f32_e32 v48, v48, v42
	v_pk_add_f32 v[36:37], v[36:37], v[46:47]
	v_sub_f32_e32 v47, v51, v42
	v_sub_f32_e32 v46, v50, v42
	v_sub_f32_e32 v43, v53, v42
	v_sub_f32_e32 v42, v52, v42
	v_pk_mul_f32 v[48:49], v[48:49], v[44:45] op_sel_hi:[1,0]
	v_pk_mul_f32 v[42:43], v[42:43], v[44:45] op_sel_hi:[1,0]
	v_pk_mul_f32 v[44:45], v[46:47], v[44:45] op_sel_hi:[1,0]
	v_cndmask_b32_e64 v33, v33, v54, s[10:11]
	v_cndmask_b32_e64 v35, v35, v55, s[10:11]
	v_pk_fma_f32 v[48:49], v[78:79], v[48:49], v[182:183]
	v_pk_fma_f32 v[44:45], v[72:73], v[44:45], v[180:181]
	v_pk_fma_f32 v[42:43], v[74:75], v[42:43], v[178:179]
	v_pk_add_f32 v[38:39], v[38:39], v[48:49]
	v_pk_add_f32 v[34:35], v[34:35], v[42:43]
	v_pk_add_f32 v[32:33], v[32:33], v[44:45]
	v_cvt_pk_bf16_f32 v36, v36, v37
	v_cvt_pk_bf16_f32 v37, v38, v39
	s_nop 0
	v_cvt_pk_bf16_f32 v38, v32, v33
	v_cvt_pk_bf16_f32 v39, v34, v35
	v_lshlrev_b32_e32 v32, 16, v36
	v_and_b32_e32 v34, 0xffff0000, v36
	v_lshlrev_b32_e32 v42, 16, v37
	v_and_b32_e32 v44, 0xffff0000, v37
	v_lshlrev_b32_e32 v46, 16, v38
	v_and_b32_e32 v48, 0xffff0000, v38
	v_lshlrev_b32_e32 v50, 16, v39
	v_and_b32_e32 v52, 0xffff0000, v39
	v_mul_f32_e32 v33, v32, v32
	v_mul_f32_e32 v35, v34, v34
	v_mul_f32_e32 v43, v42, v42
	v_mul_f32_e32 v45, v44, v44
	v_mul_f32_e32 v47, v46, v46
	v_mul_f32_e32 v49, v48, v48
	v_mul_f32_e32 v51, v50, v50
	v_mul_f32_e32 v53, v52, v52
	v_pk_add_f32 v[32:33], v[32:33], v[34:35]
	v_pk_add_f32 v[34:35], v[42:43], v[44:45]
	v_pk_add_f32 v[42:43], v[50:51], v[52:53]
	v_pk_add_f32 v[32:33], v[32:33], v[34:35]
	v_pk_add_f32 v[34:35], v[46:47], v[48:49]
	global_store_dwordx4 v[40:41], v[36:39], off offset:128
	v_pk_add_f32 v[34:35], v[34:35], v[42:43]
	s_nop 0
	v_pk_add_f32 v[32:33], v[32:33], v[34:35]
	v_mov_b32_e32 v34, v165
	v_mov_b32_e32 v35, v165
	s_nop 0
	v_mov_b32_dpp v34, v32 quad_perm:[1,0,3,2] row_mask:0xf bank_mask:0xf
	v_mov_b32_dpp v35, v33 quad_perm:[1,0,3,2] row_mask:0xf bank_mask:0xf
	v_pk_add_f32 v[32:33], v[32:33], v[34:35]
	ds_bpermute_b32 v34, v207, v32
	ds_bpermute_b32 v35, v207, v33
	s_waitcnt lgkmcnt(0)
	v_pk_add_f32 v[32:33], v[32:33], v[34:35]
	ds_bpermute_b32 v34, v208, v32
	ds_bpermute_b32 v35, v208, v33
	s_and_saveexec_b64 s[68:69], s[16:17]
	s_cbranch_execz .LBB0_840
	s_waitcnt lgkmcnt(0)
	v_pk_add_f32 v[32:33], v[32:33], v[34:35]
	v_add_co_u32_e32 v34, vcc, 0x12000, v186
	s_nop 1
	v_addc_co_u32_e32 v35, vcc, 0, v187, vcc
	v_mov_b32_e32 v252, v250
	v_mov_b32_e32 v253, v251
	v_mov_b32_e32 v254, v32
	v_mov_b32_e32 v255, v33
	global_store_dwordx4 v249, v[252:255], s[94:95] offset:1152
;     __device__ __forceinline__ void operator()(const f32x4 (&acc)[2][2][4][2], const Unit& u, int wr, int wc, int fr, int fq, const EpiCtx& X) const {
;     ...
;             for (int m = 0; m < 4; ++m) { const unsigned off = lo + (unsigned)((ai * HALF + m * 16) * 64) * 2u; raw[2 * m] = *(const u32x4*)(xb + off); raw[2 * m + 1] = *(const u32x4*)(xb + off + 128); }
; #pragma unroll
;             for (int m = 0; m < 4; ++m) {
;                 const int rl = ai * HALF + m * 16; const unsigned off = lo + (unsigned)(rl * 64) * 2u;
;                 const f32x4 o0a = acc[ai][0][m][0], o0b = acc[ai][0][m][1], o1a = acc[ai][1][m][0], o1b = acc[ai][1][m][1];
;                 const f32x4 ra_ = dpp_swap1(odd ? o0a : o1a), rb_ = dpp_swap1(odd ? o0b : o1b);
;                 const f32x4 pa[2] = {odd ? ra_ : o0a, odd ? o1a : ra_}, pb[2] = {odd ? rb_ : o0b, odd ? o1b : rb_};
; #pragma unroll
;                 for (int q = 0; q < 2; ++q) {
;                     const u32x4 w0 = raw[2 * m + q];
;                     const f32x4 r0 = (f32x4){bf_lo(w0.x), bf_hi(w0.x), bf_lo(w0.y), bf_hi(w0.y)}, r1 = (f32x4){bf_lo(w0.z), bf_hi(w0.z), bf_lo(w0.w), bf_hi(w0.w)};
;                     f32x4 y0, y1;
;                     if (RESN) { const f32x2 t = tbl[rl + q]; const float mu = t.x, ra = t.y * ALPHA; y0 = (r0 - mu) * ra * g0 + b0 + pa[q]; y1 = (r1 - mu) * ra * g1 + b1 + pb[q]; }
;                     else { y0 = r0 * ALPHA + pa[q]; y1 = r1 * ALPHA + pb[q]; }
;                     { const u32x4 w = pack8f(y0, y1); *(u32x4*)(xb + off + q * 128) = w;
;                         y0 = (f32x4){bf_lo(w.x), bf_hi(w.x), bf_lo(w.y), bf_hi(w.y)}; y1 = (f32x4){bf_lo(w.z), bf_hi(w.z), bf_lo(w.w), bf_hi(w.w)}; }
;                     float sa = ((y0[0] + y0[1]) + (y0[2] + y0[3])) + ((y1[0] + y1[1]) + (y1[2] + y1[3]));
;                     float sb = ((y0[0] * y0[0] + y0[1] * y0[1]) + (y0[2] * y0[2] + y0[3] * y0[3])) + ((y1[0] * y1[0] + y1[1] * y1[1]) + (y1[2] * y1[2] + y1[3] * y1[3]));
;                     sa += dpp_x1(sa);
;                     sb += dpp_x1(sb);
;                     sa += __shfl_xor(sa, 16); sa += __shfl_xor(sa, 32); sb += __shfl_xor(sb, 16); sb += __shfl_xor(sb, 32);
;                     if (fq == 0 && !odd) ps[(size_t)(rl + q) * 64] = (f32x2){sa, sb};
.LBB0_840:
	s_or_b64 exec, exec, s[68:69]
	s_waitcnt lgkmcnt(1)
	v_cndmask_b32_e64 v34, v28, v20, s[10:11]
	v_mov_b32_e32 v32, 0
	v_cndmask_b32_e64 v33, v29, v21, s[10:11]
	s_waitcnt lgkmcnt(0)
	v_cndmask_b32_e64 v35, v30, v22, s[10:11]
	v_mov_b32_dpp v32, v34 quad_perm:[1,0,3,2] row_mask:0xf bank_mask:0xf
	v_mov_b32_e32 v34, 0
	v_cndmask_b32_e64 v36, v31, v23, s[10:11]
	v_cndmask_b32_e64 v38, v24, v16, s[10:11]
	v_mov_b32_dpp v34, v33 quad_perm:[1,0,3,2] row_mask:0xf bank_mask:0xf
	v_mov_b32_e32 v33, 0
	v_cndmask_b32_e64 v37, v25, v17, s[10:11]
	v_cndmask_b32_e64 v39, v26, v18, s[10:11]
	v_mov_b32_dpp v33, v35 quad_perm:[1,0,3,2] row_mask:0xf bank_mask:0xf
	v_mov_b32_e32 v35, 0
	v_cndmask_b32_e64 v40, v27, v19, s[10:11]
	s_waitcnt vmcnt(9)
	v_lshlrev_b32_e32 v43, 16, v84
	v_mov_b32_dpp v35, v36 quad_perm:[1,0,3,2] row_mask:0xf bank_mask:0xf
	v_mov_b32_e32 v36, 0
	v_and_b32_e32 v44, 0xffff0000, v84
	v_cndmask_b32_e64 v29, v34, v29, s[10:11]
	v_mov_b32_dpp v36, v38 quad_perm:[1,0,3,2] row_mask:0xf bank_mask:0xf
	v_mov_b32_e32 v38, 0
	v_cndmask_b32_e64 v28, v32, v28, s[10:11]
	v_lshlrev_b32_e32 v46, 16, v85
	v_mov_b32_dpp v38, v37 quad_perm:[1,0,3,2] row_mask:0xf bank_mask:0xf
	v_mov_b32_e32 v37, 0
	v_and_b32_e32 v47, 0xffff0000, v85
	v_lshlrev_b32_e32 v48, 16, v86
	v_mov_b32_dpp v37, v39 quad_perm:[1,0,3,2] row_mask:0xf bank_mask:0xf
	v_mov_b32_e32 v39, 0
	v_and_b32_e32 v49, 0xffff0000, v86
	v_lshlrev_b32_e32 v50, 16, v87
	v_mov_b32_dpp v39, v40 quad_perm:[1,0,3,2] row_mask:0xf bank_mask:0xf
	ds_read_b64 v[40:41], v201 offset:1280
	v_and_b32_e32 v51, 0xffff0000, v87
	v_cndmask_b32_e64 v31, v35, v31, s[10:11]
	v_cndmask_b32_e64 v30, v33, v30, s[10:11]
	v_cndmask_b32_e64 v25, v38, v25, s[10:11]
	s_waitcnt lgkmcnt(0)
	v_mul_f32_e32 v42, 0x3fb504f3, v41
	v_sub_f32_e32 v45, v44, v40
	v_sub_f32_e32 v44, v43, v40
	v_pk_mul_f32 v[44:45], v[44:45], v[42:43] op_sel_hi:[1,0]
	v_sub_f32_e32 v47, v47, v40
	v_pk_fma_f32 v[44:45], v[76:77], v[44:45], v[184:185]
	v_sub_f32_e32 v46, v46, v40
	v_pk_add_f32 v[28:29], v[28:29], v[44:45]
	v_sub_f32_e32 v45, v49, v40
	v_sub_f32_e32 v44, v48, v40
	v_sub_f32_e32 v41, v51, v40
	v_sub_f32_e32 v40, v50, v40
	v_pk_mul_f32 v[46:47], v[46:47], v[42:43] op_sel_hi:[1,0]
	v_pk_mul_f32 v[40:41], v[40:41], v[42:43] op_sel_hi:[1,0]
	v_pk_mul_f32 v[42:43], v[44:45], v[42:43] op_sel_hi:[1,0]
	v_cndmask_b32_e64 v24, v36, v24, s[10:11]
	v_cndmask_b32_e64 v27, v39, v27, s[10:11]
	v_cndmask_b32_e64 v26, v37, v26, s[10:11]
	v_pk_fma_f32 v[46:47], v[78:79], v[46:47], v[182:183]
	v_pk_fma_f32 v[42:43], v[72:73], v[42:43], v[180:181]
	v_pk_fma_f32 v[40:41], v[74:75], v[40:41], v[178:179]
	v_pk_add_f32 v[30:31], v[30:31], v[46:47]
	v_pk_add_f32 v[26:27], v[26:27], v[40:41]
	v_pk_add_f32 v[24:25], v[24:25], v[42:43]
	v_cvt_pk_bf16_f32 v40, v28, v29
	v_cvt_pk_bf16_f32 v41, v30, v31
	v_mov_b32_e32 v101, v165
	v_cvt_pk_bf16_f32 v42, v24, v25
	v_cvt_pk_bf16_f32 v43, v26, v27
	v_lshlrev_b32_e32 v24, 16, v40
	v_and_b32_e32 v26, 0xffff0000, v40
	v_lshlrev_b32_e32 v28, 16, v41
	v_and_b32_e32 v30, 0xffff0000, v41
	v_lshlrev_b32_e32 v44, 16, v42
	v_and_b32_e32 v46, 0xffff0000, v42
	v_lshlrev_b32_e32 v48, 16, v43
	v_and_b32_e32 v50, 0xffff0000, v43
	v_mul_f32_e32 v25, v24, v24
	v_mul_f32_e32 v27, v26, v26
	v_mul_f32_e32 v29, v28, v28
	v_mul_f32_e32 v31, v30, v30
	v_mul_f32_e32 v45, v44, v44
	v_mul_f32_e32 v47, v46, v46
	v_mul_f32_e32 v49, v48, v48
	v_mul_f32_e32 v51, v50, v50
	v_pk_add_f32 v[24:25], v[24:25], v[26:27]
	v_pk_add_f32 v[26:27], v[28:29], v[30:31]
	v_pk_add_f32 v[28:29], v[48:49], v[50:51]
	v_pk_add_f32 v[24:25], v[24:25], v[26:27]
	v_pk_add_f32 v[26:27], v[44:45], v[46:47]
	s_nop 0
	v_pk_add_f32 v[26:27], v[26:27], v[28:29]
	s_nop 0
	v_pk_add_f32 v[24:25], v[24:25], v[26:27]
	v_mov_b32_e32 v26, v165
	v_mov_b32_e32 v27, v165
	s_nop 0
	v_mov_b32_dpp v26, v24 quad_perm:[1,0,3,2] row_mask:0xf bank_mask:0xf
	v_mov_b32_dpp v27, v25 quad_perm:[1,0,3,2] row_mask:0xf bank_mask:0xf
	v_pk_add_f32 v[24:25], v[24:25], v[26:27]
	ds_bpermute_b32 v26, v207, v24
	ds_bpermute_b32 v27, v207, v25
	s_waitcnt lgkmcnt(0)
	v_pk_add_f32 v[26:27], v[24:25], v[26:27]
	ds_bpermute_b32 v28, v208, v26
	ds_bpermute_b32 v29, v208, v27
	v_lshl_add_u64 v[24:25], s[20:21], 0, v[100:101]
	global_store_dwordx4 v[24:25], v[40:43], off
	s_and_saveexec_b64 s[68:69], s[16:17]
	s_cbranch_execz .LBB0_842
	s_waitcnt lgkmcnt(0)
	v_pk_add_f32 v[26:27], v[26:27], v[28:29]
	v_add_co_u32_e32 v28, vcc, 0x14000, v186
	s_nop 1
	v_addc_co_u32_e32 v29, vcc, 0, v187, vcc
	v_mov_b32_e32 v250, v26
	v_mov_b32_e32 v251, v27
;     __device__ __forceinline__ void operator()(const f32x4 (&acc)[2][2][4][2], const Unit& u, int wr, int wc, int fr, int fq, const EpiCtx& X) const {
;     ...
;             for (int m = 0; m < 4; ++m) { const unsigned off = lo + (unsigned)((ai * HALF + m * 16) * 64) * 2u; raw[2 * m] = *(const u32x4*)(xb + off); raw[2 * m + 1] = *(const u32x4*)(xb + off + 128); }
; #pragma unroll
;             for (int m = 0; m < 4; ++m) {
;                 const int rl = ai * HALF + m * 16; const unsigned off = lo + (unsigned)(rl * 64) * 2u;
;                 const f32x4 o0a = acc[ai][0][m][0], o0b = acc[ai][0][m][1], o1a = acc[ai][1][m][0], o1b = acc[ai][1][m][1];
;                 const f32x4 ra_ = dpp_swap1(odd ? o0a : o1a), rb_ = dpp_swap1(odd ? o0b : o1b);
;                 const f32x4 pa[2] = {odd ? ra_ : o0a, odd ? o1a : ra_}, pb[2] = {odd ? rb_ : o0b, odd ? o1b : rb_};
; #pragma unroll
;                 for (int q = 0; q < 2; ++q) {
;                     const u32x4 w0 = raw[2 * m + q];
;                     const f32x4 r0 = (f32x4){bf_lo(w0.x), bf_hi(w0.x), bf_lo(w0.y), bf_hi(w0.y)}, r1 = (f32x4){bf_lo(w0.z), bf_hi(w0.z), bf_lo(w0.w), bf_hi(w0.w)};
;                     f32x4 y0, y1;
;                     if (RESN) { const f32x2 t = tbl[rl + q]; const float mu = t.x, ra = t.y * ALPHA; y0 = (r0 - mu) * ra * g0 + b0 + pa[q]; y1 = (r1 - mu) * ra * g1 + b1 + pb[q]; }
;                     else { y0 = r0 * ALPHA + pa[q]; y1 = r1 * ALPHA + pb[q]; }
;                     { const u32x4 w = pack8f(y0, y1); *(u32x4*)(xb + off + q * 128) = w;
;                         y0 = (f32x4){bf_lo(w.x), bf_hi(w.x), bf_lo(w.y), bf_hi(w.y)}; y1 = (f32x4){bf_lo(w.z), bf_hi(w.z), bf_lo(w.w), bf_hi(w.w)}; }
;                     float sa = ((y0[0] + y0[1]) + (y0[2] + y0[3])) + ((y1[0] + y1[1]) + (y1[2] + y1[3]));
;                     float sb = ((y0[0] * y0[0] + y0[1] * y0[1]) + (y0[2] * y0[2] + y0[3] * y0[3])) + ((y1[0] * y1[0] + y1[1] * y1[1]) + (y1[2] * y1[2] + y1[3] * y1[3]));
;                     sa += dpp_x1(sa);
;                     sb += dpp_x1(sb);
;                     sa += __shfl_xor(sa, 16); sa += __shfl_xor(sa, 32); sb += __shfl_xor(sb, 16); sb += __shfl_xor(sb, 32);
;                     if (fq == 0 && !odd) ps[(size_t)(rl + q) * 64] = (f32x2){sa, sb};
.LBB0_842:
	s_or_b64 exec, exec, s[68:69]
	ds_read_b64 v[26:27], v201 offset:1288
	s_waitcnt vmcnt(9) lgkmcnt(1)
	v_lshlrev_b32_e32 v29, 16, v80
	v_and_b32_e32 v30, 0xffff0000, v80
	v_cndmask_b32_e64 v21, v21, v34, s[10:11]
	v_cndmask_b32_e64 v20, v20, v32, s[10:11]
	s_waitcnt lgkmcnt(0)
	v_mul_f32_e32 v28, 0x3fb504f3, v27
	v_sub_f32_e32 v31, v30, v26
	v_sub_f32_e32 v30, v29, v26
	v_pk_mul_f32 v[30:31], v[30:31], v[28:29] op_sel_hi:[1,0]
	v_cndmask_b32_e64 v23, v23, v35, s[10:11]
	v_cndmask_b32_e64 v22, v22, v33, s[10:11]
	v_cndmask_b32_e64 v16, v16, v36, s[10:11]
	v_cndmask_b32_e64 v18, v18, v37, s[10:11]
	v_lshlrev_b32_e32 v32, 16, v81
	v_and_b32_e32 v33, 0xffff0000, v81
	v_lshlrev_b32_e32 v34, 16, v82
	v_and_b32_e32 v35, 0xffff0000, v82
	v_lshlrev_b32_e32 v36, 16, v83
	v_and_b32_e32 v37, 0xffff0000, v83
	v_pk_fma_f32 v[30:31], v[76:77], v[30:31], v[184:185]
	v_sub_f32_e32 v33, v33, v26
	v_sub_f32_e32 v32, v32, v26
	v_pk_add_f32 v[20:21], v[20:21], v[30:31]
	v_sub_f32_e32 v31, v35, v26
	v_sub_f32_e32 v30, v34, v26
	v_sub_f32_e32 v27, v37, v26
	v_sub_f32_e32 v26, v36, v26
	v_pk_mul_f32 v[32:33], v[32:33], v[28:29] op_sel_hi:[1,0]
	v_pk_mul_f32 v[26:27], v[26:27], v[28:29] op_sel_hi:[1,0]
	v_pk_mul_f32 v[28:29], v[30:31], v[28:29] op_sel_hi:[1,0]
	v_cndmask_b32_e64 v17, v17, v38, s[10:11]
	v_cndmask_b32_e64 v19, v19, v39, s[10:11]
	v_pk_fma_f32 v[32:33], v[78:79], v[32:33], v[182:183]
	v_pk_fma_f32 v[28:29], v[72:73], v[28:29], v[180:181]
	v_pk_fma_f32 v[26:27], v[74:75], v[26:27], v[178:179]
	v_pk_add_f32 v[22:23], v[22:23], v[32:33]
	v_pk_add_f32 v[18:19], v[18:19], v[26:27]
	v_pk_add_f32 v[16:17], v[16:17], v[28:29]
	v_cvt_pk_bf16_f32 v20, v20, v21
	v_cvt_pk_bf16_f32 v21, v22, v23
	s_nop 0
	v_cvt_pk_bf16_f32 v22, v16, v17
	v_cvt_pk_bf16_f32 v23, v18, v19
	v_lshlrev_b32_e32 v16, 16, v20
	v_and_b32_e32 v18, 0xffff0000, v20
	v_lshlrev_b32_e32 v26, 16, v21
	v_and_b32_e32 v28, 0xffff0000, v21
	v_lshlrev_b32_e32 v30, 16, v22
	v_and_b32_e32 v32, 0xffff0000, v22
	v_lshlrev_b32_e32 v34, 16, v23
	v_and_b32_e32 v36, 0xffff0000, v23
	v_mul_f32_e32 v17, v16, v16
	v_mul_f32_e32 v19, v18, v18
	v_mul_f32_e32 v27, v26, v26
	v_mul_f32_e32 v29, v28, v28
	v_mul_f32_e32 v31, v30, v30
	v_mul_f32_e32 v33, v32, v32
	v_mul_f32_e32 v35, v34, v34
	v_mul_f32_e32 v37, v36, v36
	v_pk_add_f32 v[16:17], v[16:17], v[18:19]
	v_pk_add_f32 v[18:19], v[26:27], v[28:29]
	v_pk_add_f32 v[26:27], v[34:35], v[36:37]
	v_pk_add_f32 v[16:17], v[16:17], v[18:19]
	v_pk_add_f32 v[18:19], v[30:31], v[32:33]
	global_store_dwordx4 v[24:25], v[20:23], off offset:128
	v_pk_add_f32 v[18:19], v[18:19], v[26:27]
	s_nop 0
	v_pk_add_f32 v[16:17], v[16:17], v[18:19]
	v_mov_b32_e32 v18, v165
	v_mov_b32_e32 v19, v165
	s_nop 0
	v_mov_b32_dpp v18, v16 quad_perm:[1,0,3,2] row_mask:0xf bank_mask:0xf
	v_mov_b32_dpp v19, v17 quad_perm:[1,0,3,2] row_mask:0xf bank_mask:0xf
	v_pk_add_f32 v[16:17], v[16:17], v[18:19]
	ds_bpermute_b32 v18, v207, v16
	ds_bpermute_b32 v19, v207, v17
	s_waitcnt lgkmcnt(0)
	v_pk_add_f32 v[16:17], v[16:17], v[18:19]
	ds_bpermute_b32 v18, v208, v16
	ds_bpermute_b32 v19, v208, v17
	s_and_saveexec_b64 s[68:69], s[16:17]
	s_cbranch_execz .LBB0_844
	s_waitcnt lgkmcnt(0)
	v_pk_add_f32 v[16:17], v[16:17], v[18:19]
	v_add_co_u32_e32 v18, vcc, 0x14000, v186
	s_nop 1
	v_addc_co_u32_e32 v19, vcc, 0, v187, vcc
	v_mov_b32_e32 v252, v250
	v_mov_b32_e32 v253, v251
	v_mov_b32_e32 v254, v16
	v_mov_b32_e32 v255, v17
	global_store_dwordx4 v249, v[252:255], s[94:95] offset:1280
.LBB0_844:
	s_or_b64 exec, exec, s[68:69]
	s_waitcnt lgkmcnt(1)
	v_cndmask_b32_e64 v18, v12, v4, s[10:11]
	v_mov_b32_e32 v16, 0
	v_cndmask_b32_e64 v17, v13, v5, s[10:11]
	s_waitcnt lgkmcnt(0)
	v_cndmask_b32_e64 v19, v14, v6, s[10:11]
	v_mov_b32_dpp v16, v18 quad_perm:[1,0,3,2] row_mask:0xf bank_mask:0xf
	v_mov_b32_e32 v18, 0
	v_cndmask_b32_e64 v20, v15, v7, s[10:11]
	v_cndmask_b32_e64 v22, v8, v0, s[10:11]
	v_mov_b32_dpp v18, v17 quad_perm:[1,0,3,2] row_mask:0xf bank_mask:0xf
	v_mov_b32_e32 v17, 0
	v_cndmask_b32_e64 v21, v9, v1, s[10:11]
	v_cndmask_b32_e64 v23, v10, v2, s[10:11]
	v_mov_b32_dpp v17, v19 quad_perm:[1,0,3,2] row_mask:0xf bank_mask:0xf
	v_mov_b32_e32 v19, 0
	v_cndmask_b32_e64 v24, v11, v3, s[10:11]
	s_waitcnt vmcnt(10)
	v_lshlrev_b32_e32 v27, 16, v68
	v_mov_b32_dpp v19, v20 quad_perm:[1,0,3,2] row_mask:0xf bank_mask:0xf
	v_mov_b32_e32 v20, 0
	v_and_b32_e32 v28, 0xffff0000, v68
	v_cndmask_b32_e64 v13, v18, v13, s[10:11]
	v_mov_b32_dpp v20, v22 quad_perm:[1,0,3,2] row_mask:0xf bank_mask:0xf
	v_mov_b32_e32 v22, 0
	v_cndmask_b32_e64 v12, v16, v12, s[10:11]
	v_lshlrev_b32_e32 v30, 16, v69
	v_mov_b32_dpp v22, v21 quad_perm:[1,0,3,2] row_mask:0xf bank_mask:0xf
	v_mov_b32_e32 v21, 0
	v_and_b32_e32 v31, 0xffff0000, v69
	v_lshlrev_b32_e32 v32, 16, v70
	v_mov_b32_dpp v21, v23 quad_perm:[1,0,3,2] row_mask:0xf bank_mask:0xf
	v_mov_b32_e32 v23, 0
	v_and_b32_e32 v33, 0xffff0000, v70
	v_lshlrev_b32_e32 v34, 16, v71
	v_mov_b32_dpp v23, v24 quad_perm:[1,0,3,2] row_mask:0xf bank_mask:0xf
	ds_read_b64 v[24:25], v201 offset:1408
	v_and_b32_e32 v35, 0xffff0000, v71
	v_cndmask_b32_e64 v15, v19, v15, s[10:11]
	v_cndmask_b32_e64 v14, v17, v14, s[10:11]
	v_cndmask_b32_e64 v9, v22, v9, s[10:11]
	s_waitcnt lgkmcnt(0)
;     __device__ __forceinline__ void operator()(const f32x4 (&acc)[2][2][4][2], const Unit& u, int wr, int wc, int fr, int fq, const EpiCtx& X) const {
;     ...
;             for (int m = 0; m < 4; ++m) { const unsigned off = lo + (unsigned)((ai * HALF + m * 16) * 64) * 2u; raw[2 * m] = *(const u32x4*)(xb + off); raw[2 * m + 1] = *(const u32x4*)(xb + off + 128); }
; #pragma unroll
;             for (int m = 0; m < 4; ++m) {
;                 const int rl = ai * HALF + m * 16; const unsigned off = lo + (unsigned)(rl * 64) * 2u;
;                 const f32x4 o0a = acc[ai][0][m][0], o0b = acc[ai][0][m][1], o1a = acc[ai][1][m][0], o1b = acc[ai][1][m][1];
;                 const f32x4 ra_ = dpp_swap1(odd ? o0a : o1a), rb_ = dpp_swap1(odd ? o0b : o1b);
;                 const f32x4 pa[2] = {odd ? ra_ : o0a, odd ? o1a : ra_}, pb[2] = {odd ? rb_ : o0b, odd ? o1b : rb_};
; #pragma unroll
;                 for (int q = 0; q < 2; ++q) {
;                     const u32x4 w0 = raw[2 * m + q];
;                     const f32x4 r0 = (f32x4){bf_lo(w0.x), bf_hi(w0.x), bf_lo(w0.y), bf_hi(w0.y)}, r1 = (f32x4){bf_lo(w0.z), bf_hi(w0.z), bf_lo(w0.w), bf_hi(w0.w)};
;                     f32x4 y0, y1;
;                     if (RESN) { const f32x2 t = tbl[rl + q]; const float mu = t.x, ra = t.y * ALPHA; y0 = (r0 - mu) * ra * g0 + b0 + pa[q]; y1 = (r1 - mu) * ra * g1 + b1 + pb[q]; }
;                     else { y0 = r0 * ALPHA + pa[q]; y1 = r1 * ALPHA + pb[q]; }
;                     { const u32x4 w = pack8f(y0, y1); *(u32x4*)(xb + off + q * 128) = w;
;                         y0 = (f32x4){bf_lo(w.x), bf_hi(w.x), bf_lo(w.y), bf_hi(w.y)}; y1 = (f32x4){bf_lo(w.z), bf_hi(w.z), bf_lo(w.w), bf_hi(w.w)}; }
;                     float sa = ((y0[0] + y0[1]) + (y0[2] + y0[3])) + ((y1[0] + y1[1]) + (y1[2] + y1[3]));
;                     float sb = ((y0[0] * y0[0] + y0[1] * y0[1]) + (y0[2] * y0[2] + y0[3] * y0[3])) + ((y1[0] * y1[0] + y1[1] * y1[1]) + (y1[2] * y1[2] + y1[3] * y1[3]));
;                     sa += dpp_x1(sa);
;                     sb += dpp_x1(sb);
;                     sa += __shfl_xor(sa, 16); sa += __shfl_xor(sa, 32); sb += __shfl_xor(sb, 16); sb += __shfl_xor(sb, 32);
;                     if (fq == 0 && !odd) ps[(size_t)(rl + q) * 64] = (f32x2){sa, sb};
	v_mul_f32_e32 v26, 0x3fb504f3, v25
	v_sub_f32_e32 v29, v28, v24
	v_sub_f32_e32 v28, v27, v24
	v_pk_mul_f32 v[28:29], v[28:29], v[26:27] op_sel_hi:[1,0]
	v_sub_f32_e32 v31, v31, v24
	v_pk_fma_f32 v[28:29], v[76:77], v[28:29], v[184:185]
	v_sub_f32_e32 v30, v30, v24
	v_pk_add_f32 v[12:13], v[12:13], v[28:29]
	v_sub_f32_e32 v29, v33, v24
	v_sub_f32_e32 v28, v32, v24
	v_sub_f32_e32 v25, v35, v24
	v_sub_f32_e32 v24, v34, v24
	v_pk_mul_f32 v[30:31], v[30:31], v[26:27] op_sel_hi:[1,0]
	v_pk_mul_f32 v[24:25], v[24:25], v[26:27] op_sel_hi:[1,0]
	v_pk_mul_f32 v[26:27], v[28:29], v[26:27] op_sel_hi:[1,0]
	v_cndmask_b32_e64 v8, v20, v8, s[10:11]
	v_cndmask_b32_e64 v11, v23, v11, s[10:11]
	v_cndmask_b32_e64 v10, v21, v10, s[10:11]
	v_pk_fma_f32 v[30:31], v[78:79], v[30:31], v[182:183]
	v_pk_fma_f32 v[26:27], v[72:73], v[26:27], v[180:181]
	v_pk_fma_f32 v[24:25], v[74:75], v[24:25], v[178:179]
	v_pk_add_f32 v[14:15], v[14:15], v[30:31]
	v_pk_add_f32 v[10:11], v[10:11], v[24:25]
	v_pk_add_f32 v[8:9], v[8:9], v[26:27]
	v_cvt_pk_bf16_f32 v24, v12, v13
	v_cvt_pk_bf16_f32 v25, v14, v15
	s_nop 0
	v_cvt_pk_bf16_f32 v26, v8, v9
	v_cvt_pk_bf16_f32 v27, v10, v11
	v_lshlrev_b32_e32 v8, 16, v24
	v_and_b32_e32 v10, 0xffff0000, v24
	v_lshlrev_b32_e32 v12, 16, v25
	v_and_b32_e32 v14, 0xffff0000, v25
	v_lshlrev_b32_e32 v28, 16, v26
	v_and_b32_e32 v30, 0xffff0000, v26
	v_lshlrev_b32_e32 v32, 16, v27
	v_and_b32_e32 v34, 0xffff0000, v27
	v_mul_f32_e32 v9, v8, v8
	v_mul_f32_e32 v11, v10, v10
	v_mul_f32_e32 v13, v12, v12
	v_mul_f32_e32 v15, v14, v14
	v_mul_f32_e32 v29, v28, v28
	v_mul_f32_e32 v31, v30, v30
	v_mul_f32_e32 v33, v32, v32
	v_mul_f32_e32 v35, v34, v34
	v_pk_add_f32 v[8:9], v[8:9], v[10:11]
	v_pk_add_f32 v[10:11], v[12:13], v[14:15]
	v_pk_add_f32 v[12:13], v[32:33], v[34:35]
	v_pk_add_f32 v[8:9], v[8:9], v[10:11]
	v_pk_add_f32 v[10:11], v[28:29], v[30:31]
	s_nop 0
	v_pk_add_f32 v[10:11], v[10:11], v[12:13]
	s_nop 0
	v_pk_add_f32 v[8:9], v[8:9], v[10:11]
	v_mov_b32_e32 v10, v165
	v_mov_b32_e32 v11, v165
	s_nop 0
	v_mov_b32_dpp v10, v8 quad_perm:[1,0,3,2] row_mask:0xf bank_mask:0xf
	v_mov_b32_dpp v11, v9 quad_perm:[1,0,3,2] row_mask:0xf bank_mask:0xf
	v_pk_add_f32 v[8:9], v[8:9], v[10:11]
	ds_bpermute_b32 v10, v207, v8
	ds_bpermute_b32 v11, v207, v9
	s_waitcnt lgkmcnt(0)
	v_pk_add_f32 v[10:11], v[8:9], v[10:11]
	ds_bpermute_b32 v12, v208, v10
	ds_bpermute_b32 v13, v208, v11
	v_lshl_add_u64 v[8:9], s[20:21], 0, v[164:165]
	global_store_dwordx4 v[8:9], v[24:27], off
	s_and_saveexec_b64 s[20:21], s[16:17]
	s_cbranch_execz .LBB0_846
	s_waitcnt lgkmcnt(0)
	v_pk_add_f32 v[10:11], v[10:11], v[12:13]
	v_add_co_u32_e32 v12, vcc, 0x16000, v186
	s_nop 1
	v_addc_co_u32_e32 v13, vcc, 0, v187, vcc
	v_mov_b32_e32 v250, v10
	v_mov_b32_e32 v251, v11
.LBB0_846:
	s_or_b64 exec, exec, s[20:21]
	ds_read_b64 v[10:11], v201 offset:1416
	s_waitcnt vmcnt(10) lgkmcnt(1)
	v_lshlrev_b32_e32 v13, 16, v64
	v_and_b32_e32 v14, 0xffff0000, v64
	v_cndmask_b32_e64 v5, v5, v18, s[10:11]
	v_cndmask_b32_e64 v4, v4, v16, s[10:11]
	s_waitcnt lgkmcnt(0)
	v_mul_f32_e32 v12, 0x3fb504f3, v11
	v_sub_f32_e32 v15, v14, v10
	v_sub_f32_e32 v14, v13, v10
	v_pk_mul_f32 v[14:15], v[14:15], v[12:13] op_sel_hi:[1,0]
	v_cndmask_b32_e64 v7, v7, v19, s[10:11]
	v_cndmask_b32_e64 v6, v6, v17, s[10:11]
	v_cndmask_b32_e64 v0, v0, v20, s[10:11]
	v_cndmask_b32_e64 v2, v2, v21, s[10:11]
	v_lshlrev_b32_e32 v16, 16, v65
	v_and_b32_e32 v17, 0xffff0000, v65
	v_lshlrev_b32_e32 v18, 16, v66
	v_and_b32_e32 v19, 0xffff0000, v66
	v_lshlrev_b32_e32 v20, 16, v67
	v_and_b32_e32 v21, 0xffff0000, v67
	v_pk_fma_f32 v[14:15], v[76:77], v[14:15], v[184:185]
	v_sub_f32_e32 v17, v17, v10
	v_sub_f32_e32 v16, v16, v10
	v_pk_add_f32 v[4:5], v[4:5], v[14:15]
	v_sub_f32_e32 v15, v19, v10
	v_sub_f32_e32 v14, v18, v10
	v_sub_f32_e32 v11, v21, v10
	v_sub_f32_e32 v10, v20, v10
	v_pk_mul_f32 v[16:17], v[16:17], v[12:13] op_sel_hi:[1,0]
	v_pk_mul_f32 v[10:11], v[10:11], v[12:13] op_sel_hi:[1,0]
	v_pk_mul_f32 v[12:13], v[14:15], v[12:13] op_sel_hi:[1,0]
	v_cndmask_b32_e64 v1, v1, v22, s[10:11]
	v_cndmask_b32_e64 v3, v3, v23, s[10:11]
	v_pk_fma_f32 v[16:17], v[78:79], v[16:17], v[182:183]
	v_pk_fma_f32 v[12:13], v[72:73], v[12:13], v[180:181]
	v_pk_fma_f32 v[10:11], v[74:75], v[10:11], v[178:179]
	v_pk_add_f32 v[6:7], v[6:7], v[16:17]
	v_pk_add_f32 v[2:3], v[2:3], v[10:11]
	v_pk_add_f32 v[0:1], v[0:1], v[12:13]
	v_cvt_pk_bf16_f32 v4, v4, v5
	v_cvt_pk_bf16_f32 v5, v6, v7
	s_nop 0
	v_cvt_pk_bf16_f32 v6, v0, v1
	v_cvt_pk_bf16_f32 v7, v2, v3
	v_lshlrev_b32_e32 v0, 16, v4
	v_and_b32_e32 v2, 0xffff0000, v4
	v_lshlrev_b32_e32 v10, 16, v5
	v_and_b32_e32 v12, 0xffff0000, v5
	v_lshlrev_b32_e32 v14, 16, v6
	v_and_b32_e32 v16, 0xffff0000, v6
	v_lshlrev_b32_e32 v18, 16, v7
	v_and_b32_e32 v20, 0xffff0000, v7
	v_mul_f32_e32 v1, v0, v0
	v_mul_f32_e32 v3, v2, v2
	v_mul_f32_e32 v11, v10, v10
	v_mul_f32_e32 v13, v12, v12
	v_mul_f32_e32 v15, v14, v14
	v_mul_f32_e32 v17, v16, v16
	v_mul_f32_e32 v19, v18, v18
	v_mul_f32_e32 v21, v20, v20
	v_pk_add_f32 v[0:1], v[0:1], v[2:3]
	v_pk_add_f32 v[2:3], v[10:11], v[12:13]
	v_pk_add_f32 v[10:11], v[18:19], v[20:21]
	v_pk_add_f32 v[0:1], v[0:1], v[2:3]
	v_pk_add_f32 v[2:3], v[14:15], v[16:17]
	global_store_dwordx4 v[8:9], v[4:7], off offset:128
	v_pk_add_f32 v[2:3], v[2:3], v[10:11]
	s_nop 0
	v_pk_add_f32 v[0:1], v[0:1], v[2:3]
	v_mov_b32_e32 v2, v165
	v_mov_b32_e32 v3, v165
	s_nop 0
	v_mov_b32_dpp v2, v0 quad_perm:[1,0,3,2] row_mask:0xf bank_mask:0xf
	v_mov_b32_dpp v3, v1 quad_perm:[1,0,3,2] row_mask:0xf bank_mask:0xf
	v_pk_add_f32 v[0:1], v[0:1], v[2:3]
	ds_bpermute_b32 v2, v207, v0
	ds_bpermute_b32 v3, v207, v1
	s_waitcnt lgkmcnt(0)
	v_pk_add_f32 v[0:1], v[0:1], v[2:3]
	ds_bpermute_b32 v2, v208, v0
	ds_bpermute_b32 v3, v208, v1
	s_and_saveexec_b64 s[20:21], s[16:17]
	s_cbranch_execz .LBB0_848
	s_waitcnt lgkmcnt(0)
	v_pk_add_f32 v[0:1], v[0:1], v[2:3]
	v_add_co_u32_e32 v2, vcc, 0x16000, v186
	s_nop 1
	v_addc_co_u32_e32 v3, vcc, 0, v187, vcc
	v_mov_b32_e32 v252, v250
	v_mov_b32_e32 v253, v251
	v_mov_b32_e32 v254, v0
	v_mov_b32_e32 v255, v1
	global_store_dwordx4 v249, v[252:255], s[94:95] offset:1408

; #define LAS __attribute__((address_space(3)))
; __device__ __forceinline__ void build_tbl(const f32x2* PS, int pm, LAS unsigned char* lds, int wid, int lane) {
;     LAS f32x2* tbl = (LAS f32x2*)(lds + TBL_OFF);
;     const f32x2* p = PS + ((size_t)pm * BM + wid * 32) * 64 + lane;
; #pragma unroll 8
;     for (int i = 0; i < 32; ++i) {
;         const f32x2 v = p[(size_t)i * 64];
;         const float a = wave_sum(v.x), b = wave_sum(v.y);
;         if (lane == 0) { const float mu = a * (1.f / DM), var = fmaxf(b * (1.f / DM) - mu * mu, 0.f); tbl[wid * 32 + i] = (f32x2){mu, 1.f / sqrtf(var + LN_EPS)}; }
;     }
; }
; __device__ __forceinline__ void ensure_tbl(const f32x2* PS, int sid, int pm, const EpiCtx& X) {
;     volatile LAS unsigned* keyw = (volatile LAS unsigned*)(X.lds + MISC_OFF) + KEY_WORD;
;     const unsigned key = (unsigned)(sid * 64 + pm + 1);
;     if ((unsigned)__builtin_amdgcn_readfirstlane((int)keyw[0]) != key) {
;         build_tbl(PS, pm, X.lds, X.wid, X.lane);
;         asm volatile("s_waitcnt lgkmcnt(0)" ::: "memory"); __builtin_amdgcn_s_barrier(); asm volatile("" ::: "memory");
;         if (X.tid == 0) keyw[0] = key;
;     }
; }
.LBB0_928:
	s_waitcnt lgkmcnt(0)
	v_readfirstlane_b32 s5, v182
	s_cmp_eq_u32 s5, s4
	s_cbranch_scc1 .LBB0_950
	s_ashr_i32 s65, s64, 31
	s_load_dwordx2 s[18:19], s[0:1], 0xb0
	s_lshl_b32 s68, s64, 11
	s_add_u32 s68, s68, s87
	s_add_u32 s68, s68, 0x5c000000
	v_lshlrev_b32_e32 v232, 17, v179
	s_waitcnt lgkmcnt(0)
	s_add_u32 s18, s18, s68
	s_addc_u32 s19, s19, 0
	global_load_dwordx4 v[128:131], v232, s[18:19]
	global_load_dwordx4 v[132:135], v232, s[18:19] offset:16
	global_load_dwordx4 v[136:139], v232, s[18:19] offset:32
	global_load_dwordx4 v[140:143], v232, s[18:19] offset:48
	global_load_dwordx4 v[184:187], v232, s[18:19] offset:64
	global_load_dwordx4 v[188:191], v232, s[18:19] offset:80
	global_load_dwordx4 v[192:195], v232, s[18:19] offset:96
	global_load_dwordx4 v[196:199], v232, s[18:19] offset:112
	global_load_dwordx4 v[200:203], v232, s[18:19] offset:128
	global_load_dwordx4 v[204:207], v232, s[18:19] offset:144
	global_load_dwordx4 v[208:211], v232, s[18:19] offset:160
	global_load_dwordx4 v[212:215], v232, s[18:19] offset:176
	global_load_dwordx4 v[216:219], v232, s[18:19] offset:192
	global_load_dwordx4 v[220:223], v232, s[18:19] offset:208
	global_load_dwordx4 v[224:227], v232, s[18:19] offset:224
	global_load_dwordx4 v[228:231], v232, s[18:19] offset:240
	s_waitcnt vmcnt(0)
	v_permlane32_swap_b32_e32 v128, v200
	v_permlane32_swap_b32_e32 v129, v201
	v_permlane32_swap_b32_e32 v130, v202
	v_permlane32_swap_b32_e32 v131, v203
	v_permlane32_swap_b32_e32 v132, v204
	v_permlane32_swap_b32_e32 v133, v205
	v_permlane32_swap_b32_e32 v134, v206
	v_permlane32_swap_b32_e32 v135, v207
	v_permlane32_swap_b32_e32 v136, v208
	v_permlane32_swap_b32_e32 v137, v209
	v_permlane32_swap_b32_e32 v138, v210
	v_permlane32_swap_b32_e32 v139, v211
	v_permlane32_swap_b32_e32 v140, v212
	v_permlane32_swap_b32_e32 v141, v213
	v_permlane32_swap_b32_e32 v142, v214
	v_permlane32_swap_b32_e32 v143, v215
	v_permlane32_swap_b32_e32 v184, v216
	v_permlane32_swap_b32_e32 v185, v217
	v_permlane32_swap_b32_e32 v186, v218
	v_permlane32_swap_b32_e32 v187, v219
	v_permlane32_swap_b32_e32 v188, v220
	v_permlane32_swap_b32_e32 v189, v221
	v_permlane32_swap_b32_e32 v190, v222
	v_permlane32_swap_b32_e32 v191, v223
	v_permlane32_swap_b32_e32 v192, v224
	v_permlane32_swap_b32_e32 v193, v225
	v_permlane32_swap_b32_e32 v194, v226
	v_permlane32_swap_b32_e32 v195, v227
	v_permlane32_swap_b32_e32 v196, v228
	v_permlane32_swap_b32_e32 v197, v229
	v_permlane32_swap_b32_e32 v198, v230
	v_permlane32_swap_b32_e32 v199, v231
	v_pk_add_f32 v[128:129], v[128:129], v[200:201]
	v_pk_add_f32 v[130:131], v[130:131], v[202:203]
	v_pk_add_f32 v[132:133], v[132:133], v[204:205]
	v_pk_add_f32 v[134:135], v[134:135], v[206:207]
	v_pk_add_f32 v[136:137], v[136:137], v[208:209]
	v_pk_add_f32 v[138:139], v[138:139], v[210:211]
	v_pk_add_f32 v[140:141], v[140:141], v[212:213]
	v_pk_add_f32 v[142:143], v[142:143], v[214:215]
	v_pk_add_f32 v[184:185], v[184:185], v[216:217]
	v_pk_add_f32 v[186:187], v[186:187], v[218:219]
	v_pk_add_f32 v[188:189], v[188:189], v[220:221]
	v_pk_add_f32 v[190:191], v[190:191], v[222:223]
	v_pk_add_f32 v[192:193], v[192:193], v[224:225]
	v_pk_add_f32 v[194:195], v[194:195], v[226:227]
	v_pk_add_f32 v[196:197], v[196:197], v[228:229]
	v_pk_add_f32 v[198:199], v[198:199], v[230:231]
	s_nop 1
	v_permlane16_swap_b32_e32 v128, v184
	v_permlane16_swap_b32_e32 v129, v185
	v_permlane16_swap_b32_e32 v130, v186
	v_permlane16_swap_b32_e32 v131, v187
	v_permlane16_swap_b32_e32 v132, v188
	v_permlane16_swap_b32_e32 v133, v189
	v_permlane16_swap_b32_e32 v134, v190
	v_permlane16_swap_b32_e32 v135, v191
	v_permlane16_swap_b32_e32 v136, v192
	v_permlane16_swap_b32_e32 v137, v193
	v_permlane16_swap_b32_e32 v138, v194
	v_permlane16_swap_b32_e32 v139, v195
	v_permlane16_swap_b32_e32 v140, v196
	v_permlane16_swap_b32_e32 v141, v197
	v_permlane16_swap_b32_e32 v142, v198
	v_permlane16_swap_b32_e32 v143, v199
	v_pk_add_f32 v[128:129], v[128:129], v[184:185]
	v_pk_add_f32 v[130:131], v[130:131], v[186:187]
	v_pk_add_f32 v[132:133], v[132:133], v[188:189]
	v_pk_add_f32 v[134:135], v[134:135], v[190:191]
	v_pk_add_f32 v[136:137], v[136:137], v[192:193]
	v_pk_add_f32 v[138:139], v[138:139], v[194:195]
	v_pk_add_f32 v[140:141], v[140:141], v[196:197]
	v_pk_add_f32 v[142:143], v[142:143], v[198:199]
	s_nop 1
	v_add_f32_dpp v128, v128, v128 row_ror:8 row_mask:0xf bank_mask:0xf
	v_add_f32_dpp v129, v129, v129 row_ror:8 row_mask:0xf bank_mask:0xf
	v_add_f32_dpp v130, v130, v130 row_ror:8 row_mask:0xf bank_mask:0xf
	v_add_f32_dpp v131, v131, v131 row_ror:8 row_mask:0xf bank_mask:0xf
	v_add_f32_dpp v132, v132, v132 row_ror:8 row_mask:0xf bank_mask:0xf
	v_add_f32_dpp v133, v133, v133 row_ror:8 row_mask:0xf bank_mask:0xf
	v_add_f32_dpp v134, v134, v134 row_ror:8 row_mask:0xf bank_mask:0xf
	v_add_f32_dpp v135, v135, v135 row_ror:8 row_mask:0xf bank_mask:0xf
	v_add_f32_dpp v136, v136, v136 row_ror:8 row_mask:0xf bank_mask:0xf
	v_add_f32_dpp v137, v137, v137 row_ror:8 row_mask:0xf bank_mask:0xf
	v_add_f32_dpp v138, v138, v138 row_ror:8 row_mask:0xf bank_mask:0xf
	v_add_f32_dpp v139, v139, v139 row_ror:8 row_mask:0xf bank_mask:0xf
	v_add_f32_dpp v140, v140, v140 row_ror:8 row_mask:0xf bank_mask:0xf
	v_add_f32_dpp v141, v141, v141 row_ror:8 row_mask:0xf bank_mask:0xf
	v_add_f32_dpp v142, v142, v142 row_ror:8 row_mask:0xf bank_mask:0xf
	v_add_f32_dpp v143, v143, v143 row_ror:8 row_mask:0xf bank_mask:0xf
	v_add_f32_dpp v128, v128, v128 row_ror:4 row_mask:0xf bank_mask:0xf
	v_add_f32_dpp v129, v129, v129 row_ror:4 row_mask:0xf bank_mask:0xf
	v_add_f32_dpp v130, v130, v130 row_ror:4 row_mask:0xf bank_mask:0xf
; __device__ __forceinline__ void build_tbl(const f32x2* PS, int pm, LAS unsigned char* lds, int wid, int lane) {
;     ...
;     for (int i = 0; i < 32; ++i) {
;         const f32x2 v = p[(size_t)i * 64];
;         const float a = wave_sum(v.x), b = wave_sum(v.y);
;         if (lane == 0) { const float mu = a * (1.f / DM), var = fmaxf(b * (1.f / DM) - mu * mu, 0.f); tbl[wid * 32 + i] = (f32x2){mu, 1.f / sqrtf(var + LN_EPS)}; }
;     }
	v_add_f32_dpp v131, v131, v131 row_ror:4 row_mask:0xf bank_mask:0xf
	v_add_f32_dpp v132, v132, v132 row_ror:4 row_mask:0xf bank_mask:0xf
	v_add_f32_dpp v133, v133, v133 row_ror:4 row_mask:0xf bank_mask:0xf
	v_add_f32_dpp v134, v134, v134 row_ror:4 row_mask:0xf bank_mask:0xf
	v_add_f32_dpp v135, v135, v135 row_ror:4 row_mask:0xf bank_mask:0xf
	v_add_f32_dpp v136, v136, v136 row_ror:4 row_mask:0xf bank_mask:0xf
	v_add_f32_dpp v137, v137, v137 row_ror:4 row_mask:0xf bank_mask:0xf
	v_add_f32_dpp v138, v138, v138 row_ror:4 row_mask:0xf bank_mask:0xf
	v_add_f32_dpp v139, v139, v139 row_ror:4 row_mask:0xf bank_mask:0xf
	v_add_f32_dpp v140, v140, v140 row_ror:4 row_mask:0xf bank_mask:0xf
	v_add_f32_dpp v141, v141, v141 row_ror:4 row_mask:0xf bank_mask:0xf
	v_add_f32_dpp v142, v142, v142 row_ror:4 row_mask:0xf bank_mask:0xf
	v_add_f32_dpp v143, v143, v143 row_ror:4 row_mask:0xf bank_mask:0xf
	v_add_f32_dpp v128, v128, v128 row_ror:2 row_mask:0xf bank_mask:0xf
	v_add_f32_dpp v129, v129, v129 row_ror:2 row_mask:0xf bank_mask:0xf
	v_add_f32_dpp v130, v130, v130 row_ror:2 row_mask:0xf bank_mask:0xf
	v_add_f32_dpp v131, v131, v131 row_ror:2 row_mask:0xf bank_mask:0xf
	v_add_f32_dpp v132, v132, v132 row_ror:2 row_mask:0xf bank_mask:0xf
	v_add_f32_dpp v133, v133, v133 row_ror:2 row_mask:0xf bank_mask:0xf
	v_add_f32_dpp v134, v134, v134 row_ror:2 row_mask:0xf bank_mask:0xf
	v_add_f32_dpp v135, v135, v135 row_ror:2 row_mask:0xf bank_mask:0xf
	v_add_f32_dpp v136, v136, v136 row_ror:2 row_mask:0xf bank_mask:0xf
	v_add_f32_dpp v137, v137, v137 row_ror:2 row_mask:0xf bank_mask:0xf
	v_add_f32_dpp v138, v138, v138 row_ror:2 row_mask:0xf bank_mask:0xf
	v_add_f32_dpp v139, v139, v139 row_ror:2 row_mask:0xf bank_mask:0xf
	v_add_f32_dpp v140, v140, v140 row_ror:2 row_mask:0xf bank_mask:0xf
	v_add_f32_dpp v141, v141, v141 row_ror:2 row_mask:0xf bank_mask:0xf
	v_add_f32_dpp v142, v142, v142 row_ror:2 row_mask:0xf bank_mask:0xf
	v_add_f32_dpp v143, v143, v143 row_ror:2 row_mask:0xf bank_mask:0xf
	v_add_f32_dpp v128, v128, v128 row_ror:1 row_mask:0xf bank_mask:0xf
	v_add_f32_dpp v129, v129, v129 row_ror:1 row_mask:0xf bank_mask:0xf
	v_add_f32_dpp v130, v130, v130 row_ror:1 row_mask:0xf bank_mask:0xf
	v_add_f32_dpp v131, v131, v131 row_ror:1 row_mask:0xf bank_mask:0xf
	v_add_f32_dpp v132, v132, v132 row_ror:1 row_mask:0xf bank_mask:0xf
	v_add_f32_dpp v133, v133, v133 row_ror:1 row_mask:0xf bank_mask:0xf
	v_add_f32_dpp v134, v134, v134 row_ror:1 row_mask:0xf bank_mask:0xf
	v_add_f32_dpp v135, v135, v135 row_ror:1 row_mask:0xf bank_mask:0xf
	v_add_f32_dpp v136, v136, v136 row_ror:1 row_mask:0xf bank_mask:0xf
	v_add_f32_dpp v137, v137, v137 row_ror:1 row_mask:0xf bank_mask:0xf
	v_add_f32_dpp v138, v138, v138 row_ror:1 row_mask:0xf bank_mask:0xf
	v_add_f32_dpp v139, v139, v139 row_ror:1 row_mask:0xf bank_mask:0xf
	v_add_f32_dpp v140, v140, v140 row_ror:1 row_mask:0xf bank_mask:0xf
	v_add_f32_dpp v141, v141, v141 row_ror:1 row_mask:0xf bank_mask:0xf
	v_add_f32_dpp v142, v142, v142 row_ror:1 row_mask:0xf bank_mask:0xf
	v_add_f32_dpp v143, v143, v143 row_ror:1 row_mask:0xf bank_mask:0xf
	s_nop 1
	v_mul_f32_e32 v128, s26, v128
	v_mul_f32_e32 v129, s26, v129
	v_fma_f32 v129, -v128, v128, v129
	v_max_f32_e32 v129, 0, v129
	v_add_f32_e32 v129, 0x3727c5ac, v129
	v_mul_f32_e32 v234, 0x4f800000, v129
	v_cmp_gt_f32_e32 vcc, s93, v129
	s_nop 1
	v_cndmask_b32_e32 v129, v129, v234, vcc
	v_sqrt_f32_e32 v234, v129
	s_nop 0
	v_add_u32_e32 v235, -1, v234
	v_fma_f32 v237, -v235, v234, v129
	v_add_u32_e32 v236, 1, v234
	v_cmp_ge_f32_e64 s[18:19], 0, v237
	s_nop 1
	v_cndmask_b32_e64 v235, v234, v235, s[18:19]
	v_fma_f32 v234, -v236, v234, v129
	v_cmp_lt_f32_e64 s[18:19], 0, v234
	s_nop 1
	v_cndmask_b32_e64 v234, v235, v236, s[18:19]
	v_mul_f32_e32 v235, 0x37800000, v234
	v_cndmask_b32_e32 v234, v234, v235, vcc
	v_cmp_class_f32_e32 vcc, v129, v178
	s_nop 1
	v_cndmask_b32_e32 v129, v234, v129, vcc
	v_div_scale_f32 v234, s[18:19], v129, v129, 1.0
	v_rcp_f32_e32 v235, v234
	s_nop 0
	v_fma_f32 v236, -v234, v235, 1.0
	v_fmac_f32_e32 v235, v236, v235
	v_div_scale_f32 v236, vcc, 1.0, v129, 1.0
	v_mul_f32_e32 v237, v236, v235
	v_fma_f32 v238, -v234, v237, v236
	v_fmac_f32_e32 v237, v238, v235
	v_fma_f32 v234, -v234, v237, v236
	v_div_fmas_f32 v234, v234, v235, v237
	v_div_fixup_f32 v129, v234, v129, 1.0
	v_mul_f32_e32 v130, s26, v130
	v_mul_f32_e32 v131, s26, v131
	v_fma_f32 v131, -v130, v130, v131
	v_max_f32_e32 v131, 0, v131
	v_add_f32_e32 v131, 0x3727c5ac, v131
	v_mul_f32_e32 v234, 0x4f800000, v131
	v_cmp_gt_f32_e32 vcc, s93, v131
	s_nop 1
	v_cndmask_b32_e32 v131, v131, v234, vcc
	v_sqrt_f32_e32 v234, v131
	s_nop 0
	v_add_u32_e32 v235, -1, v234
	v_fma_f32 v237, -v235, v234, v131
	v_add_u32_e32 v236, 1, v234
	v_cmp_ge_f32_e64 s[18:19], 0, v237
	s_nop 1
	v_cndmask_b32_e64 v235, v234, v235, s[18:19]
	v_fma_f32 v234, -v236, v234, v131
	v_cmp_lt_f32_e64 s[18:19], 0, v234
	s_nop 1
	v_cndmask_b32_e64 v234, v235, v236, s[18:19]
	v_mul_f32_e32 v235, 0x37800000, v234
	v_cndmask_b32_e32 v234, v234, v235, vcc
	v_cmp_class_f32_e32 vcc, v131, v178
	s_nop 1
	v_cndmask_b32_e32 v131, v234, v131, vcc
	v_div_scale_f32 v234, s[18:19], v131, v131, 1.0
	v_rcp_f32_e32 v235, v234
	s_nop 0
	v_fma_f32 v236, -v234, v235, 1.0
	v_fmac_f32_e32 v235, v236, v235
	v_div_scale_f32 v236, vcc, 1.0, v131, 1.0
	v_mul_f32_e32 v237, v236, v235
	v_fma_f32 v238, -v234, v237, v236
	v_fmac_f32_e32 v237, v238, v235
	v_fma_f32 v234, -v234, v237, v236
	v_div_fmas_f32 v234, v234, v235, v237
	v_div_fixup_f32 v131, v234, v131, 1.0
	v_mul_f32_e32 v132, s26, v132
	v_mul_f32_e32 v133, s26, v133
	v_fma_f32 v133, -v132, v132, v133
	v_max_f32_e32 v133, 0, v133
; __device__ __forceinline__ void build_tbl(const f32x2* PS, int pm, LAS unsigned char* lds, int wid, int lane) {
;     ...
;         if (lane == 0) { const float mu = a * (1.f / DM), var = fmaxf(b * (1.f / DM) - mu * mu, 0.f); tbl[wid * 32 + i] = (f32x2){mu, 1.f / sqrtf(var + LN_EPS)}; }
	v_add_f32_e32 v133, 0x3727c5ac, v133
	v_mul_f32_e32 v234, 0x4f800000, v133
	v_cmp_gt_f32_e32 vcc, s93, v133
	s_nop 1
	v_cndmask_b32_e32 v133, v133, v234, vcc
	v_sqrt_f32_e32 v234, v133
	s_nop 0
	v_add_u32_e32 v235, -1, v234
	v_fma_f32 v237, -v235, v234, v133
	v_add_u32_e32 v236, 1, v234
	v_cmp_ge_f32_e64 s[18:19], 0, v237
	s_nop 1
	v_cndmask_b32_e64 v235, v234, v235, s[18:19]
	v_fma_f32 v234, -v236, v234, v133
	v_cmp_lt_f32_e64 s[18:19], 0, v234
	s_nop 1
	v_cndmask_b32_e64 v234, v235, v236, s[18:19]
	v_mul_f32_e32 v235, 0x37800000, v234
	v_cndmask_b32_e32 v234, v234, v235, vcc
	v_cmp_class_f32_e32 vcc, v133, v178
	s_nop 1
	v_cndmask_b32_e32 v133, v234, v133, vcc
	v_div_scale_f32 v234, s[18:19], v133, v133, 1.0
	v_rcp_f32_e32 v235, v234
	s_nop 0
	v_fma_f32 v236, -v234, v235, 1.0
	v_fmac_f32_e32 v235, v236, v235
	v_div_scale_f32 v236, vcc, 1.0, v133, 1.0
	v_mul_f32_e32 v237, v236, v235
	v_fma_f32 v238, -v234, v237, v236
	v_fmac_f32_e32 v237, v238, v235
	v_fma_f32 v234, -v234, v237, v236
	v_div_fmas_f32 v234, v234, v235, v237
	v_div_fixup_f32 v133, v234, v133, 1.0
	v_mul_f32_e32 v134, s26, v134
	v_mul_f32_e32 v135, s26, v135
	v_fma_f32 v135, -v134, v134, v135
	v_max_f32_e32 v135, 0, v135
	v_add_f32_e32 v135, 0x3727c5ac, v135
	v_mul_f32_e32 v234, 0x4f800000, v135
	v_cmp_gt_f32_e32 vcc, s93, v135
	s_nop 1
	v_cndmask_b32_e32 v135, v135, v234, vcc
	v_sqrt_f32_e32 v234, v135
	s_nop 0
	v_add_u32_e32 v235, -1, v234
	v_fma_f32 v237, -v235, v234, v135
	v_add_u32_e32 v236, 1, v234
	v_cmp_ge_f32_e64 s[18:19], 0, v237
	s_nop 1
	v_cndmask_b32_e64 v235, v234, v235, s[18:19]
	v_fma_f32 v234, -v236, v234, v135
	v_cmp_lt_f32_e64 s[18:19], 0, v234
	s_nop 1
	v_cndmask_b32_e64 v234, v235, v236, s[18:19]
	v_mul_f32_e32 v235, 0x37800000, v234
	v_cndmask_b32_e32 v234, v234, v235, vcc
	v_cmp_class_f32_e32 vcc, v135, v178
	s_nop 1
	v_cndmask_b32_e32 v135, v234, v135, vcc
	v_div_scale_f32 v234, s[18:19], v135, v135, 1.0
	v_rcp_f32_e32 v235, v234
	s_nop 0
	v_fma_f32 v236, -v234, v235, 1.0
	v_fmac_f32_e32 v235, v236, v235
	v_div_scale_f32 v236, vcc, 1.0, v135, 1.0
	v_mul_f32_e32 v237, v236, v235
	v_fma_f32 v238, -v234, v237, v236
	v_fmac_f32_e32 v237, v238, v235
	v_fma_f32 v234, -v234, v237, v236
	v_div_fmas_f32 v234, v234, v235, v237
	v_div_fixup_f32 v135, v234, v135, 1.0
	v_mul_f32_e32 v136, s26, v136
	v_mul_f32_e32 v137, s26, v137
	v_fma_f32 v137, -v136, v136, v137
	v_max_f32_e32 v137, 0, v137
	v_add_f32_e32 v137, 0x3727c5ac, v137
	v_mul_f32_e32 v234, 0x4f800000, v137
	v_cmp_gt_f32_e32 vcc, s93, v137
	s_nop 1
	v_cndmask_b32_e32 v137, v137, v234, vcc
	v_sqrt_f32_e32 v234, v137
	s_nop 0
	v_add_u32_e32 v235, -1, v234
	v_fma_f32 v237, -v235, v234, v137
	v_add_u32_e32 v236, 1, v234
	v_cmp_ge_f32_e64 s[18:19], 0, v237
	s_nop 1
	v_cndmask_b32_e64 v235, v234, v235, s[18:19]
	v_fma_f32 v234, -v236, v234, v137
	v_cmp_lt_f32_e64 s[18:19], 0, v234
	s_nop 1
	v_cndmask_b32_e64 v234, v235, v236, s[18:19]
	v_mul_f32_e32 v235, 0x37800000, v234
	v_cndmask_b32_e32 v234, v234, v235, vcc
	v_cmp_class_f32_e32 vcc, v137, v178
	s_nop 1
	v_cndmask_b32_e32 v137, v234, v137, vcc
	v_div_scale_f32 v234, s[18:19], v137, v137, 1.0
	v_rcp_f32_e32 v235, v234
	s_nop 0
	v_fma_f32 v236, -v234, v235, 1.0
	v_fmac_f32_e32 v235, v236, v235
	v_div_scale_f32 v236, vcc, 1.0, v137, 1.0
	v_mul_f32_e32 v237, v236, v235
	v_fma_f32 v238, -v234, v237, v236
	v_fmac_f32_e32 v237, v238, v235
	v_fma_f32 v234, -v234, v237, v236
	v_div_fmas_f32 v234, v234, v235, v237
	v_div_fixup_f32 v137, v234, v137, 1.0
	v_mul_f32_e32 v138, s26, v138
	v_mul_f32_e32 v139, s26, v139
	v_fma_f32 v139, -v138, v138, v139
	v_max_f32_e32 v139, 0, v139
	v_add_f32_e32 v139, 0x3727c5ac, v139
	v_mul_f32_e32 v234, 0x4f800000, v139
	v_cmp_gt_f32_e32 vcc, s93, v139
	s_nop 1
	v_cndmask_b32_e32 v139, v139, v234, vcc
	v_sqrt_f32_e32 v234, v139
	s_nop 0
	v_add_u32_e32 v235, -1, v234
; __device__ __forceinline__ void build_tbl(const f32x2* PS, int pm, LAS unsigned char* lds, int wid, int lane) {
;     ...
;         if (lane == 0) { const float mu = a * (1.f / DM), var = fmaxf(b * (1.f / DM) - mu * mu, 0.f); tbl[wid * 32 + i] = (f32x2){mu, 1.f / sqrtf(var + LN_EPS)}; }
; __device__ __forceinline__ void ensure_tbl(const f32x2* PS, int sid, int pm, const EpiCtx& X) {
;     ...
;         if (X.tid == 0) keyw[0] = key;
	v_fma_f32 v237, -v235, v234, v139
	v_add_u32_e32 v236, 1, v234
	v_cmp_ge_f32_e64 s[18:19], 0, v237
	s_nop 1
	v_cndmask_b32_e64 v235, v234, v235, s[18:19]
	v_fma_f32 v234, -v236, v234, v139
	v_cmp_lt_f32_e64 s[18:19], 0, v234
	s_nop 1
	v_cndmask_b32_e64 v234, v235, v236, s[18:19]
	v_mul_f32_e32 v235, 0x37800000, v234
	v_cndmask_b32_e32 v234, v234, v235, vcc
	v_cmp_class_f32_e32 vcc, v139, v178
	s_nop 1
	v_cndmask_b32_e32 v139, v234, v139, vcc
	v_div_scale_f32 v234, s[18:19], v139, v139, 1.0
	v_rcp_f32_e32 v235, v234
	s_nop 0
	v_fma_f32 v236, -v234, v235, 1.0
	v_fmac_f32_e32 v235, v236, v235
	v_div_scale_f32 v236, vcc, 1.0, v139, 1.0
	v_mul_f32_e32 v237, v236, v235
	v_fma_f32 v238, -v234, v237, v236
	v_fmac_f32_e32 v237, v238, v235
	v_fma_f32 v234, -v234, v237, v236
	v_div_fmas_f32 v234, v234, v235, v237
	v_div_fixup_f32 v139, v234, v139, 1.0
	v_mul_f32_e32 v140, s26, v140
	v_mul_f32_e32 v141, s26, v141
	v_fma_f32 v141, -v140, v140, v141
	v_max_f32_e32 v141, 0, v141
	v_add_f32_e32 v141, 0x3727c5ac, v141
	v_mul_f32_e32 v234, 0x4f800000, v141
	v_cmp_gt_f32_e32 vcc, s93, v141
	s_nop 1
	v_cndmask_b32_e32 v141, v141, v234, vcc
	v_sqrt_f32_e32 v234, v141
	s_nop 0
	v_add_u32_e32 v235, -1, v234
	v_fma_f32 v237, -v235, v234, v141
	v_add_u32_e32 v236, 1, v234
	v_cmp_ge_f32_e64 s[18:19], 0, v237
	s_nop 1
	v_cndmask_b32_e64 v235, v234, v235, s[18:19]
	v_fma_f32 v234, -v236, v234, v141
	v_cmp_lt_f32_e64 s[18:19], 0, v234
	s_nop 1
	v_cndmask_b32_e64 v234, v235, v236, s[18:19]
	v_mul_f32_e32 v235, 0x37800000, v234
	v_cndmask_b32_e32 v234, v234, v235, vcc
	v_cmp_class_f32_e32 vcc, v141, v178
	s_nop 1
	v_cndmask_b32_e32 v141, v234, v141, vcc
	v_div_scale_f32 v234, s[18:19], v141, v141, 1.0
	v_rcp_f32_e32 v235, v234
	s_nop 0
	v_fma_f32 v236, -v234, v235, 1.0
	v_fmac_f32_e32 v235, v236, v235
	v_div_scale_f32 v236, vcc, 1.0, v141, 1.0
	v_mul_f32_e32 v237, v236, v235
	v_fma_f32 v238, -v234, v237, v236
	v_fmac_f32_e32 v237, v238, v235
	v_fma_f32 v234, -v234, v237, v236
	v_div_fmas_f32 v234, v234, v235, v237
	v_div_fixup_f32 v141, v234, v141, 1.0
	v_mul_f32_e32 v142, s26, v142
	v_mul_f32_e32 v143, s26, v143
	v_fma_f32 v143, -v142, v142, v143
	v_max_f32_e32 v143, 0, v143
	v_add_f32_e32 v143, 0x3727c5ac, v143
	v_mul_f32_e32 v234, 0x4f800000, v143
	v_cmp_gt_f32_e32 vcc, s93, v143
	s_nop 1
	v_cndmask_b32_e32 v143, v143, v234, vcc
	v_sqrt_f32_e32 v234, v143
	s_nop 0
	v_add_u32_e32 v235, -1, v234
	v_fma_f32 v237, -v235, v234, v143
	v_add_u32_e32 v236, 1, v234
	v_cmp_ge_f32_e64 s[18:19], 0, v237
	s_nop 1
	v_cndmask_b32_e64 v235, v234, v235, s[18:19]
	v_fma_f32 v234, -v236, v234, v143
	v_cmp_lt_f32_e64 s[18:19], 0, v234
	s_nop 1
	v_cndmask_b32_e64 v234, v235, v236, s[18:19]
	v_mul_f32_e32 v235, 0x37800000, v234
	v_cndmask_b32_e32 v234, v234, v235, vcc
	v_cmp_class_f32_e32 vcc, v143, v178
	s_nop 1
	v_cndmask_b32_e32 v143, v234, v143, vcc
	v_div_scale_f32 v234, s[18:19], v143, v143, 1.0
	v_rcp_f32_e32 v235, v234
	s_nop 0
	v_fma_f32 v236, -v234, v235, 1.0
	v_fmac_f32_e32 v235, v236, v235
	v_div_scale_f32 v236, vcc, 1.0, v143, 1.0
	v_mul_f32_e32 v237, v236, v235
	v_fma_f32 v238, -v234, v237, v236
	v_fmac_f32_e32 v237, v238, v235
	v_fma_f32 v234, -v234, v237, v236
	v_div_fmas_f32 v234, v234, v235, v237
	v_div_fixup_f32 v143, v234, v143, 1.0
	v_lshrrev_b32_e32 v239, 4, v179
	v_lshlrev_b32_e32 v239, 6, v239
	s_add_i32 s18, s87, 0x20400
	v_add_u32_e32 v239, s18, v239
	s_mov_b64 s[68:69], exec
	s_mov_b32 exec_lo, 0x10001
	s_mov_b32 exec_hi, 0x10001
	ds_write_b64 v239, v[128:129]
	ds_write_b64 v239, v[130:131] offset:8
	ds_write_b64 v239, v[132:133] offset:16
	ds_write_b64 v239, v[134:135] offset:24
	ds_write_b64 v239, v[136:137] offset:32
	ds_write_b64 v239, v[138:139] offset:40
	ds_write_b64 v239, v[140:141] offset:48
	ds_write_b64 v239, v[142:143] offset:56
	s_mov_b64 exec, s[68:69]

; #define LAS __attribute__((address_space(3)))
; __device__ __forceinline__ void build_tbl(const f32x2* PS, int pm, LAS unsigned char* lds, int wid, int lane) {
;     LAS f32x2* tbl = (LAS f32x2*)(lds + TBL_OFF);
;     const f32x2* p = PS + ((size_t)pm * BM + wid * 32) * 64 + lane;
; #pragma unroll 8
;     for (int i = 0; i < 32; ++i) {
;         const f32x2 v = p[(size_t)i * 64];
;         const float a = wave_sum(v.x), b = wave_sum(v.y);
;         if (lane == 0) { const float mu = a * (1.f / DM), var = fmaxf(b * (1.f / DM) - mu * mu, 0.f); tbl[wid * 32 + i] = (f32x2){mu, 1.f / sqrtf(var + LN_EPS)}; }
;     }
; }
; __device__ __forceinline__ void ensure_tbl(const f32x2* PS, int sid, int pm, const EpiCtx& X) {
;     volatile LAS unsigned* keyw = (volatile LAS unsigned*)(X.lds + MISC_OFF) + KEY_WORD;
;     const unsigned key = (unsigned)(sid * 64 + pm + 1);
;     if ((unsigned)__builtin_amdgcn_readfirstlane((int)keyw[0]) != key) {
;         build_tbl(PS, pm, X.lds, X.wid, X.lane);
;         asm volatile("s_waitcnt lgkmcnt(0)" ::: "memory"); __builtin_amdgcn_s_barrier(); asm volatile("" ::: "memory");
;         if (X.tid == 0) keyw[0] = key;
;     }
; }
.LBB0_953:
	s_waitcnt lgkmcnt(0)
	v_readfirstlane_b32 s5, v182
	s_ashr_i32 s65, s64, 31
	s_cmp_eq_u32 s5, s4
	s_cbranch_scc1 .LBB0_975
	s_ashr_i32 s65, s64, 31
	s_load_dwordx2 s[18:19], s[0:1], 0xb0
	s_lshl_b32 s68, s64, 11
	s_add_u32 s68, s68, s87
	s_add_u32 s68, s68, 0x5c000000
	v_lshlrev_b32_e32 v230, 17, v179
	s_waitcnt lgkmcnt(0)
	s_add_u32 s18, s18, s68
	s_addc_u32 s19, s19, 0
	global_load_dwordx4 v[128:131], v230, s[18:19]
	global_load_dwordx4 v[132:135], v230, s[18:19] offset:16
	global_load_dwordx4 v[136:139], v230, s[18:19] offset:32
	global_load_dwordx4 v[140:143], v230, s[18:19] offset:48
	global_load_dwordx4 v[182:185], v230, s[18:19] offset:64
	global_load_dwordx4 v[186:189], v230, s[18:19] offset:80
	global_load_dwordx4 v[190:193], v230, s[18:19] offset:96
	global_load_dwordx4 v[194:197], v230, s[18:19] offset:112
	global_load_dwordx4 v[198:201], v230, s[18:19] offset:128
	global_load_dwordx4 v[202:205], v230, s[18:19] offset:144
	global_load_dwordx4 v[206:209], v230, s[18:19] offset:160
	global_load_dwordx4 v[210:213], v230, s[18:19] offset:176
	global_load_dwordx4 v[214:217], v230, s[18:19] offset:192
	global_load_dwordx4 v[218:221], v230, s[18:19] offset:208
	global_load_dwordx4 v[222:225], v230, s[18:19] offset:224
	global_load_dwordx4 v[226:229], v230, s[18:19] offset:240
	s_waitcnt vmcnt(0)
	v_permlane32_swap_b32_e32 v128, v198
	v_permlane32_swap_b32_e32 v129, v199
	v_permlane32_swap_b32_e32 v130, v200
	v_permlane32_swap_b32_e32 v131, v201
	v_permlane32_swap_b32_e32 v132, v202
	v_permlane32_swap_b32_e32 v133, v203
	v_permlane32_swap_b32_e32 v134, v204
	v_permlane32_swap_b32_e32 v135, v205
	v_permlane32_swap_b32_e32 v136, v206
	v_permlane32_swap_b32_e32 v137, v207
	v_permlane32_swap_b32_e32 v138, v208
	v_permlane32_swap_b32_e32 v139, v209
	v_permlane32_swap_b32_e32 v140, v210
	v_permlane32_swap_b32_e32 v141, v211
	v_permlane32_swap_b32_e32 v142, v212
	v_permlane32_swap_b32_e32 v143, v213
	v_permlane32_swap_b32_e32 v182, v214
	v_permlane32_swap_b32_e32 v183, v215
	v_permlane32_swap_b32_e32 v184, v216
	v_permlane32_swap_b32_e32 v185, v217
	v_permlane32_swap_b32_e32 v186, v218
	v_permlane32_swap_b32_e32 v187, v219
	v_permlane32_swap_b32_e32 v188, v220
	v_permlane32_swap_b32_e32 v189, v221
	v_permlane32_swap_b32_e32 v190, v222
	v_permlane32_swap_b32_e32 v191, v223
	v_permlane32_swap_b32_e32 v192, v224
	v_permlane32_swap_b32_e32 v193, v225
	v_permlane32_swap_b32_e32 v194, v226
	v_permlane32_swap_b32_e32 v195, v227
	v_permlane32_swap_b32_e32 v196, v228
	v_permlane32_swap_b32_e32 v197, v229
	v_pk_add_f32 v[128:129], v[128:129], v[198:199]
	v_pk_add_f32 v[130:131], v[130:131], v[200:201]
	v_pk_add_f32 v[132:133], v[132:133], v[202:203]
	v_pk_add_f32 v[134:135], v[134:135], v[204:205]
	v_pk_add_f32 v[136:137], v[136:137], v[206:207]
	v_pk_add_f32 v[138:139], v[138:139], v[208:209]
	v_pk_add_f32 v[140:141], v[140:141], v[210:211]
	v_pk_add_f32 v[142:143], v[142:143], v[212:213]
	v_pk_add_f32 v[182:183], v[182:183], v[214:215]
	v_pk_add_f32 v[184:185], v[184:185], v[216:217]
	v_pk_add_f32 v[186:187], v[186:187], v[218:219]
	v_pk_add_f32 v[188:189], v[188:189], v[220:221]
	v_pk_add_f32 v[190:191], v[190:191], v[222:223]
	v_pk_add_f32 v[192:193], v[192:193], v[224:225]
	v_pk_add_f32 v[194:195], v[194:195], v[226:227]
	v_pk_add_f32 v[196:197], v[196:197], v[228:229]
	s_nop 1
	v_permlane16_swap_b32_e32 v128, v182
	v_permlane16_swap_b32_e32 v129, v183
	v_permlane16_swap_b32_e32 v130, v184
	v_permlane16_swap_b32_e32 v131, v185
	v_permlane16_swap_b32_e32 v132, v186
	v_permlane16_swap_b32_e32 v133, v187
	v_permlane16_swap_b32_e32 v134, v188
	v_permlane16_swap_b32_e32 v135, v189
	v_permlane16_swap_b32_e32 v136, v190
	v_permlane16_swap_b32_e32 v137, v191
	v_permlane16_swap_b32_e32 v138, v192
	v_permlane16_swap_b32_e32 v139, v193
	v_permlane16_swap_b32_e32 v140, v194
	v_permlane16_swap_b32_e32 v141, v195
	v_permlane16_swap_b32_e32 v142, v196
	v_permlane16_swap_b32_e32 v143, v197
	v_pk_add_f32 v[128:129], v[128:129], v[182:183]
	v_pk_add_f32 v[130:131], v[130:131], v[184:185]
	v_pk_add_f32 v[132:133], v[132:133], v[186:187]
	v_pk_add_f32 v[134:135], v[134:135], v[188:189]
	v_pk_add_f32 v[136:137], v[136:137], v[190:191]
	v_pk_add_f32 v[138:139], v[138:139], v[192:193]
	v_pk_add_f32 v[140:141], v[140:141], v[194:195]
	v_pk_add_f32 v[142:143], v[142:143], v[196:197]
	s_nop 1
	v_add_f32_dpp v128, v128, v128 row_ror:8 row_mask:0xf bank_mask:0xf
	v_add_f32_dpp v129, v129, v129 row_ror:8 row_mask:0xf bank_mask:0xf
	v_add_f32_dpp v130, v130, v130 row_ror:8 row_mask:0xf bank_mask:0xf
	v_add_f32_dpp v131, v131, v131 row_ror:8 row_mask:0xf bank_mask:0xf
	v_add_f32_dpp v132, v132, v132 row_ror:8 row_mask:0xf bank_mask:0xf
	v_add_f32_dpp v133, v133, v133 row_ror:8 row_mask:0xf bank_mask:0xf
	v_add_f32_dpp v134, v134, v134 row_ror:8 row_mask:0xf bank_mask:0xf
	v_add_f32_dpp v135, v135, v135 row_ror:8 row_mask:0xf bank_mask:0xf
	v_add_f32_dpp v136, v136, v136 row_ror:8 row_mask:0xf bank_mask:0xf
	v_add_f32_dpp v137, v137, v137 row_ror:8 row_mask:0xf bank_mask:0xf
	v_add_f32_dpp v138, v138, v138 row_ror:8 row_mask:0xf bank_mask:0xf
	v_add_f32_dpp v139, v139, v139 row_ror:8 row_mask:0xf bank_mask:0xf
	v_add_f32_dpp v140, v140, v140 row_ror:8 row_mask:0xf bank_mask:0xf
	v_add_f32_dpp v141, v141, v141 row_ror:8 row_mask:0xf bank_mask:0xf
	v_add_f32_dpp v142, v142, v142 row_ror:8 row_mask:0xf bank_mask:0xf
	v_add_f32_dpp v143, v143, v143 row_ror:8 row_mask:0xf bank_mask:0xf
	v_add_f32_dpp v128, v128, v128 row_ror:4 row_mask:0xf bank_mask:0xf
	v_add_f32_dpp v129, v129, v129 row_ror:4 row_mask:0xf bank_mask:0xf
	v_add_f32_dpp v130, v130, v130 row_ror:4 row_mask:0xf bank_mask:0xf
; __device__ __forceinline__ void build_tbl(const f32x2* PS, int pm, LAS unsigned char* lds, int wid, int lane) {
;     ...
;     for (int i = 0; i < 32; ++i) {
;         const f32x2 v = p[(size_t)i * 64];
;         const float a = wave_sum(v.x), b = wave_sum(v.y);
;         if (lane == 0) { const float mu = a * (1.f / DM), var = fmaxf(b * (1.f / DM) - mu * mu, 0.f); tbl[wid * 32 + i] = (f32x2){mu, 1.f / sqrtf(var + LN_EPS)}; }
;     }
	v_add_f32_dpp v131, v131, v131 row_ror:4 row_mask:0xf bank_mask:0xf
	v_add_f32_dpp v132, v132, v132 row_ror:4 row_mask:0xf bank_mask:0xf
	v_add_f32_dpp v133, v133, v133 row_ror:4 row_mask:0xf bank_mask:0xf
	v_add_f32_dpp v134, v134, v134 row_ror:4 row_mask:0xf bank_mask:0xf
	v_add_f32_dpp v135, v135, v135 row_ror:4 row_mask:0xf bank_mask:0xf
	v_add_f32_dpp v136, v136, v136 row_ror:4 row_mask:0xf bank_mask:0xf
	v_add_f32_dpp v137, v137, v137 row_ror:4 row_mask:0xf bank_mask:0xf
	v_add_f32_dpp v138, v138, v138 row_ror:4 row_mask:0xf bank_mask:0xf
	v_add_f32_dpp v139, v139, v139 row_ror:4 row_mask:0xf bank_mask:0xf
	v_add_f32_dpp v140, v140, v140 row_ror:4 row_mask:0xf bank_mask:0xf
	v_add_f32_dpp v141, v141, v141 row_ror:4 row_mask:0xf bank_mask:0xf
	v_add_f32_dpp v142, v142, v142 row_ror:4 row_mask:0xf bank_mask:0xf
	v_add_f32_dpp v143, v143, v143 row_ror:4 row_mask:0xf bank_mask:0xf
	v_add_f32_dpp v128, v128, v128 row_ror:2 row_mask:0xf bank_mask:0xf
	v_add_f32_dpp v129, v129, v129 row_ror:2 row_mask:0xf bank_mask:0xf
	v_add_f32_dpp v130, v130, v130 row_ror:2 row_mask:0xf bank_mask:0xf
	v_add_f32_dpp v131, v131, v131 row_ror:2 row_mask:0xf bank_mask:0xf
	v_add_f32_dpp v132, v132, v132 row_ror:2 row_mask:0xf bank_mask:0xf
	v_add_f32_dpp v133, v133, v133 row_ror:2 row_mask:0xf bank_mask:0xf
	v_add_f32_dpp v134, v134, v134 row_ror:2 row_mask:0xf bank_mask:0xf
	v_add_f32_dpp v135, v135, v135 row_ror:2 row_mask:0xf bank_mask:0xf
	v_add_f32_dpp v136, v136, v136 row_ror:2 row_mask:0xf bank_mask:0xf
	v_add_f32_dpp v137, v137, v137 row_ror:2 row_mask:0xf bank_mask:0xf
	v_add_f32_dpp v138, v138, v138 row_ror:2 row_mask:0xf bank_mask:0xf
	v_add_f32_dpp v139, v139, v139 row_ror:2 row_mask:0xf bank_mask:0xf
	v_add_f32_dpp v140, v140, v140 row_ror:2 row_mask:0xf bank_mask:0xf
	v_add_f32_dpp v141, v141, v141 row_ror:2 row_mask:0xf bank_mask:0xf
	v_add_f32_dpp v142, v142, v142 row_ror:2 row_mask:0xf bank_mask:0xf
	v_add_f32_dpp v143, v143, v143 row_ror:2 row_mask:0xf bank_mask:0xf
	v_add_f32_dpp v128, v128, v128 row_ror:1 row_mask:0xf bank_mask:0xf
	v_add_f32_dpp v129, v129, v129 row_ror:1 row_mask:0xf bank_mask:0xf
	v_add_f32_dpp v130, v130, v130 row_ror:1 row_mask:0xf bank_mask:0xf
	v_add_f32_dpp v131, v131, v131 row_ror:1 row_mask:0xf bank_mask:0xf
	v_add_f32_dpp v132, v132, v132 row_ror:1 row_mask:0xf bank_mask:0xf
	v_add_f32_dpp v133, v133, v133 row_ror:1 row_mask:0xf bank_mask:0xf
	v_add_f32_dpp v134, v134, v134 row_ror:1 row_mask:0xf bank_mask:0xf
	v_add_f32_dpp v135, v135, v135 row_ror:1 row_mask:0xf bank_mask:0xf
	v_add_f32_dpp v136, v136, v136 row_ror:1 row_mask:0xf bank_mask:0xf
	v_add_f32_dpp v137, v137, v137 row_ror:1 row_mask:0xf bank_mask:0xf
	v_add_f32_dpp v138, v138, v138 row_ror:1 row_mask:0xf bank_mask:0xf
	v_add_f32_dpp v139, v139, v139 row_ror:1 row_mask:0xf bank_mask:0xf
	v_add_f32_dpp v140, v140, v140 row_ror:1 row_mask:0xf bank_mask:0xf
	v_add_f32_dpp v141, v141, v141 row_ror:1 row_mask:0xf bank_mask:0xf
	v_add_f32_dpp v142, v142, v142 row_ror:1 row_mask:0xf bank_mask:0xf
	v_add_f32_dpp v143, v143, v143 row_ror:1 row_mask:0xf bank_mask:0xf
	s_nop 1
	v_mul_f32_e32 v128, s26, v128
	v_mul_f32_e32 v129, s26, v129
	v_fma_f32 v129, -v128, v128, v129
	v_max_f32_e32 v129, 0, v129
	v_add_f32_e32 v129, 0x3727c5ac, v129
	v_mul_f32_e32 v232, 0x4f800000, v129
	v_cmp_gt_f32_e32 vcc, s93, v129
	s_nop 1
	v_cndmask_b32_e32 v129, v129, v232, vcc
	v_sqrt_f32_e32 v232, v129
	s_nop 0
	v_add_u32_e32 v233, -1, v232
	v_fma_f32 v235, -v233, v232, v129
	v_add_u32_e32 v234, 1, v232
	v_cmp_ge_f32_e64 s[18:19], 0, v235
	s_nop 1
	v_cndmask_b32_e64 v233, v232, v233, s[18:19]
	v_fma_f32 v232, -v234, v232, v129
	v_cmp_lt_f32_e64 s[18:19], 0, v232
	s_nop 1
	v_cndmask_b32_e64 v232, v233, v234, s[18:19]
	v_mul_f32_e32 v233, 0x37800000, v232
	v_cndmask_b32_e32 v232, v232, v233, vcc
	v_cmp_class_f32_e32 vcc, v129, v178
	s_nop 1
	v_cndmask_b32_e32 v129, v232, v129, vcc
	v_div_scale_f32 v232, s[18:19], v129, v129, 1.0
	v_rcp_f32_e32 v233, v232
	s_nop 0
	v_fma_f32 v234, -v232, v233, 1.0
	v_fmac_f32_e32 v233, v234, v233
	v_div_scale_f32 v234, vcc, 1.0, v129, 1.0
	v_mul_f32_e32 v235, v234, v233
	v_fma_f32 v236, -v232, v235, v234
	v_fmac_f32_e32 v235, v236, v233
	v_fma_f32 v232, -v232, v235, v234
	v_div_fmas_f32 v232, v232, v233, v235
	v_div_fixup_f32 v129, v232, v129, 1.0
	v_mul_f32_e32 v130, s26, v130
	v_mul_f32_e32 v131, s26, v131
	v_fma_f32 v131, -v130, v130, v131
	v_max_f32_e32 v131, 0, v131
	v_add_f32_e32 v131, 0x3727c5ac, v131
	v_mul_f32_e32 v232, 0x4f800000, v131
	v_cmp_gt_f32_e32 vcc, s93, v131
	s_nop 1
	v_cndmask_b32_e32 v131, v131, v232, vcc
	v_sqrt_f32_e32 v232, v131
	s_nop 0
	v_add_u32_e32 v233, -1, v232
	v_fma_f32 v235, -v233, v232, v131
	v_add_u32_e32 v234, 1, v232
	v_cmp_ge_f32_e64 s[18:19], 0, v235
	s_nop 1
	v_cndmask_b32_e64 v233, v232, v233, s[18:19]
	v_fma_f32 v232, -v234, v232, v131
	v_cmp_lt_f32_e64 s[18:19], 0, v232
	s_nop 1
	v_cndmask_b32_e64 v232, v233, v234, s[18:19]
	v_mul_f32_e32 v233, 0x37800000, v232
	v_cndmask_b32_e32 v232, v232, v233, vcc
	v_cmp_class_f32_e32 vcc, v131, v178
	s_nop 1
	v_cndmask_b32_e32 v131, v232, v131, vcc
	v_div_scale_f32 v232, s[18:19], v131, v131, 1.0
	v_rcp_f32_e32 v233, v232
	s_nop 0
	v_fma_f32 v234, -v232, v233, 1.0
	v_fmac_f32_e32 v233, v234, v233
	v_div_scale_f32 v234, vcc, 1.0, v131, 1.0
	v_mul_f32_e32 v235, v234, v233
	v_fma_f32 v236, -v232, v235, v234
	v_fmac_f32_e32 v235, v236, v233
	v_fma_f32 v232, -v232, v235, v234
	v_div_fmas_f32 v232, v232, v233, v235
	v_div_fixup_f32 v131, v232, v131, 1.0
	v_mul_f32_e32 v132, s26, v132
	v_mul_f32_e32 v133, s26, v133
	v_fma_f32 v133, -v132, v132, v133
	v_max_f32_e32 v133, 0, v133
; __device__ __forceinline__ void build_tbl(const f32x2* PS, int pm, LAS unsigned char* lds, int wid, int lane) {
;     ...
;         if (lane == 0) { const float mu = a * (1.f / DM), var = fmaxf(b * (1.f / DM) - mu * mu, 0.f); tbl[wid * 32 + i] = (f32x2){mu, 1.f / sqrtf(var + LN_EPS)}; }
	v_add_f32_e32 v133, 0x3727c5ac, v133
	v_mul_f32_e32 v232, 0x4f800000, v133
	v_cmp_gt_f32_e32 vcc, s93, v133
	s_nop 1
	v_cndmask_b32_e32 v133, v133, v232, vcc
	v_sqrt_f32_e32 v232, v133
	s_nop 0
	v_add_u32_e32 v233, -1, v232
	v_fma_f32 v235, -v233, v232, v133
	v_add_u32_e32 v234, 1, v232
	v_cmp_ge_f32_e64 s[18:19], 0, v235
	s_nop 1
	v_cndmask_b32_e64 v233, v232, v233, s[18:19]
	v_fma_f32 v232, -v234, v232, v133
	v_cmp_lt_f32_e64 s[18:19], 0, v232
	s_nop 1
	v_cndmask_b32_e64 v232, v233, v234, s[18:19]
	v_mul_f32_e32 v233, 0x37800000, v232
	v_cndmask_b32_e32 v232, v232, v233, vcc
	v_cmp_class_f32_e32 vcc, v133, v178
	s_nop 1
	v_cndmask_b32_e32 v133, v232, v133, vcc
	v_div_scale_f32 v232, s[18:19], v133, v133, 1.0
	v_rcp_f32_e32 v233, v232
	s_nop 0
	v_fma_f32 v234, -v232, v233, 1.0
	v_fmac_f32_e32 v233, v234, v233
	v_div_scale_f32 v234, vcc, 1.0, v133, 1.0
	v_mul_f32_e32 v235, v234, v233
	v_fma_f32 v236, -v232, v235, v234
	v_fmac_f32_e32 v235, v236, v233
	v_fma_f32 v232, -v232, v235, v234
	v_div_fmas_f32 v232, v232, v233, v235
	v_div_fixup_f32 v133, v232, v133, 1.0
	v_mul_f32_e32 v134, s26, v134
	v_mul_f32_e32 v135, s26, v135
	v_fma_f32 v135, -v134, v134, v135
	v_max_f32_e32 v135, 0, v135
	v_add_f32_e32 v135, 0x3727c5ac, v135
	v_mul_f32_e32 v232, 0x4f800000, v135
	v_cmp_gt_f32_e32 vcc, s93, v135
	s_nop 1
	v_cndmask_b32_e32 v135, v135, v232, vcc
	v_sqrt_f32_e32 v232, v135
	s_nop 0
	v_add_u32_e32 v233, -1, v232
	v_fma_f32 v235, -v233, v232, v135
	v_add_u32_e32 v234, 1, v232
	v_cmp_ge_f32_e64 s[18:19], 0, v235
	s_nop 1
	v_cndmask_b32_e64 v233, v232, v233, s[18:19]
	v_fma_f32 v232, -v234, v232, v135
	v_cmp_lt_f32_e64 s[18:19], 0, v232
	s_nop 1
	v_cndmask_b32_e64 v232, v233, v234, s[18:19]
	v_mul_f32_e32 v233, 0x37800000, v232
	v_cndmask_b32_e32 v232, v232, v233, vcc
	v_cmp_class_f32_e32 vcc, v135, v178
	s_nop 1
	v_cndmask_b32_e32 v135, v232, v135, vcc
	v_div_scale_f32 v232, s[18:19], v135, v135, 1.0
	v_rcp_f32_e32 v233, v232
	s_nop 0
	v_fma_f32 v234, -v232, v233, 1.0
	v_fmac_f32_e32 v233, v234, v233
	v_div_scale_f32 v234, vcc, 1.0, v135, 1.0
	v_mul_f32_e32 v235, v234, v233
	v_fma_f32 v236, -v232, v235, v234
	v_fmac_f32_e32 v235, v236, v233
	v_fma_f32 v232, -v232, v235, v234
	v_div_fmas_f32 v232, v232, v233, v235
	v_div_fixup_f32 v135, v232, v135, 1.0
	v_mul_f32_e32 v136, s26, v136
	v_mul_f32_e32 v137, s26, v137
	v_fma_f32 v137, -v136, v136, v137
	v_max_f32_e32 v137, 0, v137
	v_add_f32_e32 v137, 0x3727c5ac, v137
	v_mul_f32_e32 v232, 0x4f800000, v137
	v_cmp_gt_f32_e32 vcc, s93, v137
	s_nop 1
	v_cndmask_b32_e32 v137, v137, v232, vcc
	v_sqrt_f32_e32 v232, v137
	s_nop 0
	v_add_u32_e32 v233, -1, v232
	v_fma_f32 v235, -v233, v232, v137
	v_add_u32_e32 v234, 1, v232
	v_cmp_ge_f32_e64 s[18:19], 0, v235
	s_nop 1
	v_cndmask_b32_e64 v233, v232, v233, s[18:19]
	v_fma_f32 v232, -v234, v232, v137
	v_cmp_lt_f32_e64 s[18:19], 0, v232
	s_nop 1
	v_cndmask_b32_e64 v232, v233, v234, s[18:19]
	v_mul_f32_e32 v233, 0x37800000, v232
	v_cndmask_b32_e32 v232, v232, v233, vcc
	v_cmp_class_f32_e32 vcc, v137, v178
	s_nop 1
	v_cndmask_b32_e32 v137, v232, v137, vcc
	v_div_scale_f32 v232, s[18:19], v137, v137, 1.0
	v_rcp_f32_e32 v233, v232
	s_nop 0
	v_fma_f32 v234, -v232, v233, 1.0
	v_fmac_f32_e32 v233, v234, v233
	v_div_scale_f32 v234, vcc, 1.0, v137, 1.0
	v_mul_f32_e32 v235, v234, v233
	v_fma_f32 v236, -v232, v235, v234
	v_fmac_f32_e32 v235, v236, v233
	v_fma_f32 v232, -v232, v235, v234
	v_div_fmas_f32 v232, v232, v233, v235
	v_div_fixup_f32 v137, v232, v137, 1.0
	v_mul_f32_e32 v138, s26, v138
	v_mul_f32_e32 v139, s26, v139
	v_fma_f32 v139, -v138, v138, v139
	v_max_f32_e32 v139, 0, v139
	v_add_f32_e32 v139, 0x3727c5ac, v139
	v_mul_f32_e32 v232, 0x4f800000, v139
	v_cmp_gt_f32_e32 vcc, s93, v139
	s_nop 1
	v_cndmask_b32_e32 v139, v139, v232, vcc
	v_sqrt_f32_e32 v232, v139
	s_nop 0
	v_add_u32_e32 v233, -1, v232
; __device__ __forceinline__ void build_tbl(const f32x2* PS, int pm, LAS unsigned char* lds, int wid, int lane) {
;     ...
;         if (lane == 0) { const float mu = a * (1.f / DM), var = fmaxf(b * (1.f / DM) - mu * mu, 0.f); tbl[wid * 32 + i] = (f32x2){mu, 1.f / sqrtf(var + LN_EPS)}; }
; __device__ __forceinline__ void ensure_tbl(const f32x2* PS, int sid, int pm, const EpiCtx& X) {
;     ...
;         if (X.tid == 0) keyw[0] = key;
	v_fma_f32 v235, -v233, v232, v139
	v_add_u32_e32 v234, 1, v232
	v_cmp_ge_f32_e64 s[18:19], 0, v235
	s_nop 1
	v_cndmask_b32_e64 v233, v232, v233, s[18:19]
	v_fma_f32 v232, -v234, v232, v139
	v_cmp_lt_f32_e64 s[18:19], 0, v232
	s_nop 1
	v_cndmask_b32_e64 v232, v233, v234, s[18:19]
	v_mul_f32_e32 v233, 0x37800000, v232
	v_cndmask_b32_e32 v232, v232, v233, vcc
	v_cmp_class_f32_e32 vcc, v139, v178
	s_nop 1
	v_cndmask_b32_e32 v139, v232, v139, vcc
	v_div_scale_f32 v232, s[18:19], v139, v139, 1.0
	v_rcp_f32_e32 v233, v232
	s_nop 0
	v_fma_f32 v234, -v232, v233, 1.0
	v_fmac_f32_e32 v233, v234, v233
	v_div_scale_f32 v234, vcc, 1.0, v139, 1.0
	v_mul_f32_e32 v235, v234, v233
	v_fma_f32 v236, -v232, v235, v234
	v_fmac_f32_e32 v235, v236, v233
	v_fma_f32 v232, -v232, v235, v234
	v_div_fmas_f32 v232, v232, v233, v235
	v_div_fixup_f32 v139, v232, v139, 1.0
	v_mul_f32_e32 v140, s26, v140
	v_mul_f32_e32 v141, s26, v141
	v_fma_f32 v141, -v140, v140, v141
	v_max_f32_e32 v141, 0, v141
	v_add_f32_e32 v141, 0x3727c5ac, v141
	v_mul_f32_e32 v232, 0x4f800000, v141
	v_cmp_gt_f32_e32 vcc, s93, v141
	s_nop 1
	v_cndmask_b32_e32 v141, v141, v232, vcc
	v_sqrt_f32_e32 v232, v141
	s_nop 0
	v_add_u32_e32 v233, -1, v232
	v_fma_f32 v235, -v233, v232, v141
	v_add_u32_e32 v234, 1, v232
	v_cmp_ge_f32_e64 s[18:19], 0, v235
	s_nop 1
	v_cndmask_b32_e64 v233, v232, v233, s[18:19]
	v_fma_f32 v232, -v234, v232, v141
	v_cmp_lt_f32_e64 s[18:19], 0, v232
	s_nop 1
	v_cndmask_b32_e64 v232, v233, v234, s[18:19]
	v_mul_f32_e32 v233, 0x37800000, v232
	v_cndmask_b32_e32 v232, v232, v233, vcc
	v_cmp_class_f32_e32 vcc, v141, v178
	s_nop 1
	v_cndmask_b32_e32 v141, v232, v141, vcc
	v_div_scale_f32 v232, s[18:19], v141, v141, 1.0
	v_rcp_f32_e32 v233, v232
	s_nop 0
	v_fma_f32 v234, -v232, v233, 1.0
	v_fmac_f32_e32 v233, v234, v233
	v_div_scale_f32 v234, vcc, 1.0, v141, 1.0
	v_mul_f32_e32 v235, v234, v233
	v_fma_f32 v236, -v232, v235, v234
	v_fmac_f32_e32 v235, v236, v233
	v_fma_f32 v232, -v232, v235, v234
	v_div_fmas_f32 v232, v232, v233, v235
	v_div_fixup_f32 v141, v232, v141, 1.0
	v_mul_f32_e32 v142, s26, v142
	v_mul_f32_e32 v143, s26, v143
	v_fma_f32 v143, -v142, v142, v143
	v_max_f32_e32 v143, 0, v143
	v_add_f32_e32 v143, 0x3727c5ac, v143
	v_mul_f32_e32 v232, 0x4f800000, v143
	v_cmp_gt_f32_e32 vcc, s93, v143
	s_nop 1
	v_cndmask_b32_e32 v143, v143, v232, vcc
	v_sqrt_f32_e32 v232, v143
	s_nop 0
	v_add_u32_e32 v233, -1, v232
	v_fma_f32 v235, -v233, v232, v143
	v_add_u32_e32 v234, 1, v232
	v_cmp_ge_f32_e64 s[18:19], 0, v235
	s_nop 1
	v_cndmask_b32_e64 v233, v232, v233, s[18:19]
	v_fma_f32 v232, -v234, v232, v143
	v_cmp_lt_f32_e64 s[18:19], 0, v232
	s_nop 1
	v_cndmask_b32_e64 v232, v233, v234, s[18:19]
	v_mul_f32_e32 v233, 0x37800000, v232
	v_cndmask_b32_e32 v232, v232, v233, vcc
	v_cmp_class_f32_e32 vcc, v143, v178
	s_nop 1
	v_cndmask_b32_e32 v143, v232, v143, vcc
	v_div_scale_f32 v232, s[18:19], v143, v143, 1.0
	v_rcp_f32_e32 v233, v232
	s_nop 0
	v_fma_f32 v234, -v232, v233, 1.0
	v_fmac_f32_e32 v233, v234, v233
	v_div_scale_f32 v234, vcc, 1.0, v143, 1.0
	v_mul_f32_e32 v235, v234, v233
	v_fma_f32 v236, -v232, v235, v234
	v_fmac_f32_e32 v235, v236, v233
	v_fma_f32 v232, -v232, v235, v234
	v_div_fmas_f32 v232, v232, v233, v235
	v_div_fixup_f32 v143, v232, v143, 1.0
	v_lshrrev_b32_e32 v237, 4, v179
	v_lshlrev_b32_e32 v237, 6, v237
	s_add_i32 s18, s87, 0x20400
	v_add_u32_e32 v237, s18, v237
	s_mov_b64 s[68:69], exec
	s_mov_b32 exec_lo, 0x10001
	s_mov_b32 exec_hi, 0x10001
	ds_write_b64 v237, v[128:129]
	ds_write_b64 v237, v[130:131] offset:8
	ds_write_b64 v237, v[132:133] offset:16
	ds_write_b64 v237, v[134:135] offset:24
	ds_write_b64 v237, v[136:137] offset:32
	ds_write_b64 v237, v[138:139] offset:40
	ds_write_b64 v237, v[140:141] offset:48
	ds_write_b64 v237, v[142:143] offset:56
	s_mov_b64 exec, s[68:69]

; #define LAS __attribute__((address_space(3)))
;     __device__ __forceinline__ void operator()(const f32x4 (&acc)[2][2][4][2], const Unit& u, int wr, int wc, int fr, int fq, const EpiCtx& X) const {
;     ...
;         char* yb = nullptr; char* xb = (char*)(XB + (size_t)u.pm * BM * DM + (size_t)(u.pn * 4 + wc) * (BM * 64));
;         unsigned lo = (unsigned)((wr * 64 + fe) * 64 + o32 + 8 * fq) * 2u; EPI_OPAQUE(lo);
;         const int col = u.pn * BM + wc * 64 + o32 + 8 * fq;
;         f32x4 g0, g1, b0, b1;
;         if (RESN) { ensure_tbl(PSp, sidp, u.pm, X);
;             g0 = *(const f32x4*)(gp + col); g1 = *(const f32x4*)(gp + col + 4); b0 = *(const f32x4*)(bp + col) * ALPHA; b1 = *(const f32x4*)(bp + col + 4) * ALPHA; }
;         const LAS f32x2* tbl = (const LAS f32x2*)(X.lds + TBL_OFF) + wr * 64 + fe;
;         f32x2* ps = PSn + ((size_t)u.pm * BM + wr * 64 + fe) * 64 + u.pn * 4 + wc;
; #pragma unroll
;         for (int ai = 0; ai < 2; ++ai) {
;             u32x4 raw[8];
; #pragma unroll
;             for (int m = 0; m < 4; ++m) { const unsigned off = lo + (unsigned)((ai * HALF + m * 16) * 64) * 2u; raw[2 * m] = *(const u32x4*)(xb + off); raw[2 * m + 1] = *(const u32x4*)(xb + off + 128); }
; #pragma unroll
;             for (int m = 0; m < 4; ++m) {
;                 const int rl = ai * HALF + m * 16; const unsigned off = lo + (unsigned)(rl * 64) * 2u;
;                 const f32x4 o0a = acc[ai][0][m][0], o0b = acc[ai][0][m][1], o1a = acc[ai][1][m][0], o1b = acc[ai][1][m][1];
;                 const f32x4 ra_ = dpp_swap1(odd ? o0a : o1a), rb_ = dpp_swap1(odd ? o0b : o1b);
;                 const f32x4 pa[2] = {odd ? ra_ : o0a, odd ? o1a : ra_}, pb[2] = {odd ? rb_ : o0b, odd ? o1b : rb_};
; #pragma unroll
;                 for (int q = 0; q < 2; ++q) {
;                     const u32x4 w0 = raw[2 * m + q];
;                     const f32x4 r0 = (f32x4){bf_lo(w0.x), bf_hi(w0.x), bf_lo(w0.y), bf_hi(w0.y)}, r1 = (f32x4){bf_lo(w0.z), bf_hi(w0.z), bf_lo(w0.w), bf_hi(w0.w)};
;                     f32x4 y0, y1;
;                     if (RESN) { const f32x2 t = tbl[rl + q]; const float mu = t.x, ra = t.y * ALPHA; y0 = (r0 - mu) * ra * g0 + b0 + pa[q]; y1 = (r1 - mu) * ra * g1 + b1 + pb[q]; }
;                     else { y0 = r0 * ALPHA + pa[q]; y1 = r1 * ALPHA + pb[q]; }
;                     { const u32x4 w = pack8f(y0, y1); *(u32x4*)(xb + off + q * 128) = w;
.LBB0_1463:
	s_load_dwordx2 s[94:95], s[0:1], 0xb0
	s_lshl_b32 s4, s64, 2
	s_or_b32 s4, s4, s41
	s_lshl_b32 s4, s4, 17
	s_lshl_b32 s5, s66, 11
	s_add_u32 s4, s4, s5
	s_add_u32 s4, s4, 0x5c800000
	v_lshrrev_b32_e32 v249, 4, v199
	s_waitcnt lgkmcnt(0)
	s_add_u32 s94, s94, s4
	s_addc_u32 s95, s95, 0
	s_lshl_b64 s[4:5], s[66:67], 21
	s_add_u32 s20, s51, s4
	s_addc_u32 s21, s53, s5
	s_lshl_b32 s66, s64, 2
	s_or_b32 s4, s66, s41
	s_ashr_i32 s5, s4, 31
	v_lshl_add_u32 v72, s64, 8, v200
	v_ashrrev_i32_e32 v73, 31, v72
	s_lshl_b64 s[4:5], s[4:5], 15
	v_lshlrev_b64 v[72:73], 2, v[72:73]
	s_add_u32 s20, s20, s4
	v_lshl_add_u64 v[74:75], s[26:27], 0, v[72:73]
	s_addc_u32 s21, s21, s5
	global_load_dwordx4 v[194:197], v[74:75], off offset:16
	global_load_dwordx4 v[178:181], v[74:75], off
	global_load_dwordx4 v[214:217], v164, s[20:21]
	v_lshl_add_u64 v[72:73], s[24:25], 0, v[72:73]
	s_waitcnt lgkmcnt(0)
	global_load_dwordx4 v[76:79], v[72:73], off
	s_nop 0
	global_load_dwordx4 v[72:75], v[72:73], off offset:16
	v_cndmask_b32_e64 v136, v135, v127, s[10:11]
	v_cndmask_b32_e64 v137, v134, v126, s[10:11]
	v_cndmask_b32_e64 v138, v133, v125, s[10:11]
	v_cndmask_b32_e64 v139, v132, v124, s[10:11]
	v_mov_b32_e32 v189, 0
	v_mov_b32_e32 v193, 0
	v_mov_b32_e32 v191, 0
	v_mov_b32_e32 v209, 0
	v_cndmask_b32_e64 v140, v131, v123, s[10:11]
	v_cndmask_b32_e64 v141, v130, v122, s[10:11]
	v_cndmask_b32_e64 v142, v129, v121, s[10:11]
	v_cndmask_b32_e64 v143, v128, v120, s[10:11]
	v_mov_b32_e32 v210, 0
	v_mov_b32_e32 v212, 0
	v_mov_b32_e32 v211, 0
	v_mov_b32_e32 v213, 0
	v_mov_b32_dpp v189, v139 quad_perm:[1,0,3,2] row_mask:0xf bank_mask:0xf
	v_mov_b32_dpp v193, v138 quad_perm:[1,0,3,2] row_mask:0xf bank_mask:0xf
	v_mov_b32_dpp v191, v137 quad_perm:[1,0,3,2] row_mask:0xf bank_mask:0xf
	v_mov_b32_dpp v209, v136 quad_perm:[1,0,3,2] row_mask:0xf bank_mask:0xf
	v_mov_b32_dpp v210, v143 quad_perm:[1,0,3,2] row_mask:0xf bank_mask:0xf
	v_mov_b32_dpp v212, v142 quad_perm:[1,0,3,2] row_mask:0xf bank_mask:0xf
	v_mov_b32_dpp v211, v141 quad_perm:[1,0,3,2] row_mask:0xf bank_mask:0xf
	v_mov_b32_dpp v213, v140 quad_perm:[1,0,3,2] row_mask:0xf bank_mask:0xf
	v_add_u32_e32 v192, 0x800, v164
	v_add_u32_e32 v190, 0x1000, v164
	v_add_u32_e32 v188, 0x1800, v164
	ds_read_b64 v[218:219], v201
	v_cndmask_b32_e64 v221, v193, v133, s[10:11]
	v_cndmask_b32_e64 v220, v189, v132, s[10:11]
	v_cndmask_b32_e64 v223, v209, v135, s[10:11]
	v_cndmask_b32_e64 v222, v191, v134, s[10:11]
	v_cndmask_b32_e64 v225, v212, v129, s[10:11]
	v_cndmask_b32_e64 v224, v210, v128, s[10:11]
	v_cndmask_b32_e64 v227, v213, v131, s[10:11]
	v_cndmask_b32_e64 v226, v211, v130, s[10:11]
	global_load_dwordx4 v[152:155], v164, s[20:21] offset:128
	global_load_dwordx4 v[148:151], v192, s[20:21]
	global_load_dwordx4 v[144:147], v192, s[20:21] offset:128
	global_load_dwordx4 v[140:143], v190, s[20:21]
	global_load_dwordx4 v[136:139], v190, s[20:21] offset:128
	global_load_dwordx4 v[132:135], v188, s[20:21]
	global_load_dwordx4 v[128:131], v188, s[20:21] offset:128
	s_waitcnt lgkmcnt(0)
	v_mul_f32_e32 v208, 0x3fb504f3, v219
	v_lshl_add_u64 v[186:187], v[166:167], 0, s[68:69]
	s_ashr_i32 s67, s66, 31
	v_lshl_add_u64 v[186:187], s[66:67], 3, v[186:187]
	v_lshl_add_u64 v[186:187], v[186:187], 0, s[22:23]
	v_add_u32_e32 v246, 0x4000, v164
	v_add_u32_e32 v247, 0x4800, v164
	global_load_dwordx4 v[230:233], v246, s[20:21]
	global_load_dwordx4 v[234:237], v246, s[20:21] offset:128
	global_load_dwordx4 v[238:241], v247, s[20:21]
	global_load_dwordx4 v[242:245], v247, s[20:21] offset:128
	s_waitcnt vmcnt(0)
	v_pk_mul_f32 v[182:183], v[180:181], s[52:53] op_sel_hi:[1,0]
	v_pk_mul_f32 v[184:185], v[178:179], s[52:53] op_sel_hi:[1,0]
	v_pk_mul_f32 v[178:179], v[196:197], s[52:53] op_sel_hi:[1,0]
	v_pk_mul_f32 v[180:181], v[194:195], s[52:53] op_sel_hi:[1,0]
	v_lshlrev_b32_e32 v194, 16, v214
	v_and_b32_e32 v195, 0xffff0000, v214
	v_lshlrev_b32_e32 v196, 16, v215
	v_and_b32_e32 v197, 0xffff0000, v215
	v_lshlrev_b32_e32 v207, 16, v216
	v_and_b32_e32 v214, 0xffff0000, v216
	v_lshlrev_b32_e32 v216, 16, v217
	v_and_b32_e32 v217, 0xffff0000, v217
	v_sub_f32_e32 v195, v195, v218
	v_sub_f32_e32 v194, v194, v218
	v_sub_f32_e32 v197, v197, v218
	v_sub_f32_e32 v196, v196, v218
	v_sub_f32_e32 v215, v214, v218
	v_sub_f32_e32 v214, v207, v218
	v_sub_f32_e32 v217, v217, v218
	v_sub_f32_e32 v216, v216, v218
	v_pk_mul_f32 v[196:197], v[196:197], v[208:209] op_sel_hi:[1,0]
	v_pk_mul_f32 v[194:195], v[194:195], v[208:209] op_sel_hi:[1,0]
	v_pk_mul_f32 v[216:217], v[216:217], v[208:209] op_sel_hi:[1,0]
	v_pk_mul_f32 v[214:215], v[214:215], v[208:209] op_sel_hi:[1,0]
	v_pk_fma_f32 v[194:195], v[76:77], v[194:195], v[184:185]
	v_pk_fma_f32 v[196:197], v[78:79], v[196:197], v[182:183]
	v_pk_fma_f32 v[214:215], v[72:73], v[214:215], v[180:181]
	v_pk_fma_f32 v[216:217], v[74:75], v[216:217], v[178:179]
	v_pk_add_f32 v[196:197], v[222:223], v[196:197]
	v_pk_add_f32 v[194:195], v[220:221], v[194:195]
	v_pk_add_f32 v[218:219], v[226:227], v[216:217]
	v_pk_add_f32 v[216:217], v[224:225], v[214:215]
	v_cvt_pk_bf16_f32 v214, v194, v195
	v_cvt_pk_bf16_f32 v215, v196, v197
	v_and_b32_e32 v208, 64, v206
	v_cvt_pk_bf16_f32 v216, v216, v217
	v_cvt_pk_bf16_f32 v217, v218, v219
	v_lshlrev_b32_e32 v194, 16, v214
	v_and_b32_e32 v196, 0xffff0000, v214
	v_lshlrev_b32_e32 v218, 16, v215
	v_and_b32_e32 v220, 0xffff0000, v215
	v_lshlrev_b32_e32 v222, 16, v216
	v_and_b32_e32 v224, 0xffff0000, v216
	v_lshlrev_b32_e32 v226, 16, v217
	v_and_b32_e32 v228, 0xffff0000, v217
	v_mul_f32_e32 v195, v194, v194
	v_mul_f32_e32 v197, v196, v196
	v_mul_f32_e32 v219, v218, v218
	v_mul_f32_e32 v221, v220, v220
	v_mul_f32_e32 v223, v222, v222
	v_mul_f32_e32 v225, v224, v224
	v_mul_f32_e32 v227, v226, v226
	v_mul_f32_e32 v229, v228, v228
	v_pk_add_f32 v[194:195], v[194:195], v[196:197]
	v_pk_add_f32 v[196:197], v[218:219], v[220:221]
	v_pk_add_f32 v[218:219], v[226:227], v[228:229]
	v_pk_add_f32 v[194:195], v[194:195], v[196:197]
	v_pk_add_f32 v[196:197], v[222:223], v[224:225]
	v_xor_b32_e32 v207, 16, v206
	v_add_u32_e32 v208, 64, v208
	v_pk_add_f32 v[196:197], v[196:197], v[218:219]
	v_cmp_lt_i32_e32 vcc, v207, v208
	v_pk_add_f32 v[194:195], v[194:195], v[196:197]
	v_mov_b32_e32 v196, 0
	v_mov_b32_e32 v197, 0
	v_cndmask_b32_e32 v207, v206, v207, vcc
	v_mov_b32_dpp v196, v194 quad_perm:[1,0,3,2] row_mask:0xf bank_mask:0xf
	v_mov_b32_dpp v197, v195 quad_perm:[1,0,3,2] row_mask:0xf bank_mask:0xf
	v_lshlrev_b32_e32 v207, 2, v207
	v_pk_add_f32 v[194:195], v[194:195], v[196:197]
	ds_bpermute_b32 v196, v207, v194
	ds_bpermute_b32 v197, v207, v195
	v_xor_b32_e32 v218, 32, v206
	v_cmp_lt_i32_e32 vcc, v218, v208
	global_store_dwordx4 v164, v[214:217], s[20:21]
	s_waitcnt lgkmcnt(0)
	v_pk_add_f32 v[194:195], v[194:195], v[196:197]
	v_cndmask_b32_e32 v208, v206, v218, vcc
	v_lshlrev_b32_e32 v208, 2, v208
	ds_bpermute_b32 v196, v208, v194
	ds_bpermute_b32 v197, v208, v195
	s_and_saveexec_b64 s[64:65], s[16:17]
	s_cbranch_execz .LBB0_1465
; __device__ __forceinline__ u32x4 pack8f(f32x4 a, f32x4 b) { u32x4 w; w.x = cvt_pk_bf16(a[0], a[1]); w.y = cvt_pk_bf16(a[2], a[3]); w.z = cvt_pk_bf16(b[0], b[1]); w.w = cvt_pk_bf16(b[2], b[3]); return w; }
; __device__ __forceinline__ float dpp_x1(float x) { return __builtin_bit_cast(float, __builtin_amdgcn_update_dpp(0, __builtin_bit_cast(int, x), 0xB1, 0xF, 0xF, false)); }
;     __device__ __forceinline__ void operator()(const f32x4 (&acc)[2][2][4][2], const Unit& u, int wr, int wc, int fr, int fq, const EpiCtx& X) const {
;     ...
;                 for (int q = 0; q < 2; ++q) {
;                     const u32x4 w0 = raw[2 * m + q];
;                     const f32x4 r0 = (f32x4){bf_lo(w0.x), bf_hi(w0.x), bf_lo(w0.y), bf_hi(w0.y)}, r1 = (f32x4){bf_lo(w0.z), bf_hi(w0.z), bf_lo(w0.w), bf_hi(w0.w)};
;                     f32x4 y0, y1;
;                     if (RESN) { const f32x2 t = tbl[rl + q]; const float mu = t.x, ra = t.y * ALPHA; y0 = (r0 - mu) * ra * g0 + b0 + pa[q]; y1 = (r1 - mu) * ra * g1 + b1 + pb[q]; }
;                     else { y0 = r0 * ALPHA + pa[q]; y1 = r1 * ALPHA + pb[q]; }
;                     { const u32x4 w = pack8f(y0, y1); *(u32x4*)(xb + off + q * 128) = w;
;                         y0 = (f32x4){bf_lo(w.x), bf_hi(w.x), bf_lo(w.y), bf_hi(w.y)}; y1 = (f32x4){bf_lo(w.z), bf_hi(w.z), bf_lo(w.w), bf_hi(w.w)}; }
;                     float sa = ((y0[0] + y0[1]) + (y0[2] + y0[3])) + ((y1[0] + y1[1]) + (y1[2] + y1[3]));
;                     float sb = ((y0[0] * y0[0] + y0[1] * y0[1]) + (y0[2] * y0[2] + y0[3] * y0[3])) + ((y1[0] * y1[0] + y1[1] * y1[1]) + (y1[2] * y1[2] + y1[3] * y1[3]));
;                     sa += dpp_x1(sa);
;                     sb += dpp_x1(sb);
;                     sa += __shfl_xor(sa, 16); sa += __shfl_xor(sa, 32); sb += __shfl_xor(sb, 16); sb += __shfl_xor(sb, 32);
;                     if (fq == 0 && !odd) ps[(size_t)(rl + q) * 64] = (f32x2){sa, sb};
	s_waitcnt lgkmcnt(0)
	v_pk_add_f32 v[194:195], v[194:195], v[196:197]
	v_mov_b32_e32 v250, v194
	v_mov_b32_e32 v251, v195
.LBB0_1465:
	s_or_b64 exec, exec, s[64:65]
	v_cndmask_b32_e64 v125, v125, v193, s[10:11]
	v_cndmask_b32_e64 v124, v124, v189, s[10:11]
	v_cndmask_b32_e64 v126, v126, v191, s[10:11]
	v_lshlrev_b32_e32 v189, 16, v152
	v_and_b32_e32 v191, 0xffff0000, v152
	v_lshlrev_b32_e32 v193, 16, v153
	s_waitcnt lgkmcnt(1)
	v_and_b32_e32 v196, 0xffff0000, v153
	ds_read_b64 v[152:153], v201 offset:8
	v_cndmask_b32_e64 v127, v127, v209, s[10:11]
	v_cndmask_b32_e64 v120, v120, v210, s[10:11]
	v_cndmask_b32_e64 v122, v122, v211, s[10:11]
	v_lshlrev_b32_e32 v209, 16, v154
	v_and_b32_e32 v210, 0xffff0000, v154
	v_lshlrev_b32_e32 v211, 16, v155
	v_and_b32_e32 v155, 0xffff0000, v155
	s_waitcnt lgkmcnt(0)
	v_mul_f32_e32 v154, 0x3fb504f3, v153
	v_sub_f32_e32 v195, v191, v152
	v_sub_f32_e32 v194, v189, v152
	v_pk_mul_f32 v[194:195], v[194:195], v[154:155] op_sel_hi:[1,0]
	v_sub_f32_e32 v197, v196, v152
	v_pk_fma_f32 v[194:195], v[76:77], v[194:195], v[184:185]
	v_sub_f32_e32 v196, v193, v152
	v_pk_add_f32 v[124:125], v[124:125], v[194:195]
	v_sub_f32_e32 v195, v210, v152
	v_sub_f32_e32 v194, v209, v152
	v_sub_f32_e32 v153, v155, v152
	v_sub_f32_e32 v152, v211, v152
	v_pk_mul_f32 v[196:197], v[196:197], v[154:155] op_sel_hi:[1,0]
	v_pk_mul_f32 v[152:153], v[152:153], v[154:155] op_sel_hi:[1,0]
	v_pk_mul_f32 v[154:155], v[194:195], v[154:155] op_sel_hi:[1,0]
	v_cndmask_b32_e64 v121, v121, v212, s[10:11]
	v_cndmask_b32_e64 v123, v123, v213, s[10:11]
	v_pk_fma_f32 v[196:197], v[78:79], v[196:197], v[182:183]
	v_pk_fma_f32 v[154:155], v[72:73], v[154:155], v[180:181]
	v_pk_fma_f32 v[152:153], v[74:75], v[152:153], v[178:179]
	v_pk_add_f32 v[126:127], v[126:127], v[196:197]
	v_pk_add_f32 v[122:123], v[122:123], v[152:153]
	v_pk_add_f32 v[120:121], v[120:121], v[154:155]
	v_cvt_pk_bf16_f32 v124, v124, v125
	v_cvt_pk_bf16_f32 v125, v126, v127
	s_nop 0
	v_cvt_pk_bf16_f32 v126, v120, v121
	v_cvt_pk_bf16_f32 v127, v122, v123
	v_lshlrev_b32_e32 v120, 16, v124
	v_and_b32_e32 v122, 0xffff0000, v124
	v_lshlrev_b32_e32 v152, 16, v125
	v_and_b32_e32 v154, 0xffff0000, v125
	v_lshlrev_b32_e32 v194, 16, v126
	v_and_b32_e32 v196, 0xffff0000, v126
	v_lshlrev_b32_e32 v210, 16, v127
	v_and_b32_e32 v212, 0xffff0000, v127
	v_mul_f32_e32 v121, v120, v120
	v_mul_f32_e32 v123, v122, v122
	v_mul_f32_e32 v153, v152, v152
	v_mul_f32_e32 v155, v154, v154
	v_mul_f32_e32 v195, v194, v194
	v_mul_f32_e32 v197, v196, v196
	v_mul_f32_e32 v211, v210, v210
	v_mul_f32_e32 v213, v212, v212
	v_pk_add_f32 v[120:121], v[120:121], v[122:123]
	v_pk_add_f32 v[122:123], v[152:153], v[154:155]
	v_pk_add_f32 v[152:153], v[210:211], v[212:213]
	v_pk_add_f32 v[120:121], v[120:121], v[122:123]
	v_pk_add_f32 v[122:123], v[194:195], v[196:197]
	s_nop 0
	v_pk_add_f32 v[122:123], v[122:123], v[152:153]
	v_lshl_add_u64 v[152:153], s[20:21], 0, v[164:165]
	v_pk_add_f32 v[120:121], v[120:121], v[122:123]
	v_mov_b32_e32 v122, v165
	v_mov_b32_e32 v123, v165
	global_store_dwordx4 v[152:153], v[124:127], off offset:128
	v_mov_b32_dpp v122, v120 quad_perm:[1,0,3,2] row_mask:0xf bank_mask:0xf
	v_mov_b32_dpp v123, v121 quad_perm:[1,0,3,2] row_mask:0xf bank_mask:0xf
	v_pk_add_f32 v[120:121], v[120:121], v[122:123]
	ds_bpermute_b32 v122, v207, v120
	ds_bpermute_b32 v123, v207, v121
	s_waitcnt lgkmcnt(0)
	v_pk_add_f32 v[120:121], v[120:121], v[122:123]
	ds_bpermute_b32 v122, v208, v120
	ds_bpermute_b32 v123, v208, v121
	s_and_saveexec_b64 s[64:65], s[16:17]
	s_cbranch_execz .LBB0_1467
	s_waitcnt lgkmcnt(0)
	v_pk_add_f32 v[120:121], v[120:121], v[122:123]
	v_mov_b32_e32 v252, v250
	v_mov_b32_e32 v253, v251
	v_mov_b32_e32 v254, v120
	v_mov_b32_e32 v255, v121
	global_store_dwordx4 v249, v[252:255], s[94:95]
.LBB0_1467:
	s_or_b64 exec, exec, s[64:65]
	s_waitcnt lgkmcnt(1)
	v_cndmask_b32_e64 v122, v116, v108, s[10:11]
	v_mov_b32_e32 v120, 0
	v_cndmask_b32_e64 v121, v117, v109, s[10:11]
	s_waitcnt lgkmcnt(0)
	v_cndmask_b32_e64 v123, v118, v110, s[10:11]
	v_mov_b32_dpp v120, v122 quad_perm:[1,0,3,2] row_mask:0xf bank_mask:0xf
	v_mov_b32_e32 v122, 0
	v_cndmask_b32_e64 v124, v119, v111, s[10:11]
	v_cndmask_b32_e64 v126, v112, v104, s[10:11]
	v_mov_b32_dpp v122, v121 quad_perm:[1,0,3,2] row_mask:0xf bank_mask:0xf
	v_mov_b32_e32 v121, 0
	v_cndmask_b32_e64 v125, v113, v105, s[10:11]
	v_cndmask_b32_e64 v127, v114, v106, s[10:11]
	v_mov_b32_dpp v121, v123 quad_perm:[1,0,3,2] row_mask:0xf bank_mask:0xf
	v_mov_b32_e32 v123, 0
	v_cndmask_b32_e64 v152, v115, v107, s[10:11]
	v_and_b32_e32 v153, 0xffff0000, v148
	v_mov_b32_dpp v123, v124 quad_perm:[1,0,3,2] row_mask:0xf bank_mask:0xf
	v_mov_b32_e32 v124, 0
	v_lshlrev_b32_e32 v154, 16, v149
	v_and_b32_e32 v155, 0xffff0000, v149
	v_mov_b32_dpp v124, v126 quad_perm:[1,0,3,2] row_mask:0xf bank_mask:0xf
	v_mov_b32_e32 v126, 0
	v_lshlrev_b32_e32 v189, 16, v150
	v_and_b32_e32 v191, 0xffff0000, v150
	v_mov_b32_dpp v126, v125 quad_perm:[1,0,3,2] row_mask:0xf bank_mask:0xf
	v_mov_b32_e32 v125, 0
	v_lshlrev_b32_e32 v193, 16, v151
	v_and_b32_e32 v151, 0xffff0000, v151
	v_mov_b32_dpp v125, v127 quad_perm:[1,0,3,2] row_mask:0xf bank_mask:0xf
	v_mov_b32_e32 v127, 0
	v_cndmask_b32_e64 v117, v122, v117, s[10:11]
	v_cndmask_b32_e64 v116, v120, v116, s[10:11]
	v_mov_b32_dpp v127, v152 quad_perm:[1,0,3,2] row_mask:0xf bank_mask:0xf
	v_lshlrev_b32_e32 v152, 16, v148
	ds_read_b64 v[148:149], v201 offset:128
	v_cndmask_b32_e64 v119, v123, v119, s[10:11]
	v_cndmask_b32_e64 v118, v121, v118, s[10:11]
	v_cndmask_b32_e64 v113, v126, v113, s[10:11]
	v_cndmask_b32_e64 v112, v124, v112, s[10:11]
	s_waitcnt lgkmcnt(0)
; __device__ __forceinline__ u32x4 pack8f(f32x4 a, f32x4 b) { u32x4 w; w.x = cvt_pk_bf16(a[0], a[1]); w.y = cvt_pk_bf16(a[2], a[3]); w.z = cvt_pk_bf16(b[0], b[1]); w.w = cvt_pk_bf16(b[2], b[3]); return w; }
;     __device__ __forceinline__ void operator()(const f32x4 (&acc)[2][2][4][2], const Unit& u, int wr, int wc, int fr, int fq, const EpiCtx& X) const {
;     ...
;             for (int m = 0; m < 4; ++m) {
;                 const int rl = ai * HALF + m * 16; const unsigned off = lo + (unsigned)(rl * 64) * 2u;
;                 const f32x4 o0a = acc[ai][0][m][0], o0b = acc[ai][0][m][1], o1a = acc[ai][1][m][0], o1b = acc[ai][1][m][1];
;                 const f32x4 ra_ = dpp_swap1(odd ? o0a : o1a), rb_ = dpp_swap1(odd ? o0b : o1b);
;                 const f32x4 pa[2] = {odd ? ra_ : o0a, odd ? o1a : ra_}, pb[2] = {odd ? rb_ : o0b, odd ? o1b : rb_};
; #pragma unroll
;                 for (int q = 0; q < 2; ++q) {
;                     const u32x4 w0 = raw[2 * m + q];
;                     const f32x4 r0 = (f32x4){bf_lo(w0.x), bf_hi(w0.x), bf_lo(w0.y), bf_hi(w0.y)}, r1 = (f32x4){bf_lo(w0.z), bf_hi(w0.z), bf_lo(w0.w), bf_hi(w0.w)};
;                     f32x4 y0, y1;
;                     if (RESN) { const f32x2 t = tbl[rl + q]; const float mu = t.x, ra = t.y * ALPHA; y0 = (r0 - mu) * ra * g0 + b0 + pa[q]; y1 = (r1 - mu) * ra * g1 + b1 + pb[q]; }
;                     else { y0 = r0 * ALPHA + pa[q]; y1 = r1 * ALPHA + pb[q]; }
;                     { const u32x4 w = pack8f(y0, y1); *(u32x4*)(xb + off + q * 128) = w;
;                         y0 = (f32x4){bf_lo(w.x), bf_hi(w.x), bf_lo(w.y), bf_hi(w.y)}; y1 = (f32x4){bf_lo(w.z), bf_hi(w.z), bf_lo(w.w), bf_hi(w.w)}; }
;                     float sa = ((y0[0] + y0[1]) + (y0[2] + y0[3])) + ((y1[0] + y1[1]) + (y1[2] + y1[3]));
;                     float sb = ((y0[0] * y0[0] + y0[1] * y0[1]) + (y0[2] * y0[2] + y0[3] * y0[3])) + ((y1[0] * y1[0] + y1[1] * y1[1]) + (y1[2] * y1[2] + y1[3] * y1[3]));
;                     sa += dpp_x1(sa);
;                     sb += dpp_x1(sb);
;                     sa += __shfl_xor(sa, 16); sa += __shfl_xor(sa, 32); sb += __shfl_xor(sb, 16); sb += __shfl_xor(sb, 32);
;                     if (fq == 0 && !odd) ps[(size_t)(rl + q) * 64] = (f32x2){sa, sb};
	v_mul_f32_e32 v150, 0x3fb504f3, v149
	v_sub_f32_e32 v153, v153, v148
	v_sub_f32_e32 v152, v152, v148
	v_pk_mul_f32 v[152:153], v[152:153], v[150:151] op_sel_hi:[1,0]
	v_sub_f32_e32 v155, v155, v148
	v_pk_fma_f32 v[152:153], v[76:77], v[152:153], v[184:185]
	v_sub_f32_e32 v154, v154, v148
	v_pk_add_f32 v[116:117], v[116:117], v[152:153]
	v_sub_f32_e32 v153, v191, v148
	v_sub_f32_e32 v152, v189, v148
	v_sub_f32_e32 v149, v151, v148
	v_sub_f32_e32 v148, v193, v148
	v_pk_mul_f32 v[154:155], v[154:155], v[150:151] op_sel_hi:[1,0]
	v_pk_mul_f32 v[148:149], v[148:149], v[150:151] op_sel_hi:[1,0]
	v_pk_mul_f32 v[150:151], v[152:153], v[150:151] op_sel_hi:[1,0]
	v_cndmask_b32_e64 v115, v127, v115, s[10:11]
	v_cndmask_b32_e64 v114, v125, v114, s[10:11]
	v_pk_fma_f32 v[154:155], v[78:79], v[154:155], v[182:183]
	v_pk_fma_f32 v[150:151], v[72:73], v[150:151], v[180:181]
	v_pk_fma_f32 v[148:149], v[74:75], v[148:149], v[178:179]
	v_pk_add_f32 v[118:119], v[118:119], v[154:155]
	v_pk_add_f32 v[114:115], v[114:115], v[148:149]
	v_pk_add_f32 v[112:113], v[112:113], v[150:151]
	v_cvt_pk_bf16_f32 v148, v116, v117
	v_cvt_pk_bf16_f32 v149, v118, v119
	v_mov_b32_e32 v193, v165
	v_cvt_pk_bf16_f32 v150, v112, v113
	v_cvt_pk_bf16_f32 v151, v114, v115
	v_lshlrev_b32_e32 v112, 16, v148
	v_and_b32_e32 v114, 0xffff0000, v148
	v_lshlrev_b32_e32 v116, 16, v149
	v_and_b32_e32 v118, 0xffff0000, v149
	v_lshlrev_b32_e32 v152, 16, v150
	v_and_b32_e32 v154, 0xffff0000, v150
	v_lshlrev_b32_e32 v194, 16, v151
	v_and_b32_e32 v196, 0xffff0000, v151
	v_mul_f32_e32 v113, v112, v112
	v_mul_f32_e32 v115, v114, v114
	v_mul_f32_e32 v117, v116, v116
	v_mul_f32_e32 v119, v118, v118
	v_mul_f32_e32 v153, v152, v152
	v_mul_f32_e32 v155, v154, v154
	v_mul_f32_e32 v195, v194, v194
	v_mul_f32_e32 v197, v196, v196
	v_pk_add_f32 v[112:113], v[112:113], v[114:115]
	v_pk_add_f32 v[114:115], v[116:117], v[118:119]
	v_pk_add_f32 v[116:117], v[194:195], v[196:197]
	v_pk_add_f32 v[112:113], v[112:113], v[114:115]
	v_pk_add_f32 v[114:115], v[152:153], v[154:155]
	s_nop 0
	v_pk_add_f32 v[114:115], v[114:115], v[116:117]
	s_nop 0
	v_pk_add_f32 v[112:113], v[112:113], v[114:115]
	v_mov_b32_e32 v114, v165
	v_mov_b32_e32 v115, v165
	s_nop 0
	v_mov_b32_dpp v114, v112 quad_perm:[1,0,3,2] row_mask:0xf bank_mask:0xf
	v_mov_b32_dpp v115, v113 quad_perm:[1,0,3,2] row_mask:0xf bank_mask:0xf
	v_pk_add_f32 v[112:113], v[112:113], v[114:115]
	ds_bpermute_b32 v114, v207, v112
	ds_bpermute_b32 v115, v207, v113
	s_waitcnt lgkmcnt(0)
	v_pk_add_f32 v[114:115], v[112:113], v[114:115]
	ds_bpermute_b32 v116, v208, v114
	ds_bpermute_b32 v117, v208, v115
	v_lshl_add_u64 v[112:113], s[20:21], 0, v[192:193]
	global_store_dwordx4 v[112:113], v[148:151], off
	s_and_saveexec_b64 s[64:65], s[16:17]
	s_cbranch_execz .LBB0_1469
	s_waitcnt lgkmcnt(0)
	v_pk_add_f32 v[114:115], v[114:115], v[116:117]
	v_add_co_u32_e32 v116, vcc, 0x2000, v186
	s_nop 1
	v_addc_co_u32_e32 v117, vcc, 0, v187, vcc
	v_mov_b32_e32 v250, v114
	v_mov_b32_e32 v251, v115
.LBB0_1469:
	s_or_b64 exec, exec, s[64:65]
	ds_read_b64 v[114:115], v201 offset:136
	s_waitcnt lgkmcnt(1)
	v_lshlrev_b32_e32 v117, 16, v144
	v_and_b32_e32 v118, 0xffff0000, v144
	v_cndmask_b32_e64 v109, v109, v122, s[10:11]
	v_cndmask_b32_e64 v108, v108, v120, s[10:11]
	s_waitcnt lgkmcnt(0)
	v_mul_f32_e32 v116, 0x3fb504f3, v115
	v_sub_f32_e32 v119, v118, v114
	v_sub_f32_e32 v118, v117, v114
	v_pk_mul_f32 v[118:119], v[118:119], v[116:117] op_sel_hi:[1,0]
	v_cndmask_b32_e64 v111, v111, v123, s[10:11]
	v_cndmask_b32_e64 v110, v110, v121, s[10:11]
	v_cndmask_b32_e64 v104, v104, v124, s[10:11]
	v_cndmask_b32_e64 v106, v106, v125, s[10:11]
	v_lshlrev_b32_e32 v120, 16, v145
	v_and_b32_e32 v121, 0xffff0000, v145
	v_lshlrev_b32_e32 v122, 16, v146
	v_and_b32_e32 v123, 0xffff0000, v146
	v_lshlrev_b32_e32 v124, 16, v147
	v_and_b32_e32 v125, 0xffff0000, v147
	v_pk_fma_f32 v[118:119], v[76:77], v[118:119], v[184:185]
	v_sub_f32_e32 v121, v121, v114
	v_sub_f32_e32 v120, v120, v114
	v_pk_add_f32 v[108:109], v[108:109], v[118:119]
	v_sub_f32_e32 v119, v123, v114
	v_sub_f32_e32 v118, v122, v114
	v_sub_f32_e32 v115, v125, v114
	v_sub_f32_e32 v114, v124, v114
	v_pk_mul_f32 v[120:121], v[120:121], v[116:117] op_sel_hi:[1,0]
	v_pk_mul_f32 v[114:115], v[114:115], v[116:117] op_sel_hi:[1,0]
	v_pk_mul_f32 v[116:117], v[118:119], v[116:117] op_sel_hi:[1,0]
	v_cndmask_b32_e64 v105, v105, v126, s[10:11]
	v_cndmask_b32_e64 v107, v107, v127, s[10:11]
	v_pk_fma_f32 v[120:121], v[78:79], v[120:121], v[182:183]
	v_pk_fma_f32 v[116:117], v[72:73], v[116:117], v[180:181]
	v_pk_fma_f32 v[114:115], v[74:75], v[114:115], v[178:179]
	v_pk_add_f32 v[110:111], v[110:111], v[120:121]
	v_pk_add_f32 v[106:107], v[106:107], v[114:115]
	v_pk_add_f32 v[104:105], v[104:105], v[116:117]
	v_cvt_pk_bf16_f32 v108, v108, v109
	v_cvt_pk_bf16_f32 v109, v110, v111
	s_nop 0
	v_cvt_pk_bf16_f32 v110, v104, v105
	v_cvt_pk_bf16_f32 v111, v106, v107
	v_lshlrev_b32_e32 v104, 16, v108
	v_and_b32_e32 v106, 0xffff0000, v108
	v_lshlrev_b32_e32 v114, 16, v109
	v_and_b32_e32 v116, 0xffff0000, v109
	v_lshlrev_b32_e32 v118, 16, v110
	v_and_b32_e32 v120, 0xffff0000, v110
	v_lshlrev_b32_e32 v122, 16, v111
	v_and_b32_e32 v124, 0xffff0000, v111
	v_mul_f32_e32 v105, v104, v104
	v_mul_f32_e32 v107, v106, v106
	v_mul_f32_e32 v115, v114, v114
	v_mul_f32_e32 v117, v116, v116
	v_mul_f32_e32 v119, v118, v118
	v_mul_f32_e32 v121, v120, v120
	v_mul_f32_e32 v123, v122, v122
	v_mul_f32_e32 v125, v124, v124
	v_pk_add_f32 v[104:105], v[104:105], v[106:107]
	v_pk_add_f32 v[106:107], v[114:115], v[116:117]
	v_pk_add_f32 v[114:115], v[122:123], v[124:125]
	v_pk_add_f32 v[104:105], v[104:105], v[106:107]
	v_pk_add_f32 v[106:107], v[118:119], v[120:121]
	global_store_dwordx4 v[112:113], v[108:111], off offset:128
	v_pk_add_f32 v[106:107], v[106:107], v[114:115]
	s_nop 0
	v_pk_add_f32 v[104:105], v[104:105], v[106:107]
	v_mov_b32_e32 v106, v165
	v_mov_b32_e32 v107, v165
	s_nop 0
	v_mov_b32_dpp v106, v104 quad_perm:[1,0,3,2] row_mask:0xf bank_mask:0xf
	v_mov_b32_dpp v107, v105 quad_perm:[1,0,3,2] row_mask:0xf bank_mask:0xf
	v_pk_add_f32 v[104:105], v[104:105], v[106:107]
	ds_bpermute_b32 v106, v207, v104
	ds_bpermute_b32 v107, v207, v105
	s_waitcnt lgkmcnt(0)
	v_pk_add_f32 v[104:105], v[104:105], v[106:107]
	ds_bpermute_b32 v106, v208, v104
	ds_bpermute_b32 v107, v208, v105
	s_and_saveexec_b64 s[64:65], s[16:17]
	s_cbranch_execz .LBB0_1471
	s_waitcnt lgkmcnt(0)
	v_pk_add_f32 v[104:105], v[104:105], v[106:107]
	v_add_co_u32_e32 v106, vcc, 0x2000, v186
	s_nop 1
	v_addc_co_u32_e32 v107, vcc, 0, v187, vcc
	v_mov_b32_e32 v252, v250
	v_mov_b32_e32 v253, v251
	v_mov_b32_e32 v254, v104
	v_mov_b32_e32 v255, v105
	global_store_dwordx4 v249, v[252:255], s[94:95] offset:128
; __device__ __forceinline__ u32x4 pack8f(f32x4 a, f32x4 b) { u32x4 w; w.x = cvt_pk_bf16(a[0], a[1]); w.y = cvt_pk_bf16(a[2], a[3]); w.z = cvt_pk_bf16(b[0], b[1]); w.w = cvt_pk_bf16(b[2], b[3]); return w; }
;     __device__ __forceinline__ void operator()(const f32x4 (&acc)[2][2][4][2], const Unit& u, int wr, int wc, int fr, int fq, const EpiCtx& X) const {
;     ...
;             for (int m = 0; m < 4; ++m) {
;                 const int rl = ai * HALF + m * 16; const unsigned off = lo + (unsigned)(rl * 64) * 2u;
;                 const f32x4 o0a = acc[ai][0][m][0], o0b = acc[ai][0][m][1], o1a = acc[ai][1][m][0], o1b = acc[ai][1][m][1];
;                 const f32x4 ra_ = dpp_swap1(odd ? o0a : o1a), rb_ = dpp_swap1(odd ? o0b : o1b);
;                 const f32x4 pa[2] = {odd ? ra_ : o0a, odd ? o1a : ra_}, pb[2] = {odd ? rb_ : o0b, odd ? o1b : rb_};
; #pragma unroll
;                 for (int q = 0; q < 2; ++q) {
;                     const u32x4 w0 = raw[2 * m + q];
;                     const f32x4 r0 = (f32x4){bf_lo(w0.x), bf_hi(w0.x), bf_lo(w0.y), bf_hi(w0.y)}, r1 = (f32x4){bf_lo(w0.z), bf_hi(w0.z), bf_lo(w0.w), bf_hi(w0.w)};
;                     f32x4 y0, y1;
;                     if (RESN) { const f32x2 t = tbl[rl + q]; const float mu = t.x, ra = t.y * ALPHA; y0 = (r0 - mu) * ra * g0 + b0 + pa[q]; y1 = (r1 - mu) * ra * g1 + b1 + pb[q]; }
;                     else { y0 = r0 * ALPHA + pa[q]; y1 = r1 * ALPHA + pb[q]; }
;                     { const u32x4 w = pack8f(y0, y1); *(u32x4*)(xb + off + q * 128) = w;
;                         y0 = (f32x4){bf_lo(w.x), bf_hi(w.x), bf_lo(w.y), bf_hi(w.y)}; y1 = (f32x4){bf_lo(w.z), bf_hi(w.z), bf_lo(w.w), bf_hi(w.w)}; }
;                     float sa = ((y0[0] + y0[1]) + (y0[2] + y0[3])) + ((y1[0] + y1[1]) + (y1[2] + y1[3]));
;                     float sb = ((y0[0] * y0[0] + y0[1] * y0[1]) + (y0[2] * y0[2] + y0[3] * y0[3])) + ((y1[0] * y1[0] + y1[1] * y1[1]) + (y1[2] * y1[2] + y1[3] * y1[3]));
;                     sa += dpp_x1(sa);
;                     sb += dpp_x1(sb);
;                     sa += __shfl_xor(sa, 16); sa += __shfl_xor(sa, 32); sb += __shfl_xor(sb, 16); sb += __shfl_xor(sb, 32);
;                     if (fq == 0 && !odd) ps[(size_t)(rl + q) * 64] = (f32x2){sa, sb};
.LBB0_1471:
	s_or_b64 exec, exec, s[64:65]
	s_waitcnt lgkmcnt(1)
	v_cndmask_b32_e64 v106, v100, v92, s[10:11]
	v_mov_b32_e32 v104, 0
	v_cndmask_b32_e64 v105, v101, v93, s[10:11]
	s_waitcnt lgkmcnt(0)
	v_cndmask_b32_e64 v107, v102, v94, s[10:11]
	v_mov_b32_dpp v104, v106 quad_perm:[1,0,3,2] row_mask:0xf bank_mask:0xf
	v_mov_b32_e32 v106, 0
	v_cndmask_b32_e64 v108, v103, v95, s[10:11]
	v_cndmask_b32_e64 v110, v96, v88, s[10:11]
	v_mov_b32_dpp v106, v105 quad_perm:[1,0,3,2] row_mask:0xf bank_mask:0xf
	v_mov_b32_e32 v105, 0
	v_cndmask_b32_e64 v109, v97, v89, s[10:11]
	v_cndmask_b32_e64 v111, v98, v90, s[10:11]
	v_mov_b32_dpp v105, v107 quad_perm:[1,0,3,2] row_mask:0xf bank_mask:0xf
	v_mov_b32_e32 v107, 0
	v_cndmask_b32_e64 v112, v99, v91, s[10:11]
	v_lshlrev_b32_e32 v115, 16, v140
	v_mov_b32_dpp v107, v108 quad_perm:[1,0,3,2] row_mask:0xf bank_mask:0xf
	v_mov_b32_e32 v108, 0
	v_and_b32_e32 v116, 0xffff0000, v140
	v_cndmask_b32_e64 v101, v106, v101, s[10:11]
	v_mov_b32_dpp v108, v110 quad_perm:[1,0,3,2] row_mask:0xf bank_mask:0xf
	v_mov_b32_e32 v110, 0
	v_cndmask_b32_e64 v100, v104, v100, s[10:11]
	v_lshlrev_b32_e32 v118, 16, v141
	v_mov_b32_dpp v110, v109 quad_perm:[1,0,3,2] row_mask:0xf bank_mask:0xf
	v_mov_b32_e32 v109, 0
	v_and_b32_e32 v119, 0xffff0000, v141
	v_lshlrev_b32_e32 v120, 16, v142
	v_mov_b32_dpp v109, v111 quad_perm:[1,0,3,2] row_mask:0xf bank_mask:0xf
	v_mov_b32_e32 v111, 0
	v_and_b32_e32 v121, 0xffff0000, v142
	v_lshlrev_b32_e32 v122, 16, v143
	v_mov_b32_dpp v111, v112 quad_perm:[1,0,3,2] row_mask:0xf bank_mask:0xf
	ds_read_b64 v[112:113], v201 offset:256
	v_and_b32_e32 v123, 0xffff0000, v143
	v_cndmask_b32_e64 v103, v107, v103, s[10:11]
	v_cndmask_b32_e64 v102, v105, v102, s[10:11]
	v_cndmask_b32_e64 v97, v110, v97, s[10:11]
	s_waitcnt lgkmcnt(0)
	v_mul_f32_e32 v114, 0x3fb504f3, v113
	v_sub_f32_e32 v117, v116, v112
	v_sub_f32_e32 v116, v115, v112
	v_pk_mul_f32 v[116:117], v[116:117], v[114:115] op_sel_hi:[1,0]
	v_sub_f32_e32 v119, v119, v112
	v_pk_fma_f32 v[116:117], v[76:77], v[116:117], v[184:185]
	v_sub_f32_e32 v118, v118, v112
	v_pk_add_f32 v[100:101], v[100:101], v[116:117]
	v_sub_f32_e32 v117, v121, v112
	v_sub_f32_e32 v116, v120, v112
	v_sub_f32_e32 v113, v123, v112
	v_sub_f32_e32 v112, v122, v112
	v_pk_mul_f32 v[118:119], v[118:119], v[114:115] op_sel_hi:[1,0]
	v_pk_mul_f32 v[112:113], v[112:113], v[114:115] op_sel_hi:[1,0]
	v_pk_mul_f32 v[114:115], v[116:117], v[114:115] op_sel_hi:[1,0]
	v_cndmask_b32_e64 v96, v108, v96, s[10:11]
	v_cndmask_b32_e64 v99, v111, v99, s[10:11]
	v_cndmask_b32_e64 v98, v109, v98, s[10:11]
	v_pk_fma_f32 v[118:119], v[78:79], v[118:119], v[182:183]
	v_pk_fma_f32 v[114:115], v[72:73], v[114:115], v[180:181]
	v_pk_fma_f32 v[112:113], v[74:75], v[112:113], v[178:179]
	v_pk_add_f32 v[102:103], v[102:103], v[118:119]
	v_pk_add_f32 v[98:99], v[98:99], v[112:113]
	v_pk_add_f32 v[96:97], v[96:97], v[114:115]
	v_cvt_pk_bf16_f32 v112, v100, v101
	v_cvt_pk_bf16_f32 v113, v102, v103
	v_mov_b32_e32 v191, v165
	v_cvt_pk_bf16_f32 v114, v96, v97
	v_cvt_pk_bf16_f32 v115, v98, v99
	v_lshlrev_b32_e32 v96, 16, v112
	v_and_b32_e32 v98, 0xffff0000, v112
	v_lshlrev_b32_e32 v100, 16, v113
	v_and_b32_e32 v102, 0xffff0000, v113
	v_lshlrev_b32_e32 v116, 16, v114
	v_and_b32_e32 v118, 0xffff0000, v114
	v_lshlrev_b32_e32 v120, 16, v115
	v_and_b32_e32 v122, 0xffff0000, v115
	v_mul_f32_e32 v97, v96, v96
	v_mul_f32_e32 v99, v98, v98
	v_mul_f32_e32 v101, v100, v100
	v_mul_f32_e32 v103, v102, v102
	v_mul_f32_e32 v117, v116, v116
	v_mul_f32_e32 v119, v118, v118
	v_mul_f32_e32 v121, v120, v120
	v_mul_f32_e32 v123, v122, v122
	v_pk_add_f32 v[96:97], v[96:97], v[98:99]
	v_pk_add_f32 v[98:99], v[100:101], v[102:103]
	v_pk_add_f32 v[100:101], v[120:121], v[122:123]
	v_pk_add_f32 v[96:97], v[96:97], v[98:99]
	v_pk_add_f32 v[98:99], v[116:117], v[118:119]
	s_nop 0
	v_pk_add_f32 v[98:99], v[98:99], v[100:101]
	s_nop 0
	v_pk_add_f32 v[96:97], v[96:97], v[98:99]
	v_mov_b32_e32 v98, v165
	v_mov_b32_e32 v99, v165
	s_nop 0
	v_mov_b32_dpp v98, v96 quad_perm:[1,0,3,2] row_mask:0xf bank_mask:0xf
	v_mov_b32_dpp v99, v97 quad_perm:[1,0,3,2] row_mask:0xf bank_mask:0xf
	v_pk_add_f32 v[96:97], v[96:97], v[98:99]
	ds_bpermute_b32 v98, v207, v96
	ds_bpermute_b32 v99, v207, v97
	s_waitcnt lgkmcnt(0)
	v_pk_add_f32 v[98:99], v[96:97], v[98:99]
	ds_bpermute_b32 v100, v208, v98
	ds_bpermute_b32 v101, v208, v99
	v_lshl_add_u64 v[96:97], s[20:21], 0, v[190:191]
	global_store_dwordx4 v[96:97], v[112:115], off
	s_and_saveexec_b64 s[64:65], s[16:17]
	s_cbranch_execz .LBB0_1473
	s_waitcnt lgkmcnt(0)
	v_pk_add_f32 v[98:99], v[98:99], v[100:101]
	v_add_co_u32_e32 v100, vcc, 0x4000, v186
	s_nop 1
	v_addc_co_u32_e32 v101, vcc, 0, v187, vcc
	v_mov_b32_e32 v250, v98
	v_mov_b32_e32 v251, v99
; __device__ __forceinline__ u32x4 pack8f(f32x4 a, f32x4 b) { u32x4 w; w.x = cvt_pk_bf16(a[0], a[1]); w.y = cvt_pk_bf16(a[2], a[3]); w.z = cvt_pk_bf16(b[0], b[1]); w.w = cvt_pk_bf16(b[2], b[3]); return w; }
;     __device__ __forceinline__ void operator()(const f32x4 (&acc)[2][2][4][2], const Unit& u, int wr, int wc, int fr, int fq, const EpiCtx& X) const {
;     ...
;             for (int m = 0; m < 4; ++m) {
;                 const int rl = ai * HALF + m * 16; const unsigned off = lo + (unsigned)(rl * 64) * 2u;
;                 const f32x4 o0a = acc[ai][0][m][0], o0b = acc[ai][0][m][1], o1a = acc[ai][1][m][0], o1b = acc[ai][1][m][1];
;                 const f32x4 ra_ = dpp_swap1(odd ? o0a : o1a), rb_ = dpp_swap1(odd ? o0b : o1b);
;                 const f32x4 pa[2] = {odd ? ra_ : o0a, odd ? o1a : ra_}, pb[2] = {odd ? rb_ : o0b, odd ? o1b : rb_};
; #pragma unroll
;                 for (int q = 0; q < 2; ++q) {
;                     const u32x4 w0 = raw[2 * m + q];
;                     const f32x4 r0 = (f32x4){bf_lo(w0.x), bf_hi(w0.x), bf_lo(w0.y), bf_hi(w0.y)}, r1 = (f32x4){bf_lo(w0.z), bf_hi(w0.z), bf_lo(w0.w), bf_hi(w0.w)};
;                     f32x4 y0, y1;
;                     if (RESN) { const f32x2 t = tbl[rl + q]; const float mu = t.x, ra = t.y * ALPHA; y0 = (r0 - mu) * ra * g0 + b0 + pa[q]; y1 = (r1 - mu) * ra * g1 + b1 + pb[q]; }
;                     else { y0 = r0 * ALPHA + pa[q]; y1 = r1 * ALPHA + pb[q]; }
;                     { const u32x4 w = pack8f(y0, y1); *(u32x4*)(xb + off + q * 128) = w;
;                         y0 = (f32x4){bf_lo(w.x), bf_hi(w.x), bf_lo(w.y), bf_hi(w.y)}; y1 = (f32x4){bf_lo(w.z), bf_hi(w.z), bf_lo(w.w), bf_hi(w.w)}; }
;                     float sa = ((y0[0] + y0[1]) + (y0[2] + y0[3])) + ((y1[0] + y1[1]) + (y1[2] + y1[3]));
;                     float sb = ((y0[0] * y0[0] + y0[1] * y0[1]) + (y0[2] * y0[2] + y0[3] * y0[3])) + ((y1[0] * y1[0] + y1[1] * y1[1]) + (y1[2] * y1[2] + y1[3] * y1[3]));
;                     sa += dpp_x1(sa);
;                     sb += dpp_x1(sb);
;                     sa += __shfl_xor(sa, 16); sa += __shfl_xor(sa, 32); sb += __shfl_xor(sb, 16); sb += __shfl_xor(sb, 32);
;                     if (fq == 0 && !odd) ps[(size_t)(rl + q) * 64] = (f32x2){sa, sb};
.LBB0_1473:
	s_or_b64 exec, exec, s[64:65]
	ds_read_b64 v[98:99], v201 offset:264
	s_waitcnt lgkmcnt(1)
	v_lshlrev_b32_e32 v101, 16, v136
	v_and_b32_e32 v102, 0xffff0000, v136
	v_cndmask_b32_e64 v93, v93, v106, s[10:11]
	v_cndmask_b32_e64 v92, v92, v104, s[10:11]
	s_waitcnt lgkmcnt(0)
	v_mul_f32_e32 v100, 0x3fb504f3, v99
	v_sub_f32_e32 v103, v102, v98
	v_sub_f32_e32 v102, v101, v98
	v_pk_mul_f32 v[102:103], v[102:103], v[100:101] op_sel_hi:[1,0]
	v_cndmask_b32_e64 v95, v95, v107, s[10:11]
	v_cndmask_b32_e64 v94, v94, v105, s[10:11]
	v_cndmask_b32_e64 v88, v88, v108, s[10:11]
	v_cndmask_b32_e64 v90, v90, v109, s[10:11]
	v_lshlrev_b32_e32 v104, 16, v137
	v_and_b32_e32 v105, 0xffff0000, v137
	v_lshlrev_b32_e32 v106, 16, v138
	v_and_b32_e32 v107, 0xffff0000, v138
	v_lshlrev_b32_e32 v108, 16, v139
	v_and_b32_e32 v109, 0xffff0000, v139
	v_pk_fma_f32 v[102:103], v[76:77], v[102:103], v[184:185]
	v_sub_f32_e32 v105, v105, v98
	v_sub_f32_e32 v104, v104, v98
	v_pk_add_f32 v[92:93], v[92:93], v[102:103]
	v_sub_f32_e32 v103, v107, v98
	v_sub_f32_e32 v102, v106, v98
	v_sub_f32_e32 v99, v109, v98
	v_sub_f32_e32 v98, v108, v98
	v_pk_mul_f32 v[104:105], v[104:105], v[100:101] op_sel_hi:[1,0]
	v_pk_mul_f32 v[98:99], v[98:99], v[100:101] op_sel_hi:[1,0]
	v_pk_mul_f32 v[100:101], v[102:103], v[100:101] op_sel_hi:[1,0]
	v_cndmask_b32_e64 v89, v89, v110, s[10:11]
	v_cndmask_b32_e64 v91, v91, v111, s[10:11]
	v_pk_fma_f32 v[104:105], v[78:79], v[104:105], v[182:183]
	v_pk_fma_f32 v[100:101], v[72:73], v[100:101], v[180:181]
	v_pk_fma_f32 v[98:99], v[74:75], v[98:99], v[178:179]
	v_pk_add_f32 v[94:95], v[94:95], v[104:105]
	v_pk_add_f32 v[90:91], v[90:91], v[98:99]
	v_pk_add_f32 v[88:89], v[88:89], v[100:101]
	v_cvt_pk_bf16_f32 v92, v92, v93
	v_cvt_pk_bf16_f32 v93, v94, v95
	s_nop 0
	v_cvt_pk_bf16_f32 v94, v88, v89
	v_cvt_pk_bf16_f32 v95, v90, v91
	v_lshlrev_b32_e32 v88, 16, v92
	v_and_b32_e32 v90, 0xffff0000, v92
	v_lshlrev_b32_e32 v98, 16, v93
	v_and_b32_e32 v100, 0xffff0000, v93
	v_lshlrev_b32_e32 v102, 16, v94
	v_and_b32_e32 v104, 0xffff0000, v94
	v_lshlrev_b32_e32 v106, 16, v95
	v_and_b32_e32 v108, 0xffff0000, v95
	v_mul_f32_e32 v89, v88, v88
	v_mul_f32_e32 v91, v90, v90
	v_mul_f32_e32 v99, v98, v98
	v_mul_f32_e32 v101, v100, v100
	v_mul_f32_e32 v103, v102, v102
	v_mul_f32_e32 v105, v104, v104
	v_mul_f32_e32 v107, v106, v106
	v_mul_f32_e32 v109, v108, v108
	v_pk_add_f32 v[88:89], v[88:89], v[90:91]
	v_pk_add_f32 v[90:91], v[98:99], v[100:101]
	v_pk_add_f32 v[98:99], v[106:107], v[108:109]
	v_pk_add_f32 v[88:89], v[88:89], v[90:91]
	v_pk_add_f32 v[90:91], v[102:103], v[104:105]
	global_store_dwordx4 v[96:97], v[92:95], off offset:128
	v_pk_add_f32 v[90:91], v[90:91], v[98:99]
	s_nop 0
	v_pk_add_f32 v[88:89], v[88:89], v[90:91]
	v_mov_b32_e32 v90, v165
	v_mov_b32_e32 v91, v165
	s_nop 0
	v_mov_b32_dpp v90, v88 quad_perm:[1,0,3,2] row_mask:0xf bank_mask:0xf
	v_mov_b32_dpp v91, v89 quad_perm:[1,0,3,2] row_mask:0xf bank_mask:0xf
	v_pk_add_f32 v[88:89], v[88:89], v[90:91]
	ds_bpermute_b32 v90, v207, v88
	ds_bpermute_b32 v91, v207, v89
	s_waitcnt lgkmcnt(0)
	v_pk_add_f32 v[88:89], v[88:89], v[90:91]
	ds_bpermute_b32 v90, v208, v88
	ds_bpermute_b32 v91, v208, v89
	s_and_saveexec_b64 s[64:65], s[16:17]
	s_cbranch_execz .LBB0_1475
	s_waitcnt lgkmcnt(0)
	v_pk_add_f32 v[88:89], v[88:89], v[90:91]
	v_add_co_u32_e32 v90, vcc, 0x4000, v186
	s_nop 1
	v_addc_co_u32_e32 v91, vcc, 0, v187, vcc
	v_mov_b32_e32 v252, v250
	v_mov_b32_e32 v253, v251
	v_mov_b32_e32 v254, v88
	v_mov_b32_e32 v255, v89
	global_store_dwordx4 v249, v[252:255], s[94:95] offset:256
.LBB0_1475:
	s_or_b64 exec, exec, s[64:65]
	s_waitcnt lgkmcnt(1)
	v_cndmask_b32_e64 v90, v84, v68, s[10:11]
	v_mov_b32_e32 v88, 0
	v_cndmask_b32_e64 v89, v85, v69, s[10:11]
	s_waitcnt lgkmcnt(0)
	v_cndmask_b32_e64 v91, v86, v70, s[10:11]
	v_mov_b32_dpp v88, v90 quad_perm:[1,0,3,2] row_mask:0xf bank_mask:0xf
	v_mov_b32_e32 v90, 0
	v_cndmask_b32_e64 v92, v87, v71, s[10:11]
	v_cndmask_b32_e64 v94, v80, v64, s[10:11]
	v_mov_b32_dpp v90, v89 quad_perm:[1,0,3,2] row_mask:0xf bank_mask:0xf
	v_mov_b32_e32 v89, 0
	v_cndmask_b32_e64 v93, v81, v65, s[10:11]
	v_cndmask_b32_e64 v95, v82, v66, s[10:11]
	v_mov_b32_dpp v89, v91 quad_perm:[1,0,3,2] row_mask:0xf bank_mask:0xf
	v_mov_b32_e32 v91, 0
	v_cndmask_b32_e64 v96, v83, v67, s[10:11]
	v_lshlrev_b32_e32 v99, 16, v132
	v_mov_b32_dpp v91, v92 quad_perm:[1,0,3,2] row_mask:0xf bank_mask:0xf
	v_mov_b32_e32 v92, 0
	v_and_b32_e32 v100, 0xffff0000, v132
	v_cndmask_b32_e64 v85, v90, v85, s[10:11]
	v_mov_b32_dpp v92, v94 quad_perm:[1,0,3,2] row_mask:0xf bank_mask:0xf
	v_mov_b32_e32 v94, 0
	v_cndmask_b32_e64 v84, v88, v84, s[10:11]
	v_lshlrev_b32_e32 v102, 16, v133
	v_mov_b32_dpp v94, v93 quad_perm:[1,0,3,2] row_mask:0xf bank_mask:0xf
	v_mov_b32_e32 v93, 0
	v_and_b32_e32 v103, 0xffff0000, v133
	v_lshlrev_b32_e32 v104, 16, v134
	v_mov_b32_dpp v93, v95 quad_perm:[1,0,3,2] row_mask:0xf bank_mask:0xf
	v_mov_b32_e32 v95, 0
	v_and_b32_e32 v105, 0xffff0000, v134
	v_lshlrev_b32_e32 v106, 16, v135
	v_mov_b32_dpp v95, v96 quad_perm:[1,0,3,2] row_mask:0xf bank_mask:0xf
	ds_read_b64 v[96:97], v201 offset:384
	v_and_b32_e32 v107, 0xffff0000, v135
	v_cndmask_b32_e64 v87, v91, v87, s[10:11]
	v_cndmask_b32_e64 v86, v89, v86, s[10:11]
	v_cndmask_b32_e64 v81, v94, v81, s[10:11]
	s_waitcnt lgkmcnt(0)
; __device__ __forceinline__ u32x4 pack8f(f32x4 a, f32x4 b) { u32x4 w; w.x = cvt_pk_bf16(a[0], a[1]); w.y = cvt_pk_bf16(a[2], a[3]); w.z = cvt_pk_bf16(b[0], b[1]); w.w = cvt_pk_bf16(b[2], b[3]); return w; }
;     __device__ __forceinline__ void operator()(const f32x4 (&acc)[2][2][4][2], const Unit& u, int wr, int wc, int fr, int fq, const EpiCtx& X) const {
;     ...
;             for (int m = 0; m < 4; ++m) {
;                 const int rl = ai * HALF + m * 16; const unsigned off = lo + (unsigned)(rl * 64) * 2u;
;                 const f32x4 o0a = acc[ai][0][m][0], o0b = acc[ai][0][m][1], o1a = acc[ai][1][m][0], o1b = acc[ai][1][m][1];
;                 const f32x4 ra_ = dpp_swap1(odd ? o0a : o1a), rb_ = dpp_swap1(odd ? o0b : o1b);
;                 const f32x4 pa[2] = {odd ? ra_ : o0a, odd ? o1a : ra_}, pb[2] = {odd ? rb_ : o0b, odd ? o1b : rb_};
; #pragma unroll
;                 for (int q = 0; q < 2; ++q) {
;                     const u32x4 w0 = raw[2 * m + q];
;                     const f32x4 r0 = (f32x4){bf_lo(w0.x), bf_hi(w0.x), bf_lo(w0.y), bf_hi(w0.y)}, r1 = (f32x4){bf_lo(w0.z), bf_hi(w0.z), bf_lo(w0.w), bf_hi(w0.w)};
;                     f32x4 y0, y1;
;                     if (RESN) { const f32x2 t = tbl[rl + q]; const float mu = t.x, ra = t.y * ALPHA; y0 = (r0 - mu) * ra * g0 + b0 + pa[q]; y1 = (r1 - mu) * ra * g1 + b1 + pb[q]; }
;                     else { y0 = r0 * ALPHA + pa[q]; y1 = r1 * ALPHA + pb[q]; }
;                     { const u32x4 w = pack8f(y0, y1); *(u32x4*)(xb + off + q * 128) = w;
;                         y0 = (f32x4){bf_lo(w.x), bf_hi(w.x), bf_lo(w.y), bf_hi(w.y)}; y1 = (f32x4){bf_lo(w.z), bf_hi(w.z), bf_lo(w.w), bf_hi(w.w)}; }
;                     float sa = ((y0[0] + y0[1]) + (y0[2] + y0[3])) + ((y1[0] + y1[1]) + (y1[2] + y1[3]));
;                     float sb = ((y0[0] * y0[0] + y0[1] * y0[1]) + (y0[2] * y0[2] + y0[3] * y0[3])) + ((y1[0] * y1[0] + y1[1] * y1[1]) + (y1[2] * y1[2] + y1[3] * y1[3]));
;                     sa += dpp_x1(sa);
;                     sb += dpp_x1(sb);
;                     sa += __shfl_xor(sa, 16); sa += __shfl_xor(sa, 32); sb += __shfl_xor(sb, 16); sb += __shfl_xor(sb, 32);
;                     if (fq == 0 && !odd) ps[(size_t)(rl + q) * 64] = (f32x2){sa, sb};
	v_mul_f32_e32 v98, 0x3fb504f3, v97
	v_sub_f32_e32 v101, v100, v96
	v_sub_f32_e32 v100, v99, v96
	v_pk_mul_f32 v[100:101], v[100:101], v[98:99] op_sel_hi:[1,0]
	v_sub_f32_e32 v103, v103, v96
	v_pk_fma_f32 v[100:101], v[76:77], v[100:101], v[184:185]
	v_sub_f32_e32 v102, v102, v96
	v_pk_add_f32 v[84:85], v[84:85], v[100:101]
	v_sub_f32_e32 v101, v105, v96
	v_sub_f32_e32 v100, v104, v96
	v_sub_f32_e32 v97, v107, v96
	v_sub_f32_e32 v96, v106, v96
	v_pk_mul_f32 v[102:103], v[102:103], v[98:99] op_sel_hi:[1,0]
	v_pk_mul_f32 v[96:97], v[96:97], v[98:99] op_sel_hi:[1,0]
	v_pk_mul_f32 v[98:99], v[100:101], v[98:99] op_sel_hi:[1,0]
	v_cndmask_b32_e64 v80, v92, v80, s[10:11]
	v_cndmask_b32_e64 v83, v95, v83, s[10:11]
	v_cndmask_b32_e64 v82, v93, v82, s[10:11]
	v_pk_fma_f32 v[102:103], v[78:79], v[102:103], v[182:183]
	v_pk_fma_f32 v[98:99], v[72:73], v[98:99], v[180:181]
	v_pk_fma_f32 v[96:97], v[74:75], v[96:97], v[178:179]
	v_pk_add_f32 v[86:87], v[86:87], v[102:103]
	v_pk_add_f32 v[82:83], v[82:83], v[96:97]
	v_pk_add_f32 v[80:81], v[80:81], v[98:99]
	v_cvt_pk_bf16_f32 v96, v84, v85
	v_cvt_pk_bf16_f32 v97, v86, v87
	v_mov_b32_e32 v189, v165
	v_cvt_pk_bf16_f32 v98, v80, v81
	v_cvt_pk_bf16_f32 v99, v82, v83
	v_lshlrev_b32_e32 v80, 16, v96
	v_and_b32_e32 v82, 0xffff0000, v96
	v_lshlrev_b32_e32 v84, 16, v97
	v_and_b32_e32 v86, 0xffff0000, v97
	v_lshlrev_b32_e32 v100, 16, v98
	v_and_b32_e32 v102, 0xffff0000, v98
	v_lshlrev_b32_e32 v104, 16, v99
	v_and_b32_e32 v106, 0xffff0000, v99
	v_mul_f32_e32 v81, v80, v80
	v_mul_f32_e32 v83, v82, v82
	v_mul_f32_e32 v85, v84, v84
	v_mul_f32_e32 v87, v86, v86
	v_mul_f32_e32 v101, v100, v100
	v_mul_f32_e32 v103, v102, v102
	v_mul_f32_e32 v105, v104, v104
	v_mul_f32_e32 v107, v106, v106
	v_pk_add_f32 v[80:81], v[80:81], v[82:83]
	v_pk_add_f32 v[82:83], v[84:85], v[86:87]
	v_pk_add_f32 v[84:85], v[104:105], v[106:107]
	v_pk_add_f32 v[80:81], v[80:81], v[82:83]
	v_pk_add_f32 v[82:83], v[100:101], v[102:103]
	s_nop 0
	v_pk_add_f32 v[82:83], v[82:83], v[84:85]
	s_nop 0
	v_pk_add_f32 v[80:81], v[80:81], v[82:83]
	v_mov_b32_e32 v82, v165
	v_mov_b32_e32 v83, v165
	s_nop 0
	v_mov_b32_dpp v82, v80 quad_perm:[1,0,3,2] row_mask:0xf bank_mask:0xf
	v_mov_b32_dpp v83, v81 quad_perm:[1,0,3,2] row_mask:0xf bank_mask:0xf
	v_pk_add_f32 v[80:81], v[80:81], v[82:83]
	ds_bpermute_b32 v82, v207, v80
	ds_bpermute_b32 v83, v207, v81
	s_waitcnt lgkmcnt(0)
	v_pk_add_f32 v[82:83], v[80:81], v[82:83]
	ds_bpermute_b32 v84, v208, v82
	ds_bpermute_b32 v85, v208, v83
	v_lshl_add_u64 v[80:81], s[20:21], 0, v[188:189]
	global_store_dwordx4 v[80:81], v[96:99], off
	s_and_saveexec_b64 s[64:65], s[16:17]
	s_cbranch_execz .LBB0_1477
	s_waitcnt lgkmcnt(0)
	v_pk_add_f32 v[82:83], v[82:83], v[84:85]
	v_add_co_u32_e32 v84, vcc, 0x6000, v186
	s_nop 1
	v_addc_co_u32_e32 v85, vcc, 0, v187, vcc
	v_mov_b32_e32 v250, v82
	v_mov_b32_e32 v251, v83
.LBB0_1477:
	s_or_b64 exec, exec, s[64:65]
	ds_read_b64 v[82:83], v201 offset:392
	s_waitcnt lgkmcnt(1)
	v_lshlrev_b32_e32 v85, 16, v128
	v_and_b32_e32 v86, 0xffff0000, v128
	v_cndmask_b32_e64 v69, v69, v90, s[10:11]
	v_cndmask_b32_e64 v68, v68, v88, s[10:11]
	s_waitcnt lgkmcnt(0)
	v_mul_f32_e32 v84, 0x3fb504f3, v83
	v_sub_f32_e32 v87, v86, v82
	v_sub_f32_e32 v86, v85, v82
	v_pk_mul_f32 v[86:87], v[86:87], v[84:85] op_sel_hi:[1,0]
	v_cndmask_b32_e64 v71, v71, v91, s[10:11]
	v_cndmask_b32_e64 v70, v70, v89, s[10:11]
	v_cndmask_b32_e64 v64, v64, v92, s[10:11]
	v_cndmask_b32_e64 v66, v66, v93, s[10:11]
	v_lshlrev_b32_e32 v88, 16, v129
	v_and_b32_e32 v89, 0xffff0000, v129
	v_lshlrev_b32_e32 v90, 16, v130
	v_and_b32_e32 v91, 0xffff0000, v130
	v_lshlrev_b32_e32 v92, 16, v131
	v_and_b32_e32 v93, 0xffff0000, v131
	v_pk_fma_f32 v[86:87], v[76:77], v[86:87], v[184:185]
	v_sub_f32_e32 v89, v89, v82
	v_sub_f32_e32 v88, v88, v82
	v_pk_add_f32 v[68:69], v[68:69], v[86:87]
	v_sub_f32_e32 v87, v91, v82
	v_sub_f32_e32 v86, v90, v82
	v_sub_f32_e32 v83, v93, v82
	v_sub_f32_e32 v82, v92, v82
	v_pk_mul_f32 v[88:89], v[88:89], v[84:85] op_sel_hi:[1,0]
	v_pk_mul_f32 v[82:83], v[82:83], v[84:85] op_sel_hi:[1,0]
	v_pk_mul_f32 v[84:85], v[86:87], v[84:85] op_sel_hi:[1,0]
	v_cndmask_b32_e64 v65, v65, v94, s[10:11]
	v_cndmask_b32_e64 v67, v67, v95, s[10:11]
	v_pk_fma_f32 v[88:89], v[78:79], v[88:89], v[182:183]
	v_pk_fma_f32 v[84:85], v[72:73], v[84:85], v[180:181]
	v_pk_fma_f32 v[82:83], v[74:75], v[82:83], v[178:179]
	v_pk_add_f32 v[70:71], v[70:71], v[88:89]
	v_pk_add_f32 v[66:67], v[66:67], v[82:83]
	v_pk_add_f32 v[64:65], v[64:65], v[84:85]
	v_cvt_pk_bf16_f32 v68, v68, v69
	v_cvt_pk_bf16_f32 v69, v70, v71
	s_nop 0
	v_cvt_pk_bf16_f32 v70, v64, v65
	v_cvt_pk_bf16_f32 v71, v66, v67
	v_lshlrev_b32_e32 v64, 16, v68
	v_and_b32_e32 v66, 0xffff0000, v68
	v_lshlrev_b32_e32 v82, 16, v69
	v_and_b32_e32 v84, 0xffff0000, v69
	v_lshlrev_b32_e32 v86, 16, v70
	v_and_b32_e32 v88, 0xffff0000, v70
	v_lshlrev_b32_e32 v90, 16, v71
	v_and_b32_e32 v92, 0xffff0000, v71
	v_mul_f32_e32 v65, v64, v64
	v_mul_f32_e32 v67, v66, v66
	v_mul_f32_e32 v83, v82, v82
	v_mul_f32_e32 v85, v84, v84
	v_mul_f32_e32 v87, v86, v86
	v_mul_f32_e32 v89, v88, v88
	v_mul_f32_e32 v91, v90, v90
	v_mul_f32_e32 v93, v92, v92
	v_pk_add_f32 v[64:65], v[64:65], v[66:67]
	v_pk_add_f32 v[66:67], v[82:83], v[84:85]
	v_pk_add_f32 v[82:83], v[90:91], v[92:93]
	v_pk_add_f32 v[64:65], v[64:65], v[66:67]
	v_pk_add_f32 v[66:67], v[86:87], v[88:89]
	global_store_dwordx4 v[80:81], v[68:71], off offset:128
	v_pk_add_f32 v[66:67], v[66:67], v[82:83]
	s_nop 0
	v_pk_add_f32 v[64:65], v[64:65], v[66:67]
	v_mov_b32_e32 v66, v165
	v_mov_b32_e32 v67, v165
	s_nop 0
	v_mov_b32_dpp v66, v64 quad_perm:[1,0,3,2] row_mask:0xf bank_mask:0xf
	v_mov_b32_dpp v67, v65 quad_perm:[1,0,3,2] row_mask:0xf bank_mask:0xf
	v_pk_add_f32 v[64:65], v[64:65], v[66:67]
	ds_bpermute_b32 v66, v207, v64
	ds_bpermute_b32 v67, v207, v65
	s_waitcnt lgkmcnt(0)
	v_pk_add_f32 v[64:65], v[64:65], v[66:67]
	ds_bpermute_b32 v66, v208, v64
	ds_bpermute_b32 v67, v208, v65
	s_and_saveexec_b64 s[64:65], s[16:17]
	s_cbranch_execz .LBB0_1479
	s_waitcnt lgkmcnt(0)
	v_pk_add_f32 v[64:65], v[64:65], v[66:67]
	v_add_co_u32_e32 v66, vcc, 0x6000, v186
	s_nop 1
	v_addc_co_u32_e32 v67, vcc, 0, v187, vcc
	v_mov_b32_e32 v252, v250
	v_mov_b32_e32 v253, v251
	v_mov_b32_e32 v254, v64
	v_mov_b32_e32 v255, v65
	global_store_dwordx4 v249, v[252:255], s[94:95] offset:384
;     __device__ __forceinline__ void operator()(const f32x4 (&acc)[2][2][4][2], const Unit& u, int wr, int wc, int fr, int fq, const EpiCtx& X) const {
;     ...
;             for (int m = 0; m < 4; ++m) { const unsigned off = lo + (unsigned)((ai * HALF + m * 16) * 64) * 2u; raw[2 * m] = *(const u32x4*)(xb + off); raw[2 * m + 1] = *(const u32x4*)(xb + off + 128); }
; #pragma unroll
;             for (int m = 0; m < 4; ++m) {
;                 const int rl = ai * HALF + m * 16; const unsigned off = lo + (unsigned)(rl * 64) * 2u;
;                 const f32x4 o0a = acc[ai][0][m][0], o0b = acc[ai][0][m][1], o1a = acc[ai][1][m][0], o1b = acc[ai][1][m][1];
;                 const f32x4 ra_ = dpp_swap1(odd ? o0a : o1a), rb_ = dpp_swap1(odd ? o0b : o1b);
;                 const f32x4 pa[2] = {odd ? ra_ : o0a, odd ? o1a : ra_}, pb[2] = {odd ? rb_ : o0b, odd ? o1b : rb_};
; #pragma unroll
;                 for (int q = 0; q < 2; ++q) {
;                     const u32x4 w0 = raw[2 * m + q];
;                     const f32x4 r0 = (f32x4){bf_lo(w0.x), bf_hi(w0.x), bf_lo(w0.y), bf_hi(w0.y)}, r1 = (f32x4){bf_lo(w0.z), bf_hi(w0.z), bf_lo(w0.w), bf_hi(w0.w)};
;                     f32x4 y0, y1;
;                     if (RESN) { const f32x2 t = tbl[rl + q]; const float mu = t.x, ra = t.y * ALPHA; y0 = (r0 - mu) * ra * g0 + b0 + pa[q]; y1 = (r1 - mu) * ra * g1 + b1 + pb[q]; }
;                     else { y0 = r0 * ALPHA + pa[q]; y1 = r1 * ALPHA + pb[q]; }
;                     { const u32x4 w = pack8f(y0, y1); *(u32x4*)(xb + off + q * 128) = w;
;                         y0 = (f32x4){bf_lo(w.x), bf_hi(w.x), bf_lo(w.y), bf_hi(w.y)}; y1 = (f32x4){bf_lo(w.z), bf_hi(w.z), bf_lo(w.w), bf_hi(w.w)}; }
;                     float sa = ((y0[0] + y0[1]) + (y0[2] + y0[3])) + ((y1[0] + y1[1]) + (y1[2] + y1[3]));
;                     float sb = ((y0[0] * y0[0] + y0[1] * y0[1]) + (y0[2] * y0[2] + y0[3] * y0[3])) + ((y1[0] * y1[0] + y1[1] * y1[1]) + (y1[2] * y1[2] + y1[3] * y1[3]));
;                     sa += dpp_x1(sa);
;                     sb += dpp_x1(sb);
;                     sa += __shfl_xor(sa, 16); sa += __shfl_xor(sa, 32); sb += __shfl_xor(sb, 16); sb += __shfl_xor(sb, 32);
;                     if (fq == 0 && !odd) ps[(size_t)(rl + q) * 64] = (f32x2){sa, sb};
.LBB0_1479:
	s_or_b64 exec, exec, s[64:65]
	v_add_u32_e32 v104, 0x4000, v164
	v_mov_b32_e32 v112, v230
	v_mov_b32_e32 v113, v231
	v_mov_b32_e32 v114, v232
	v_mov_b32_e32 v115, v233
	v_add_u32_e32 v102, 0x4800, v164
	v_add_u32_e32 v100, 0x5000, v164
	v_add_u32_e32 v164, 0x5800, v164
	v_mov_b32_e32 v96, v234
	v_mov_b32_e32 v97, v235
	v_mov_b32_e32 v98, v236
	v_mov_b32_e32 v99, v237
	v_mov_b32_e32 v92, v238
	v_mov_b32_e32 v93, v239
	v_mov_b32_e32 v94, v240
	v_mov_b32_e32 v95, v241
	v_mov_b32_e32 v88, v242
	v_mov_b32_e32 v89, v243
	v_mov_b32_e32 v90, v244
	v_mov_b32_e32 v91, v245
	global_load_dwordx4 v[84:87], v100, s[20:21]
	global_load_dwordx4 v[80:83], v100, s[20:21] offset:128
	global_load_dwordx4 v[68:71], v164, s[20:21]
	s_waitcnt lgkmcnt(0)
	global_load_dwordx4 v[64:67], v164, s[20:21] offset:128
	v_cndmask_b32_e64 v116, v62, v54, s[10:11]
	v_cndmask_b32_e64 v117, v61, v53, s[10:11]
	v_mov_b32_e32 v105, 0
	v_mov_b32_e32 v103, 0
	v_cndmask_b32_e64 v111, v63, v55, s[10:11]
	v_mov_b32_dpp v105, v117 quad_perm:[1,0,3,2] row_mask:0xf bank_mask:0xf
	v_mov_b32_dpp v103, v116 quad_perm:[1,0,3,2] row_mask:0xf bank_mask:0xf
	ds_read_b64 v[116:117], v201 offset:1024
	v_cndmask_b32_e64 v118, v60, v52, s[10:11]
	v_mov_b32_e32 v101, 0
	v_mov_b32_e32 v106, 0
	v_cndmask_b32_e64 v119, v59, v51, s[10:11]
	v_cndmask_b32_e64 v120, v58, v50, s[10:11]
	v_cndmask_b32_e64 v121, v57, v49, s[10:11]
	v_cndmask_b32_e64 v122, v56, v48, s[10:11]
	v_mov_b32_e32 v107, 0
	v_mov_b32_e32 v109, 0
	v_mov_b32_e32 v108, 0
	v_mov_b32_e32 v110, 0
	v_mov_b32_dpp v101, v118 quad_perm:[1,0,3,2] row_mask:0xf bank_mask:0xf
	v_mov_b32_dpp v106, v111 quad_perm:[1,0,3,2] row_mask:0xf bank_mask:0xf
	v_mov_b32_dpp v107, v122 quad_perm:[1,0,3,2] row_mask:0xf bank_mask:0xf
	v_mov_b32_dpp v109, v121 quad_perm:[1,0,3,2] row_mask:0xf bank_mask:0xf
	v_mov_b32_dpp v108, v120 quad_perm:[1,0,3,2] row_mask:0xf bank_mask:0xf
	v_mov_b32_dpp v110, v119 quad_perm:[1,0,3,2] row_mask:0xf bank_mask:0xf
	s_waitcnt lgkmcnt(0)
	v_mul_f32_e32 v118, 0x3fb504f3, v117
	v_cndmask_b32_e64 v61, v105, v61, s[10:11]
	v_cndmask_b32_e64 v60, v101, v60, s[10:11]
	v_cndmask_b32_e64 v63, v106, v63, s[10:11]
	v_cndmask_b32_e64 v62, v103, v62, s[10:11]
	v_cndmask_b32_e64 v57, v109, v57, s[10:11]
	v_cndmask_b32_e64 v56, v107, v56, s[10:11]
	v_cndmask_b32_e64 v59, v110, v59, s[10:11]
	v_cndmask_b32_e64 v58, v108, v58, s[10:11]
	v_lshlrev_b32_e32 v111, 16, v112
	v_and_b32_e32 v112, 0xffff0000, v112
	v_lshlrev_b32_e32 v117, 16, v113
	v_and_b32_e32 v119, 0xffff0000, v113
	v_lshlrev_b32_e32 v120, 16, v114
	v_and_b32_e32 v121, 0xffff0000, v114
	v_lshlrev_b32_e32 v122, 16, v115
	v_and_b32_e32 v123, 0xffff0000, v115
	v_sub_f32_e32 v113, v112, v116
	v_sub_f32_e32 v112, v111, v116
	v_sub_f32_e32 v115, v119, v116
	v_sub_f32_e32 v114, v117, v116
	v_sub_f32_e32 v121, v121, v116
	v_sub_f32_e32 v120, v120, v116
	v_sub_f32_e32 v117, v123, v116
	v_sub_f32_e32 v116, v122, v116
	v_pk_mul_f32 v[114:115], v[114:115], v[118:119] op_sel_hi:[1,0]
	v_pk_mul_f32 v[112:113], v[112:113], v[118:119] op_sel_hi:[1,0]
	v_pk_mul_f32 v[116:117], v[116:117], v[118:119] op_sel_hi:[1,0]
	v_pk_mul_f32 v[118:119], v[120:121], v[118:119] op_sel_hi:[1,0]
	v_pk_fma_f32 v[112:113], v[76:77], v[112:113], v[184:185]
	v_pk_fma_f32 v[114:115], v[78:79], v[114:115], v[182:183]
	v_pk_fma_f32 v[118:119], v[72:73], v[118:119], v[180:181]
	v_pk_fma_f32 v[116:117], v[74:75], v[116:117], v[178:179]
	v_pk_add_f32 v[62:63], v[62:63], v[114:115]
	v_pk_add_f32 v[60:61], v[60:61], v[112:113]
	v_pk_add_f32 v[58:59], v[58:59], v[116:117]
	v_pk_add_f32 v[56:57], v[56:57], v[118:119]
	v_cvt_pk_bf16_f32 v60, v60, v61
	v_cvt_pk_bf16_f32 v61, v62, v63
	s_nop 0
	v_cvt_pk_bf16_f32 v62, v56, v57
	v_cvt_pk_bf16_f32 v63, v58, v59
	v_lshlrev_b32_e32 v56, 16, v60
	v_and_b32_e32 v58, 0xffff0000, v60
	v_lshlrev_b32_e32 v112, 16, v61
	v_and_b32_e32 v114, 0xffff0000, v61
	v_lshlrev_b32_e32 v116, 16, v62
	v_and_b32_e32 v118, 0xffff0000, v62
	v_lshlrev_b32_e32 v120, 16, v63
	v_and_b32_e32 v122, 0xffff0000, v63
	v_mul_f32_e32 v57, v56, v56
	v_mul_f32_e32 v59, v58, v58
	v_mul_f32_e32 v113, v112, v112
	v_mul_f32_e32 v115, v114, v114
	v_mul_f32_e32 v117, v116, v116
	v_mul_f32_e32 v119, v118, v118
	v_mul_f32_e32 v121, v120, v120
	v_mul_f32_e32 v123, v122, v122
	v_pk_add_f32 v[56:57], v[56:57], v[58:59]
	v_pk_add_f32 v[58:59], v[112:113], v[114:115]
	v_pk_add_f32 v[112:113], v[120:121], v[122:123]
	v_pk_add_f32 v[56:57], v[56:57], v[58:59]
	v_pk_add_f32 v[58:59], v[116:117], v[118:119]
	global_store_dwordx4 v104, v[60:63], s[20:21]
	v_pk_add_f32 v[58:59], v[58:59], v[112:113]
	s_nop 0
	v_pk_add_f32 v[56:57], v[56:57], v[58:59]
	v_mov_b32_e32 v58, v165
	v_mov_b32_e32 v59, v165
	s_nop 0
	v_mov_b32_dpp v58, v56 quad_perm:[1,0,3,2] row_mask:0xf bank_mask:0xf
	v_mov_b32_dpp v59, v57 quad_perm:[1,0,3,2] row_mask:0xf bank_mask:0xf
	v_pk_add_f32 v[56:57], v[56:57], v[58:59]
	ds_bpermute_b32 v58, v207, v56
	ds_bpermute_b32 v59, v207, v57
	s_waitcnt lgkmcnt(0)
	v_pk_add_f32 v[56:57], v[56:57], v[58:59]
	ds_bpermute_b32 v58, v208, v56
	ds_bpermute_b32 v59, v208, v57
	s_and_saveexec_b64 s[64:65], s[16:17]
	s_cbranch_execz .LBB0_1481
	s_waitcnt lgkmcnt(0)
	v_pk_add_f32 v[56:57], v[56:57], v[58:59]
	v_add_co_u32_e32 v58, vcc, 0x10000, v186
	s_nop 1
	v_addc_co_u32_e32 v59, vcc, 0, v187, vcc
	v_mov_b32_e32 v250, v56
	v_mov_b32_e32 v251, v57
; __device__ __forceinline__ u32x4 pack8f(f32x4 a, f32x4 b) { u32x4 w; w.x = cvt_pk_bf16(a[0], a[1]); w.y = cvt_pk_bf16(a[2], a[3]); w.z = cvt_pk_bf16(b[0], b[1]); w.w = cvt_pk_bf16(b[2], b[3]); return w; }
;     __device__ __forceinline__ void operator()(const f32x4 (&acc)[2][2][4][2], const Unit& u, int wr, int wc, int fr, int fq, const EpiCtx& X) const {
;     ...
;             for (int m = 0; m < 4; ++m) {
;                 const int rl = ai * HALF + m * 16; const unsigned off = lo + (unsigned)(rl * 64) * 2u;
;                 const f32x4 o0a = acc[ai][0][m][0], o0b = acc[ai][0][m][1], o1a = acc[ai][1][m][0], o1b = acc[ai][1][m][1];
;                 const f32x4 ra_ = dpp_swap1(odd ? o0a : o1a), rb_ = dpp_swap1(odd ? o0b : o1b);
;                 const f32x4 pa[2] = {odd ? ra_ : o0a, odd ? o1a : ra_}, pb[2] = {odd ? rb_ : o0b, odd ? o1b : rb_};
; #pragma unroll
;                 for (int q = 0; q < 2; ++q) {
;                     const u32x4 w0 = raw[2 * m + q];
;                     const f32x4 r0 = (f32x4){bf_lo(w0.x), bf_hi(w0.x), bf_lo(w0.y), bf_hi(w0.y)}, r1 = (f32x4){bf_lo(w0.z), bf_hi(w0.z), bf_lo(w0.w), bf_hi(w0.w)};
;                     f32x4 y0, y1;
;                     if (RESN) { const f32x2 t = tbl[rl + q]; const float mu = t.x, ra = t.y * ALPHA; y0 = (r0 - mu) * ra * g0 + b0 + pa[q]; y1 = (r1 - mu) * ra * g1 + b1 + pb[q]; }
;                     else { y0 = r0 * ALPHA + pa[q]; y1 = r1 * ALPHA + pb[q]; }
;                     { const u32x4 w = pack8f(y0, y1); *(u32x4*)(xb + off + q * 128) = w;
;                         y0 = (f32x4){bf_lo(w.x), bf_hi(w.x), bf_lo(w.y), bf_hi(w.y)}; y1 = (f32x4){bf_lo(w.z), bf_hi(w.z), bf_lo(w.w), bf_hi(w.w)}; }
;                     float sa = ((y0[0] + y0[1]) + (y0[2] + y0[3])) + ((y1[0] + y1[1]) + (y1[2] + y1[3]));
;                     float sb = ((y0[0] * y0[0] + y0[1] * y0[1]) + (y0[2] * y0[2] + y0[3] * y0[3])) + ((y1[0] * y1[0] + y1[1] * y1[1]) + (y1[2] * y1[2] + y1[3] * y1[3]));
;                     sa += dpp_x1(sa);
;                     sb += dpp_x1(sb);
;                     sa += __shfl_xor(sa, 16); sa += __shfl_xor(sa, 32); sb += __shfl_xor(sb, 16); sb += __shfl_xor(sb, 32);
;                     if (fq == 0 && !odd) ps[(size_t)(rl + q) * 64] = (f32x2){sa, sb};
.LBB0_1481:
	s_or_b64 exec, exec, s[64:65]
	ds_read_b64 v[56:57], v201 offset:1032
	s_waitcnt lgkmcnt(1)
	v_lshlrev_b32_e32 v59, 16, v96
	v_and_b32_e32 v60, 0xffff0000, v96
	v_cndmask_b32_e64 v53, v53, v105, s[10:11]
	v_cndmask_b32_e64 v52, v52, v101, s[10:11]
	s_waitcnt lgkmcnt(0)
	v_mul_f32_e32 v58, 0x3fb504f3, v57
	v_sub_f32_e32 v61, v60, v56
	v_sub_f32_e32 v60, v59, v56
	v_pk_mul_f32 v[60:61], v[60:61], v[58:59] op_sel_hi:[1,0]
	v_lshlrev_b32_e32 v62, 16, v97
	v_and_b32_e32 v63, 0xffff0000, v97
	v_lshlrev_b32_e32 v96, 16, v98
	v_and_b32_e32 v97, 0xffff0000, v98
	v_lshlrev_b32_e32 v98, 16, v99
	v_and_b32_e32 v99, 0xffff0000, v99
	v_pk_fma_f32 v[60:61], v[76:77], v[60:61], v[184:185]
	v_sub_f32_e32 v63, v63, v56
	v_sub_f32_e32 v62, v62, v56
	v_pk_add_f32 v[52:53], v[52:53], v[60:61]
	v_sub_f32_e32 v61, v97, v56
	v_sub_f32_e32 v60, v96, v56
	v_sub_f32_e32 v57, v99, v56
	v_sub_f32_e32 v56, v98, v56
	v_pk_mul_f32 v[62:63], v[62:63], v[58:59] op_sel_hi:[1,0]
	v_pk_mul_f32 v[56:57], v[56:57], v[58:59] op_sel_hi:[1,0]
	v_pk_mul_f32 v[58:59], v[60:61], v[58:59] op_sel_hi:[1,0]
	v_cndmask_b32_e64 v55, v55, v106, s[10:11]
	v_cndmask_b32_e64 v54, v54, v103, s[10:11]
	v_cndmask_b32_e64 v49, v49, v109, s[10:11]
	v_cndmask_b32_e64 v48, v48, v107, s[10:11]
	v_cndmask_b32_e64 v51, v51, v110, s[10:11]
	v_cndmask_b32_e64 v50, v50, v108, s[10:11]
	v_pk_fma_f32 v[62:63], v[78:79], v[62:63], v[182:183]
	v_pk_fma_f32 v[58:59], v[72:73], v[58:59], v[180:181]
	v_pk_fma_f32 v[56:57], v[74:75], v[56:57], v[178:179]
	v_pk_add_f32 v[54:55], v[54:55], v[62:63]
	v_pk_add_f32 v[50:51], v[50:51], v[56:57]
	v_pk_add_f32 v[48:49], v[48:49], v[58:59]
	v_cvt_pk_bf16_f32 v52, v52, v53
	v_cvt_pk_bf16_f32 v53, v54, v55
	v_mov_b32_e32 v105, v165
	v_cvt_pk_bf16_f32 v54, v48, v49
	v_cvt_pk_bf16_f32 v55, v50, v51
	v_lshlrev_b32_e32 v48, 16, v52
	v_and_b32_e32 v50, 0xffff0000, v52
	v_lshlrev_b32_e32 v56, 16, v53
	v_and_b32_e32 v58, 0xffff0000, v53
	v_lshlrev_b32_e32 v60, 16, v54
	v_and_b32_e32 v62, 0xffff0000, v54
	v_lshlrev_b32_e32 v96, 16, v55
	v_and_b32_e32 v98, 0xffff0000, v55
	v_mul_f32_e32 v49, v48, v48
	v_mul_f32_e32 v51, v50, v50
	v_mul_f32_e32 v57, v56, v56
	v_mul_f32_e32 v59, v58, v58
	v_mul_f32_e32 v61, v60, v60
	v_mul_f32_e32 v63, v62, v62
	v_mul_f32_e32 v97, v96, v96
	v_mul_f32_e32 v99, v98, v98
	v_pk_add_f32 v[48:49], v[48:49], v[50:51]
	v_pk_add_f32 v[50:51], v[56:57], v[58:59]
	v_pk_add_f32 v[56:57], v[96:97], v[98:99]
	v_pk_add_f32 v[48:49], v[48:49], v[50:51]
	v_pk_add_f32 v[50:51], v[60:61], v[62:63]
	s_nop 0
	v_pk_add_f32 v[50:51], v[50:51], v[56:57]
	v_lshl_add_u64 v[56:57], s[20:21], 0, v[104:105]
	v_pk_add_f32 v[48:49], v[48:49], v[50:51]
	v_mov_b32_e32 v50, v165
	v_mov_b32_e32 v51, v165
	global_store_dwordx4 v[56:57], v[52:55], off offset:128
	v_mov_b32_dpp v50, v48 quad_perm:[1,0,3,2] row_mask:0xf bank_mask:0xf
	v_mov_b32_dpp v51, v49 quad_perm:[1,0,3,2] row_mask:0xf bank_mask:0xf
	v_pk_add_f32 v[48:49], v[48:49], v[50:51]
	ds_bpermute_b32 v50, v207, v48
	ds_bpermute_b32 v51, v207, v49
	s_waitcnt lgkmcnt(0)
	v_pk_add_f32 v[48:49], v[48:49], v[50:51]
	ds_bpermute_b32 v50, v208, v48
	ds_bpermute_b32 v51, v208, v49
	s_and_saveexec_b64 s[64:65], s[16:17]
	s_cbranch_execz .LBB0_1483
	s_waitcnt lgkmcnt(0)
	v_pk_add_f32 v[48:49], v[48:49], v[50:51]
	v_add_co_u32_e32 v50, vcc, 0x10000, v186
	s_nop 1
	v_addc_co_u32_e32 v51, vcc, 0, v187, vcc
	v_mov_b32_e32 v252, v250
	v_mov_b32_e32 v253, v251
	v_mov_b32_e32 v254, v48
	v_mov_b32_e32 v255, v49
	global_store_dwordx4 v249, v[252:255], s[94:95] offset:1024
.LBB0_1483:
	s_or_b64 exec, exec, s[64:65]
	s_waitcnt lgkmcnt(1)
	v_cndmask_b32_e64 v50, v44, v36, s[10:11]
	v_mov_b32_e32 v48, 0
	v_cndmask_b32_e64 v49, v45, v37, s[10:11]
	s_waitcnt lgkmcnt(0)
	v_cndmask_b32_e64 v51, v46, v38, s[10:11]
	v_mov_b32_dpp v48, v50 quad_perm:[1,0,3,2] row_mask:0xf bank_mask:0xf
	v_mov_b32_e32 v50, 0
	v_cndmask_b32_e64 v52, v47, v39, s[10:11]
	v_cndmask_b32_e64 v54, v40, v32, s[10:11]
	v_mov_b32_dpp v50, v49 quad_perm:[1,0,3,2] row_mask:0xf bank_mask:0xf
	v_mov_b32_e32 v49, 0
	v_cndmask_b32_e64 v53, v41, v33, s[10:11]
	v_cndmask_b32_e64 v55, v42, v34, s[10:11]
	v_mov_b32_dpp v49, v51 quad_perm:[1,0,3,2] row_mask:0xf bank_mask:0xf
	v_mov_b32_e32 v51, 0
	v_cndmask_b32_e64 v56, v43, v35, s[10:11]
	v_lshlrev_b32_e32 v59, 16, v92
	v_mov_b32_dpp v51, v52 quad_perm:[1,0,3,2] row_mask:0xf bank_mask:0xf
	v_mov_b32_e32 v52, 0
	v_and_b32_e32 v60, 0xffff0000, v92
	v_cndmask_b32_e64 v45, v50, v45, s[10:11]
	v_mov_b32_dpp v52, v54 quad_perm:[1,0,3,2] row_mask:0xf bank_mask:0xf
	v_mov_b32_e32 v54, 0
	v_cndmask_b32_e64 v44, v48, v44, s[10:11]
	v_lshlrev_b32_e32 v62, 16, v93
	v_mov_b32_dpp v54, v53 quad_perm:[1,0,3,2] row_mask:0xf bank_mask:0xf
	v_mov_b32_e32 v53, 0
	v_and_b32_e32 v63, 0xffff0000, v93
	v_lshlrev_b32_e32 v92, 16, v94
	v_mov_b32_dpp v53, v55 quad_perm:[1,0,3,2] row_mask:0xf bank_mask:0xf
	v_mov_b32_e32 v55, 0
	v_and_b32_e32 v93, 0xffff0000, v94
	v_lshlrev_b32_e32 v94, 16, v95
	v_mov_b32_dpp v55, v56 quad_perm:[1,0,3,2] row_mask:0xf bank_mask:0xf
	ds_read_b64 v[56:57], v201 offset:1152
	v_and_b32_e32 v95, 0xffff0000, v95
	v_cndmask_b32_e64 v47, v51, v47, s[10:11]
	v_cndmask_b32_e64 v46, v49, v46, s[10:11]
	v_cndmask_b32_e64 v41, v54, v41, s[10:11]
	s_waitcnt lgkmcnt(0)
; __device__ __forceinline__ u32x4 pack8f(f32x4 a, f32x4 b) { u32x4 w; w.x = cvt_pk_bf16(a[0], a[1]); w.y = cvt_pk_bf16(a[2], a[3]); w.z = cvt_pk_bf16(b[0], b[1]); w.w = cvt_pk_bf16(b[2], b[3]); return w; }
;     __device__ __forceinline__ void operator()(const f32x4 (&acc)[2][2][4][2], const Unit& u, int wr, int wc, int fr, int fq, const EpiCtx& X) const {
;     ...
;             for (int m = 0; m < 4; ++m) {
;                 const int rl = ai * HALF + m * 16; const unsigned off = lo + (unsigned)(rl * 64) * 2u;
;                 const f32x4 o0a = acc[ai][0][m][0], o0b = acc[ai][0][m][1], o1a = acc[ai][1][m][0], o1b = acc[ai][1][m][1];
;                 const f32x4 ra_ = dpp_swap1(odd ? o0a : o1a), rb_ = dpp_swap1(odd ? o0b : o1b);
;                 const f32x4 pa[2] = {odd ? ra_ : o0a, odd ? o1a : ra_}, pb[2] = {odd ? rb_ : o0b, odd ? o1b : rb_};
; #pragma unroll
;                 for (int q = 0; q < 2; ++q) {
;                     const u32x4 w0 = raw[2 * m + q];
;                     const f32x4 r0 = (f32x4){bf_lo(w0.x), bf_hi(w0.x), bf_lo(w0.y), bf_hi(w0.y)}, r1 = (f32x4){bf_lo(w0.z), bf_hi(w0.z), bf_lo(w0.w), bf_hi(w0.w)};
;                     f32x4 y0, y1;
;                     if (RESN) { const f32x2 t = tbl[rl + q]; const float mu = t.x, ra = t.y * ALPHA; y0 = (r0 - mu) * ra * g0 + b0 + pa[q]; y1 = (r1 - mu) * ra * g1 + b1 + pb[q]; }
;                     else { y0 = r0 * ALPHA + pa[q]; y1 = r1 * ALPHA + pb[q]; }
;                     { const u32x4 w = pack8f(y0, y1); *(u32x4*)(xb + off + q * 128) = w;
;                         y0 = (f32x4){bf_lo(w.x), bf_hi(w.x), bf_lo(w.y), bf_hi(w.y)}; y1 = (f32x4){bf_lo(w.z), bf_hi(w.z), bf_lo(w.w), bf_hi(w.w)}; }
;                     float sa = ((y0[0] + y0[1]) + (y0[2] + y0[3])) + ((y1[0] + y1[1]) + (y1[2] + y1[3]));
;                     float sb = ((y0[0] * y0[0] + y0[1] * y0[1]) + (y0[2] * y0[2] + y0[3] * y0[3])) + ((y1[0] * y1[0] + y1[1] * y1[1]) + (y1[2] * y1[2] + y1[3] * y1[3]));
;                     sa += dpp_x1(sa);
;                     sb += dpp_x1(sb);
;                     sa += __shfl_xor(sa, 16); sa += __shfl_xor(sa, 32); sb += __shfl_xor(sb, 16); sb += __shfl_xor(sb, 32);
;                     if (fq == 0 && !odd) ps[(size_t)(rl + q) * 64] = (f32x2){sa, sb};
	v_mul_f32_e32 v58, 0x3fb504f3, v57
	v_sub_f32_e32 v61, v60, v56
	v_sub_f32_e32 v60, v59, v56
	v_pk_mul_f32 v[60:61], v[60:61], v[58:59] op_sel_hi:[1,0]
	v_sub_f32_e32 v63, v63, v56
	v_pk_fma_f32 v[60:61], v[76:77], v[60:61], v[184:185]
	v_sub_f32_e32 v62, v62, v56
	v_pk_add_f32 v[44:45], v[44:45], v[60:61]
	v_sub_f32_e32 v61, v93, v56
	v_sub_f32_e32 v60, v92, v56
	v_sub_f32_e32 v57, v95, v56
	v_sub_f32_e32 v56, v94, v56
	v_pk_mul_f32 v[62:63], v[62:63], v[58:59] op_sel_hi:[1,0]
	v_pk_mul_f32 v[56:57], v[56:57], v[58:59] op_sel_hi:[1,0]
	v_pk_mul_f32 v[58:59], v[60:61], v[58:59] op_sel_hi:[1,0]
	v_cndmask_b32_e64 v40, v52, v40, s[10:11]
	v_cndmask_b32_e64 v43, v55, v43, s[10:11]
	v_cndmask_b32_e64 v42, v53, v42, s[10:11]
	v_pk_fma_f32 v[62:63], v[78:79], v[62:63], v[182:183]
	v_pk_fma_f32 v[58:59], v[72:73], v[58:59], v[180:181]
	v_pk_fma_f32 v[56:57], v[74:75], v[56:57], v[178:179]
	v_pk_add_f32 v[46:47], v[46:47], v[62:63]
	v_pk_add_f32 v[42:43], v[42:43], v[56:57]
	v_pk_add_f32 v[40:41], v[40:41], v[58:59]
	v_cvt_pk_bf16_f32 v56, v44, v45
	v_cvt_pk_bf16_f32 v57, v46, v47
	v_mov_b32_e32 v103, v165
	v_cvt_pk_bf16_f32 v58, v40, v41
	v_cvt_pk_bf16_f32 v59, v42, v43
	v_lshlrev_b32_e32 v40, 16, v56
	v_and_b32_e32 v42, 0xffff0000, v56
	v_lshlrev_b32_e32 v44, 16, v57
	v_and_b32_e32 v46, 0xffff0000, v57
	v_lshlrev_b32_e32 v60, 16, v58
	v_and_b32_e32 v62, 0xffff0000, v58
	v_lshlrev_b32_e32 v92, 16, v59
	v_and_b32_e32 v94, 0xffff0000, v59
	v_mul_f32_e32 v41, v40, v40
	v_mul_f32_e32 v43, v42, v42
	v_mul_f32_e32 v45, v44, v44
	v_mul_f32_e32 v47, v46, v46
	v_mul_f32_e32 v61, v60, v60
	v_mul_f32_e32 v63, v62, v62
	v_mul_f32_e32 v93, v92, v92
	v_mul_f32_e32 v95, v94, v94
	v_pk_add_f32 v[40:41], v[40:41], v[42:43]
	v_pk_add_f32 v[42:43], v[44:45], v[46:47]
	v_pk_add_f32 v[44:45], v[92:93], v[94:95]
	v_pk_add_f32 v[40:41], v[40:41], v[42:43]
	v_pk_add_f32 v[42:43], v[60:61], v[62:63]
	s_nop 0
	v_pk_add_f32 v[42:43], v[42:43], v[44:45]
	s_nop 0
	v_pk_add_f32 v[40:41], v[40:41], v[42:43]
	v_mov_b32_e32 v42, v165
	v_mov_b32_e32 v43, v165
	s_nop 0
	v_mov_b32_dpp v42, v40 quad_perm:[1,0,3,2] row_mask:0xf bank_mask:0xf
	v_mov_b32_dpp v43, v41 quad_perm:[1,0,3,2] row_mask:0xf bank_mask:0xf
	v_pk_add_f32 v[40:41], v[40:41], v[42:43]
	ds_bpermute_b32 v42, v207, v40
	ds_bpermute_b32 v43, v207, v41
	s_waitcnt lgkmcnt(0)
	v_pk_add_f32 v[42:43], v[40:41], v[42:43]
	ds_bpermute_b32 v44, v208, v42
	ds_bpermute_b32 v45, v208, v43
	v_lshl_add_u64 v[40:41], s[20:21], 0, v[102:103]
	global_store_dwordx4 v[40:41], v[56:59], off
	s_and_saveexec_b64 s[64:65], s[16:17]
	s_cbranch_execz .LBB0_1485
	s_waitcnt lgkmcnt(0)
	v_pk_add_f32 v[42:43], v[42:43], v[44:45]
	v_add_co_u32_e32 v44, vcc, 0x12000, v186
	s_nop 1
	v_addc_co_u32_e32 v45, vcc, 0, v187, vcc
	v_mov_b32_e32 v250, v42
	v_mov_b32_e32 v251, v43
.LBB0_1485:
	s_or_b64 exec, exec, s[64:65]
	ds_read_b64 v[42:43], v201 offset:1160
	s_waitcnt lgkmcnt(1)
	v_lshlrev_b32_e32 v45, 16, v88
	v_and_b32_e32 v46, 0xffff0000, v88
	v_cndmask_b32_e64 v37, v37, v50, s[10:11]
	v_cndmask_b32_e64 v36, v36, v48, s[10:11]
	s_waitcnt lgkmcnt(0)
	v_mul_f32_e32 v44, 0x3fb504f3, v43
	v_sub_f32_e32 v47, v46, v42
	v_sub_f32_e32 v46, v45, v42
	v_pk_mul_f32 v[46:47], v[46:47], v[44:45] op_sel_hi:[1,0]
	v_cndmask_b32_e64 v39, v39, v51, s[10:11]
	v_cndmask_b32_e64 v38, v38, v49, s[10:11]
	v_cndmask_b32_e64 v32, v32, v52, s[10:11]
	v_cndmask_b32_e64 v34, v34, v53, s[10:11]
	v_lshlrev_b32_e32 v48, 16, v89
	v_and_b32_e32 v49, 0xffff0000, v89
	v_lshlrev_b32_e32 v50, 16, v90
	v_and_b32_e32 v51, 0xffff0000, v90
	v_lshlrev_b32_e32 v52, 16, v91
	v_and_b32_e32 v53, 0xffff0000, v91
	v_pk_fma_f32 v[46:47], v[76:77], v[46:47], v[184:185]
	v_sub_f32_e32 v49, v49, v42
	v_sub_f32_e32 v48, v48, v42
	v_pk_add_f32 v[36:37], v[36:37], v[46:47]
	v_sub_f32_e32 v47, v51, v42
	v_sub_f32_e32 v46, v50, v42
	v_sub_f32_e32 v43, v53, v42
	v_sub_f32_e32 v42, v52, v42
	v_pk_mul_f32 v[48:49], v[48:49], v[44:45] op_sel_hi:[1,0]
	v_pk_mul_f32 v[42:43], v[42:43], v[44:45] op_sel_hi:[1,0]
	v_pk_mul_f32 v[44:45], v[46:47], v[44:45] op_sel_hi:[1,0]
	v_cndmask_b32_e64 v33, v33, v54, s[10:11]
	v_cndmask_b32_e64 v35, v35, v55, s[10:11]
	v_pk_fma_f32 v[48:49], v[78:79], v[48:49], v[182:183]
	v_pk_fma_f32 v[44:45], v[72:73], v[44:45], v[180:181]
	v_pk_fma_f32 v[42:43], v[74:75], v[42:43], v[178:179]
	v_pk_add_f32 v[38:39], v[38:39], v[48:49]
	v_pk_add_f32 v[34:35], v[34:35], v[42:43]
	v_pk_add_f32 v[32:33], v[32:33], v[44:45]
	v_cvt_pk_bf16_f32 v36, v36, v37
	v_cvt_pk_bf16_f32 v37, v38, v39
	s_nop 0
	v_cvt_pk_bf16_f32 v38, v32, v33
	v_cvt_pk_bf16_f32 v39, v34, v35
	v_lshlrev_b32_e32 v32, 16, v36
	v_and_b32_e32 v34, 0xffff0000, v36
	v_lshlrev_b32_e32 v42, 16, v37
	v_and_b32_e32 v44, 0xffff0000, v37
	v_lshlrev_b32_e32 v46, 16, v38
	v_and_b32_e32 v48, 0xffff0000, v38
	v_lshlrev_b32_e32 v50, 16, v39
	v_and_b32_e32 v52, 0xffff0000, v39
	v_mul_f32_e32 v33, v32, v32
	v_mul_f32_e32 v35, v34, v34
	v_mul_f32_e32 v43, v42, v42
	v_mul_f32_e32 v45, v44, v44
	v_mul_f32_e32 v47, v46, v46
	v_mul_f32_e32 v49, v48, v48
	v_mul_f32_e32 v51, v50, v50
	v_mul_f32_e32 v53, v52, v52
	v_pk_add_f32 v[32:33], v[32:33], v[34:35]
	v_pk_add_f32 v[34:35], v[42:43], v[44:45]
	v_pk_add_f32 v[42:43], v[50:51], v[52:53]
	v_pk_add_f32 v[32:33], v[32:33], v[34:35]
	v_pk_add_f32 v[34:35], v[46:47], v[48:49]
	global_store_dwordx4 v[40:41], v[36:39], off offset:128
	v_pk_add_f32 v[34:35], v[34:35], v[42:43]
	s_nop 0
	v_pk_add_f32 v[32:33], v[32:33], v[34:35]
	v_mov_b32_e32 v34, v165
	v_mov_b32_e32 v35, v165
	s_nop 0
	v_mov_b32_dpp v34, v32 quad_perm:[1,0,3,2] row_mask:0xf bank_mask:0xf
	v_mov_b32_dpp v35, v33 quad_perm:[1,0,3,2] row_mask:0xf bank_mask:0xf
	v_pk_add_f32 v[32:33], v[32:33], v[34:35]
	ds_bpermute_b32 v34, v207, v32
	ds_bpermute_b32 v35, v207, v33
	s_waitcnt lgkmcnt(0)
	v_pk_add_f32 v[32:33], v[32:33], v[34:35]
	ds_bpermute_b32 v34, v208, v32
	ds_bpermute_b32 v35, v208, v33
	s_and_saveexec_b64 s[64:65], s[16:17]
	s_cbranch_execz .LBB0_1487
	s_waitcnt lgkmcnt(0)
	v_pk_add_f32 v[32:33], v[32:33], v[34:35]
	v_add_co_u32_e32 v34, vcc, 0x12000, v186
	s_nop 1
	v_addc_co_u32_e32 v35, vcc, 0, v187, vcc
	v_mov_b32_e32 v252, v250
	v_mov_b32_e32 v253, v251
	v_mov_b32_e32 v254, v32
	v_mov_b32_e32 v255, v33
	global_store_dwordx4 v249, v[252:255], s[94:95] offset:1152
; __device__ __forceinline__ u32x4 pack8f(f32x4 a, f32x4 b) { u32x4 w; w.x = cvt_pk_bf16(a[0], a[1]); w.y = cvt_pk_bf16(a[2], a[3]); w.z = cvt_pk_bf16(b[0], b[1]); w.w = cvt_pk_bf16(b[2], b[3]); return w; }
;     __device__ __forceinline__ void operator()(const f32x4 (&acc)[2][2][4][2], const Unit& u, int wr, int wc, int fr, int fq, const EpiCtx& X) const {
;     ...
;             for (int m = 0; m < 4; ++m) {
;                 const int rl = ai * HALF + m * 16; const unsigned off = lo + (unsigned)(rl * 64) * 2u;
;                 const f32x4 o0a = acc[ai][0][m][0], o0b = acc[ai][0][m][1], o1a = acc[ai][1][m][0], o1b = acc[ai][1][m][1];
;                 const f32x4 ra_ = dpp_swap1(odd ? o0a : o1a), rb_ = dpp_swap1(odd ? o0b : o1b);
;                 const f32x4 pa[2] = {odd ? ra_ : o0a, odd ? o1a : ra_}, pb[2] = {odd ? rb_ : o0b, odd ? o1b : rb_};
; #pragma unroll
;                 for (int q = 0; q < 2; ++q) {
;                     const u32x4 w0 = raw[2 * m + q];
;                     const f32x4 r0 = (f32x4){bf_lo(w0.x), bf_hi(w0.x), bf_lo(w0.y), bf_hi(w0.y)}, r1 = (f32x4){bf_lo(w0.z), bf_hi(w0.z), bf_lo(w0.w), bf_hi(w0.w)};
;                     f32x4 y0, y1;
;                     if (RESN) { const f32x2 t = tbl[rl + q]; const float mu = t.x, ra = t.y * ALPHA; y0 = (r0 - mu) * ra * g0 + b0 + pa[q]; y1 = (r1 - mu) * ra * g1 + b1 + pb[q]; }
;                     else { y0 = r0 * ALPHA + pa[q]; y1 = r1 * ALPHA + pb[q]; }
;                     { const u32x4 w = pack8f(y0, y1); *(u32x4*)(xb + off + q * 128) = w;
;                         y0 = (f32x4){bf_lo(w.x), bf_hi(w.x), bf_lo(w.y), bf_hi(w.y)}; y1 = (f32x4){bf_lo(w.z), bf_hi(w.z), bf_lo(w.w), bf_hi(w.w)}; }
;                     float sa = ((y0[0] + y0[1]) + (y0[2] + y0[3])) + ((y1[0] + y1[1]) + (y1[2] + y1[3]));
;                     float sb = ((y0[0] * y0[0] + y0[1] * y0[1]) + (y0[2] * y0[2] + y0[3] * y0[3])) + ((y1[0] * y1[0] + y1[1] * y1[1]) + (y1[2] * y1[2] + y1[3] * y1[3]));
;                     sa += dpp_x1(sa);
;                     sb += dpp_x1(sb);
;                     sa += __shfl_xor(sa, 16); sa += __shfl_xor(sa, 32); sb += __shfl_xor(sb, 16); sb += __shfl_xor(sb, 32);
;                     if (fq == 0 && !odd) ps[(size_t)(rl + q) * 64] = (f32x2){sa, sb};
.LBB0_1487:
	s_or_b64 exec, exec, s[64:65]
	s_waitcnt lgkmcnt(1)
	v_cndmask_b32_e64 v34, v28, v20, s[10:11]
	v_mov_b32_e32 v32, 0
	v_cndmask_b32_e64 v33, v29, v21, s[10:11]
	s_waitcnt lgkmcnt(0)
	v_cndmask_b32_e64 v35, v30, v22, s[10:11]
	v_mov_b32_dpp v32, v34 quad_perm:[1,0,3,2] row_mask:0xf bank_mask:0xf
	v_mov_b32_e32 v34, 0
	v_cndmask_b32_e64 v36, v31, v23, s[10:11]
	v_cndmask_b32_e64 v38, v24, v16, s[10:11]
	v_mov_b32_dpp v34, v33 quad_perm:[1,0,3,2] row_mask:0xf bank_mask:0xf
	v_mov_b32_e32 v33, 0
	v_cndmask_b32_e64 v37, v25, v17, s[10:11]
	v_cndmask_b32_e64 v39, v26, v18, s[10:11]
	v_mov_b32_dpp v33, v35 quad_perm:[1,0,3,2] row_mask:0xf bank_mask:0xf
	v_mov_b32_e32 v35, 0
	v_cndmask_b32_e64 v40, v27, v19, s[10:11]
	s_waitcnt vmcnt(9)
	v_lshlrev_b32_e32 v43, 16, v84
	v_mov_b32_dpp v35, v36 quad_perm:[1,0,3,2] row_mask:0xf bank_mask:0xf
	v_mov_b32_e32 v36, 0
	v_and_b32_e32 v44, 0xffff0000, v84
	v_cndmask_b32_e64 v29, v34, v29, s[10:11]
	v_mov_b32_dpp v36, v38 quad_perm:[1,0,3,2] row_mask:0xf bank_mask:0xf
	v_mov_b32_e32 v38, 0
	v_cndmask_b32_e64 v28, v32, v28, s[10:11]
	v_lshlrev_b32_e32 v46, 16, v85
	v_mov_b32_dpp v38, v37 quad_perm:[1,0,3,2] row_mask:0xf bank_mask:0xf
	v_mov_b32_e32 v37, 0
	v_and_b32_e32 v47, 0xffff0000, v85
	v_lshlrev_b32_e32 v48, 16, v86
	v_mov_b32_dpp v37, v39 quad_perm:[1,0,3,2] row_mask:0xf bank_mask:0xf
	v_mov_b32_e32 v39, 0
	v_and_b32_e32 v49, 0xffff0000, v86
	v_lshlrev_b32_e32 v50, 16, v87
	v_mov_b32_dpp v39, v40 quad_perm:[1,0,3,2] row_mask:0xf bank_mask:0xf
	ds_read_b64 v[40:41], v201 offset:1280
	v_and_b32_e32 v51, 0xffff0000, v87
	v_cndmask_b32_e64 v31, v35, v31, s[10:11]
	v_cndmask_b32_e64 v30, v33, v30, s[10:11]
	v_cndmask_b32_e64 v25, v38, v25, s[10:11]
	s_waitcnt lgkmcnt(0)
	v_mul_f32_e32 v42, 0x3fb504f3, v41
	v_sub_f32_e32 v45, v44, v40
	v_sub_f32_e32 v44, v43, v40
	v_pk_mul_f32 v[44:45], v[44:45], v[42:43] op_sel_hi:[1,0]
	v_sub_f32_e32 v47, v47, v40
	v_pk_fma_f32 v[44:45], v[76:77], v[44:45], v[184:185]
	v_sub_f32_e32 v46, v46, v40
	v_pk_add_f32 v[28:29], v[28:29], v[44:45]
	v_sub_f32_e32 v45, v49, v40
	v_sub_f32_e32 v44, v48, v40
	v_sub_f32_e32 v41, v51, v40
	v_sub_f32_e32 v40, v50, v40
	v_pk_mul_f32 v[46:47], v[46:47], v[42:43] op_sel_hi:[1,0]
	v_pk_mul_f32 v[40:41], v[40:41], v[42:43] op_sel_hi:[1,0]
	v_pk_mul_f32 v[42:43], v[44:45], v[42:43] op_sel_hi:[1,0]
	v_cndmask_b32_e64 v24, v36, v24, s[10:11]
	v_cndmask_b32_e64 v27, v39, v27, s[10:11]
	v_cndmask_b32_e64 v26, v37, v26, s[10:11]
	v_pk_fma_f32 v[46:47], v[78:79], v[46:47], v[182:183]
	v_pk_fma_f32 v[42:43], v[72:73], v[42:43], v[180:181]
	v_pk_fma_f32 v[40:41], v[74:75], v[40:41], v[178:179]
	v_pk_add_f32 v[30:31], v[30:31], v[46:47]
	v_pk_add_f32 v[26:27], v[26:27], v[40:41]
	v_pk_add_f32 v[24:25], v[24:25], v[42:43]
	v_cvt_pk_bf16_f32 v40, v28, v29
	v_cvt_pk_bf16_f32 v41, v30, v31
	v_mov_b32_e32 v101, v165
	v_cvt_pk_bf16_f32 v42, v24, v25
	v_cvt_pk_bf16_f32 v43, v26, v27
	v_lshlrev_b32_e32 v24, 16, v40
	v_and_b32_e32 v26, 0xffff0000, v40
	v_lshlrev_b32_e32 v28, 16, v41
	v_and_b32_e32 v30, 0xffff0000, v41
	v_lshlrev_b32_e32 v44, 16, v42
	v_and_b32_e32 v46, 0xffff0000, v42
	v_lshlrev_b32_e32 v48, 16, v43
	v_and_b32_e32 v50, 0xffff0000, v43
	v_mul_f32_e32 v25, v24, v24
	v_mul_f32_e32 v27, v26, v26
	v_mul_f32_e32 v29, v28, v28
	v_mul_f32_e32 v31, v30, v30
	v_mul_f32_e32 v45, v44, v44
	v_mul_f32_e32 v47, v46, v46
	v_mul_f32_e32 v49, v48, v48
	v_mul_f32_e32 v51, v50, v50
	v_pk_add_f32 v[24:25], v[24:25], v[26:27]
	v_pk_add_f32 v[26:27], v[28:29], v[30:31]
	v_pk_add_f32 v[28:29], v[48:49], v[50:51]
	v_pk_add_f32 v[24:25], v[24:25], v[26:27]
	v_pk_add_f32 v[26:27], v[44:45], v[46:47]
	s_nop 0
	v_pk_add_f32 v[26:27], v[26:27], v[28:29]
	s_nop 0
	v_pk_add_f32 v[24:25], v[24:25], v[26:27]
	v_mov_b32_e32 v26, v165
	v_mov_b32_e32 v27, v165
	s_nop 0
	v_mov_b32_dpp v26, v24 quad_perm:[1,0,3,2] row_mask:0xf bank_mask:0xf
	v_mov_b32_dpp v27, v25 quad_perm:[1,0,3,2] row_mask:0xf bank_mask:0xf
	v_pk_add_f32 v[24:25], v[24:25], v[26:27]
	ds_bpermute_b32 v26, v207, v24
	ds_bpermute_b32 v27, v207, v25
	s_waitcnt lgkmcnt(0)
	v_pk_add_f32 v[26:27], v[24:25], v[26:27]
	ds_bpermute_b32 v28, v208, v26
	ds_bpermute_b32 v29, v208, v27
	v_lshl_add_u64 v[24:25], s[20:21], 0, v[100:101]
	global_store_dwordx4 v[24:25], v[40:43], off
	s_and_saveexec_b64 s[64:65], s[16:17]
	s_cbranch_execz .LBB0_1489
	s_waitcnt lgkmcnt(0)
	v_pk_add_f32 v[26:27], v[26:27], v[28:29]
	v_add_co_u32_e32 v28, vcc, 0x14000, v186
	s_nop 1
	v_addc_co_u32_e32 v29, vcc, 0, v187, vcc
	v_mov_b32_e32 v250, v26
	v_mov_b32_e32 v251, v27
; __device__ __forceinline__ u32x4 pack8f(f32x4 a, f32x4 b) { u32x4 w; w.x = cvt_pk_bf16(a[0], a[1]); w.y = cvt_pk_bf16(a[2], a[3]); w.z = cvt_pk_bf16(b[0], b[1]); w.w = cvt_pk_bf16(b[2], b[3]); return w; }
;     __device__ __forceinline__ void operator()(const f32x4 (&acc)[2][2][4][2], const Unit& u, int wr, int wc, int fr, int fq, const EpiCtx& X) const {
;     ...
;             for (int m = 0; m < 4; ++m) {
;                 const int rl = ai * HALF + m * 16; const unsigned off = lo + (unsigned)(rl * 64) * 2u;
;                 const f32x4 o0a = acc[ai][0][m][0], o0b = acc[ai][0][m][1], o1a = acc[ai][1][m][0], o1b = acc[ai][1][m][1];
;                 const f32x4 ra_ = dpp_swap1(odd ? o0a : o1a), rb_ = dpp_swap1(odd ? o0b : o1b);
;                 const f32x4 pa[2] = {odd ? ra_ : o0a, odd ? o1a : ra_}, pb[2] = {odd ? rb_ : o0b, odd ? o1b : rb_};
; #pragma unroll
;                 for (int q = 0; q < 2; ++q) {
;                     const u32x4 w0 = raw[2 * m + q];
;                     const f32x4 r0 = (f32x4){bf_lo(w0.x), bf_hi(w0.x), bf_lo(w0.y), bf_hi(w0.y)}, r1 = (f32x4){bf_lo(w0.z), bf_hi(w0.z), bf_lo(w0.w), bf_hi(w0.w)};
;                     f32x4 y0, y1;
;                     if (RESN) { const f32x2 t = tbl[rl + q]; const float mu = t.x, ra = t.y * ALPHA; y0 = (r0 - mu) * ra * g0 + b0 + pa[q]; y1 = (r1 - mu) * ra * g1 + b1 + pb[q]; }
;                     else { y0 = r0 * ALPHA + pa[q]; y1 = r1 * ALPHA + pb[q]; }
;                     { const u32x4 w = pack8f(y0, y1); *(u32x4*)(xb + off + q * 128) = w;
;                         y0 = (f32x4){bf_lo(w.x), bf_hi(w.x), bf_lo(w.y), bf_hi(w.y)}; y1 = (f32x4){bf_lo(w.z), bf_hi(w.z), bf_lo(w.w), bf_hi(w.w)}; }
;                     float sa = ((y0[0] + y0[1]) + (y0[2] + y0[3])) + ((y1[0] + y1[1]) + (y1[2] + y1[3]));
;                     float sb = ((y0[0] * y0[0] + y0[1] * y0[1]) + (y0[2] * y0[2] + y0[3] * y0[3])) + ((y1[0] * y1[0] + y1[1] * y1[1]) + (y1[2] * y1[2] + y1[3] * y1[3]));
;                     sa += dpp_x1(sa);
;                     sb += dpp_x1(sb);
;                     sa += __shfl_xor(sa, 16); sa += __shfl_xor(sa, 32); sb += __shfl_xor(sb, 16); sb += __shfl_xor(sb, 32);
;                     if (fq == 0 && !odd) ps[(size_t)(rl + q) * 64] = (f32x2){sa, sb};
.LBB0_1489:
	s_or_b64 exec, exec, s[64:65]
	ds_read_b64 v[26:27], v201 offset:1288
	s_waitcnt vmcnt(9) lgkmcnt(1)
	v_lshlrev_b32_e32 v29, 16, v80
	v_and_b32_e32 v30, 0xffff0000, v80
	v_cndmask_b32_e64 v21, v21, v34, s[10:11]
	v_cndmask_b32_e64 v20, v20, v32, s[10:11]
	s_waitcnt lgkmcnt(0)
	v_mul_f32_e32 v28, 0x3fb504f3, v27
	v_sub_f32_e32 v31, v30, v26
	v_sub_f32_e32 v30, v29, v26
	v_pk_mul_f32 v[30:31], v[30:31], v[28:29] op_sel_hi:[1,0]
	v_cndmask_b32_e64 v23, v23, v35, s[10:11]
	v_cndmask_b32_e64 v22, v22, v33, s[10:11]
	v_cndmask_b32_e64 v16, v16, v36, s[10:11]
	v_cndmask_b32_e64 v18, v18, v37, s[10:11]
	v_lshlrev_b32_e32 v32, 16, v81
	v_and_b32_e32 v33, 0xffff0000, v81
	v_lshlrev_b32_e32 v34, 16, v82
	v_and_b32_e32 v35, 0xffff0000, v82
	v_lshlrev_b32_e32 v36, 16, v83
	v_and_b32_e32 v37, 0xffff0000, v83
	v_pk_fma_f32 v[30:31], v[76:77], v[30:31], v[184:185]
	v_sub_f32_e32 v33, v33, v26
	v_sub_f32_e32 v32, v32, v26
	v_pk_add_f32 v[20:21], v[20:21], v[30:31]
	v_sub_f32_e32 v31, v35, v26
	v_sub_f32_e32 v30, v34, v26
	v_sub_f32_e32 v27, v37, v26
	v_sub_f32_e32 v26, v36, v26
	v_pk_mul_f32 v[32:33], v[32:33], v[28:29] op_sel_hi:[1,0]
	v_pk_mul_f32 v[26:27], v[26:27], v[28:29] op_sel_hi:[1,0]
	v_pk_mul_f32 v[28:29], v[30:31], v[28:29] op_sel_hi:[1,0]
	v_cndmask_b32_e64 v17, v17, v38, s[10:11]
	v_cndmask_b32_e64 v19, v19, v39, s[10:11]
	v_pk_fma_f32 v[32:33], v[78:79], v[32:33], v[182:183]
	v_pk_fma_f32 v[28:29], v[72:73], v[28:29], v[180:181]
	v_pk_fma_f32 v[26:27], v[74:75], v[26:27], v[178:179]
	v_pk_add_f32 v[22:23], v[22:23], v[32:33]
	v_pk_add_f32 v[18:19], v[18:19], v[26:27]
	v_pk_add_f32 v[16:17], v[16:17], v[28:29]
	v_cvt_pk_bf16_f32 v20, v20, v21
	v_cvt_pk_bf16_f32 v21, v22, v23
	s_nop 0
	v_cvt_pk_bf16_f32 v22, v16, v17
	v_cvt_pk_bf16_f32 v23, v18, v19
	v_lshlrev_b32_e32 v16, 16, v20
	v_and_b32_e32 v18, 0xffff0000, v20
	v_lshlrev_b32_e32 v26, 16, v21
	v_and_b32_e32 v28, 0xffff0000, v21
	v_lshlrev_b32_e32 v30, 16, v22
	v_and_b32_e32 v32, 0xffff0000, v22
	v_lshlrev_b32_e32 v34, 16, v23
	v_and_b32_e32 v36, 0xffff0000, v23
	v_mul_f32_e32 v17, v16, v16
	v_mul_f32_e32 v19, v18, v18
	v_mul_f32_e32 v27, v26, v26
	v_mul_f32_e32 v29, v28, v28
	v_mul_f32_e32 v31, v30, v30
	v_mul_f32_e32 v33, v32, v32
	v_mul_f32_e32 v35, v34, v34
	v_mul_f32_e32 v37, v36, v36
	v_pk_add_f32 v[16:17], v[16:17], v[18:19]
	v_pk_add_f32 v[18:19], v[26:27], v[28:29]
	v_pk_add_f32 v[26:27], v[34:35], v[36:37]
	v_pk_add_f32 v[16:17], v[16:17], v[18:19]
	v_pk_add_f32 v[18:19], v[30:31], v[32:33]
	global_store_dwordx4 v[24:25], v[20:23], off offset:128
	v_pk_add_f32 v[18:19], v[18:19], v[26:27]
	s_nop 0
	v_pk_add_f32 v[16:17], v[16:17], v[18:19]
	v_mov_b32_e32 v18, v165
	v_mov_b32_e32 v19, v165
	s_nop 0
	v_mov_b32_dpp v18, v16 quad_perm:[1,0,3,2] row_mask:0xf bank_mask:0xf
	v_mov_b32_dpp v19, v17 quad_perm:[1,0,3,2] row_mask:0xf bank_mask:0xf
	v_pk_add_f32 v[16:17], v[16:17], v[18:19]
	ds_bpermute_b32 v18, v207, v16
	ds_bpermute_b32 v19, v207, v17
	s_waitcnt lgkmcnt(0)
	v_pk_add_f32 v[16:17], v[16:17], v[18:19]
	ds_bpermute_b32 v18, v208, v16
	ds_bpermute_b32 v19, v208, v17
	s_and_saveexec_b64 s[64:65], s[16:17]
	s_cbranch_execz .LBB0_1491
	s_waitcnt lgkmcnt(0)
	v_pk_add_f32 v[16:17], v[16:17], v[18:19]
	v_add_co_u32_e32 v18, vcc, 0x14000, v186
	s_nop 1
	v_addc_co_u32_e32 v19, vcc, 0, v187, vcc
	v_mov_b32_e32 v252, v250
	v_mov_b32_e32 v253, v251
	v_mov_b32_e32 v254, v16
	v_mov_b32_e32 v255, v17
	global_store_dwordx4 v249, v[252:255], s[94:95] offset:1280
; __device__ __forceinline__ u32x4 pack8f(f32x4 a, f32x4 b) { u32x4 w; w.x = cvt_pk_bf16(a[0], a[1]); w.y = cvt_pk_bf16(a[2], a[3]); w.z = cvt_pk_bf16(b[0], b[1]); w.w = cvt_pk_bf16(b[2], b[3]); return w; }
;     __device__ __forceinline__ void operator()(const f32x4 (&acc)[2][2][4][2], const Unit& u, int wr, int wc, int fr, int fq, const EpiCtx& X) const {
;     ...
;             for (int m = 0; m < 4; ++m) {
;                 const int rl = ai * HALF + m * 16; const unsigned off = lo + (unsigned)(rl * 64) * 2u;
;                 const f32x4 o0a = acc[ai][0][m][0], o0b = acc[ai][0][m][1], o1a = acc[ai][1][m][0], o1b = acc[ai][1][m][1];
;                 const f32x4 ra_ = dpp_swap1(odd ? o0a : o1a), rb_ = dpp_swap1(odd ? o0b : o1b);
;                 const f32x4 pa[2] = {odd ? ra_ : o0a, odd ? o1a : ra_}, pb[2] = {odd ? rb_ : o0b, odd ? o1b : rb_};
; #pragma unroll
;                 for (int q = 0; q < 2; ++q) {
;                     const u32x4 w0 = raw[2 * m + q];
;                     const f32x4 r0 = (f32x4){bf_lo(w0.x), bf_hi(w0.x), bf_lo(w0.y), bf_hi(w0.y)}, r1 = (f32x4){bf_lo(w0.z), bf_hi(w0.z), bf_lo(w0.w), bf_hi(w0.w)};
;                     f32x4 y0, y1;
;                     if (RESN) { const f32x2 t = tbl[rl + q]; const float mu = t.x, ra = t.y * ALPHA; y0 = (r0 - mu) * ra * g0 + b0 + pa[q]; y1 = (r1 - mu) * ra * g1 + b1 + pb[q]; }
;                     else { y0 = r0 * ALPHA + pa[q]; y1 = r1 * ALPHA + pb[q]; }
;                     { const u32x4 w = pack8f(y0, y1); *(u32x4*)(xb + off + q * 128) = w;
;                         y0 = (f32x4){bf_lo(w.x), bf_hi(w.x), bf_lo(w.y), bf_hi(w.y)}; y1 = (f32x4){bf_lo(w.z), bf_hi(w.z), bf_lo(w.w), bf_hi(w.w)}; }
;                     float sa = ((y0[0] + y0[1]) + (y0[2] + y0[3])) + ((y1[0] + y1[1]) + (y1[2] + y1[3]));
;                     float sb = ((y0[0] * y0[0] + y0[1] * y0[1]) + (y0[2] * y0[2] + y0[3] * y0[3])) + ((y1[0] * y1[0] + y1[1] * y1[1]) + (y1[2] * y1[2] + y1[3] * y1[3]));
;                     sa += dpp_x1(sa);
;                     sb += dpp_x1(sb);
;                     sa += __shfl_xor(sa, 16); sa += __shfl_xor(sa, 32); sb += __shfl_xor(sb, 16); sb += __shfl_xor(sb, 32);
;                     if (fq == 0 && !odd) ps[(size_t)(rl + q) * 64] = (f32x2){sa, sb};
.LBB0_1491:
	s_or_b64 exec, exec, s[64:65]
	s_waitcnt lgkmcnt(1)
	v_cndmask_b32_e64 v18, v12, v4, s[10:11]
	v_mov_b32_e32 v16, 0
	v_cndmask_b32_e64 v17, v13, v5, s[10:11]
	s_waitcnt lgkmcnt(0)
	v_cndmask_b32_e64 v19, v14, v6, s[10:11]
	v_mov_b32_dpp v16, v18 quad_perm:[1,0,3,2] row_mask:0xf bank_mask:0xf
	v_mov_b32_e32 v18, 0
	v_cndmask_b32_e64 v20, v15, v7, s[10:11]
	v_cndmask_b32_e64 v22, v8, v0, s[10:11]
	v_mov_b32_dpp v18, v17 quad_perm:[1,0,3,2] row_mask:0xf bank_mask:0xf
	v_mov_b32_e32 v17, 0
	v_cndmask_b32_e64 v21, v9, v1, s[10:11]
	v_cndmask_b32_e64 v23, v10, v2, s[10:11]
	v_mov_b32_dpp v17, v19 quad_perm:[1,0,3,2] row_mask:0xf bank_mask:0xf
	v_mov_b32_e32 v19, 0
	v_cndmask_b32_e64 v24, v11, v3, s[10:11]
	s_waitcnt vmcnt(10)
	v_lshlrev_b32_e32 v27, 16, v68
	v_mov_b32_dpp v19, v20 quad_perm:[1,0,3,2] row_mask:0xf bank_mask:0xf
	v_mov_b32_e32 v20, 0
	v_and_b32_e32 v28, 0xffff0000, v68
	v_cndmask_b32_e64 v13, v18, v13, s[10:11]
	v_mov_b32_dpp v20, v22 quad_perm:[1,0,3,2] row_mask:0xf bank_mask:0xf
	v_mov_b32_e32 v22, 0
	v_cndmask_b32_e64 v12, v16, v12, s[10:11]
	v_lshlrev_b32_e32 v30, 16, v69
	v_mov_b32_dpp v22, v21 quad_perm:[1,0,3,2] row_mask:0xf bank_mask:0xf
	v_mov_b32_e32 v21, 0
	v_and_b32_e32 v31, 0xffff0000, v69
	v_lshlrev_b32_e32 v32, 16, v70
	v_mov_b32_dpp v21, v23 quad_perm:[1,0,3,2] row_mask:0xf bank_mask:0xf
	v_mov_b32_e32 v23, 0
	v_and_b32_e32 v33, 0xffff0000, v70
	v_lshlrev_b32_e32 v34, 16, v71
	v_mov_b32_dpp v23, v24 quad_perm:[1,0,3,2] row_mask:0xf bank_mask:0xf
	ds_read_b64 v[24:25], v201 offset:1408
	v_and_b32_e32 v35, 0xffff0000, v71
	v_cndmask_b32_e64 v15, v19, v15, s[10:11]
	v_cndmask_b32_e64 v14, v17, v14, s[10:11]
	v_cndmask_b32_e64 v9, v22, v9, s[10:11]
	s_waitcnt lgkmcnt(0)
	v_mul_f32_e32 v26, 0x3fb504f3, v25
	v_sub_f32_e32 v29, v28, v24
	v_sub_f32_e32 v28, v27, v24
	v_pk_mul_f32 v[28:29], v[28:29], v[26:27] op_sel_hi:[1,0]
	v_sub_f32_e32 v31, v31, v24
	v_pk_fma_f32 v[28:29], v[76:77], v[28:29], v[184:185]
	v_sub_f32_e32 v30, v30, v24
	v_pk_add_f32 v[12:13], v[12:13], v[28:29]
	v_sub_f32_e32 v29, v33, v24
	v_sub_f32_e32 v28, v32, v24
	v_sub_f32_e32 v25, v35, v24
	v_sub_f32_e32 v24, v34, v24
	v_pk_mul_f32 v[30:31], v[30:31], v[26:27] op_sel_hi:[1,0]
	v_pk_mul_f32 v[24:25], v[24:25], v[26:27] op_sel_hi:[1,0]
	v_pk_mul_f32 v[26:27], v[28:29], v[26:27] op_sel_hi:[1,0]
	v_cndmask_b32_e64 v8, v20, v8, s[10:11]
	v_cndmask_b32_e64 v11, v23, v11, s[10:11]
	v_cndmask_b32_e64 v10, v21, v10, s[10:11]
	v_pk_fma_f32 v[30:31], v[78:79], v[30:31], v[182:183]
	v_pk_fma_f32 v[26:27], v[72:73], v[26:27], v[180:181]
	v_pk_fma_f32 v[24:25], v[74:75], v[24:25], v[178:179]
	v_pk_add_f32 v[14:15], v[14:15], v[30:31]
	v_pk_add_f32 v[10:11], v[10:11], v[24:25]
	v_pk_add_f32 v[8:9], v[8:9], v[26:27]
	v_cvt_pk_bf16_f32 v24, v12, v13
	v_cvt_pk_bf16_f32 v25, v14, v15
	s_nop 0
	v_cvt_pk_bf16_f32 v26, v8, v9
	v_cvt_pk_bf16_f32 v27, v10, v11
	v_lshlrev_b32_e32 v8, 16, v24
	v_and_b32_e32 v10, 0xffff0000, v24
	v_lshlrev_b32_e32 v12, 16, v25
	v_and_b32_e32 v14, 0xffff0000, v25
	v_lshlrev_b32_e32 v28, 16, v26
	v_and_b32_e32 v30, 0xffff0000, v26
	v_lshlrev_b32_e32 v32, 16, v27
	v_and_b32_e32 v34, 0xffff0000, v27
	v_mul_f32_e32 v9, v8, v8
	v_mul_f32_e32 v11, v10, v10
	v_mul_f32_e32 v13, v12, v12
	v_mul_f32_e32 v15, v14, v14
	v_mul_f32_e32 v29, v28, v28
	v_mul_f32_e32 v31, v30, v30
	v_mul_f32_e32 v33, v32, v32
	v_mul_f32_e32 v35, v34, v34
	v_pk_add_f32 v[8:9], v[8:9], v[10:11]
	v_pk_add_f32 v[10:11], v[12:13], v[14:15]
	v_pk_add_f32 v[12:13], v[32:33], v[34:35]
	v_pk_add_f32 v[8:9], v[8:9], v[10:11]
	v_pk_add_f32 v[10:11], v[28:29], v[30:31]
	s_nop 0
	v_pk_add_f32 v[10:11], v[10:11], v[12:13]
	s_nop 0
	v_pk_add_f32 v[8:9], v[8:9], v[10:11]
	v_mov_b32_e32 v10, v165
	v_mov_b32_e32 v11, v165
	s_nop 0
	v_mov_b32_dpp v10, v8 quad_perm:[1,0,3,2] row_mask:0xf bank_mask:0xf
	v_mov_b32_dpp v11, v9 quad_perm:[1,0,3,2] row_mask:0xf bank_mask:0xf
	v_pk_add_f32 v[8:9], v[8:9], v[10:11]
	ds_bpermute_b32 v10, v207, v8
	ds_bpermute_b32 v11, v207, v9
	s_waitcnt lgkmcnt(0)
	v_pk_add_f32 v[10:11], v[8:9], v[10:11]
	ds_bpermute_b32 v12, v208, v10
	ds_bpermute_b32 v13, v208, v11
	v_lshl_add_u64 v[8:9], s[20:21], 0, v[164:165]
	global_store_dwordx4 v[8:9], v[24:27], off
	s_and_saveexec_b64 s[20:21], s[16:17]
	s_cbranch_execz .LBB0_1493
	s_waitcnt lgkmcnt(0)
	v_pk_add_f32 v[10:11], v[10:11], v[12:13]
	v_add_co_u32_e32 v12, vcc, 0x16000, v186
	s_nop 1
	v_addc_co_u32_e32 v13, vcc, 0, v187, vcc
	v_mov_b32_e32 v250, v10
	v_mov_b32_e32 v251, v11

; #define LAS __attribute__((address_space(3)))
; __device__ __forceinline__ void build_tbl(const f32x2* PS, int pm, LAS unsigned char* lds, int wid, int lane) {
;     LAS f32x2* tbl = (LAS f32x2*)(lds + TBL_OFF);
;     const f32x2* p = PS + ((size_t)pm * BM + wid * 32) * 64 + lane;
; #pragma unroll 8
;     for (int i = 0; i < 32; ++i) {
;         const f32x2 v = p[(size_t)i * 64];
;         const float a = wave_sum(v.x), b = wave_sum(v.y);
;         if (lane == 0) { const float mu = a * (1.f / DM), var = fmaxf(b * (1.f / DM) - mu * mu, 0.f); tbl[wid * 32 + i] = (f32x2){mu, 1.f / sqrtf(var + LN_EPS)}; }
.LBB0_1573:
	v_mov_b32_e32 v128, s65
	ds_read_b32 v128, v128
	s_add_i32 s25, s52, 0x81
	s_ashr_i32 s53, s52, 31
	s_waitcnt lgkmcnt(0)
	v_readfirstlane_b32 s16, v128
	s_cmp_eq_u32 s16, s25
	s_cbranch_scc1 .LBB0_1595
	s_ashr_i32 s53, s52, 31
	s_load_dwordx2 s[16:17], s[0:1], 0xb0
	s_lshl_b32 s56, s52, 11
	s_add_u32 s56, s56, s62
	s_add_u32 s56, s56, 0x5c800000
	v_lshlrev_b32_e32 v222, 17, v168
	s_waitcnt lgkmcnt(0)
	s_add_u32 s16, s16, s56
	s_addc_u32 s17, s17, 0
	global_load_dwordx4 v[128:131], v222, s[16:17]
	global_load_dwordx4 v[132:135], v222, s[16:17] offset:16
	global_load_dwordx4 v[136:139], v222, s[16:17] offset:32
	global_load_dwordx4 v[170:173], v222, s[16:17] offset:48
	global_load_dwordx4 v[174:177], v222, s[16:17] offset:64
	global_load_dwordx4 v[178:181], v222, s[16:17] offset:80
	global_load_dwordx4 v[182:185], v222, s[16:17] offset:96
	global_load_dwordx4 v[186:189], v222, s[16:17] offset:112
	global_load_dwordx4 v[190:193], v222, s[16:17] offset:128
	global_load_dwordx4 v[194:197], v222, s[16:17] offset:144
	global_load_dwordx4 v[198:201], v222, s[16:17] offset:160
	global_load_dwordx4 v[202:205], v222, s[16:17] offset:176
	global_load_dwordx4 v[206:209], v222, s[16:17] offset:192
	global_load_dwordx4 v[210:213], v222, s[16:17] offset:208
	global_load_dwordx4 v[214:217], v222, s[16:17] offset:224
	global_load_dwordx4 v[218:221], v222, s[16:17] offset:240
	s_waitcnt vmcnt(0)
	v_permlane32_swap_b32_e32 v128, v190
	v_permlane32_swap_b32_e32 v129, v191
	v_permlane32_swap_b32_e32 v130, v192
	v_permlane32_swap_b32_e32 v131, v193
	v_permlane32_swap_b32_e32 v132, v194
	v_permlane32_swap_b32_e32 v133, v195
	v_permlane32_swap_b32_e32 v134, v196
	v_permlane32_swap_b32_e32 v135, v197
	v_permlane32_swap_b32_e32 v136, v198
	v_permlane32_swap_b32_e32 v137, v199
	v_permlane32_swap_b32_e32 v138, v200
	v_permlane32_swap_b32_e32 v139, v201
	v_permlane32_swap_b32_e32 v170, v202
	v_permlane32_swap_b32_e32 v171, v203
	v_permlane32_swap_b32_e32 v172, v204
	v_permlane32_swap_b32_e32 v173, v205
	v_permlane32_swap_b32_e32 v174, v206
	v_permlane32_swap_b32_e32 v175, v207
	v_permlane32_swap_b32_e32 v176, v208
	v_permlane32_swap_b32_e32 v177, v209
	v_permlane32_swap_b32_e32 v178, v210
	v_permlane32_swap_b32_e32 v179, v211
	v_permlane32_swap_b32_e32 v180, v212
	v_permlane32_swap_b32_e32 v181, v213
	v_permlane32_swap_b32_e32 v182, v214
	v_permlane32_swap_b32_e32 v183, v215
	v_permlane32_swap_b32_e32 v184, v216
	v_permlane32_swap_b32_e32 v185, v217
	v_permlane32_swap_b32_e32 v186, v218
	v_permlane32_swap_b32_e32 v187, v219
	v_permlane32_swap_b32_e32 v188, v220
	v_permlane32_swap_b32_e32 v189, v221
	v_pk_add_f32 v[128:129], v[128:129], v[190:191]
	v_pk_add_f32 v[130:131], v[130:131], v[192:193]
	v_pk_add_f32 v[132:133], v[132:133], v[194:195]
	v_pk_add_f32 v[134:135], v[134:135], v[196:197]
	v_pk_add_f32 v[136:137], v[136:137], v[198:199]
	v_pk_add_f32 v[138:139], v[138:139], v[200:201]
	v_pk_add_f32 v[170:171], v[170:171], v[202:203]
	v_pk_add_f32 v[172:173], v[172:173], v[204:205]
	v_pk_add_f32 v[174:175], v[174:175], v[206:207]
	v_pk_add_f32 v[176:177], v[176:177], v[208:209]
	v_pk_add_f32 v[178:179], v[178:179], v[210:211]
	v_pk_add_f32 v[180:181], v[180:181], v[212:213]
	v_pk_add_f32 v[182:183], v[182:183], v[214:215]
	v_pk_add_f32 v[184:185], v[184:185], v[216:217]
	v_pk_add_f32 v[186:187], v[186:187], v[218:219]
	v_pk_add_f32 v[188:189], v[188:189], v[220:221]
	s_nop 1
	v_permlane16_swap_b32_e32 v128, v174
	v_permlane16_swap_b32_e32 v129, v175
	v_permlane16_swap_b32_e32 v130, v176
	v_permlane16_swap_b32_e32 v131, v177
	v_permlane16_swap_b32_e32 v132, v178
	v_permlane16_swap_b32_e32 v133, v179
	v_permlane16_swap_b32_e32 v134, v180
	v_permlane16_swap_b32_e32 v135, v181
	v_permlane16_swap_b32_e32 v136, v182
	v_permlane16_swap_b32_e32 v137, v183
	v_permlane16_swap_b32_e32 v138, v184
	v_permlane16_swap_b32_e32 v139, v185
	v_permlane16_swap_b32_e32 v170, v186
	v_permlane16_swap_b32_e32 v171, v187
	v_permlane16_swap_b32_e32 v172, v188
	v_permlane16_swap_b32_e32 v173, v189
	v_pk_add_f32 v[128:129], v[128:129], v[174:175]
	v_pk_add_f32 v[130:131], v[130:131], v[176:177]
	v_pk_add_f32 v[132:133], v[132:133], v[178:179]
	v_pk_add_f32 v[134:135], v[134:135], v[180:181]
	v_pk_add_f32 v[136:137], v[136:137], v[182:183]
	v_pk_add_f32 v[138:139], v[138:139], v[184:185]
	v_pk_add_f32 v[170:171], v[170:171], v[186:187]
	v_pk_add_f32 v[172:173], v[172:173], v[188:189]
	s_nop 1
	v_add_f32_dpp v128, v128, v128 row_ror:8 row_mask:0xf bank_mask:0xf
	v_add_f32_dpp v129, v129, v129 row_ror:8 row_mask:0xf bank_mask:0xf
	v_add_f32_dpp v130, v130, v130 row_ror:8 row_mask:0xf bank_mask:0xf
	v_add_f32_dpp v131, v131, v131 row_ror:8 row_mask:0xf bank_mask:0xf
	v_add_f32_dpp v132, v132, v132 row_ror:8 row_mask:0xf bank_mask:0xf
	v_add_f32_dpp v133, v133, v133 row_ror:8 row_mask:0xf bank_mask:0xf
	v_add_f32_dpp v134, v134, v134 row_ror:8 row_mask:0xf bank_mask:0xf
	v_add_f32_dpp v135, v135, v135 row_ror:8 row_mask:0xf bank_mask:0xf
	v_add_f32_dpp v136, v136, v136 row_ror:8 row_mask:0xf bank_mask:0xf
	v_add_f32_dpp v137, v137, v137 row_ror:8 row_mask:0xf bank_mask:0xf
	v_add_f32_dpp v138, v138, v138 row_ror:8 row_mask:0xf bank_mask:0xf
	v_add_f32_dpp v139, v139, v139 row_ror:8 row_mask:0xf bank_mask:0xf
	v_add_f32_dpp v170, v170, v170 row_ror:8 row_mask:0xf bank_mask:0xf
	v_add_f32_dpp v171, v171, v171 row_ror:8 row_mask:0xf bank_mask:0xf
	v_add_f32_dpp v172, v172, v172 row_ror:8 row_mask:0xf bank_mask:0xf
	v_add_f32_dpp v173, v173, v173 row_ror:8 row_mask:0xf bank_mask:0xf
	v_add_f32_dpp v128, v128, v128 row_ror:4 row_mask:0xf bank_mask:0xf
	v_add_f32_dpp v129, v129, v129 row_ror:4 row_mask:0xf bank_mask:0xf
; __device__ __forceinline__ void build_tbl(const f32x2* PS, int pm, LAS unsigned char* lds, int wid, int lane) {
;     ...
;         const float a = wave_sum(v.x), b = wave_sum(v.y);
;         if (lane == 0) { const float mu = a * (1.f / DM), var = fmaxf(b * (1.f / DM) - mu * mu, 0.f); tbl[wid * 32 + i] = (f32x2){mu, 1.f / sqrtf(var + LN_EPS)}; }
	v_add_f32_dpp v130, v130, v130 row_ror:4 row_mask:0xf bank_mask:0xf
	v_add_f32_dpp v131, v131, v131 row_ror:4 row_mask:0xf bank_mask:0xf
	v_add_f32_dpp v132, v132, v132 row_ror:4 row_mask:0xf bank_mask:0xf
	v_add_f32_dpp v133, v133, v133 row_ror:4 row_mask:0xf bank_mask:0xf
	v_add_f32_dpp v134, v134, v134 row_ror:4 row_mask:0xf bank_mask:0xf
	v_add_f32_dpp v135, v135, v135 row_ror:4 row_mask:0xf bank_mask:0xf
	v_add_f32_dpp v136, v136, v136 row_ror:4 row_mask:0xf bank_mask:0xf
	v_add_f32_dpp v137, v137, v137 row_ror:4 row_mask:0xf bank_mask:0xf
	v_add_f32_dpp v138, v138, v138 row_ror:4 row_mask:0xf bank_mask:0xf
	v_add_f32_dpp v139, v139, v139 row_ror:4 row_mask:0xf bank_mask:0xf
	v_add_f32_dpp v170, v170, v170 row_ror:4 row_mask:0xf bank_mask:0xf
	v_add_f32_dpp v171, v171, v171 row_ror:4 row_mask:0xf bank_mask:0xf
	v_add_f32_dpp v172, v172, v172 row_ror:4 row_mask:0xf bank_mask:0xf
	v_add_f32_dpp v173, v173, v173 row_ror:4 row_mask:0xf bank_mask:0xf
	v_add_f32_dpp v128, v128, v128 row_ror:2 row_mask:0xf bank_mask:0xf
	v_add_f32_dpp v129, v129, v129 row_ror:2 row_mask:0xf bank_mask:0xf
	v_add_f32_dpp v130, v130, v130 row_ror:2 row_mask:0xf bank_mask:0xf
	v_add_f32_dpp v131, v131, v131 row_ror:2 row_mask:0xf bank_mask:0xf
	v_add_f32_dpp v132, v132, v132 row_ror:2 row_mask:0xf bank_mask:0xf
	v_add_f32_dpp v133, v133, v133 row_ror:2 row_mask:0xf bank_mask:0xf
	v_add_f32_dpp v134, v134, v134 row_ror:2 row_mask:0xf bank_mask:0xf
	v_add_f32_dpp v135, v135, v135 row_ror:2 row_mask:0xf bank_mask:0xf
	v_add_f32_dpp v136, v136, v136 row_ror:2 row_mask:0xf bank_mask:0xf
	v_add_f32_dpp v137, v137, v137 row_ror:2 row_mask:0xf bank_mask:0xf
	v_add_f32_dpp v138, v138, v138 row_ror:2 row_mask:0xf bank_mask:0xf
	v_add_f32_dpp v139, v139, v139 row_ror:2 row_mask:0xf bank_mask:0xf
	v_add_f32_dpp v170, v170, v170 row_ror:2 row_mask:0xf bank_mask:0xf
	v_add_f32_dpp v171, v171, v171 row_ror:2 row_mask:0xf bank_mask:0xf
	v_add_f32_dpp v172, v172, v172 row_ror:2 row_mask:0xf bank_mask:0xf
	v_add_f32_dpp v173, v173, v173 row_ror:2 row_mask:0xf bank_mask:0xf
	v_add_f32_dpp v128, v128, v128 row_ror:1 row_mask:0xf bank_mask:0xf
	v_add_f32_dpp v129, v129, v129 row_ror:1 row_mask:0xf bank_mask:0xf
	v_add_f32_dpp v130, v130, v130 row_ror:1 row_mask:0xf bank_mask:0xf
	v_add_f32_dpp v131, v131, v131 row_ror:1 row_mask:0xf bank_mask:0xf
	v_add_f32_dpp v132, v132, v132 row_ror:1 row_mask:0xf bank_mask:0xf
	v_add_f32_dpp v133, v133, v133 row_ror:1 row_mask:0xf bank_mask:0xf
	v_add_f32_dpp v134, v134, v134 row_ror:1 row_mask:0xf bank_mask:0xf
	v_add_f32_dpp v135, v135, v135 row_ror:1 row_mask:0xf bank_mask:0xf
	v_add_f32_dpp v136, v136, v136 row_ror:1 row_mask:0xf bank_mask:0xf
	v_add_f32_dpp v137, v137, v137 row_ror:1 row_mask:0xf bank_mask:0xf
	v_add_f32_dpp v138, v138, v138 row_ror:1 row_mask:0xf bank_mask:0xf
	v_add_f32_dpp v139, v139, v139 row_ror:1 row_mask:0xf bank_mask:0xf
	v_add_f32_dpp v170, v170, v170 row_ror:1 row_mask:0xf bank_mask:0xf
	v_add_f32_dpp v171, v171, v171 row_ror:1 row_mask:0xf bank_mask:0xf
	v_add_f32_dpp v172, v172, v172 row_ror:1 row_mask:0xf bank_mask:0xf
	v_add_f32_dpp v173, v173, v173 row_ror:1 row_mask:0xf bank_mask:0xf
	s_nop 1
	v_mul_f32_e32 v128, s22, v128
	v_mul_f32_e32 v129, s22, v129
	v_fma_f32 v129, -v128, v128, v129
	v_max_f32_e32 v129, 0, v129
	v_add_f32_e32 v129, 0x3727c5ac, v129
	v_mul_f32_e32 v224, 0x4f800000, v129
	v_cmp_gt_f32_e32 vcc, s66, v129
	s_nop 1
	v_cndmask_b32_e32 v129, v129, v224, vcc
	v_sqrt_f32_e32 v224, v129
	s_nop 0
	v_add_u32_e32 v225, -1, v224
	v_fma_f32 v227, -v225, v224, v129
	v_add_u32_e32 v226, 1, v224
	v_cmp_ge_f32_e64 s[16:17], 0, v227
	s_nop 1
	v_cndmask_b32_e64 v225, v224, v225, s[16:17]
	v_fma_f32 v224, -v226, v224, v129
	v_cmp_lt_f32_e64 s[16:17], 0, v224
	s_nop 1
	v_cndmask_b32_e64 v224, v225, v226, s[16:17]
	v_mul_f32_e32 v225, 0x37800000, v224
	v_cndmask_b32_e32 v224, v224, v225, vcc
	v_cmp_class_f32_e32 vcc, v129, v167
	s_nop 1
	v_cndmask_b32_e32 v129, v224, v129, vcc
	v_div_scale_f32 v224, s[16:17], v129, v129, 1.0
	v_rcp_f32_e32 v225, v224
	s_nop 0
	v_fma_f32 v226, -v224, v225, 1.0
	v_fmac_f32_e32 v225, v226, v225
	v_div_scale_f32 v226, vcc, 1.0, v129, 1.0
	v_mul_f32_e32 v227, v226, v225
	v_fma_f32 v228, -v224, v227, v226
	v_fmac_f32_e32 v227, v228, v225
	v_fma_f32 v224, -v224, v227, v226
	v_div_fmas_f32 v224, v224, v225, v227
	v_div_fixup_f32 v129, v224, v129, 1.0
	v_mul_f32_e32 v130, s22, v130
	v_mul_f32_e32 v131, s22, v131
	v_fma_f32 v131, -v130, v130, v131
	v_max_f32_e32 v131, 0, v131
	v_add_f32_e32 v131, 0x3727c5ac, v131
	v_mul_f32_e32 v224, 0x4f800000, v131
	v_cmp_gt_f32_e32 vcc, s66, v131
	s_nop 1
	v_cndmask_b32_e32 v131, v131, v224, vcc
	v_sqrt_f32_e32 v224, v131
	s_nop 0
	v_add_u32_e32 v225, -1, v224
	v_fma_f32 v227, -v225, v224, v131
	v_add_u32_e32 v226, 1, v224
	v_cmp_ge_f32_e64 s[16:17], 0, v227
	s_nop 1
	v_cndmask_b32_e64 v225, v224, v225, s[16:17]
	v_fma_f32 v224, -v226, v224, v131
	v_cmp_lt_f32_e64 s[16:17], 0, v224
	s_nop 1
	v_cndmask_b32_e64 v224, v225, v226, s[16:17]
	v_mul_f32_e32 v225, 0x37800000, v224
	v_cndmask_b32_e32 v224, v224, v225, vcc
	v_cmp_class_f32_e32 vcc, v131, v167
	s_nop 1
	v_cndmask_b32_e32 v131, v224, v131, vcc
	v_div_scale_f32 v224, s[16:17], v131, v131, 1.0
	v_rcp_f32_e32 v225, v224
	s_nop 0
	v_fma_f32 v226, -v224, v225, 1.0
	v_fmac_f32_e32 v225, v226, v225
	v_div_scale_f32 v226, vcc, 1.0, v131, 1.0
	v_mul_f32_e32 v227, v226, v225
	v_fma_f32 v228, -v224, v227, v226
	v_fmac_f32_e32 v227, v228, v225
	v_fma_f32 v224, -v224, v227, v226
	v_div_fmas_f32 v224, v224, v225, v227
	v_div_fixup_f32 v131, v224, v131, 1.0
	v_mul_f32_e32 v132, s22, v132
	v_mul_f32_e32 v133, s22, v133
; __device__ __forceinline__ void build_tbl(const f32x2* PS, int pm, LAS unsigned char* lds, int wid, int lane) {
;     ...
;         if (lane == 0) { const float mu = a * (1.f / DM), var = fmaxf(b * (1.f / DM) - mu * mu, 0.f); tbl[wid * 32 + i] = (f32x2){mu, 1.f / sqrtf(var + LN_EPS)}; }
	v_fma_f32 v133, -v132, v132, v133
	v_max_f32_e32 v133, 0, v133
	v_add_f32_e32 v133, 0x3727c5ac, v133
	v_mul_f32_e32 v224, 0x4f800000, v133
	v_cmp_gt_f32_e32 vcc, s66, v133
	s_nop 1
	v_cndmask_b32_e32 v133, v133, v224, vcc
	v_sqrt_f32_e32 v224, v133
	s_nop 0
	v_add_u32_e32 v225, -1, v224
	v_fma_f32 v227, -v225, v224, v133
	v_add_u32_e32 v226, 1, v224
	v_cmp_ge_f32_e64 s[16:17], 0, v227
	s_nop 1
	v_cndmask_b32_e64 v225, v224, v225, s[16:17]
	v_fma_f32 v224, -v226, v224, v133
	v_cmp_lt_f32_e64 s[16:17], 0, v224
	s_nop 1
	v_cndmask_b32_e64 v224, v225, v226, s[16:17]
	v_mul_f32_e32 v225, 0x37800000, v224
	v_cndmask_b32_e32 v224, v224, v225, vcc
	v_cmp_class_f32_e32 vcc, v133, v167
	s_nop 1
	v_cndmask_b32_e32 v133, v224, v133, vcc
	v_div_scale_f32 v224, s[16:17], v133, v133, 1.0
	v_rcp_f32_e32 v225, v224
	s_nop 0
	v_fma_f32 v226, -v224, v225, 1.0
	v_fmac_f32_e32 v225, v226, v225
	v_div_scale_f32 v226, vcc, 1.0, v133, 1.0
	v_mul_f32_e32 v227, v226, v225
	v_fma_f32 v228, -v224, v227, v226
	v_fmac_f32_e32 v227, v228, v225
	v_fma_f32 v224, -v224, v227, v226
	v_div_fmas_f32 v224, v224, v225, v227
	v_div_fixup_f32 v133, v224, v133, 1.0
	v_mul_f32_e32 v134, s22, v134
	v_mul_f32_e32 v135, s22, v135
	v_fma_f32 v135, -v134, v134, v135
	v_max_f32_e32 v135, 0, v135
	v_add_f32_e32 v135, 0x3727c5ac, v135
	v_mul_f32_e32 v224, 0x4f800000, v135
	v_cmp_gt_f32_e32 vcc, s66, v135
	s_nop 1
	v_cndmask_b32_e32 v135, v135, v224, vcc
	v_sqrt_f32_e32 v224, v135
	s_nop 0
	v_add_u32_e32 v225, -1, v224
	v_fma_f32 v227, -v225, v224, v135
	v_add_u32_e32 v226, 1, v224
	v_cmp_ge_f32_e64 s[16:17], 0, v227
	s_nop 1
	v_cndmask_b32_e64 v225, v224, v225, s[16:17]
	v_fma_f32 v224, -v226, v224, v135
	v_cmp_lt_f32_e64 s[16:17], 0, v224
	s_nop 1
	v_cndmask_b32_e64 v224, v225, v226, s[16:17]
	v_mul_f32_e32 v225, 0x37800000, v224
	v_cndmask_b32_e32 v224, v224, v225, vcc
	v_cmp_class_f32_e32 vcc, v135, v167
	s_nop 1
	v_cndmask_b32_e32 v135, v224, v135, vcc
	v_div_scale_f32 v224, s[16:17], v135, v135, 1.0
	v_rcp_f32_e32 v225, v224
	s_nop 0
	v_fma_f32 v226, -v224, v225, 1.0
	v_fmac_f32_e32 v225, v226, v225
	v_div_scale_f32 v226, vcc, 1.0, v135, 1.0
	v_mul_f32_e32 v227, v226, v225
	v_fma_f32 v228, -v224, v227, v226
	v_fmac_f32_e32 v227, v228, v225
	v_fma_f32 v224, -v224, v227, v226
	v_div_fmas_f32 v224, v224, v225, v227
	v_div_fixup_f32 v135, v224, v135, 1.0
	v_mul_f32_e32 v136, s22, v136
	v_mul_f32_e32 v137, s22, v137
	v_fma_f32 v137, -v136, v136, v137
	v_max_f32_e32 v137, 0, v137
	v_add_f32_e32 v137, 0x3727c5ac, v137
	v_mul_f32_e32 v224, 0x4f800000, v137
	v_cmp_gt_f32_e32 vcc, s66, v137
	s_nop 1
	v_cndmask_b32_e32 v137, v137, v224, vcc
	v_sqrt_f32_e32 v224, v137
	s_nop 0
	v_add_u32_e32 v225, -1, v224
	v_fma_f32 v227, -v225, v224, v137
	v_add_u32_e32 v226, 1, v224
	v_cmp_ge_f32_e64 s[16:17], 0, v227
	s_nop 1
	v_cndmask_b32_e64 v225, v224, v225, s[16:17]
	v_fma_f32 v224, -v226, v224, v137
	v_cmp_lt_f32_e64 s[16:17], 0, v224
	s_nop 1
	v_cndmask_b32_e64 v224, v225, v226, s[16:17]
	v_mul_f32_e32 v225, 0x37800000, v224
	v_cndmask_b32_e32 v224, v224, v225, vcc
	v_cmp_class_f32_e32 vcc, v137, v167
	s_nop 1
	v_cndmask_b32_e32 v137, v224, v137, vcc
	v_div_scale_f32 v224, s[16:17], v137, v137, 1.0
	v_rcp_f32_e32 v225, v224
	s_nop 0
	v_fma_f32 v226, -v224, v225, 1.0
	v_fmac_f32_e32 v225, v226, v225
	v_div_scale_f32 v226, vcc, 1.0, v137, 1.0
	v_mul_f32_e32 v227, v226, v225
	v_fma_f32 v228, -v224, v227, v226
	v_fmac_f32_e32 v227, v228, v225
	v_fma_f32 v224, -v224, v227, v226
	v_div_fmas_f32 v224, v224, v225, v227
	v_div_fixup_f32 v137, v224, v137, 1.0
	v_mul_f32_e32 v138, s22, v138
	v_mul_f32_e32 v139, s22, v139
	v_fma_f32 v139, -v138, v138, v139
	v_max_f32_e32 v139, 0, v139
	v_add_f32_e32 v139, 0x3727c5ac, v139
	v_mul_f32_e32 v224, 0x4f800000, v139
	v_cmp_gt_f32_e32 vcc, s66, v139
	s_nop 1
	v_cndmask_b32_e32 v139, v139, v224, vcc
	v_sqrt_f32_e32 v224, v139
; #define LAS __attribute__((address_space(3)))
; __device__ __forceinline__ void build_tbl(const f32x2* PS, int pm, LAS unsigned char* lds, int wid, int lane) {
;     ...
;         if (lane == 0) { const float mu = a * (1.f / DM), var = fmaxf(b * (1.f / DM) - mu * mu, 0.f); tbl[wid * 32 + i] = (f32x2){mu, 1.f / sqrtf(var + LN_EPS)}; }
;     }
; }
; __device__ __forceinline__ void ensure_tbl(const f32x2* PS, int sid, int pm, const EpiCtx& X) {
;     volatile LAS unsigned* keyw = (volatile LAS unsigned*)(X.lds + MISC_OFF) + KEY_WORD;
;     const unsigned key = (unsigned)(sid * 64 + pm + 1);
;     if ((unsigned)__builtin_amdgcn_readfirstlane((int)keyw[0]) != key) {
;         build_tbl(PS, pm, X.lds, X.wid, X.lane);
;         asm volatile("s_waitcnt lgkmcnt(0)" ::: "memory"); __builtin_amdgcn_s_barrier(); asm volatile("" ::: "memory");
;         if (X.tid == 0) keyw[0] = key;
	s_nop 0
	v_add_u32_e32 v225, -1, v224
	v_fma_f32 v227, -v225, v224, v139
	v_add_u32_e32 v226, 1, v224
	v_cmp_ge_f32_e64 s[16:17], 0, v227
	s_nop 1
	v_cndmask_b32_e64 v225, v224, v225, s[16:17]
	v_fma_f32 v224, -v226, v224, v139
	v_cmp_lt_f32_e64 s[16:17], 0, v224
	s_nop 1
	v_cndmask_b32_e64 v224, v225, v226, s[16:17]
	v_mul_f32_e32 v225, 0x37800000, v224
	v_cndmask_b32_e32 v224, v224, v225, vcc
	v_cmp_class_f32_e32 vcc, v139, v167
	s_nop 1
	v_cndmask_b32_e32 v139, v224, v139, vcc
	v_div_scale_f32 v224, s[16:17], v139, v139, 1.0
	v_rcp_f32_e32 v225, v224
	s_nop 0
	v_fma_f32 v226, -v224, v225, 1.0
	v_fmac_f32_e32 v225, v226, v225
	v_div_scale_f32 v226, vcc, 1.0, v139, 1.0
	v_mul_f32_e32 v227, v226, v225
	v_fma_f32 v228, -v224, v227, v226
	v_fmac_f32_e32 v227, v228, v225
	v_fma_f32 v224, -v224, v227, v226
	v_div_fmas_f32 v224, v224, v225, v227
	v_div_fixup_f32 v139, v224, v139, 1.0
	v_mul_f32_e32 v170, s22, v170
	v_mul_f32_e32 v171, s22, v171
	v_fma_f32 v171, -v170, v170, v171
	v_max_f32_e32 v171, 0, v171
	v_add_f32_e32 v171, 0x3727c5ac, v171
	v_mul_f32_e32 v224, 0x4f800000, v171
	v_cmp_gt_f32_e32 vcc, s66, v171
	s_nop 1
	v_cndmask_b32_e32 v171, v171, v224, vcc
	v_sqrt_f32_e32 v224, v171
	s_nop 0
	v_add_u32_e32 v225, -1, v224
	v_fma_f32 v227, -v225, v224, v171
	v_add_u32_e32 v226, 1, v224
	v_cmp_ge_f32_e64 s[16:17], 0, v227
	s_nop 1
	v_cndmask_b32_e64 v225, v224, v225, s[16:17]
	v_fma_f32 v224, -v226, v224, v171
	v_cmp_lt_f32_e64 s[16:17], 0, v224
	s_nop 1
	v_cndmask_b32_e64 v224, v225, v226, s[16:17]
	v_mul_f32_e32 v225, 0x37800000, v224
	v_cndmask_b32_e32 v224, v224, v225, vcc
	v_cmp_class_f32_e32 vcc, v171, v167
	s_nop 1
	v_cndmask_b32_e32 v171, v224, v171, vcc
	v_div_scale_f32 v224, s[16:17], v171, v171, 1.0
	v_rcp_f32_e32 v225, v224
	s_nop 0
	v_fma_f32 v226, -v224, v225, 1.0
	v_fmac_f32_e32 v225, v226, v225
	v_div_scale_f32 v226, vcc, 1.0, v171, 1.0
	v_mul_f32_e32 v227, v226, v225
	v_fma_f32 v228, -v224, v227, v226
	v_fmac_f32_e32 v227, v228, v225
	v_fma_f32 v224, -v224, v227, v226
	v_div_fmas_f32 v224, v224, v225, v227
	v_div_fixup_f32 v171, v224, v171, 1.0
	v_mul_f32_e32 v172, s22, v172
	v_mul_f32_e32 v173, s22, v173
	v_fma_f32 v173, -v172, v172, v173
	v_max_f32_e32 v173, 0, v173
	v_add_f32_e32 v173, 0x3727c5ac, v173
	v_mul_f32_e32 v224, 0x4f800000, v173
	v_cmp_gt_f32_e32 vcc, s66, v173
	s_nop 1
	v_cndmask_b32_e32 v173, v173, v224, vcc
	v_sqrt_f32_e32 v224, v173
	s_nop 0
	v_add_u32_e32 v225, -1, v224
	v_fma_f32 v227, -v225, v224, v173
	v_add_u32_e32 v226, 1, v224
	v_cmp_ge_f32_e64 s[16:17], 0, v227
	s_nop 1
	v_cndmask_b32_e64 v225, v224, v225, s[16:17]
	v_fma_f32 v224, -v226, v224, v173
	v_cmp_lt_f32_e64 s[16:17], 0, v224
	s_nop 1
	v_cndmask_b32_e64 v224, v225, v226, s[16:17]
	v_mul_f32_e32 v225, 0x37800000, v224
	v_cndmask_b32_e32 v224, v224, v225, vcc
	v_cmp_class_f32_e32 vcc, v173, v167
	s_nop 1
	v_cndmask_b32_e32 v173, v224, v173, vcc
	v_div_scale_f32 v224, s[16:17], v173, v173, 1.0
	v_rcp_f32_e32 v225, v224
	s_nop 0
	v_fma_f32 v226, -v224, v225, 1.0
	v_fmac_f32_e32 v225, v226, v225
	v_div_scale_f32 v226, vcc, 1.0, v173, 1.0
	v_mul_f32_e32 v227, v226, v225
	v_fma_f32 v228, -v224, v227, v226
	v_fmac_f32_e32 v227, v228, v225
	v_fma_f32 v224, -v224, v227, v226
	v_div_fmas_f32 v224, v224, v225, v227
	v_div_fixup_f32 v173, v224, v173, 1.0
	v_lshrrev_b32_e32 v229, 4, v168
	v_lshlrev_b32_e32 v229, 6, v229
	s_add_i32 s16, s62, 0x20400
	v_add_u32_e32 v229, s16, v229
	s_mov_b64 s[56:57], exec
	s_mov_b32 exec_lo, 0x10001
	s_mov_b32 exec_hi, 0x10001
	ds_write_b64 v229, v[128:129]
	ds_write_b64 v229, v[130:131] offset:8
	ds_write_b64 v229, v[132:133] offset:16
	ds_write_b64 v229, v[134:135] offset:24
	ds_write_b64 v229, v[136:137] offset:32
	ds_write_b64 v229, v[138:139] offset:40
	ds_write_b64 v229, v[170:171] offset:48
	ds_write_b64 v229, v[172:173] offset:56
	s_mov_b64 exec, s[56:57]

; __global__ void __launch_bounds__(NTHR, 2) mega_fwd(Args) {
	.amdhsa_kernel _Z8mega_fwd4Args
		.amdhsa_group_segment_fixed_size 0
		.amdhsa_private_segment_fixed_size 0
		.amdhsa_kernarg_size 448
		.amdhsa_user_sgpr_count 2
		.amdhsa_user_sgpr_dispatch_ptr 0
		.amdhsa_user_sgpr_queue_ptr 0
		.amdhsa_user_sgpr_kernarg_segment_ptr 1
		.amdhsa_user_sgpr_dispatch_id 0
		.amdhsa_user_sgpr_kernarg_preload_length 0
		.amdhsa_user_sgpr_kernarg_preload_offset 0
		.amdhsa_user_sgpr_private_segment_size 0
		.amdhsa_uses_dynamic_stack 0
		.amdhsa_enable_private_segment 0
		.amdhsa_system_sgpr_workgroup_id_x 1
		.amdhsa_system_sgpr_workgroup_id_y 0
		.amdhsa_system_sgpr_workgroup_id_z 0
		.amdhsa_system_sgpr_workgroup_info 0
		.amdhsa_system_vgpr_workitem_id 0
		.amdhsa_next_free_vgpr 256
		.amdhsa_next_free_sgpr 98
		.amdhsa_accum_offset 256
		.amdhsa_reserve_vcc 1
		.amdhsa_float_round_mode_32 0
		.amdhsa_float_round_mode_16_64 0
		.amdhsa_float_denorm_mode_32 3
		.amdhsa_float_denorm_mode_16_64 3
		.amdhsa_dx10_clamp 1
		.amdhsa_ieee_mode 1
		.amdhsa_fp16_overflow 0
		.amdhsa_tg_split 0
		.amdhsa_exception_fp_ieee_invalid_op 0
		.amdhsa_exception_fp_denorm_src 0
		.amdhsa_exception_fp_ieee_div_zero 0
		.amdhsa_exception_fp_ieee_overflow 0
		.amdhsa_exception_fp_ieee_underflow 0
		.amdhsa_exception_fp_ieee_inexact 0
		.amdhsa_exception_int_div_zero 0
	.end_amdhsa_kernel

; __global__ void __launch_bounds__(NTHR, 2) mega_fwd(Args) {
amdhsa.kernels:
  - .agpr_count:     0
    .args:
      - .offset:         0
        .size:           192
        .value_kind:     by_value
      - .offset:         192
        .size:           4
        .value_kind:     hidden_block_count_x
      - .offset:         196
        .size:           4
        .value_kind:     hidden_block_count_y
      - .offset:         200
        .size:           4
        .value_kind:     hidden_block_count_z
      - .offset:         204
        .size:           2
        .value_kind:     hidden_group_size_x
      - .offset:         206
        .size:           2
        .value_kind:     hidden_group_size_y
      - .offset:         208
        .size:           2
        .value_kind:     hidden_group_size_z
      - .offset:         210
        .size:           2
        .value_kind:     hidden_remainder_x
      - .offset:         212
        .size:           2
        .value_kind:     hidden_remainder_y
      - .offset:         214
        .size:           2
        .value_kind:     hidden_remainder_z
      - .offset:         232
        .size:           8
        .value_kind:     hidden_global_offset_x
      - .offset:         240
        .size:           8
        .value_kind:     hidden_global_offset_y
      - .offset:         248
        .size:           8
        .value_kind:     hidden_global_offset_z
      - .offset:         256
        .size:           2
        .value_kind:     hidden_grid_dims
      - .offset:         312
        .size:           4
        .value_kind:     hidden_dynamic_lds_size
    .group_segment_fixed_size: 0
    .kernarg_segment_align: 8
    .kernarg_segment_size: 448
    .language:       OpenCL C
    .language_version:
      - 2
      - 0
    .max_flat_workgroup_size: 512
    .name:           _Z8mega_fwd4Args
    .private_segment_fixed_size: 0
    .sgpr_count:     104
    .sgpr_spill_count: 28
    .symbol:         _Z8mega_fwd4Args.kd
    .uniform_work_group_size: 1
    .uses_dynamic_stack: false
    .vgpr_count:     256
    .vgpr_spill_count: 0
    .wavefront_size: 64
